# combined small reductions + f16-domain key build in the top-k (-560 VALU per lane in stage A/B)
# baseline (speedup 1.0000x reference)
; #define LAS __attribute__((address_space(3)))
; __device__ __forceinline__ unsigned f2key(float f) { const unsigned u = __float_as_uint(f); return (u & 0x80000000u) ? ~u : (u | 0x80000000u); }
; #define CE_DESC(a, b) do { const unsigned _mx = (a) > (b) ? (a) : (b), _mn = (a) > (b) ? (b) : (a); (a) = _mx; (b) = _mn; } while (0)
; __device__ __forceinline__ void sort16_desc(unsigned (&k)[16]) {
; #pragma unroll
;     for (int size = 2; size <= 16; size <<= 1)
; #pragma unroll
;         for (int stride = size >> 1; stride > 0; stride >>= 1)
; #pragma unroll
;             for (int i = 0; i < 16; ++i) { const int j = i ^ stride;
;                 if (j > i) { if ((i & size) == 0) CE_DESC(k[i], k[j]); else CE_DESC(k[j], k[i]); } }
; }
; __device__ __forceinline__ void peer_tile(const Args& A, LAS unsigned char* lds, int tile) {
;     ...
;     LAS unsigned* idx = (LAS unsigned*)(lds + PE_IDX) + (w * 64 + lane) * 33;
;     LAS u32x2* SEL = (LAS u32x2*)(lds + PE_SEL);
;     {
;         const int tg = w & 3, hg = w >> 2, tl = 16 * tg + l15;
;         const size_t m = (size_t)tile * 64 + tl;
;         unsigned LA[4][2][16];
; #pragma unroll
;         for (int hh = 0; hh < 4; ++hh) {
;             const int h = 4 * hg + hh;
; #pragma unroll
;             for (int p = 0; p < 2; ++p) {
;                 const int hp = 2 * h + p;
;                 unsigned k0[16], k1[16];
;                 { const bf16_t* sp = QRY + m * 2048 + hp * 128 + 32 * g;
;                   const u32x4 s0 = *(const u32x4*)sp, s1 = *(const u32x4*)(sp + 8), s2 = *(const u32x4*)(sp + 16), s3 = *(const u32x4*)(sp + 24);
;                   const unsigned sw[16] = {s0.x, s0.y, s0.z, s0.w, s1.x, s1.y, s1.z, s1.w, s2.x, s2.y, s2.z, s2.w, s3.x, s3.y, s3.z, s3.w};
; #pragma unroll
;                   for (int i = 0; i < 16; ++i) {
;                       const float lo = (float)__builtin_bit_cast(_Float16, (unsigned short)(sw[i] & 0xffffu)), hi = (float)__builtin_bit_cast(_Float16, (unsigned short)(sw[i] >> 16));
;                       const unsigned klo = (f2key(lo) & ~127u) | (unsigned)(127 - (32 * g + 2 * i)), khi = (f2key(hi) & ~127u) | (unsigned)(127 - (32 * g + 2 * i + 1));
;                       if (i < 8) { k0[2 * i] = klo; k0[2 * i + 1] = khi; } else { k1[2 * (i - 8)] = klo; k1[2 * (i - 8) + 1] = khi; } } }
;                 sort16_desc(k0); sort16_desc(k1); merge16(k0, k1);
.LBB0_699:
	s_mov_b64 exec, -1
	s_mov_b32 s33, 0x80000000
	s_mov_b32 s40, 0x7fffff80
	s_mov_b32 s41, 0x7fffffff
	s_mov_b32 s42, 0x000f000f
	s_mov_b32 s43, 0x7fff7fff
	s_mov_b32 s44, 0xffff0000
	v_and_b32_e32 v68, 63, v214
	v_lshrrev_b32_e32 v66, 6, v214
	s_nop 0
	v_readfirstlane_b32 s36, v66
	s_lshl_b32 s0, s2, 18
	s_lshl_b32 s1, s36, 9
	s_add_u32 s34, s54, s0
	s_addc_u32 s35, s55, 0
	s_add_u32 s34, s34, s1
	s_addc_u32 s35, s35, 0
	v_lshrrev_b32_e32 v66, 3, v68
	v_and_b32_e32 v64, 7, v68
	v_lshlrev_b32_e32 v64, 4, v64
	v_mul_u32_u24_e32 v65, 0x90, v66
	v_lshl_add_u32 v66, v66, 12, v64
	s_mul_i32 s0, s36, 0x2400
	s_cmp_eq_u32 s36, 7
	s_cselect_b32 s0, 0x21000, s0
	v_add3_u32 v64, v64, v65, s0
	v_mul_u32_u24_e32 v65, 0x90, v68
	v_add_u32_e32 v65, s0, v65
	v_mul_u32_u24_e32 v67, 0x84, v68
	v_lshlrev_b32_e32 v68, 10, v68
	s_lshl_b32 s1, s36, 7
	s_add_i32 s1, s1, 0x11000
	v_add_u32_e32 v67, s0, v67
	v_add_u32_e32 v68, s1, v68
	s_mov_b64 s[38:39], s[34:35]
	global_load_dwordx4 v[0:3], v66, s[38:39] offset:0
	s_add_u32 s38, s38, 0x8000
	s_addc_u32 s39, s39, 0
	global_load_dwordx4 v[4:7], v66, s[38:39] offset:0
	s_add_u32 s38, s38, 0x8000
	s_addc_u32 s39, s39, 0
	global_load_dwordx4 v[8:11], v66, s[38:39] offset:0
	s_add_u32 s38, s38, 0x8000
	s_addc_u32 s39, s39, 0
	global_load_dwordx4 v[12:15], v66, s[38:39] offset:0
	s_add_u32 s38, s38, 0x8000
	s_addc_u32 s39, s39, 0
	global_load_dwordx4 v[16:19], v66, s[38:39] offset:0
	s_add_u32 s38, s38, 0x8000
	s_addc_u32 s39, s39, 0
	global_load_dwordx4 v[20:23], v66, s[38:39] offset:0
	s_add_u32 s38, s38, 0x8000
	s_addc_u32 s39, s39, 0
	global_load_dwordx4 v[24:27], v66, s[38:39] offset:0
	s_add_u32 s38, s38, 0x8000
	s_addc_u32 s39, s39, 0
	global_load_dwordx4 v[28:31], v66, s[38:39] offset:0
	s_mov_b64 s[38:39], s[34:35]
	global_load_dwordx4 v[32:35], v66, s[38:39] offset:128
	s_add_u32 s38, s38, 0x8000
	s_addc_u32 s39, s39, 0
	global_load_dwordx4 v[36:39], v66, s[38:39] offset:128
	s_add_u32 s38, s38, 0x8000
	s_addc_u32 s39, s39, 0
	global_load_dwordx4 v[40:43], v66, s[38:39] offset:128
	s_add_u32 s38, s38, 0x8000
	s_addc_u32 s39, s39, 0
	global_load_dwordx4 v[44:47], v66, s[38:39] offset:128
	s_add_u32 s38, s38, 0x8000
	s_addc_u32 s39, s39, 0
	global_load_dwordx4 v[48:51], v66, s[38:39] offset:128
	s_add_u32 s38, s38, 0x8000
	s_addc_u32 s39, s39, 0
	global_load_dwordx4 v[52:55], v66, s[38:39] offset:128
	s_add_u32 s38, s38, 0x8000
	s_addc_u32 s39, s39, 0
	global_load_dwordx4 v[56:59], v66, s[38:39] offset:128
	s_add_u32 s38, s38, 0x8000
	s_addc_u32 s39, s39, 0
	global_load_dwordx4 v[60:63], v66, s[38:39] offset:128
	s_waitcnt vmcnt(8)
	ds_write_b128 v64, v[0:3] offset:0
	ds_write_b128 v64, v[4:7] offset:1152
	ds_write_b128 v64, v[8:11] offset:2304
	ds_write_b128 v64, v[12:15] offset:3456
	ds_write_b128 v64, v[16:19] offset:4608
	ds_write_b128 v64, v[20:23] offset:5760
	ds_write_b128 v64, v[24:27] offset:6912
	ds_write_b128 v64, v[28:31] offset:8064
	s_waitcnt lgkmcnt(0)
	ds_read_b128 v[0:3], v65 offset:0
	ds_read_b128 v[4:7], v65 offset:16
	ds_read_b128 v[8:11], v65 offset:32
	ds_read_b128 v[12:15], v65 offset:48
	ds_read_b128 v[16:19], v65 offset:64
	ds_read_b128 v[20:23], v65 offset:80
	ds_read_b128 v[24:27], v65 offset:96
	ds_read_b128 v[28:31], v65 offset:112
	s_waitcnt lgkmcnt(0)
	v_pk_ashrrev_i16 v70, s42, v0
	v_bitop3_b32 v70, v0, v70, s43 bitop3:0x2d
	v_lshl_or_b32 v71, v70, 16, 63
	v_and_or_b32 v72, v70, s44, 62
	v_pk_ashrrev_i16 v70, s42, v1
	v_bitop3_b32 v70, v1, v70, s43 bitop3:0x2d
	v_lshl_or_b32 v73, v70, 16, 61
	v_and_or_b32 v74, v70, s44, 60
	v_pk_ashrrev_i16 v70, s42, v2
	v_bitop3_b32 v70, v2, v70, s43 bitop3:0x2d
	v_lshl_or_b32 v75, v70, 16, 59
	v_and_or_b32 v76, v70, s44, 58
	v_pk_ashrrev_i16 v70, s42, v3
	v_bitop3_b32 v70, v3, v70, s43 bitop3:0x2d
	v_lshl_or_b32 v77, v70, 16, 57
	v_and_or_b32 v78, v70, s44, 56
	v_pk_ashrrev_i16 v70, s42, v4
	v_bitop3_b32 v70, v4, v70, s43 bitop3:0x2d
	v_lshl_or_b32 v79, v70, 16, 55
	v_and_or_b32 v80, v70, s44, 54
	v_pk_ashrrev_i16 v70, s42, v5
	v_bitop3_b32 v70, v5, v70, s43 bitop3:0x2d
	v_lshl_or_b32 v81, v70, 16, 53
	v_and_or_b32 v82, v70, s44, 52
	v_pk_ashrrev_i16 v70, s42, v6
	v_bitop3_b32 v70, v6, v70, s43 bitop3:0x2d
	v_lshl_or_b32 v83, v70, 16, 51
	v_and_or_b32 v84, v70, s44, 50
	v_pk_ashrrev_i16 v70, s42, v7
	v_bitop3_b32 v70, v7, v70, s43 bitop3:0x2d
	v_lshl_or_b32 v85, v70, 16, 49
	v_and_or_b32 v86, v70, s44, 48
	v_max_u32_e32 v70, v71, v84
	v_min_u32_e32 v84, v71, v84
	v_max_u32_e32 v71, v72, v83
	v_min_u32_e32 v83, v72, v83
	v_max_u32_e32 v72, v73, v86
	v_min_u32_e32 v86, v73, v86
	v_max_u32_e32 v73, v74, v85
	v_min_u32_e32 v85, v74, v85
	v_max_u32_e32 v74, v75, v79
	v_min_u32_e32 v79, v75, v79
	v_max_u32_e32 v75, v76, v77
	v_min_u32_e32 v77, v76, v77
	v_max_u32_e32 v76, v78, v82
	v_min_u32_e32 v82, v78, v82
	v_max_u32_e32 v78, v80, v81
	v_min_u32_e32 v81, v80, v81
	v_max_u32_e32 v80, v70, v75
	v_min_u32_e32 v75, v70, v75
	v_max_u32_e32 v70, v71, v76
	v_min_u32_e32 v76, v71, v76
	v_max_u32_e32 v71, v72, v78
	v_min_u32_e32 v78, v72, v78
	v_max_u32_e32 v72, v73, v74
	v_min_u32_e32 v74, v73, v74
	v_max_u32_e32 v73, v77, v84
	v_min_u32_e32 v84, v77, v84
	v_max_u32_e32 v77, v79, v85
	v_min_u32_e32 v85, v79, v85
	v_max_u32_e32 v79, v81, v86
	v_min_u32_e32 v86, v81, v86
	v_max_u32_e32 v81, v82, v83
	v_min_u32_e32 v83, v82, v83
	v_max_u32_e32 v82, v80, v70
	v_min_u32_e32 v70, v80, v70
	v_max_u32_e32 v80, v71, v72
	v_min_u32_e32 v72, v71, v72
	v_max_u32_e32 v71, v74, v75
	v_min_u32_e32 v75, v74, v75
	v_max_u32_e32 v74, v73, v77
	v_min_u32_e32 v77, v73, v77
	v_max_u32_e32 v73, v76, v78
	v_min_u32_e32 v78, v76, v78
	v_max_u32_e32 v76, v79, v81
; __device__ __forceinline__ unsigned f2key(float f) { const unsigned u = __float_as_uint(f); return (u & 0x80000000u) ? ~u : (u | 0x80000000u); }
; #define CE_DESC(a, b) do { const unsigned _mx = (a) > (b) ? (a) : (b), _mn = (a) > (b) ? (b) : (a); (a) = _mx; (b) = _mn; } while (0)
; __device__ __forceinline__ void sort16_desc(unsigned (&k)[16]) {
; #pragma unroll
;     for (int size = 2; size <= 16; size <<= 1)
; #pragma unroll
;         for (int stride = size >> 1; stride > 0; stride >>= 1)
; #pragma unroll
;             for (int i = 0; i < 16; ++i) { const int j = i ^ stride;
;                 if (j > i) { if ((i & size) == 0) CE_DESC(k[i], k[j]); else CE_DESC(k[j], k[i]); } }
; }
; __device__ __forceinline__ void merge16(unsigned (&a)[16], const unsigned (&b)[16]) {
; #pragma unroll
;     for (int i = 0; i < 16; ++i) a[i] = a[i] > b[15 - i] ? a[i] : b[15 - i];
; #pragma unroll
;     for (int stride = 8; stride > 0; stride >>= 1)
; #pragma unroll
;         for (int i = 0; i < 16; ++i) { const int j = i ^ stride; if (j > i) CE_DESC(a[i], a[j]); }
; }
; __device__ __forceinline__ void peer_tile(const Args& A, LAS unsigned char* lds, int tile) {
;     ...
;                   for (int i = 0; i < 16; ++i) {
;                       const float lo = (float)__builtin_bit_cast(_Float16, (unsigned short)(sw[i] & 0xffffu)), hi = (float)__builtin_bit_cast(_Float16, (unsigned short)(sw[i] >> 16));
;                       const unsigned klo = (f2key(lo) & ~127u) | (unsigned)(127 - (32 * g + 2 * i)), khi = (f2key(hi) & ~127u) | (unsigned)(127 - (32 * g + 2 * i + 1));
;                       if (i < 8) { k0[2 * i] = klo; k0[2 * i + 1] = khi; } else { k1[2 * (i - 8)] = klo; k1[2 * (i - 8) + 1] = khi; } } }
;                 sort16_desc(k0); sort16_desc(k1); merge16(k0, k1);
	v_min_u32_e32 v81, v79, v81
	v_max_u32_e32 v79, v83, v84
	v_min_u32_e32 v84, v83, v84
	v_max_u32_e32 v83, v85, v86
	v_min_u32_e32 v86, v85, v86
	v_max_u32_e32 v85, v82, v80
	v_min_u32_e32 v80, v82, v80
	v_max_u32_e32 v82, v70, v72
	v_min_u32_e32 v72, v70, v72
	v_max_u32_e32 v70, v71, v76
	v_min_u32_e32 v76, v71, v76
	v_max_u32_e32 v71, v75, v81
	v_min_u32_e32 v81, v75, v81
	v_max_u32_e32 v75, v74, v73
	v_min_u32_e32 v73, v74, v73
	v_max_u32_e32 v74, v77, v78
	v_min_u32_e32 v78, v77, v78
	v_max_u32_e32 v77, v79, v83
	v_min_u32_e32 v83, v79, v83
	v_max_u32_e32 v79, v84, v86
	v_min_u32_e32 v86, v84, v86
	v_max_u32_e32 v84, v82, v80
	v_min_u32_e32 v80, v82, v80
	v_max_u32_e32 v82, v72, v77
	v_min_u32_e32 v77, v72, v77
	v_max_u32_e32 v72, v70, v75
	v_min_u32_e32 v75, v70, v75
	v_max_u32_e32 v70, v71, v73
	v_min_u32_e32 v73, v71, v73
	v_max_u32_e32 v71, v74, v76
	v_min_u32_e32 v76, v74, v76
	v_max_u32_e32 v74, v78, v81
	v_min_u32_e32 v81, v78, v81
	v_max_u32_e32 v78, v79, v83
	v_min_u32_e32 v83, v79, v83
	v_max_u32_e32 v79, v84, v72
	v_min_u32_e32 v72, v84, v72
	v_max_u32_e32 v84, v80, v75
	v_min_u32_e32 v75, v80, v75
	v_max_u32_e32 v80, v70, v71
	v_min_u32_e32 v71, v70, v71
	v_max_u32_e32 v70, v73, v76
	v_min_u32_e32 v76, v73, v76
	v_max_u32_e32 v73, v74, v78
	v_min_u32_e32 v78, v74, v78
	v_max_u32_e32 v74, v81, v83
	v_min_u32_e32 v83, v81, v83
	v_max_u32_e32 v81, v84, v72
	v_min_u32_e32 v72, v84, v72
	v_max_u32_e32 v84, v82, v75
	v_min_u32_e32 v75, v82, v75
	v_max_u32_e32 v82, v73, v77
	v_min_u32_e32 v77, v73, v77
	v_max_u32_e32 v73, v74, v78
	v_min_u32_e32 v78, v74, v78
	v_max_u32_e32 v74, v84, v80
	v_min_u32_e32 v80, v84, v80
	v_max_u32_e32 v84, v75, v71
	v_min_u32_e32 v71, v75, v71
	v_max_u32_e32 v75, v70, v82
	v_min_u32_e32 v82, v70, v82
	v_max_u32_e32 v70, v76, v77
	v_min_u32_e32 v77, v76, v77
	v_max_u32_e32 v76, v74, v72
	v_min_u32_e32 v72, v74, v72
	v_max_u32_e32 v74, v80, v84
	v_min_u32_e32 v84, v80, v84
	v_max_u32_e32 v80, v75, v71
	v_min_u32_e32 v71, v75, v71
	v_max_u32_e32 v75, v82, v70
	v_min_u32_e32 v70, v82, v70
	v_max_u32_e32 v82, v73, v77
	v_min_u32_e32 v77, v73, v77
	v_max_u32_e32 v73, v84, v80
	v_min_u32_e32 v80, v84, v80
	v_max_u32_e32 v84, v71, v75
	v_min_u32_e32 v75, v71, v75
	v_pk_ashrrev_i16 v71, s42, v8
	v_bitop3_b32 v71, v8, v71, s43 bitop3:0x2d
	v_lshl_or_b32 v87, v71, 16, 47
	v_and_or_b32 v88, v71, s44, 46
	v_pk_ashrrev_i16 v71, s42, v9
	v_bitop3_b32 v71, v9, v71, s43 bitop3:0x2d
	v_lshl_or_b32 v89, v71, 16, 45
	v_and_or_b32 v90, v71, s44, 44
	v_pk_ashrrev_i16 v71, s42, v10
	v_bitop3_b32 v71, v10, v71, s43 bitop3:0x2d
	v_lshl_or_b32 v91, v71, 16, 43
	v_and_or_b32 v92, v71, s44, 42
	v_pk_ashrrev_i16 v71, s42, v11
	v_bitop3_b32 v71, v11, v71, s43 bitop3:0x2d
	v_lshl_or_b32 v93, v71, 16, 41
	v_and_or_b32 v94, v71, s44, 40
	v_pk_ashrrev_i16 v71, s42, v12
	v_bitop3_b32 v71, v12, v71, s43 bitop3:0x2d
	v_lshl_or_b32 v95, v71, 16, 39
	v_and_or_b32 v96, v71, s44, 38
	v_pk_ashrrev_i16 v71, s42, v13
	v_bitop3_b32 v71, v13, v71, s43 bitop3:0x2d
	v_lshl_or_b32 v97, v71, 16, 37
	v_and_or_b32 v98, v71, s44, 36
	v_pk_ashrrev_i16 v71, s42, v14
	v_bitop3_b32 v71, v14, v71, s43 bitop3:0x2d
	v_lshl_or_b32 v99, v71, 16, 35
	v_and_or_b32 v100, v71, s44, 34
	v_pk_ashrrev_i16 v71, s42, v15
	v_bitop3_b32 v71, v15, v71, s43 bitop3:0x2d
	v_lshl_or_b32 v101, v71, 16, 33
	v_and_or_b32 v102, v71, s44, 32
	v_max_u32_e32 v71, v87, v100
	v_min_u32_e32 v100, v87, v100
	v_max_u32_e32 v87, v88, v99
	v_min_u32_e32 v99, v88, v99
	v_max_u32_e32 v88, v89, v102
	v_min_u32_e32 v102, v89, v102
	v_max_u32_e32 v89, v90, v101
	v_min_u32_e32 v101, v90, v101
	v_max_u32_e32 v90, v91, v95
	v_min_u32_e32 v95, v91, v95
	v_max_u32_e32 v91, v92, v93
	v_min_u32_e32 v93, v92, v93
	v_max_u32_e32 v92, v94, v98
	v_min_u32_e32 v98, v94, v98
	v_max_u32_e32 v94, v96, v97
	v_min_u32_e32 v97, v96, v97
	v_max_u32_e32 v96, v71, v91
	v_min_u32_e32 v91, v71, v91
	v_max_u32_e32 v71, v87, v92
	v_min_u32_e32 v92, v87, v92
	v_max_u32_e32 v87, v88, v94
	v_min_u32_e32 v94, v88, v94
	v_max_u32_e32 v88, v89, v90
	v_min_u32_e32 v90, v89, v90
	v_max_u32_e32 v89, v93, v100
	v_min_u32_e32 v100, v93, v100
	v_max_u32_e32 v93, v95, v101
	v_min_u32_e32 v101, v95, v101
	v_max_u32_e32 v95, v97, v102
	v_min_u32_e32 v102, v97, v102
	v_max_u32_e32 v97, v98, v99
	v_min_u32_e32 v99, v98, v99
	v_max_u32_e32 v98, v96, v71
	v_min_u32_e32 v71, v96, v71
	v_max_u32_e32 v96, v87, v88
	v_min_u32_e32 v88, v87, v88
	v_max_u32_e32 v87, v90, v91
	v_min_u32_e32 v91, v90, v91
	v_max_u32_e32 v90, v89, v93
	v_min_u32_e32 v93, v89, v93
	v_max_u32_e32 v89, v92, v94
	v_min_u32_e32 v94, v92, v94
	v_max_u32_e32 v92, v95, v97
	v_min_u32_e32 v97, v95, v97
	v_max_u32_e32 v95, v99, v100
	v_min_u32_e32 v100, v99, v100
	v_max_u32_e32 v99, v101, v102
	v_min_u32_e32 v102, v101, v102
	v_max_u32_e32 v101, v98, v96
	v_min_u32_e32 v96, v98, v96
	v_max_u32_e32 v98, v71, v88
	v_min_u32_e32 v88, v71, v88
	v_max_u32_e32 v71, v87, v92
	v_min_u32_e32 v92, v87, v92
	v_max_u32_e32 v87, v91, v97
	v_min_u32_e32 v97, v91, v97
	v_max_u32_e32 v91, v90, v89
	v_min_u32_e32 v89, v90, v89
	v_max_u32_e32 v90, v93, v94
	v_min_u32_e32 v94, v93, v94
	v_max_u32_e32 v93, v95, v99
	v_min_u32_e32 v99, v95, v99
	v_max_u32_e32 v95, v100, v102
	v_min_u32_e32 v102, v100, v102
	v_max_u32_e32 v100, v98, v96
	v_min_u32_e32 v96, v98, v96
	v_max_u32_e32 v98, v88, v93
	v_min_u32_e32 v93, v88, v93
	v_max_u32_e32 v88, v71, v91
	v_min_u32_e32 v91, v71, v91
	v_max_u32_e32 v71, v87, v89
	v_min_u32_e32 v89, v87, v89
	v_max_u32_e32 v87, v90, v92
	v_min_u32_e32 v92, v90, v92
	v_max_u32_e32 v90, v94, v97
	v_min_u32_e32 v97, v94, v97
	v_max_u32_e32 v94, v95, v99
; __device__ __forceinline__ unsigned f2key(float f) { const unsigned u = __float_as_uint(f); return (u & 0x80000000u) ? ~u : (u | 0x80000000u); }
; #define CE_DESC(a, b) do { const unsigned _mx = (a) > (b) ? (a) : (b), _mn = (a) > (b) ? (b) : (a); (a) = _mx; (b) = _mn; } while (0)
; __device__ __forceinline__ void sort16_desc(unsigned (&k)[16]) {
; #pragma unroll
;     for (int size = 2; size <= 16; size <<= 1)
; #pragma unroll
;         for (int stride = size >> 1; stride > 0; stride >>= 1)
; #pragma unroll
;             for (int i = 0; i < 16; ++i) { const int j = i ^ stride;
;                 if (j > i) { if ((i & size) == 0) CE_DESC(k[i], k[j]); else CE_DESC(k[j], k[i]); } }
; }
; __device__ __forceinline__ void merge16(unsigned (&a)[16], const unsigned (&b)[16]) {
; #pragma unroll
;     for (int i = 0; i < 16; ++i) a[i] = a[i] > b[15 - i] ? a[i] : b[15 - i];
; #pragma unroll
;     for (int stride = 8; stride > 0; stride >>= 1)
; #pragma unroll
;         for (int i = 0; i < 16; ++i) { const int j = i ^ stride; if (j > i) CE_DESC(a[i], a[j]); }
; }
; __device__ __forceinline__ void peer_tile(const Args& A, LAS unsigned char* lds, int tile) {
;     ...
;                   for (int i = 0; i < 16; ++i) {
;                       const float lo = (float)__builtin_bit_cast(_Float16, (unsigned short)(sw[i] & 0xffffu)), hi = (float)__builtin_bit_cast(_Float16, (unsigned short)(sw[i] >> 16));
;                       const unsigned klo = (f2key(lo) & ~127u) | (unsigned)(127 - (32 * g + 2 * i)), khi = (f2key(hi) & ~127u) | (unsigned)(127 - (32 * g + 2 * i + 1));
;                       if (i < 8) { k0[2 * i] = klo; k0[2 * i + 1] = khi; } else { k1[2 * (i - 8)] = klo; k1[2 * (i - 8) + 1] = khi; } } }
;                 sort16_desc(k0); sort16_desc(k1); merge16(k0, k1);
	v_min_u32_e32 v99, v95, v99
	v_max_u32_e32 v95, v100, v88
	v_min_u32_e32 v88, v100, v88
	v_max_u32_e32 v100, v96, v91
	v_min_u32_e32 v91, v96, v91
	v_max_u32_e32 v96, v71, v87
	v_min_u32_e32 v87, v71, v87
	v_max_u32_e32 v71, v89, v92
	v_min_u32_e32 v92, v89, v92
	v_max_u32_e32 v89, v90, v94
	v_min_u32_e32 v94, v90, v94
	v_max_u32_e32 v90, v97, v99
	v_min_u32_e32 v99, v97, v99
	v_max_u32_e32 v97, v100, v88
	v_min_u32_e32 v88, v100, v88
	v_max_u32_e32 v100, v98, v91
	v_min_u32_e32 v91, v98, v91
	v_max_u32_e32 v98, v89, v93
	v_min_u32_e32 v93, v89, v93
	v_max_u32_e32 v89, v90, v94
	v_min_u32_e32 v94, v90, v94
	v_max_u32_e32 v90, v100, v96
	v_min_u32_e32 v96, v100, v96
	v_max_u32_e32 v100, v91, v87
	v_min_u32_e32 v87, v91, v87
	v_max_u32_e32 v91, v71, v98
	v_min_u32_e32 v98, v71, v98
	v_max_u32_e32 v71, v92, v93
	v_min_u32_e32 v93, v92, v93
	v_max_u32_e32 v92, v90, v88
	v_min_u32_e32 v88, v90, v88
	v_max_u32_e32 v90, v96, v100
	v_min_u32_e32 v100, v96, v100
	v_max_u32_e32 v96, v91, v87
	v_min_u32_e32 v87, v91, v87
	v_max_u32_e32 v91, v98, v71
	v_min_u32_e32 v71, v98, v71
	v_max_u32_e32 v98, v89, v93
	v_min_u32_e32 v93, v89, v93
	v_max_u32_e32 v89, v100, v96
	v_min_u32_e32 v96, v100, v96
	v_max_u32_e32 v100, v87, v91
	v_min_u32_e32 v91, v87, v91
	v_max_u32_e32 v85, v85, v102
	v_max_u32_e32 v79, v79, v99
	v_max_u32_e32 v81, v81, v94
	v_max_u32_e32 v76, v76, v93
	v_max_u32_e32 v72, v72, v98
	v_max_u32_e32 v74, v74, v71
	v_max_u32_e32 v73, v73, v91
	v_max_u32_e32 v80, v80, v100
	v_max_u32_e32 v84, v84, v96
	v_max_u32_e32 v75, v75, v89
	v_max_u32_e32 v70, v70, v90
	v_max_u32_e32 v82, v82, v88
	v_max_u32_e32 v77, v77, v92
	v_max_u32_e32 v78, v78, v97
	v_max_u32_e32 v83, v83, v95
	v_max_u32_e32 v86, v86, v101
	v_max_u32_e32 v102, v85, v84
	v_min_u32_e32 v84, v85, v84
	v_max_u32_e32 v85, v79, v75
	v_min_u32_e32 v75, v79, v75
	v_max_u32_e32 v79, v81, v70
	v_min_u32_e32 v70, v81, v70
	v_max_u32_e32 v81, v76, v82
	v_min_u32_e32 v82, v76, v82
	v_max_u32_e32 v76, v72, v77
	v_min_u32_e32 v77, v72, v77
	v_max_u32_e32 v72, v74, v78
	v_min_u32_e32 v78, v74, v78
	v_max_u32_e32 v74, v73, v83
	v_min_u32_e32 v83, v73, v83
	v_max_u32_e32 v73, v80, v86
	v_min_u32_e32 v86, v80, v86
	v_max_u32_e32 v80, v102, v76
	v_min_u32_e32 v76, v102, v76
	v_max_u32_e32 v102, v85, v72
	v_min_u32_e32 v72, v85, v72
	v_max_u32_e32 v85, v79, v74
	v_min_u32_e32 v74, v79, v74
	v_max_u32_e32 v79, v81, v73
	v_min_u32_e32 v73, v81, v73
	v_max_u32_e32 v81, v84, v77
	v_min_u32_e32 v77, v84, v77
	v_max_u32_e32 v84, v75, v78
	v_min_u32_e32 v78, v75, v78
	v_max_u32_e32 v75, v70, v83
	v_min_u32_e32 v83, v70, v83
	v_max_u32_e32 v70, v82, v86
	v_min_u32_e32 v86, v82, v86
	v_max_u32_e32 v82, v80, v85
	v_min_u32_e32 v85, v80, v85
	v_max_u32_e32 v80, v102, v79
	v_min_u32_e32 v79, v102, v79
	v_max_u32_e32 v102, v76, v74
	v_min_u32_e32 v74, v76, v74
	v_max_u32_e32 v76, v72, v73
	v_min_u32_e32 v73, v72, v73
	v_max_u32_e32 v72, v81, v75
	v_min_u32_e32 v75, v81, v75
	v_max_u32_e32 v81, v84, v70
	v_min_u32_e32 v70, v84, v70
	v_max_u32_e32 v84, v77, v83
	v_min_u32_e32 v83, v77, v83
	v_max_u32_e32 v77, v78, v86
	v_min_u32_e32 v86, v78, v86
	v_max_u32_e32 v78, v82, v80
	v_min_u32_e32 v80, v82, v80
	v_max_u32_e32 v82, v85, v79
	v_min_u32_e32 v79, v85, v79
	v_max_u32_e32 v85, v102, v76
	v_min_u32_e32 v76, v102, v76
	v_max_u32_e32 v102, v74, v73
	v_min_u32_e32 v73, v74, v73
	v_max_u32_e32 v74, v72, v81
	v_min_u32_e32 v81, v72, v81
	v_max_u32_e32 v72, v75, v70
	v_min_u32_e32 v70, v75, v70
	v_max_u32_e32 v75, v84, v77
	v_min_u32_e32 v77, v84, v77
	v_max_u32_e32 v84, v83, v86
	v_min_u32_e32 v86, v83, v86
	v_pk_ashrrev_i16 v83, s42, v16
	v_bitop3_b32 v83, v16, v83, s43 bitop3:0x2d
	v_lshl_or_b32 v99, v83, 16, 31
	v_and_or_b32 v94, v83, s44, 30
	v_pk_ashrrev_i16 v83, s42, v17
	v_bitop3_b32 v83, v17, v83, s43 bitop3:0x2d
	v_lshl_or_b32 v93, v83, 16, 29
	v_and_or_b32 v98, v83, s44, 28
	v_pk_ashrrev_i16 v83, s42, v18
	v_bitop3_b32 v83, v18, v83, s43 bitop3:0x2d
	v_lshl_or_b32 v71, v83, 16, 27
	v_and_or_b32 v91, v83, s44, 26
	v_pk_ashrrev_i16 v83, s42, v19
	v_bitop3_b32 v83, v19, v83, s43 bitop3:0x2d
	v_lshl_or_b32 v100, v83, 16, 25
	v_and_or_b32 v96, v83, s44, 24
	v_pk_ashrrev_i16 v83, s42, v20
	v_bitop3_b32 v83, v20, v83, s43 bitop3:0x2d
	v_lshl_or_b32 v89, v83, 16, 23
	v_and_or_b32 v90, v83, s44, 22
	v_pk_ashrrev_i16 v83, s42, v21
	v_bitop3_b32 v83, v21, v83, s43 bitop3:0x2d
	v_lshl_or_b32 v88, v83, 16, 21
	v_and_or_b32 v92, v83, s44, 20
	v_pk_ashrrev_i16 v83, s42, v22
	v_bitop3_b32 v83, v22, v83, s43 bitop3:0x2d
	v_lshl_or_b32 v97, v83, 16, 19
	v_and_or_b32 v95, v83, s44, 18
	v_pk_ashrrev_i16 v83, s42, v23
	v_bitop3_b32 v83, v23, v83, s43 bitop3:0x2d
	v_lshl_or_b32 v101, v83, 16, 17
	v_and_or_b32 v87, v83, s44, 16
	v_max_u32_e32 v83, v99, v95
	v_min_u32_e32 v95, v99, v95
	v_max_u32_e32 v99, v94, v97
	v_min_u32_e32 v97, v94, v97
	v_max_u32_e32 v94, v93, v87
	v_min_u32_e32 v87, v93, v87
	v_max_u32_e32 v93, v98, v101
	v_min_u32_e32 v101, v98, v101
	v_max_u32_e32 v98, v71, v89
	v_min_u32_e32 v89, v71, v89
	v_max_u32_e32 v71, v91, v100
	v_min_u32_e32 v100, v91, v100
	v_max_u32_e32 v91, v96, v92
	v_min_u32_e32 v92, v96, v92
	v_max_u32_e32 v96, v90, v88
	v_min_u32_e32 v88, v90, v88
	v_max_u32_e32 v90, v83, v71
	v_min_u32_e32 v71, v83, v71
	v_max_u32_e32 v83, v99, v91
	v_min_u32_e32 v91, v99, v91
	v_max_u32_e32 v99, v94, v96
	v_min_u32_e32 v96, v94, v96
	v_max_u32_e32 v94, v93, v98
	v_min_u32_e32 v98, v93, v98
	v_max_u32_e32 v93, v100, v95
	v_min_u32_e32 v95, v100, v95
	v_max_u32_e32 v100, v89, v101
	v_min_u32_e32 v101, v89, v101
	v_max_u32_e32 v89, v88, v87
	v_min_u32_e32 v87, v88, v87
	v_max_u32_e32 v88, v92, v97
; __device__ __forceinline__ unsigned f2key(float f) { const unsigned u = __float_as_uint(f); return (u & 0x80000000u) ? ~u : (u | 0x80000000u); }
; #define CE_DESC(a, b) do { const unsigned _mx = (a) > (b) ? (a) : (b), _mn = (a) > (b) ? (b) : (a); (a) = _mx; (b) = _mn; } while (0)
; __device__ __forceinline__ void sort16_desc(unsigned (&k)[16]) {
; #pragma unroll
;     for (int size = 2; size <= 16; size <<= 1)
; #pragma unroll
;         for (int stride = size >> 1; stride > 0; stride >>= 1)
; #pragma unroll
;             for (int i = 0; i < 16; ++i) { const int j = i ^ stride;
;                 if (j > i) { if ((i & size) == 0) CE_DESC(k[i], k[j]); else CE_DESC(k[j], k[i]); } }
; }
; __device__ __forceinline__ void merge16(unsigned (&a)[16], const unsigned (&b)[16]) {
; #pragma unroll
;     for (int i = 0; i < 16; ++i) a[i] = a[i] > b[15 - i] ? a[i] : b[15 - i];
; #pragma unroll
;     for (int stride = 8; stride > 0; stride >>= 1)
; #pragma unroll
;         for (int i = 0; i < 16; ++i) { const int j = i ^ stride; if (j > i) CE_DESC(a[i], a[j]); }
; }
; __device__ __forceinline__ void peer_tile(const Args& A, LAS unsigned char* lds, int tile) {
;     ...
;                   for (int i = 0; i < 16; ++i) {
;                       const float lo = (float)__builtin_bit_cast(_Float16, (unsigned short)(sw[i] & 0xffffu)), hi = (float)__builtin_bit_cast(_Float16, (unsigned short)(sw[i] >> 16));
;                       const unsigned klo = (f2key(lo) & ~127u) | (unsigned)(127 - (32 * g + 2 * i)), khi = (f2key(hi) & ~127u) | (unsigned)(127 - (32 * g + 2 * i + 1));
;                       if (i < 8) { k0[2 * i] = klo; k0[2 * i + 1] = khi; } else { k1[2 * (i - 8)] = klo; k1[2 * (i - 8) + 1] = khi; } } }
;                 sort16_desc(k0); sort16_desc(k1); merge16(k0, k1);
	v_min_u32_e32 v97, v92, v97
	v_max_u32_e32 v92, v90, v83
	v_min_u32_e32 v83, v90, v83
	v_max_u32_e32 v90, v99, v94
	v_min_u32_e32 v94, v99, v94
	v_max_u32_e32 v99, v98, v71
	v_min_u32_e32 v71, v98, v71
	v_max_u32_e32 v98, v93, v100
	v_min_u32_e32 v100, v93, v100
	v_max_u32_e32 v93, v91, v96
	v_min_u32_e32 v96, v91, v96
	v_max_u32_e32 v91, v89, v88
	v_min_u32_e32 v88, v89, v88
	v_max_u32_e32 v89, v97, v95
	v_min_u32_e32 v95, v97, v95
	v_max_u32_e32 v97, v101, v87
	v_min_u32_e32 v87, v101, v87
	v_max_u32_e32 v101, v92, v90
	v_min_u32_e32 v90, v92, v90
	v_max_u32_e32 v92, v83, v94
	v_min_u32_e32 v94, v83, v94
	v_max_u32_e32 v83, v99, v91
	v_min_u32_e32 v91, v99, v91
	v_max_u32_e32 v99, v71, v88
	v_min_u32_e32 v88, v71, v88
	v_max_u32_e32 v71, v98, v93
	v_min_u32_e32 v93, v98, v93
	v_max_u32_e32 v98, v100, v96
	v_min_u32_e32 v96, v100, v96
	v_max_u32_e32 v100, v89, v97
	v_min_u32_e32 v97, v89, v97
	v_max_u32_e32 v89, v95, v87
	v_min_u32_e32 v87, v95, v87
	v_max_u32_e32 v95, v92, v90
	v_min_u32_e32 v90, v92, v90
	v_max_u32_e32 v92, v94, v100
	v_min_u32_e32 v100, v94, v100
	v_max_u32_e32 v94, v83, v71
	v_min_u32_e32 v71, v83, v71
	v_max_u32_e32 v83, v99, v93
	v_min_u32_e32 v93, v99, v93
	v_max_u32_e32 v99, v98, v91
	v_min_u32_e32 v91, v98, v91
	v_max_u32_e32 v98, v96, v88
	v_min_u32_e32 v88, v96, v88
	v_max_u32_e32 v96, v89, v97
	v_min_u32_e32 v97, v89, v97
	v_max_u32_e32 v89, v95, v94
	v_min_u32_e32 v94, v95, v94
	v_max_u32_e32 v95, v90, v71
	v_min_u32_e32 v71, v90, v71
	v_max_u32_e32 v90, v83, v99
	v_min_u32_e32 v99, v83, v99
	v_max_u32_e32 v83, v93, v91
	v_min_u32_e32 v91, v93, v91
	v_max_u32_e32 v93, v98, v96
	v_min_u32_e32 v96, v98, v96
	v_max_u32_e32 v98, v88, v97
	v_min_u32_e32 v97, v88, v97
	v_max_u32_e32 v88, v95, v94
	v_min_u32_e32 v94, v95, v94
	v_max_u32_e32 v95, v92, v71
	v_min_u32_e32 v71, v92, v71
	v_max_u32_e32 v92, v93, v100
	v_min_u32_e32 v100, v93, v100
	v_max_u32_e32 v93, v98, v96
	v_min_u32_e32 v96, v98, v96
	v_max_u32_e32 v98, v95, v90
	v_min_u32_e32 v90, v95, v90
	v_max_u32_e32 v95, v71, v99
	v_min_u32_e32 v99, v71, v99
	v_max_u32_e32 v71, v83, v92
	v_min_u32_e32 v92, v83, v92
	v_max_u32_e32 v83, v91, v100
	v_min_u32_e32 v100, v91, v100
	v_max_u32_e32 v91, v98, v94
	v_min_u32_e32 v94, v98, v94
	v_max_u32_e32 v98, v90, v95
	v_min_u32_e32 v95, v90, v95
	v_max_u32_e32 v90, v71, v99
	v_min_u32_e32 v99, v71, v99
	v_max_u32_e32 v71, v92, v83
	v_min_u32_e32 v83, v92, v83
	v_max_u32_e32 v92, v93, v100
	v_min_u32_e32 v100, v93, v100
	v_max_u32_e32 v93, v95, v90
	v_min_u32_e32 v90, v95, v90
	v_max_u32_e32 v95, v99, v71
	v_min_u32_e32 v71, v99, v71
	v_max_u32_e32 v78, v78, v87
	v_max_u32_e32 v80, v80, v97
	v_max_u32_e32 v82, v82, v96
	v_max_u32_e32 v79, v79, v100
	v_max_u32_e32 v85, v85, v92
	v_max_u32_e32 v76, v76, v83
	v_max_u32_e32 v102, v102, v71
	v_max_u32_e32 v73, v73, v95
	v_max_u32_e32 v74, v74, v90
	v_max_u32_e32 v81, v81, v93
	v_max_u32_e32 v72, v72, v98
	v_max_u32_e32 v70, v70, v94
	v_max_u32_e32 v75, v75, v91
	v_max_u32_e32 v77, v77, v88
	v_max_u32_e32 v84, v84, v89
	v_max_u32_e32 v86, v86, v101
	v_max_u32_e32 v87, v78, v74
	v_min_u32_e32 v74, v78, v74
	v_max_u32_e32 v78, v80, v81
	v_min_u32_e32 v81, v80, v81
	v_max_u32_e32 v80, v82, v72
	v_min_u32_e32 v72, v82, v72
	v_max_u32_e32 v82, v79, v70
	v_min_u32_e32 v70, v79, v70
	v_max_u32_e32 v79, v85, v75
	v_min_u32_e32 v75, v85, v75
	v_max_u32_e32 v85, v76, v77
	v_min_u32_e32 v77, v76, v77
	v_max_u32_e32 v76, v102, v84
	v_min_u32_e32 v84, v102, v84
	v_max_u32_e32 v102, v73, v86
	v_min_u32_e32 v86, v73, v86
	v_max_u32_e32 v73, v87, v79
	v_min_u32_e32 v79, v87, v79
	v_max_u32_e32 v87, v78, v85
	v_min_u32_e32 v85, v78, v85
	v_max_u32_e32 v78, v80, v76
	v_min_u32_e32 v76, v80, v76
	v_max_u32_e32 v80, v82, v102
	v_min_u32_e32 v102, v82, v102
	v_max_u32_e32 v82, v74, v75
	v_min_u32_e32 v75, v74, v75
	v_max_u32_e32 v74, v81, v77
	v_min_u32_e32 v77, v81, v77
	v_max_u32_e32 v81, v72, v84
	v_min_u32_e32 v84, v72, v84
	v_max_u32_e32 v72, v70, v86
	v_min_u32_e32 v86, v70, v86
	v_max_u32_e32 v70, v73, v78
	v_min_u32_e32 v78, v73, v78
	v_max_u32_e32 v73, v87, v80
	v_min_u32_e32 v80, v87, v80
	v_max_u32_e32 v87, v79, v76
	v_min_u32_e32 v76, v79, v76
	v_max_u32_e32 v79, v85, v102
	v_min_u32_e32 v102, v85, v102
	v_max_u32_e32 v85, v82, v81
	v_min_u32_e32 v81, v82, v81
	v_max_u32_e32 v82, v74, v72
	v_min_u32_e32 v72, v74, v72
	v_max_u32_e32 v74, v75, v84
	v_min_u32_e32 v84, v75, v84
	v_max_u32_e32 v75, v77, v86
	v_min_u32_e32 v86, v77, v86
	v_max_u32_e32 v77, v70, v73
	v_min_u32_e32 v73, v70, v73
	v_max_u32_e32 v70, v78, v80
	v_min_u32_e32 v80, v78, v80
	v_max_u32_e32 v78, v87, v79
	v_min_u32_e32 v79, v87, v79
	v_max_u32_e32 v87, v76, v102
	v_min_u32_e32 v102, v76, v102
	v_max_u32_e32 v76, v85, v82
	v_min_u32_e32 v82, v85, v82
	v_max_u32_e32 v85, v81, v72
	v_min_u32_e32 v72, v81, v72
	v_max_u32_e32 v81, v74, v75
	v_min_u32_e32 v75, v74, v75
	v_max_u32_e32 v74, v84, v86
	v_min_u32_e32 v86, v84, v86
	v_pk_ashrrev_i16 v84, s42, v24
	v_bitop3_b32 v84, v24, v84, s43 bitop3:0x2d
	v_lshl_or_b32 v97, v84, 16, 15
	v_and_or_b32 v96, v84, s44, 14
	v_pk_ashrrev_i16 v84, s42, v25
	v_bitop3_b32 v84, v25, v84, s43 bitop3:0x2d
	v_lshl_or_b32 v100, v84, 16, 13
	v_and_or_b32 v92, v84, s44, 12
	v_pk_ashrrev_i16 v84, s42, v26
	v_bitop3_b32 v84, v26, v84, s43 bitop3:0x2d
	v_lshl_or_b32 v83, v84, 16, 11
	v_and_or_b32 v71, v84, s44, 10
	v_pk_ashrrev_i16 v84, s42, v27
	v_bitop3_b32 v84, v27, v84, s43 bitop3:0x2d
	v_lshl_or_b32 v95, v84, 16, 9
	v_and_or_b32 v90, v84, s44, 8
	v_pk_ashrrev_i16 v84, s42, v28
	v_bitop3_b32 v84, v28, v84, s43 bitop3:0x2d
	v_lshl_or_b32 v93, v84, 16, 7
	v_and_or_b32 v98, v84, s44, 6
; __device__ __forceinline__ unsigned f2key(float f) { const unsigned u = __float_as_uint(f); return (u & 0x80000000u) ? ~u : (u | 0x80000000u); }
; #define CE_DESC(a, b) do { const unsigned _mx = (a) > (b) ? (a) : (b), _mn = (a) > (b) ? (b) : (a); (a) = _mx; (b) = _mn; } while (0)
; __device__ __forceinline__ void sort16_desc(unsigned (&k)[16]) {
; #pragma unroll
;     for (int size = 2; size <= 16; size <<= 1)
; #pragma unroll
;         for (int stride = size >> 1; stride > 0; stride >>= 1)
; #pragma unroll
;             for (int i = 0; i < 16; ++i) { const int j = i ^ stride;
;                 if (j > i) { if ((i & size) == 0) CE_DESC(k[i], k[j]); else CE_DESC(k[j], k[i]); } }
; }
; __device__ __forceinline__ void merge16(unsigned (&a)[16], const unsigned (&b)[16]) {
; #pragma unroll
;     for (int i = 0; i < 16; ++i) a[i] = a[i] > b[15 - i] ? a[i] : b[15 - i];
; #pragma unroll
;     for (int stride = 8; stride > 0; stride >>= 1)
; #pragma unroll
;         for (int i = 0; i < 16; ++i) { const int j = i ^ stride; if (j > i) CE_DESC(a[i], a[j]); }
; }
; __device__ __forceinline__ void peer_tile(const Args& A, LAS unsigned char* lds, int tile) {
;     ...
;                   for (int i = 0; i < 16; ++i) {
;                       const float lo = (float)__builtin_bit_cast(_Float16, (unsigned short)(sw[i] & 0xffffu)), hi = (float)__builtin_bit_cast(_Float16, (unsigned short)(sw[i] >> 16));
;                       const unsigned klo = (f2key(lo) & ~127u) | (unsigned)(127 - (32 * g + 2 * i)), khi = (f2key(hi) & ~127u) | (unsigned)(127 - (32 * g + 2 * i + 1));
;                       if (i < 8) { k0[2 * i] = klo; k0[2 * i + 1] = khi; } else { k1[2 * (i - 8)] = klo; k1[2 * (i - 8) + 1] = khi; } } }
;                 sort16_desc(k0); sort16_desc(k1); merge16(k0, k1);
	v_pk_ashrrev_i16 v84, s42, v29
	v_bitop3_b32 v84, v29, v84, s43 bitop3:0x2d
	v_lshl_or_b32 v94, v84, 16, 5
	v_and_or_b32 v91, v84, s44, 4
	v_pk_ashrrev_i16 v84, s42, v30
	v_bitop3_b32 v84, v30, v84, s43 bitop3:0x2d
	v_lshl_or_b32 v88, v84, 16, 3
	v_and_or_b32 v89, v84, s44, 2
	v_pk_ashrrev_i16 v84, s42, v31
	v_bitop3_b32 v84, v31, v84, s43 bitop3:0x2d
	v_lshl_or_b32 v101, v84, 16, 1
	v_and_or_b32 v99, v84, s44, 0
	v_max_u32_e32 v84, v97, v89
	v_min_u32_e32 v89, v97, v89
	v_max_u32_e32 v97, v96, v88
	v_min_u32_e32 v88, v96, v88
	v_max_u32_e32 v96, v100, v99
	v_min_u32_e32 v99, v100, v99
	v_max_u32_e32 v100, v92, v101
	v_min_u32_e32 v101, v92, v101
	v_max_u32_e32 v92, v83, v93
	v_min_u32_e32 v93, v83, v93
	v_max_u32_e32 v83, v71, v95
	v_min_u32_e32 v95, v71, v95
	v_max_u32_e32 v71, v90, v91
	v_min_u32_e32 v91, v90, v91
	v_max_u32_e32 v90, v98, v94
	v_min_u32_e32 v94, v98, v94
	v_max_u32_e32 v98, v84, v83
	v_min_u32_e32 v83, v84, v83
	v_max_u32_e32 v84, v97, v71
	v_min_u32_e32 v71, v97, v71
	v_max_u32_e32 v97, v96, v90
	v_min_u32_e32 v90, v96, v90
	v_max_u32_e32 v96, v100, v92
	v_min_u32_e32 v92, v100, v92
	v_max_u32_e32 v100, v95, v89
	v_min_u32_e32 v89, v95, v89
	v_max_u32_e32 v95, v93, v101
	v_min_u32_e32 v101, v93, v101
	v_max_u32_e32 v93, v94, v99
	v_min_u32_e32 v99, v94, v99
	v_max_u32_e32 v94, v91, v88
	v_min_u32_e32 v88, v91, v88
	v_max_u32_e32 v91, v98, v84
	v_min_u32_e32 v84, v98, v84
	v_max_u32_e32 v98, v97, v96
	v_min_u32_e32 v96, v97, v96
	v_max_u32_e32 v97, v92, v83
	v_min_u32_e32 v83, v92, v83
	v_max_u32_e32 v92, v100, v95
	v_min_u32_e32 v95, v100, v95
	v_max_u32_e32 v100, v71, v90
	v_min_u32_e32 v90, v71, v90
	v_max_u32_e32 v71, v93, v94
	v_min_u32_e32 v94, v93, v94
	v_max_u32_e32 v93, v88, v89
	v_min_u32_e32 v89, v88, v89
	v_max_u32_e32 v88, v101, v99
	v_min_u32_e32 v99, v101, v99
	v_max_u32_e32 v101, v91, v98
	v_min_u32_e32 v98, v91, v98
	v_max_u32_e32 v91, v84, v96
	v_min_u32_e32 v96, v84, v96
	v_max_u32_e32 v84, v97, v71
	v_min_u32_e32 v71, v97, v71
	v_max_u32_e32 v97, v83, v94
	v_min_u32_e32 v94, v83, v94
	v_max_u32_e32 v83, v92, v100
	v_min_u32_e32 v100, v92, v100
	v_max_u32_e32 v92, v95, v90
	v_min_u32_e32 v90, v95, v90
	v_max_u32_e32 v95, v93, v88
	v_min_u32_e32 v88, v93, v88
	v_max_u32_e32 v93, v89, v99
	v_min_u32_e32 v99, v89, v99
	v_max_u32_e32 v89, v91, v98
	v_min_u32_e32 v98, v91, v98
	v_max_u32_e32 v91, v96, v95
	v_min_u32_e32 v95, v96, v95
	v_max_u32_e32 v96, v84, v83
	v_min_u32_e32 v83, v84, v83
	v_max_u32_e32 v84, v97, v100
	v_min_u32_e32 v100, v97, v100
	v_max_u32_e32 v97, v92, v71
	v_min_u32_e32 v71, v92, v71
	v_max_u32_e32 v92, v90, v94
	v_min_u32_e32 v94, v90, v94
	v_max_u32_e32 v90, v93, v88
	v_min_u32_e32 v88, v93, v88
	v_max_u32_e32 v93, v89, v96
	v_min_u32_e32 v96, v89, v96
	v_max_u32_e32 v89, v98, v83
	v_min_u32_e32 v83, v98, v83
	v_max_u32_e32 v98, v84, v97
	v_min_u32_e32 v97, v84, v97
	v_max_u32_e32 v84, v100, v71
	v_min_u32_e32 v71, v100, v71
	v_max_u32_e32 v100, v92, v90
	v_min_u32_e32 v90, v92, v90
	v_max_u32_e32 v92, v94, v88
	v_min_u32_e32 v88, v94, v88
	v_max_u32_e32 v94, v89, v96
	v_min_u32_e32 v96, v89, v96
	v_max_u32_e32 v89, v91, v83
	v_min_u32_e32 v83, v91, v83
	v_max_u32_e32 v91, v100, v95
	v_min_u32_e32 v95, v100, v95
	v_max_u32_e32 v100, v92, v90
	v_min_u32_e32 v90, v92, v90
	v_max_u32_e32 v92, v89, v98
	v_min_u32_e32 v98, v89, v98
	v_max_u32_e32 v89, v83, v97
	v_min_u32_e32 v97, v83, v97
	v_max_u32_e32 v83, v84, v91
	v_min_u32_e32 v91, v84, v91
	v_max_u32_e32 v84, v71, v95
	v_min_u32_e32 v95, v71, v95
	v_max_u32_e32 v71, v92, v96
	v_min_u32_e32 v96, v92, v96
	v_max_u32_e32 v92, v98, v89
	v_min_u32_e32 v89, v98, v89
	v_max_u32_e32 v98, v83, v97
	v_min_u32_e32 v97, v83, v97
	v_max_u32_e32 v83, v91, v84
	v_min_u32_e32 v84, v91, v84
	v_max_u32_e32 v91, v100, v95
	v_min_u32_e32 v95, v100, v95
	v_max_u32_e32 v100, v89, v98
	v_min_u32_e32 v98, v89, v98
	v_max_u32_e32 v89, v97, v83
	v_min_u32_e32 v83, v97, v83
	v_max_u32_e32 v77, v77, v99
	v_max_u32_e32 v73, v73, v88
	v_max_u32_e32 v70, v70, v90
	v_max_u32_e32 v80, v80, v95
	v_max_u32_e32 v78, v78, v91
	v_max_u32_e32 v79, v79, v84
	v_max_u32_e32 v87, v87, v83
	v_max_u32_e32 v102, v102, v89
	v_max_u32_e32 v76, v76, v98
	v_max_u32_e32 v82, v82, v100
	v_max_u32_e32 v85, v85, v92
	v_max_u32_e32 v72, v72, v96
	v_max_u32_e32 v81, v81, v71
	v_max_u32_e32 v75, v75, v94
	v_max_u32_e32 v74, v74, v93
	v_max_u32_e32 v86, v86, v101
	v_max_u32_e32 v99, v77, v76
	v_min_u32_e32 v76, v77, v76
	v_max_u32_e32 v77, v73, v82
	v_min_u32_e32 v82, v73, v82
	v_max_u32_e32 v73, v70, v85
	v_min_u32_e32 v85, v70, v85
	v_max_u32_e32 v70, v80, v72
	v_min_u32_e32 v72, v80, v72
	v_max_u32_e32 v80, v78, v81
	v_min_u32_e32 v81, v78, v81
	v_max_u32_e32 v78, v79, v75
	v_min_u32_e32 v75, v79, v75
	v_max_u32_e32 v79, v87, v74
	v_min_u32_e32 v74, v87, v74
	v_max_u32_e32 v87, v102, v86
	v_min_u32_e32 v86, v102, v86
	v_max_u32_e32 v102, v99, v80
	v_min_u32_e32 v80, v99, v80
	v_max_u32_e32 v99, v77, v78
	v_min_u32_e32 v78, v77, v78
	v_max_u32_e32 v77, v73, v79
	v_min_u32_e32 v79, v73, v79
	v_max_u32_e32 v73, v70, v87
	v_min_u32_e32 v87, v70, v87
	v_max_u32_e32 v70, v76, v81
	v_min_u32_e32 v81, v76, v81
	v_max_u32_e32 v76, v82, v75
	v_min_u32_e32 v75, v82, v75
	v_max_u32_e32 v82, v85, v74
	v_min_u32_e32 v74, v85, v74
	v_max_u32_e32 v85, v72, v86
	v_min_u32_e32 v86, v72, v86
	v_max_u32_e32 v72, v102, v77
	v_min_u32_e32 v77, v102, v77
	v_max_u32_e32 v102, v99, v73
	v_min_u32_e32 v73, v99, v73
	v_max_u32_e32 v99, v80, v79
	v_min_u32_e32 v79, v80, v79
	v_max_u32_e32 v80, v78, v87
	v_min_u32_e32 v87, v78, v87
	v_max_u32_e32 v78, v70, v82
	v_min_u32_e32 v82, v70, v82
	v_max_u32_e32 v70, v76, v85
; __device__ __forceinline__ unsigned f2key(float f) { const unsigned u = __float_as_uint(f); return (u & 0x80000000u) ? ~u : (u | 0x80000000u); }
; #define CE_DESC(a, b) do { const unsigned _mx = (a) > (b) ? (a) : (b), _mn = (a) > (b) ? (b) : (a); (a) = _mx; (b) = _mn; } while (0)
; __device__ __forceinline__ void merge16(unsigned (&a)[16], const unsigned (&b)[16]) {
; #pragma unroll
;     for (int i = 0; i < 16; ++i) a[i] = a[i] > b[15 - i] ? a[i] : b[15 - i];
; #pragma unroll
;     for (int stride = 8; stride > 0; stride >>= 1)
; #pragma unroll
;         for (int i = 0; i < 16; ++i) { const int j = i ^ stride; if (j > i) CE_DESC(a[i], a[j]); }
; }
; __device__ __forceinline__ void peer_tile(const Args& A, LAS unsigned char* lds, int tile) {
;     ...
;                 { const bf16_t* sp = QRY + m * 2048 + hp * 128 + 32 * g;
;                   const u32x4 s0 = *(const u32x4*)sp, s1 = *(const u32x4*)(sp + 8), s2 = *(const u32x4*)(sp + 16), s3 = *(const u32x4*)(sp + 24);
;                   const unsigned sw[16] = {s0.x, s0.y, s0.z, s0.w, s1.x, s1.y, s1.z, s1.w, s2.x, s2.y, s2.z, s2.w, s3.x, s3.y, s3.z, s3.w};
; #pragma unroll
;                   for (int i = 0; i < 16; ++i) {
;                       const float lo = (float)__builtin_bit_cast(_Float16, (unsigned short)(sw[i] & 0xffffu)), hi = (float)__builtin_bit_cast(_Float16, (unsigned short)(sw[i] >> 16));
;                       const unsigned klo = (f2key(lo) & ~127u) | (unsigned)(127 - (32 * g + 2 * i)), khi = (f2key(hi) & ~127u) | (unsigned)(127 - (32 * g + 2 * i + 1));
;                       if (i < 8) { k0[2 * i] = klo; k0[2 * i + 1] = khi; } else { k1[2 * (i - 8)] = klo; k1[2 * (i - 8) + 1] = khi; } } }
;                 sort16_desc(k0); sort16_desc(k1); merge16(k0, k1);
	v_min_u32_e32 v85, v76, v85
	v_max_u32_e32 v76, v81, v74
	v_min_u32_e32 v74, v81, v74
	v_max_u32_e32 v81, v75, v86
	v_min_u32_e32 v86, v75, v86
	v_max_u32_e32 v75, v72, v102
	v_min_u32_e32 v102, v72, v102
	v_max_u32_e32 v72, v77, v73
	v_min_u32_e32 v73, v77, v73
	v_max_u32_e32 v77, v99, v80
	v_min_u32_e32 v80, v99, v80
	v_max_u32_e32 v99, v79, v87
	v_min_u32_e32 v87, v79, v87
	v_max_u32_e32 v79, v78, v70
	v_min_u32_e32 v70, v78, v70
	v_max_u32_e32 v78, v82, v85
	v_min_u32_e32 v85, v82, v85
	v_max_u32_e32 v82, v76, v81
	v_min_u32_e32 v81, v76, v81
	v_max_u32_e32 v76, v74, v86
	v_min_u32_e32 v86, v74, v86
	v_or_b32_e32 v75, 64, v75
	v_or_b32_e32 v102, 64, v102
	v_or_b32_e32 v72, 64, v72
	v_or_b32_e32 v73, 64, v73
	v_or_b32_e32 v77, 64, v77
	v_or_b32_e32 v80, 64, v80
	v_or_b32_e32 v99, 64, v99
	v_or_b32_e32 v87, 64, v87
	v_or_b32_e32 v79, 64, v79
	v_or_b32_e32 v70, 64, v70
	v_or_b32_e32 v78, 64, v78
	v_or_b32_e32 v85, 64, v85
	v_or_b32_e32 v82, 64, v82
	v_or_b32_e32 v81, 64, v81
	v_or_b32_e32 v76, 64, v76
	v_or_b32_e32 v86, 64, v86
	s_mov_b64 s[38:39], s[34:35]
	global_load_dwordx4 v[0:3], v66, s[38:39] offset:256
	s_add_u32 s38, s38, 0x8000
	s_addc_u32 s39, s39, 0
	global_load_dwordx4 v[4:7], v66, s[38:39] offset:256
	s_add_u32 s38, s38, 0x8000
	s_addc_u32 s39, s39, 0
	global_load_dwordx4 v[8:11], v66, s[38:39] offset:256
	s_add_u32 s38, s38, 0x8000
	s_addc_u32 s39, s39, 0
	global_load_dwordx4 v[12:15], v66, s[38:39] offset:256
	s_add_u32 s38, s38, 0x8000
	s_addc_u32 s39, s39, 0
	global_load_dwordx4 v[16:19], v66, s[38:39] offset:256
	s_add_u32 s38, s38, 0x8000
	s_addc_u32 s39, s39, 0
	global_load_dwordx4 v[20:23], v66, s[38:39] offset:256
	s_add_u32 s38, s38, 0x8000
	s_addc_u32 s39, s39, 0
	global_load_dwordx4 v[24:27], v66, s[38:39] offset:256
	s_add_u32 s38, s38, 0x8000
	s_addc_u32 s39, s39, 0
	global_load_dwordx4 v[28:31], v66, s[38:39] offset:256
	s_waitcnt vmcnt(8)
	ds_write_b128 v64, v[32:35] offset:0
	ds_write_b128 v64, v[36:39] offset:1152
	ds_write_b128 v64, v[40:43] offset:2304
	ds_write_b128 v64, v[44:47] offset:3456
	ds_write_b128 v64, v[48:51] offset:4608
	ds_write_b128 v64, v[52:55] offset:5760
	ds_write_b128 v64, v[56:59] offset:6912
	ds_write_b128 v64, v[60:63] offset:8064
	s_waitcnt lgkmcnt(0)
	ds_read_b128 v[32:35], v65 offset:0
	ds_read_b128 v[36:39], v65 offset:16
	ds_read_b128 v[40:43], v65 offset:32
	ds_read_b128 v[44:47], v65 offset:48
	ds_read_b128 v[48:51], v65 offset:64
	ds_read_b128 v[52:55], v65 offset:80
	ds_read_b128 v[56:59], v65 offset:96
	ds_read_b128 v[60:63], v65 offset:112
	s_waitcnt lgkmcnt(0)
	v_pk_ashrrev_i16 v74, s42, v32
	v_bitop3_b32 v74, v32, v74, s43 bitop3:0x2d
	v_lshl_or_b32 v88, v74, 16, 63
	v_and_or_b32 v90, v74, s44, 62
	v_pk_ashrrev_i16 v74, s42, v33
	v_bitop3_b32 v74, v33, v74, s43 bitop3:0x2d
	v_lshl_or_b32 v95, v74, 16, 61
	v_and_or_b32 v91, v74, s44, 60
	v_pk_ashrrev_i16 v74, s42, v34
	v_bitop3_b32 v74, v34, v74, s43 bitop3:0x2d
	v_lshl_or_b32 v84, v74, 16, 59
	v_and_or_b32 v83, v74, s44, 58
	v_pk_ashrrev_i16 v74, s42, v35
	v_bitop3_b32 v74, v35, v74, s43 bitop3:0x2d
	v_lshl_or_b32 v89, v74, 16, 57
	v_and_or_b32 v98, v74, s44, 56
	v_pk_ashrrev_i16 v74, s42, v36
	v_bitop3_b32 v74, v36, v74, s43 bitop3:0x2d
	v_lshl_or_b32 v100, v74, 16, 55
	v_and_or_b32 v92, v74, s44, 54
	v_pk_ashrrev_i16 v74, s42, v37
	v_bitop3_b32 v74, v37, v74, s43 bitop3:0x2d
	v_lshl_or_b32 v96, v74, 16, 53
	v_and_or_b32 v71, v74, s44, 52
	v_pk_ashrrev_i16 v74, s42, v38
	v_bitop3_b32 v74, v38, v74, s43 bitop3:0x2d
	v_lshl_or_b32 v94, v74, 16, 51
	v_and_or_b32 v93, v74, s44, 50
	v_pk_ashrrev_i16 v74, s42, v39
	v_bitop3_b32 v74, v39, v74, s43 bitop3:0x2d
	v_lshl_or_b32 v101, v74, 16, 49
	v_and_or_b32 v97, v74, s44, 48
	v_max_u32_e32 v74, v88, v93
	v_min_u32_e32 v93, v88, v93
	v_max_u32_e32 v88, v90, v94
	v_min_u32_e32 v94, v90, v94
	v_max_u32_e32 v90, v95, v97
	v_min_u32_e32 v97, v95, v97
	v_max_u32_e32 v95, v91, v101
	v_min_u32_e32 v101, v91, v101
	v_max_u32_e32 v91, v84, v100
	v_min_u32_e32 v100, v84, v100
	v_max_u32_e32 v84, v83, v89
	v_min_u32_e32 v89, v83, v89
	v_max_u32_e32 v83, v98, v71
	v_min_u32_e32 v71, v98, v71
	v_max_u32_e32 v98, v92, v96
	v_min_u32_e32 v96, v92, v96
	v_max_u32_e32 v92, v74, v84
	v_min_u32_e32 v84, v74, v84
	v_max_u32_e32 v74, v88, v83
	v_min_u32_e32 v83, v88, v83
	v_max_u32_e32 v88, v90, v98
	v_min_u32_e32 v98, v90, v98
	v_max_u32_e32 v90, v95, v91
	v_min_u32_e32 v91, v95, v91
	v_max_u32_e32 v95, v89, v93
	v_min_u32_e32 v93, v89, v93
	v_max_u32_e32 v89, v100, v101
	v_min_u32_e32 v101, v100, v101
	v_max_u32_e32 v100, v96, v97
	v_min_u32_e32 v97, v96, v97
	v_max_u32_e32 v96, v71, v94
	v_min_u32_e32 v94, v71, v94
	v_max_u32_e32 v71, v92, v74
	v_min_u32_e32 v74, v92, v74
	v_max_u32_e32 v92, v88, v90
	v_min_u32_e32 v90, v88, v90
	v_max_u32_e32 v88, v91, v84
	v_min_u32_e32 v84, v91, v84
	v_max_u32_e32 v91, v95, v89
	v_min_u32_e32 v89, v95, v89
	v_max_u32_e32 v95, v83, v98
	v_min_u32_e32 v98, v83, v98
	v_max_u32_e32 v83, v100, v96
	v_min_u32_e32 v96, v100, v96
	v_max_u32_e32 v100, v94, v93
	v_min_u32_e32 v93, v94, v93
	v_max_u32_e32 v94, v101, v97
	v_min_u32_e32 v97, v101, v97
	v_max_u32_e32 v101, v71, v92
	v_min_u32_e32 v92, v71, v92
	v_max_u32_e32 v71, v74, v90
	v_min_u32_e32 v90, v74, v90
	v_max_u32_e32 v74, v88, v83
	v_min_u32_e32 v83, v88, v83
	v_max_u32_e32 v88, v84, v96
	v_min_u32_e32 v96, v84, v96
	v_max_u32_e32 v84, v91, v95
	v_min_u32_e32 v95, v91, v95
	v_max_u32_e32 v91, v89, v98
	v_min_u32_e32 v98, v89, v98
	v_max_u32_e32 v89, v100, v94
	v_min_u32_e32 v94, v100, v94
	v_max_u32_e32 v100, v93, v97
	v_min_u32_e32 v97, v93, v97
	v_max_u32_e32 v93, v71, v92
	v_min_u32_e32 v92, v71, v92
; __device__ __forceinline__ unsigned f2key(float f) { const unsigned u = __float_as_uint(f); return (u & 0x80000000u) ? ~u : (u | 0x80000000u); }
; #define CE_DESC(a, b) do { const unsigned _mx = (a) > (b) ? (a) : (b), _mn = (a) > (b) ? (b) : (a); (a) = _mx; (b) = _mn; } while (0)
; __device__ __forceinline__ void sort16_desc(unsigned (&k)[16]) {
; #pragma unroll
;     for (int size = 2; size <= 16; size <<= 1)
; #pragma unroll
;         for (int stride = size >> 1; stride > 0; stride >>= 1)
; #pragma unroll
;             for (int i = 0; i < 16; ++i) { const int j = i ^ stride;
;                 if (j > i) { if ((i & size) == 0) CE_DESC(k[i], k[j]); else CE_DESC(k[j], k[i]); } }
; }
; __device__ __forceinline__ void merge16(unsigned (&a)[16], const unsigned (&b)[16]) {
; #pragma unroll
;     for (int i = 0; i < 16; ++i) a[i] = a[i] > b[15 - i] ? a[i] : b[15 - i];
; #pragma unroll
;     for (int stride = 8; stride > 0; stride >>= 1)
; #pragma unroll
;         for (int i = 0; i < 16; ++i) { const int j = i ^ stride; if (j > i) CE_DESC(a[i], a[j]); }
; }
; __device__ __forceinline__ void peer_tile(const Args& A, LAS unsigned char* lds, int tile) {
;     ...
;                   for (int i = 0; i < 16; ++i) {
;                       const float lo = (float)__builtin_bit_cast(_Float16, (unsigned short)(sw[i] & 0xffffu)), hi = (float)__builtin_bit_cast(_Float16, (unsigned short)(sw[i] >> 16));
;                       const unsigned klo = (f2key(lo) & ~127u) | (unsigned)(127 - (32 * g + 2 * i)), khi = (f2key(hi) & ~127u) | (unsigned)(127 - (32 * g + 2 * i + 1));
;                       if (i < 8) { k0[2 * i] = klo; k0[2 * i + 1] = khi; } else { k1[2 * (i - 8)] = klo; k1[2 * (i - 8) + 1] = khi; } } }
;                 sort16_desc(k0); sort16_desc(k1); merge16(k0, k1);
	v_max_u32_e32 v71, v90, v89
	v_min_u32_e32 v89, v90, v89
	v_max_u32_e32 v90, v74, v84
	v_min_u32_e32 v84, v74, v84
	v_max_u32_e32 v74, v88, v95
	v_min_u32_e32 v95, v88, v95
	v_max_u32_e32 v88, v91, v83
	v_min_u32_e32 v83, v91, v83
	v_max_u32_e32 v91, v98, v96
	v_min_u32_e32 v96, v98, v96
	v_max_u32_e32 v98, v100, v94
	v_min_u32_e32 v94, v100, v94
	v_max_u32_e32 v100, v93, v90
	v_min_u32_e32 v90, v93, v90
	v_max_u32_e32 v93, v92, v84
	v_min_u32_e32 v84, v92, v84
	v_max_u32_e32 v92, v74, v88
	v_min_u32_e32 v88, v74, v88
	v_max_u32_e32 v74, v95, v83
	v_min_u32_e32 v83, v95, v83
	v_max_u32_e32 v95, v91, v98
	v_min_u32_e32 v98, v91, v98
	v_max_u32_e32 v91, v96, v94
	v_min_u32_e32 v94, v96, v94
	v_max_u32_e32 v96, v93, v90
	v_min_u32_e32 v90, v93, v90
	v_max_u32_e32 v93, v71, v84
	v_min_u32_e32 v84, v71, v84
	v_max_u32_e32 v71, v95, v89
	v_min_u32_e32 v89, v95, v89
	v_max_u32_e32 v95, v91, v98
	v_min_u32_e32 v98, v91, v98
	v_max_u32_e32 v91, v93, v92
	v_min_u32_e32 v92, v93, v92
	v_max_u32_e32 v93, v84, v88
	v_min_u32_e32 v88, v84, v88
	v_max_u32_e32 v84, v74, v71
	v_min_u32_e32 v71, v74, v71
	v_max_u32_e32 v74, v83, v89
	v_min_u32_e32 v89, v83, v89
	v_max_u32_e32 v83, v91, v90
	v_min_u32_e32 v90, v91, v90
	v_max_u32_e32 v91, v92, v93
	v_min_u32_e32 v93, v92, v93
	v_max_u32_e32 v92, v84, v88
	v_min_u32_e32 v88, v84, v88
	v_max_u32_e32 v84, v71, v74
	v_min_u32_e32 v74, v71, v74
	v_max_u32_e32 v71, v95, v89
	v_min_u32_e32 v89, v95, v89
	v_max_u32_e32 v95, v93, v92
	v_min_u32_e32 v92, v93, v92
	v_max_u32_e32 v93, v88, v84
	v_min_u32_e32 v84, v88, v84
	v_max_u32_e32 v75, v75, v97
	v_max_u32_e32 v102, v102, v94
	v_max_u32_e32 v72, v72, v98
	v_max_u32_e32 v73, v73, v89
	v_max_u32_e32 v77, v77, v71
	v_max_u32_e32 v80, v80, v74
	v_max_u32_e32 v99, v99, v84
	v_max_u32_e32 v87, v87, v93
	v_max_u32_e32 v79, v79, v92
	v_max_u32_e32 v70, v70, v95
	v_max_u32_e32 v78, v78, v91
	v_max_u32_e32 v85, v85, v90
	v_max_u32_e32 v82, v82, v83
	v_max_u32_e32 v81, v81, v96
	v_max_u32_e32 v76, v76, v100
	v_max_u32_e32 v86, v86, v101
	v_max_u32_e32 v97, v75, v79
	v_min_u32_e32 v79, v75, v79
	v_max_u32_e32 v75, v102, v70
	v_min_u32_e32 v70, v102, v70
	v_max_u32_e32 v102, v72, v78
	v_min_u32_e32 v78, v72, v78
	v_max_u32_e32 v72, v73, v85
	v_min_u32_e32 v85, v73, v85
	v_max_u32_e32 v73, v77, v82
	v_min_u32_e32 v82, v77, v82
	v_max_u32_e32 v77, v80, v81
	v_min_u32_e32 v81, v80, v81
	v_max_u32_e32 v80, v99, v76
	v_min_u32_e32 v76, v99, v76
	v_max_u32_e32 v99, v87, v86
	v_min_u32_e32 v86, v87, v86
	v_max_u32_e32 v87, v97, v73
	v_min_u32_e32 v73, v97, v73
	v_max_u32_e32 v97, v75, v77
	v_min_u32_e32 v77, v75, v77
	v_max_u32_e32 v75, v102, v80
	v_min_u32_e32 v80, v102, v80
	v_max_u32_e32 v102, v72, v99
	v_min_u32_e32 v99, v72, v99
	v_max_u32_e32 v72, v79, v82
	v_min_u32_e32 v82, v79, v82
	v_max_u32_e32 v79, v70, v81
	v_min_u32_e32 v81, v70, v81
	v_max_u32_e32 v70, v78, v76
	v_min_u32_e32 v76, v78, v76
	v_max_u32_e32 v78, v85, v86
	v_min_u32_e32 v86, v85, v86
	v_max_u32_e32 v85, v87, v75
	v_min_u32_e32 v75, v87, v75
	v_max_u32_e32 v87, v97, v102
	v_min_u32_e32 v102, v97, v102
	v_max_u32_e32 v97, v73, v80
	v_min_u32_e32 v80, v73, v80
	v_max_u32_e32 v73, v77, v99
	v_min_u32_e32 v99, v77, v99
	v_max_u32_e32 v77, v72, v70
	v_min_u32_e32 v70, v72, v70
	v_max_u32_e32 v72, v79, v78
	v_min_u32_e32 v78, v79, v78
	v_max_u32_e32 v79, v82, v76
	v_min_u32_e32 v76, v82, v76
	v_max_u32_e32 v82, v81, v86
	v_min_u32_e32 v86, v81, v86
	v_max_u32_e32 v81, v85, v87
	v_min_u32_e32 v87, v85, v87
	v_max_u32_e32 v85, v75, v102
	v_min_u32_e32 v102, v75, v102
	v_max_u32_e32 v75, v97, v73
	v_min_u32_e32 v73, v97, v73
	v_max_u32_e32 v97, v80, v99
	v_min_u32_e32 v99, v80, v99
	v_max_u32_e32 v80, v77, v72
	v_min_u32_e32 v72, v77, v72
	v_max_u32_e32 v77, v70, v78
	v_min_u32_e32 v78, v70, v78
	v_max_u32_e32 v70, v79, v82
	v_min_u32_e32 v82, v79, v82
	v_max_u32_e32 v79, v76, v86
	v_min_u32_e32 v86, v76, v86
	v_pk_ashrrev_i16 v76, s42, v40
	v_bitop3_b32 v76, v40, v76, s43 bitop3:0x2d
	v_lshl_or_b32 v94, v76, 16, 47
	v_and_or_b32 v98, v76, s44, 46
	v_pk_ashrrev_i16 v76, s42, v41
	v_bitop3_b32 v76, v41, v76, s43 bitop3:0x2d
	v_lshl_or_b32 v89, v76, 16, 45
	v_and_or_b32 v71, v76, s44, 44
	v_pk_ashrrev_i16 v76, s42, v42
	v_bitop3_b32 v76, v42, v76, s43 bitop3:0x2d
	v_lshl_or_b32 v74, v76, 16, 43
	v_and_or_b32 v84, v76, s44, 42
	v_pk_ashrrev_i16 v76, s42, v43
	v_bitop3_b32 v76, v43, v76, s43 bitop3:0x2d
	v_lshl_or_b32 v93, v76, 16, 41
	v_and_or_b32 v92, v76, s44, 40
	v_pk_ashrrev_i16 v76, s42, v44
	v_bitop3_b32 v76, v44, v76, s43 bitop3:0x2d
	v_lshl_or_b32 v95, v76, 16, 39
	v_and_or_b32 v91, v76, s44, 38
	v_pk_ashrrev_i16 v76, s42, v45
	v_bitop3_b32 v76, v45, v76, s43 bitop3:0x2d
	v_lshl_or_b32 v90, v76, 16, 37
	v_and_or_b32 v83, v76, s44, 36
	v_pk_ashrrev_i16 v76, s42, v46
	v_bitop3_b32 v76, v46, v76, s43 bitop3:0x2d
	v_lshl_or_b32 v96, v76, 16, 35
	v_and_or_b32 v100, v76, s44, 34
	v_pk_ashrrev_i16 v76, s42, v47
	v_bitop3_b32 v76, v47, v76, s43 bitop3:0x2d
	v_lshl_or_b32 v101, v76, 16, 33
	v_and_or_b32 v88, v76, s44, 32
	v_max_u32_e32 v76, v94, v100
	v_min_u32_e32 v100, v94, v100
	v_max_u32_e32 v94, v98, v96
	v_min_u32_e32 v96, v98, v96
	v_max_u32_e32 v98, v89, v88
	v_min_u32_e32 v88, v89, v88
	v_max_u32_e32 v89, v71, v101
	v_min_u32_e32 v101, v71, v101
	v_max_u32_e32 v71, v74, v95
	v_min_u32_e32 v95, v74, v95
	v_max_u32_e32 v74, v84, v93
	v_min_u32_e32 v93, v84, v93
	v_max_u32_e32 v84, v92, v83
	v_min_u32_e32 v83, v92, v83
	v_max_u32_e32 v92, v91, v90
	v_min_u32_e32 v90, v91, v90
	v_max_u32_e32 v91, v76, v74
	v_min_u32_e32 v74, v76, v74
	v_max_u32_e32 v76, v94, v84
	v_min_u32_e32 v84, v94, v84
	v_max_u32_e32 v94, v98, v92
; __device__ __forceinline__ unsigned f2key(float f) { const unsigned u = __float_as_uint(f); return (u & 0x80000000u) ? ~u : (u | 0x80000000u); }
; #define CE_DESC(a, b) do { const unsigned _mx = (a) > (b) ? (a) : (b), _mn = (a) > (b) ? (b) : (a); (a) = _mx; (b) = _mn; } while (0)
; __device__ __forceinline__ void sort16_desc(unsigned (&k)[16]) {
; #pragma unroll
;     for (int size = 2; size <= 16; size <<= 1)
; #pragma unroll
;         for (int stride = size >> 1; stride > 0; stride >>= 1)
; #pragma unroll
;             for (int i = 0; i < 16; ++i) { const int j = i ^ stride;
;                 if (j > i) { if ((i & size) == 0) CE_DESC(k[i], k[j]); else CE_DESC(k[j], k[i]); } }
; }
; __device__ __forceinline__ void merge16(unsigned (&a)[16], const unsigned (&b)[16]) {
; #pragma unroll
;     for (int i = 0; i < 16; ++i) a[i] = a[i] > b[15 - i] ? a[i] : b[15 - i];
; #pragma unroll
;     for (int stride = 8; stride > 0; stride >>= 1)
; #pragma unroll
;         for (int i = 0; i < 16; ++i) { const int j = i ^ stride; if (j > i) CE_DESC(a[i], a[j]); }
; }
; __device__ __forceinline__ void peer_tile(const Args& A, LAS unsigned char* lds, int tile) {
;     ...
;                   for (int i = 0; i < 16; ++i) {
;                       const float lo = (float)__builtin_bit_cast(_Float16, (unsigned short)(sw[i] & 0xffffu)), hi = (float)__builtin_bit_cast(_Float16, (unsigned short)(sw[i] >> 16));
;                       const unsigned klo = (f2key(lo) & ~127u) | (unsigned)(127 - (32 * g + 2 * i)), khi = (f2key(hi) & ~127u) | (unsigned)(127 - (32 * g + 2 * i + 1));
;                       if (i < 8) { k0[2 * i] = klo; k0[2 * i + 1] = khi; } else { k1[2 * (i - 8)] = klo; k1[2 * (i - 8) + 1] = khi; } } }
;                 sort16_desc(k0); sort16_desc(k1); merge16(k0, k1);
	v_min_u32_e32 v92, v98, v92
	v_max_u32_e32 v98, v89, v71
	v_min_u32_e32 v71, v89, v71
	v_max_u32_e32 v89, v93, v100
	v_min_u32_e32 v100, v93, v100
	v_max_u32_e32 v93, v95, v101
	v_min_u32_e32 v101, v95, v101
	v_max_u32_e32 v95, v90, v88
	v_min_u32_e32 v88, v90, v88
	v_max_u32_e32 v90, v83, v96
	v_min_u32_e32 v96, v83, v96
	v_max_u32_e32 v83, v91, v76
	v_min_u32_e32 v76, v91, v76
	v_max_u32_e32 v91, v94, v98
	v_min_u32_e32 v98, v94, v98
	v_max_u32_e32 v94, v71, v74
	v_min_u32_e32 v74, v71, v74
	v_max_u32_e32 v71, v89, v93
	v_min_u32_e32 v93, v89, v93
	v_max_u32_e32 v89, v84, v92
	v_min_u32_e32 v92, v84, v92
	v_max_u32_e32 v84, v95, v90
	v_min_u32_e32 v90, v95, v90
	v_max_u32_e32 v95, v96, v100
	v_min_u32_e32 v100, v96, v100
	v_max_u32_e32 v96, v101, v88
	v_min_u32_e32 v88, v101, v88
	v_max_u32_e32 v101, v83, v91
	v_min_u32_e32 v91, v83, v91
	v_max_u32_e32 v83, v76, v98
	v_min_u32_e32 v98, v76, v98
	v_max_u32_e32 v76, v94, v84
	v_min_u32_e32 v84, v94, v84
	v_max_u32_e32 v94, v74, v90
	v_min_u32_e32 v90, v74, v90
	v_max_u32_e32 v74, v71, v89
	v_min_u32_e32 v89, v71, v89
	v_max_u32_e32 v71, v93, v92
	v_min_u32_e32 v92, v93, v92
	v_max_u32_e32 v93, v95, v96
	v_min_u32_e32 v96, v95, v96
	v_max_u32_e32 v95, v100, v88
	v_min_u32_e32 v88, v100, v88
	v_max_u32_e32 v100, v83, v91
	v_min_u32_e32 v91, v83, v91
	v_max_u32_e32 v83, v98, v93
	v_min_u32_e32 v93, v98, v93
	v_max_u32_e32 v98, v76, v74
	v_min_u32_e32 v74, v76, v74
	v_max_u32_e32 v76, v94, v89
	v_min_u32_e32 v89, v94, v89
	v_max_u32_e32 v94, v71, v84
	v_min_u32_e32 v84, v71, v84
	v_max_u32_e32 v71, v92, v90
	v_min_u32_e32 v90, v92, v90
	v_max_u32_e32 v92, v95, v96
	v_min_u32_e32 v96, v95, v96
	v_max_u32_e32 v95, v100, v98
	v_min_u32_e32 v98, v100, v98
	v_max_u32_e32 v100, v91, v74
	v_min_u32_e32 v74, v91, v74
	v_max_u32_e32 v91, v76, v94
	v_min_u32_e32 v94, v76, v94
	v_max_u32_e32 v76, v89, v84
	v_min_u32_e32 v84, v89, v84
	v_max_u32_e32 v89, v71, v92
	v_min_u32_e32 v92, v71, v92
	v_max_u32_e32 v71, v90, v96
	v_min_u32_e32 v96, v90, v96
	v_max_u32_e32 v90, v100, v98
	v_min_u32_e32 v98, v100, v98
	v_max_u32_e32 v100, v83, v74
	v_min_u32_e32 v74, v83, v74
	v_max_u32_e32 v83, v89, v93
	v_min_u32_e32 v93, v89, v93
	v_max_u32_e32 v89, v71, v92
	v_min_u32_e32 v92, v71, v92
	v_max_u32_e32 v71, v100, v91
	v_min_u32_e32 v91, v100, v91
	v_max_u32_e32 v100, v74, v94
	v_min_u32_e32 v94, v74, v94
	v_max_u32_e32 v74, v76, v83
	v_min_u32_e32 v83, v76, v83
	v_max_u32_e32 v76, v84, v93
	v_min_u32_e32 v93, v84, v93
	v_max_u32_e32 v84, v71, v98
	v_min_u32_e32 v98, v71, v98
	v_max_u32_e32 v71, v91, v100
	v_min_u32_e32 v100, v91, v100
	v_max_u32_e32 v91, v74, v94
	v_min_u32_e32 v94, v74, v94
	v_max_u32_e32 v74, v83, v76
	v_min_u32_e32 v76, v83, v76
	v_max_u32_e32 v83, v89, v93
	v_min_u32_e32 v93, v89, v93
	v_max_u32_e32 v89, v100, v91
	v_min_u32_e32 v91, v100, v91
	v_max_u32_e32 v100, v94, v74
	v_min_u32_e32 v74, v94, v74
	v_max_u32_e32 v81, v81, v88
	v_max_u32_e32 v87, v87, v96
	v_max_u32_e32 v85, v85, v92
	v_max_u32_e32 v102, v102, v93
	v_max_u32_e32 v75, v75, v83
	v_max_u32_e32 v73, v73, v76
	v_max_u32_e32 v97, v97, v74
	v_max_u32_e32 v99, v99, v100
	v_max_u32_e32 v80, v80, v91
	v_max_u32_e32 v72, v72, v89
	v_max_u32_e32 v77, v77, v71
	v_max_u32_e32 v78, v78, v98
	v_max_u32_e32 v70, v70, v84
	v_max_u32_e32 v82, v82, v90
	v_max_u32_e32 v79, v79, v95
	v_max_u32_e32 v86, v86, v101
	v_max_u32_e32 v88, v81, v80
	v_min_u32_e32 v80, v81, v80
	v_max_u32_e32 v81, v87, v72
	v_min_u32_e32 v72, v87, v72
	v_max_u32_e32 v87, v85, v77
	v_min_u32_e32 v77, v85, v77
	v_max_u32_e32 v85, v102, v78
	v_min_u32_e32 v78, v102, v78
	v_max_u32_e32 v102, v75, v70
	v_min_u32_e32 v70, v75, v70
	v_max_u32_e32 v75, v73, v82
	v_min_u32_e32 v82, v73, v82
	v_max_u32_e32 v73, v97, v79
	v_min_u32_e32 v79, v97, v79
	v_max_u32_e32 v97, v99, v86
	v_min_u32_e32 v86, v99, v86
	v_max_u32_e32 v99, v88, v102
	v_min_u32_e32 v102, v88, v102
	v_max_u32_e32 v88, v81, v75
	v_min_u32_e32 v75, v81, v75
	v_max_u32_e32 v81, v87, v73
	v_min_u32_e32 v73, v87, v73
	v_max_u32_e32 v87, v85, v97
	v_min_u32_e32 v97, v85, v97
	v_max_u32_e32 v85, v80, v70
	v_min_u32_e32 v70, v80, v70
	v_max_u32_e32 v80, v72, v82
	v_min_u32_e32 v82, v72, v82
	v_max_u32_e32 v72, v77, v79
	v_min_u32_e32 v79, v77, v79
	v_max_u32_e32 v77, v78, v86
	v_min_u32_e32 v86, v78, v86
	v_max_u32_e32 v78, v99, v81
	v_min_u32_e32 v81, v99, v81
	v_max_u32_e32 v99, v88, v87
	v_min_u32_e32 v87, v88, v87
	v_max_u32_e32 v88, v102, v73
	v_min_u32_e32 v73, v102, v73
	v_max_u32_e32 v102, v75, v97
	v_min_u32_e32 v97, v75, v97
	v_max_u32_e32 v75, v85, v72
	v_min_u32_e32 v72, v85, v72
	v_max_u32_e32 v85, v80, v77
	v_min_u32_e32 v77, v80, v77
	v_max_u32_e32 v80, v70, v79
	v_min_u32_e32 v79, v70, v79
	v_max_u32_e32 v70, v82, v86
	v_min_u32_e32 v86, v82, v86
	v_max_u32_e32 v82, v78, v99
	v_min_u32_e32 v99, v78, v99
	v_max_u32_e32 v78, v81, v87
	v_min_u32_e32 v87, v81, v87
	v_max_u32_e32 v81, v88, v102
	v_min_u32_e32 v102, v88, v102
	v_max_u32_e32 v88, v73, v97
	v_min_u32_e32 v97, v73, v97
	v_max_u32_e32 v73, v75, v85
	v_min_u32_e32 v85, v75, v85
	v_max_u32_e32 v75, v72, v77
	v_min_u32_e32 v77, v72, v77
	v_max_u32_e32 v72, v80, v70
	v_min_u32_e32 v70, v80, v70
	v_max_u32_e32 v80, v79, v86
	v_min_u32_e32 v86, v79, v86
	v_pk_ashrrev_i16 v79, s42, v48
	v_bitop3_b32 v79, v48, v79, s43 bitop3:0x2d
	v_lshl_or_b32 v96, v79, 16, 31
	v_and_or_b32 v92, v79, s44, 30
	v_pk_ashrrev_i16 v79, s42, v49
	v_bitop3_b32 v79, v49, v79, s43 bitop3:0x2d
	v_lshl_or_b32 v93, v79, 16, 29
	v_and_or_b32 v83, v79, s44, 28
	v_pk_ashrrev_i16 v79, s42, v50
	v_bitop3_b32 v79, v50, v79, s43 bitop3:0x2d
	v_lshl_or_b32 v76, v79, 16, 27
; __device__ __forceinline__ unsigned f2key(float f) { const unsigned u = __float_as_uint(f); return (u & 0x80000000u) ? ~u : (u | 0x80000000u); }
; #define CE_DESC(a, b) do { const unsigned _mx = (a) > (b) ? (a) : (b), _mn = (a) > (b) ? (b) : (a); (a) = _mx; (b) = _mn; } while (0)
; __device__ __forceinline__ void sort16_desc(unsigned (&k)[16]) {
; #pragma unroll
;     for (int size = 2; size <= 16; size <<= 1)
; #pragma unroll
;         for (int stride = size >> 1; stride > 0; stride >>= 1)
; #pragma unroll
;             for (int i = 0; i < 16; ++i) { const int j = i ^ stride;
;                 if (j > i) { if ((i & size) == 0) CE_DESC(k[i], k[j]); else CE_DESC(k[j], k[i]); } }
; }
; __device__ __forceinline__ void merge16(unsigned (&a)[16], const unsigned (&b)[16]) {
; #pragma unroll
;     for (int i = 0; i < 16; ++i) a[i] = a[i] > b[15 - i] ? a[i] : b[15 - i];
; #pragma unroll
;     for (int stride = 8; stride > 0; stride >>= 1)
; #pragma unroll
;         for (int i = 0; i < 16; ++i) { const int j = i ^ stride; if (j > i) CE_DESC(a[i], a[j]); }
; }
; __device__ __forceinline__ void peer_tile(const Args& A, LAS unsigned char* lds, int tile) {
;     ...
;                   for (int i = 0; i < 16; ++i) {
;                       const float lo = (float)__builtin_bit_cast(_Float16, (unsigned short)(sw[i] & 0xffffu)), hi = (float)__builtin_bit_cast(_Float16, (unsigned short)(sw[i] >> 16));
;                       const unsigned klo = (f2key(lo) & ~127u) | (unsigned)(127 - (32 * g + 2 * i)), khi = (f2key(hi) & ~127u) | (unsigned)(127 - (32 * g + 2 * i + 1));
;                       if (i < 8) { k0[2 * i] = klo; k0[2 * i + 1] = khi; } else { k1[2 * (i - 8)] = klo; k1[2 * (i - 8) + 1] = khi; } } }
;                 sort16_desc(k0); sort16_desc(k1); merge16(k0, k1);
	v_and_or_b32 v74, v79, s44, 26
	v_pk_ashrrev_i16 v79, s42, v51
	v_bitop3_b32 v79, v51, v79, s43 bitop3:0x2d
	v_lshl_or_b32 v100, v79, 16, 25
	v_and_or_b32 v91, v79, s44, 24
	v_pk_ashrrev_i16 v79, s42, v52
	v_bitop3_b32 v79, v52, v79, s43 bitop3:0x2d
	v_lshl_or_b32 v89, v79, 16, 23
	v_and_or_b32 v71, v79, s44, 22
	v_pk_ashrrev_i16 v79, s42, v53
	v_bitop3_b32 v79, v53, v79, s43 bitop3:0x2d
	v_lshl_or_b32 v98, v79, 16, 21
	v_and_or_b32 v84, v79, s44, 20
	v_pk_ashrrev_i16 v79, s42, v54
	v_bitop3_b32 v79, v54, v79, s43 bitop3:0x2d
	v_lshl_or_b32 v90, v79, 16, 19
	v_and_or_b32 v95, v79, s44, 18
	v_pk_ashrrev_i16 v79, s42, v55
	v_bitop3_b32 v79, v55, v79, s43 bitop3:0x2d
	v_lshl_or_b32 v101, v79, 16, 17
	v_and_or_b32 v94, v79, s44, 16
	v_max_u32_e32 v79, v96, v95
	v_min_u32_e32 v95, v96, v95
	v_max_u32_e32 v96, v92, v90
	v_min_u32_e32 v90, v92, v90
	v_max_u32_e32 v92, v93, v94
	v_min_u32_e32 v94, v93, v94
	v_max_u32_e32 v93, v83, v101
	v_min_u32_e32 v101, v83, v101
	v_max_u32_e32 v83, v76, v89
	v_min_u32_e32 v89, v76, v89
	v_max_u32_e32 v76, v74, v100
	v_min_u32_e32 v100, v74, v100
	v_max_u32_e32 v74, v91, v84
	v_min_u32_e32 v84, v91, v84
	v_max_u32_e32 v91, v71, v98
	v_min_u32_e32 v98, v71, v98
	v_max_u32_e32 v71, v79, v76
	v_min_u32_e32 v76, v79, v76
	v_max_u32_e32 v79, v96, v74
	v_min_u32_e32 v74, v96, v74
	v_max_u32_e32 v96, v92, v91
	v_min_u32_e32 v91, v92, v91
	v_max_u32_e32 v92, v93, v83
	v_min_u32_e32 v83, v93, v83
	v_max_u32_e32 v93, v100, v95
	v_min_u32_e32 v95, v100, v95
	v_max_u32_e32 v100, v89, v101
	v_min_u32_e32 v101, v89, v101
	v_max_u32_e32 v89, v98, v94
	v_min_u32_e32 v94, v98, v94
	v_max_u32_e32 v98, v84, v90
	v_min_u32_e32 v90, v84, v90
	v_max_u32_e32 v84, v71, v79
	v_min_u32_e32 v79, v71, v79
	v_max_u32_e32 v71, v96, v92
	v_min_u32_e32 v92, v96, v92
	v_max_u32_e32 v96, v83, v76
	v_min_u32_e32 v76, v83, v76
	v_max_u32_e32 v83, v93, v100
	v_min_u32_e32 v100, v93, v100
	v_max_u32_e32 v93, v74, v91
	v_min_u32_e32 v91, v74, v91
	v_max_u32_e32 v74, v89, v98
	v_min_u32_e32 v98, v89, v98
	v_max_u32_e32 v89, v90, v95
	v_min_u32_e32 v95, v90, v95
	v_max_u32_e32 v90, v101, v94
	v_min_u32_e32 v94, v101, v94
	v_max_u32_e32 v101, v84, v71
	v_min_u32_e32 v71, v84, v71
	v_max_u32_e32 v84, v79, v92
	v_min_u32_e32 v92, v79, v92
	v_max_u32_e32 v79, v96, v74
	v_min_u32_e32 v74, v96, v74
	v_max_u32_e32 v96, v76, v98
	v_min_u32_e32 v98, v76, v98
	v_max_u32_e32 v76, v83, v93
	v_min_u32_e32 v93, v83, v93
	v_max_u32_e32 v83, v100, v91
	v_min_u32_e32 v91, v100, v91
	v_max_u32_e32 v100, v89, v90
	v_min_u32_e32 v90, v89, v90
	v_max_u32_e32 v89, v95, v94
	v_min_u32_e32 v94, v95, v94
	v_max_u32_e32 v95, v84, v71
	v_min_u32_e32 v71, v84, v71
	v_max_u32_e32 v84, v92, v100
	v_min_u32_e32 v100, v92, v100
	v_max_u32_e32 v92, v79, v76
	v_min_u32_e32 v76, v79, v76
	v_max_u32_e32 v79, v96, v93
	v_min_u32_e32 v93, v96, v93
	v_max_u32_e32 v96, v83, v74
	v_min_u32_e32 v74, v83, v74
	v_max_u32_e32 v83, v91, v98
	v_min_u32_e32 v98, v91, v98
	v_max_u32_e32 v91, v89, v90
	v_min_u32_e32 v90, v89, v90
	v_max_u32_e32 v89, v95, v92
	v_min_u32_e32 v92, v95, v92
	v_max_u32_e32 v95, v71, v76
	v_min_u32_e32 v76, v71, v76
	v_max_u32_e32 v71, v79, v96
	v_min_u32_e32 v96, v79, v96
	v_max_u32_e32 v79, v93, v74
	v_min_u32_e32 v74, v93, v74
	v_max_u32_e32 v93, v83, v91
	v_min_u32_e32 v91, v83, v91
	v_max_u32_e32 v83, v98, v90
	v_min_u32_e32 v90, v98, v90
	v_max_u32_e32 v98, v95, v92
	v_min_u32_e32 v92, v95, v92
	v_max_u32_e32 v95, v84, v76
	v_min_u32_e32 v76, v84, v76
	v_max_u32_e32 v84, v93, v100
	v_min_u32_e32 v100, v93, v100
	v_max_u32_e32 v93, v83, v91
	v_min_u32_e32 v91, v83, v91
	v_max_u32_e32 v83, v95, v71
	v_min_u32_e32 v71, v95, v71
	v_max_u32_e32 v95, v76, v96
	v_min_u32_e32 v96, v76, v96
	v_max_u32_e32 v76, v79, v84
	v_min_u32_e32 v84, v79, v84
	v_max_u32_e32 v79, v74, v100
	v_min_u32_e32 v100, v74, v100
	v_max_u32_e32 v74, v83, v92
	v_min_u32_e32 v92, v83, v92
	v_max_u32_e32 v83, v71, v95
	v_min_u32_e32 v95, v71, v95
	v_max_u32_e32 v71, v76, v96
	v_min_u32_e32 v96, v76, v96
	v_max_u32_e32 v76, v84, v79
	v_min_u32_e32 v79, v84, v79
	v_max_u32_e32 v84, v93, v100
	v_min_u32_e32 v100, v93, v100
	v_max_u32_e32 v93, v95, v71
	v_min_u32_e32 v71, v95, v71
	v_max_u32_e32 v95, v96, v76
	v_min_u32_e32 v76, v96, v76
	v_max_u32_e32 v82, v82, v94
	v_max_u32_e32 v99, v99, v90
	v_max_u32_e32 v78, v78, v91
	v_max_u32_e32 v87, v87, v100
	v_max_u32_e32 v81, v81, v84
	v_max_u32_e32 v102, v102, v79
	v_max_u32_e32 v88, v88, v76
	v_max_u32_e32 v97, v97, v95
	v_max_u32_e32 v73, v73, v71
	v_max_u32_e32 v85, v85, v93
	v_max_u32_e32 v75, v75, v83
	v_max_u32_e32 v77, v77, v92
	v_max_u32_e32 v72, v72, v74
	v_max_u32_e32 v70, v70, v98
	v_max_u32_e32 v80, v80, v89
	v_max_u32_e32 v86, v86, v101
	v_max_u32_e32 v94, v82, v73
	v_min_u32_e32 v73, v82, v73
	v_max_u32_e32 v82, v99, v85
	v_min_u32_e32 v85, v99, v85
	v_max_u32_e32 v99, v78, v75
	v_min_u32_e32 v75, v78, v75
	v_max_u32_e32 v78, v87, v77
	v_min_u32_e32 v77, v87, v77
	v_max_u32_e32 v87, v81, v72
	v_min_u32_e32 v72, v81, v72
	v_max_u32_e32 v81, v102, v70
	v_min_u32_e32 v70, v102, v70
	v_max_u32_e32 v102, v88, v80
	v_min_u32_e32 v80, v88, v80
	v_max_u32_e32 v88, v97, v86
	v_min_u32_e32 v86, v97, v86
	v_max_u32_e32 v97, v94, v87
	v_min_u32_e32 v87, v94, v87
	v_max_u32_e32 v94, v82, v81
	v_min_u32_e32 v81, v82, v81
	v_max_u32_e32 v82, v99, v102
	v_min_u32_e32 v102, v99, v102
	v_max_u32_e32 v99, v78, v88
	v_min_u32_e32 v88, v78, v88
	v_max_u32_e32 v78, v73, v72
	v_min_u32_e32 v72, v73, v72
	v_max_u32_e32 v73, v85, v70
	v_min_u32_e32 v70, v85, v70
	v_max_u32_e32 v85, v75, v80
	v_min_u32_e32 v80, v75, v80
	v_max_u32_e32 v75, v77, v86
	v_min_u32_e32 v86, v77, v86
; __device__ __forceinline__ unsigned f2key(float f) { const unsigned u = __float_as_uint(f); return (u & 0x80000000u) ? ~u : (u | 0x80000000u); }
; #define CE_DESC(a, b) do { const unsigned _mx = (a) > (b) ? (a) : (b), _mn = (a) > (b) ? (b) : (a); (a) = _mx; (b) = _mn; } while (0)
; __device__ __forceinline__ void sort16_desc(unsigned (&k)[16]) {
; #pragma unroll
;     for (int size = 2; size <= 16; size <<= 1)
; #pragma unroll
;         for (int stride = size >> 1; stride > 0; stride >>= 1)
; #pragma unroll
;             for (int i = 0; i < 16; ++i) { const int j = i ^ stride;
;                 if (j > i) { if ((i & size) == 0) CE_DESC(k[i], k[j]); else CE_DESC(k[j], k[i]); } }
; }
; __device__ __forceinline__ void merge16(unsigned (&a)[16], const unsigned (&b)[16]) {
; #pragma unroll
;     for (int i = 0; i < 16; ++i) a[i] = a[i] > b[15 - i] ? a[i] : b[15 - i];
; #pragma unroll
;     for (int stride = 8; stride > 0; stride >>= 1)
; #pragma unroll
;         for (int i = 0; i < 16; ++i) { const int j = i ^ stride; if (j > i) CE_DESC(a[i], a[j]); }
; }
; __device__ __forceinline__ void peer_tile(const Args& A, LAS unsigned char* lds, int tile) {
;     ...
;                   for (int i = 0; i < 16; ++i) {
;                       const float lo = (float)__builtin_bit_cast(_Float16, (unsigned short)(sw[i] & 0xffffu)), hi = (float)__builtin_bit_cast(_Float16, (unsigned short)(sw[i] >> 16));
;                       const unsigned klo = (f2key(lo) & ~127u) | (unsigned)(127 - (32 * g + 2 * i)), khi = (f2key(hi) & ~127u) | (unsigned)(127 - (32 * g + 2 * i + 1));
;                       if (i < 8) { k0[2 * i] = klo; k0[2 * i + 1] = khi; } else { k1[2 * (i - 8)] = klo; k1[2 * (i - 8) + 1] = khi; } } }
;                 sort16_desc(k0); sort16_desc(k1); merge16(k0, k1);
	v_max_u32_e32 v77, v97, v82
	v_min_u32_e32 v82, v97, v82
	v_max_u32_e32 v97, v94, v99
	v_min_u32_e32 v99, v94, v99
	v_max_u32_e32 v94, v87, v102
	v_min_u32_e32 v102, v87, v102
	v_max_u32_e32 v87, v81, v88
	v_min_u32_e32 v88, v81, v88
	v_max_u32_e32 v81, v78, v85
	v_min_u32_e32 v85, v78, v85
	v_max_u32_e32 v78, v73, v75
	v_min_u32_e32 v75, v73, v75
	v_max_u32_e32 v73, v72, v80
	v_min_u32_e32 v80, v72, v80
	v_max_u32_e32 v72, v70, v86
	v_min_u32_e32 v86, v70, v86
	v_max_u32_e32 v70, v77, v97
	v_min_u32_e32 v97, v77, v97
	v_max_u32_e32 v77, v82, v99
	v_min_u32_e32 v99, v82, v99
	v_max_u32_e32 v82, v94, v87
	v_min_u32_e32 v87, v94, v87
	v_max_u32_e32 v94, v102, v88
	v_min_u32_e32 v88, v102, v88
	v_max_u32_e32 v102, v81, v78
	v_min_u32_e32 v78, v81, v78
	v_max_u32_e32 v81, v85, v75
	v_min_u32_e32 v75, v85, v75
	v_max_u32_e32 v85, v73, v72
	v_min_u32_e32 v72, v73, v72
	v_max_u32_e32 v73, v80, v86
	v_min_u32_e32 v86, v80, v86
	v_pk_ashrrev_i16 v80, s42, v56
	v_bitop3_b32 v80, v56, v80, s43 bitop3:0x2d
	v_lshl_or_b32 v90, v80, 16, 15
	v_and_or_b32 v91, v80, s44, 14
	v_pk_ashrrev_i16 v80, s42, v57
	v_bitop3_b32 v80, v57, v80, s43 bitop3:0x2d
	v_lshl_or_b32 v100, v80, 16, 13
	v_and_or_b32 v84, v80, s44, 12
	v_pk_ashrrev_i16 v80, s42, v58
	v_bitop3_b32 v80, v58, v80, s43 bitop3:0x2d
	v_lshl_or_b32 v79, v80, 16, 11
	v_and_or_b32 v76, v80, s44, 10
	v_pk_ashrrev_i16 v80, s42, v59
	v_bitop3_b32 v80, v59, v80, s43 bitop3:0x2d
	v_lshl_or_b32 v95, v80, 16, 9
	v_and_or_b32 v71, v80, s44, 8
	v_pk_ashrrev_i16 v80, s42, v60
	v_bitop3_b32 v80, v60, v80, s43 bitop3:0x2d
	v_lshl_or_b32 v93, v80, 16, 7
	v_and_or_b32 v83, v80, s44, 6
	v_pk_ashrrev_i16 v80, s42, v61
	v_bitop3_b32 v80, v61, v80, s43 bitop3:0x2d
	v_lshl_or_b32 v92, v80, 16, 5
	v_and_or_b32 v74, v80, s44, 4
	v_pk_ashrrev_i16 v80, s42, v62
	v_bitop3_b32 v80, v62, v80, s43 bitop3:0x2d
	v_lshl_or_b32 v98, v80, 16, 3
	v_and_or_b32 v89, v80, s44, 2
	v_pk_ashrrev_i16 v80, s42, v63
	v_bitop3_b32 v80, v63, v80, s43 bitop3:0x2d
	v_lshl_or_b32 v101, v80, 16, 1
	v_and_or_b32 v96, v80, s44, 0
	v_max_u32_e32 v80, v90, v89
	v_min_u32_e32 v89, v90, v89
	v_max_u32_e32 v90, v91, v98
	v_min_u32_e32 v98, v91, v98
	v_max_u32_e32 v91, v100, v96
	v_min_u32_e32 v96, v100, v96
	v_max_u32_e32 v100, v84, v101
	v_min_u32_e32 v101, v84, v101
	v_max_u32_e32 v84, v79, v93
	v_min_u32_e32 v93, v79, v93
	v_max_u32_e32 v79, v76, v95
	v_min_u32_e32 v95, v76, v95
	v_max_u32_e32 v76, v71, v74
	v_min_u32_e32 v74, v71, v74
	v_max_u32_e32 v71, v83, v92
	v_min_u32_e32 v92, v83, v92
	v_max_u32_e32 v83, v80, v79
	v_min_u32_e32 v79, v80, v79
	v_max_u32_e32 v80, v90, v76
	v_min_u32_e32 v76, v90, v76
	v_max_u32_e32 v90, v91, v71
	v_min_u32_e32 v71, v91, v71
	v_max_u32_e32 v91, v100, v84
	v_min_u32_e32 v84, v100, v84
	v_max_u32_e32 v100, v95, v89
	v_min_u32_e32 v89, v95, v89
	v_max_u32_e32 v95, v93, v101
	v_min_u32_e32 v101, v93, v101
	v_max_u32_e32 v93, v92, v96
	v_min_u32_e32 v96, v92, v96
	v_max_u32_e32 v92, v74, v98
	v_min_u32_e32 v98, v74, v98
	v_max_u32_e32 v74, v83, v80
	v_min_u32_e32 v80, v83, v80
	v_max_u32_e32 v83, v90, v91
	v_min_u32_e32 v91, v90, v91
	v_max_u32_e32 v90, v84, v79
	v_min_u32_e32 v79, v84, v79
	v_max_u32_e32 v84, v100, v95
	v_min_u32_e32 v95, v100, v95
	v_max_u32_e32 v100, v76, v71
	v_min_u32_e32 v71, v76, v71
	v_max_u32_e32 v76, v93, v92
	v_min_u32_e32 v92, v93, v92
	v_max_u32_e32 v93, v98, v89
	v_min_u32_e32 v89, v98, v89
	v_max_u32_e32 v98, v101, v96
	v_min_u32_e32 v96, v101, v96
	v_max_u32_e32 v101, v74, v83
	v_min_u32_e32 v83, v74, v83
	v_max_u32_e32 v74, v80, v91
	v_min_u32_e32 v91, v80, v91
	v_max_u32_e32 v80, v90, v76
	v_min_u32_e32 v76, v90, v76
	v_max_u32_e32 v90, v79, v92
	v_min_u32_e32 v92, v79, v92
	v_max_u32_e32 v79, v84, v100
	v_min_u32_e32 v100, v84, v100
	v_max_u32_e32 v84, v95, v71
	v_min_u32_e32 v71, v95, v71
	v_max_u32_e32 v95, v93, v98
	v_min_u32_e32 v98, v93, v98
	v_max_u32_e32 v93, v89, v96
	v_min_u32_e32 v96, v89, v96
	v_max_u32_e32 v89, v74, v83
	v_min_u32_e32 v83, v74, v83
	v_max_u32_e32 v74, v91, v95
	v_min_u32_e32 v95, v91, v95
	v_max_u32_e32 v91, v80, v79
	v_min_u32_e32 v79, v80, v79
	v_max_u32_e32 v80, v90, v100
	v_min_u32_e32 v100, v90, v100
	v_max_u32_e32 v90, v84, v76
	v_min_u32_e32 v76, v84, v76
	v_max_u32_e32 v84, v71, v92
	v_min_u32_e32 v92, v71, v92
	v_max_u32_e32 v71, v93, v98
	v_min_u32_e32 v98, v93, v98
	v_max_u32_e32 v93, v89, v91
	v_min_u32_e32 v91, v89, v91
	v_max_u32_e32 v89, v83, v79
	v_min_u32_e32 v79, v83, v79
	v_max_u32_e32 v83, v80, v90
	v_min_u32_e32 v90, v80, v90
	v_max_u32_e32 v80, v100, v76
	v_min_u32_e32 v76, v100, v76
	v_max_u32_e32 v100, v84, v71
	v_min_u32_e32 v71, v84, v71
	v_max_u32_e32 v84, v92, v98
	v_min_u32_e32 v98, v92, v98
	v_max_u32_e32 v92, v89, v91
	v_min_u32_e32 v91, v89, v91
	v_max_u32_e32 v89, v74, v79
	v_min_u32_e32 v79, v74, v79
	v_max_u32_e32 v74, v100, v95
	v_min_u32_e32 v95, v100, v95
	v_max_u32_e32 v100, v84, v71
	v_min_u32_e32 v71, v84, v71
	v_max_u32_e32 v84, v89, v83
	v_min_u32_e32 v83, v89, v83
	v_max_u32_e32 v89, v79, v90
	v_min_u32_e32 v90, v79, v90
	v_max_u32_e32 v79, v80, v74
	v_min_u32_e32 v74, v80, v74
	v_max_u32_e32 v80, v76, v95
	v_min_u32_e32 v95, v76, v95
	v_max_u32_e32 v76, v84, v91
	v_min_u32_e32 v91, v84, v91
	v_max_u32_e32 v84, v83, v89
	v_min_u32_e32 v89, v83, v89
	v_max_u32_e32 v83, v79, v90
	v_min_u32_e32 v90, v79, v90
	v_max_u32_e32 v79, v74, v80
	v_min_u32_e32 v80, v74, v80
	v_max_u32_e32 v74, v100, v95
	v_min_u32_e32 v95, v100, v95
	v_max_u32_e32 v100, v89, v83
	v_min_u32_e32 v83, v89, v83
	v_max_u32_e32 v89, v90, v79
	v_min_u32_e32 v79, v90, v79
	v_max_u32_e32 v70, v70, v96
	v_max_u32_e32 v97, v97, v98
	v_max_u32_e32 v77, v77, v71
; __device__ __forceinline__ unsigned f2key(float f) { const unsigned u = __float_as_uint(f); return (u & 0x80000000u) ? ~u : (u | 0x80000000u); }
; #define CE_DESC(a, b) do { const unsigned _mx = (a) > (b) ? (a) : (b), _mn = (a) > (b) ? (b) : (a); (a) = _mx; (b) = _mn; } while (0)
; __device__ __forceinline__ void sort16_desc(unsigned (&k)[16]) {
; #pragma unroll
;     for (int size = 2; size <= 16; size <<= 1)
; #pragma unroll
;         for (int stride = size >> 1; stride > 0; stride >>= 1)
; #pragma unroll
;             for (int i = 0; i < 16; ++i) { const int j = i ^ stride;
;                 if (j > i) { if ((i & size) == 0) CE_DESC(k[i], k[j]); else CE_DESC(k[j], k[i]); } }
; }
; __device__ __forceinline__ void merge16(unsigned (&a)[16], const unsigned (&b)[16]) {
; #pragma unroll
;     for (int i = 0; i < 16; ++i) a[i] = a[i] > b[15 - i] ? a[i] : b[15 - i];
; #pragma unroll
;     for (int stride = 8; stride > 0; stride >>= 1)
; #pragma unroll
;         for (int i = 0; i < 16; ++i) { const int j = i ^ stride; if (j > i) CE_DESC(a[i], a[j]); }
; }
; __device__ __forceinline__ void peer_tile(const Args& A, LAS unsigned char* lds, int tile) {
;     ...
;                 { const bf16_t* sp = QRY + m * 2048 + hp * 128 + 32 * g;
;                   const u32x4 s0 = *(const u32x4*)sp, s1 = *(const u32x4*)(sp + 8), s2 = *(const u32x4*)(sp + 16), s3 = *(const u32x4*)(sp + 24);
;                   const unsigned sw[16] = {s0.x, s0.y, s0.z, s0.w, s1.x, s1.y, s1.z, s1.w, s2.x, s2.y, s2.z, s2.w, s3.x, s3.y, s3.z, s3.w};
; #pragma unroll
;                   for (int i = 0; i < 16; ++i) {
;                       const float lo = (float)__builtin_bit_cast(_Float16, (unsigned short)(sw[i] & 0xffffu)), hi = (float)__builtin_bit_cast(_Float16, (unsigned short)(sw[i] >> 16));
;                       const unsigned klo = (f2key(lo) & ~127u) | (unsigned)(127 - (32 * g + 2 * i)), khi = (f2key(hi) & ~127u) | (unsigned)(127 - (32 * g + 2 * i + 1));
;                       if (i < 8) { k0[2 * i] = klo; k0[2 * i + 1] = khi; } else { k1[2 * (i - 8)] = klo; k1[2 * (i - 8) + 1] = khi; } } }
;                 sort16_desc(k0); sort16_desc(k1); merge16(k0, k1);
	v_max_u32_e32 v99, v99, v95
	v_max_u32_e32 v82, v82, v74
	v_max_u32_e32 v87, v87, v80
	v_max_u32_e32 v94, v94, v79
	v_max_u32_e32 v88, v88, v89
	v_max_u32_e32 v102, v102, v83
	v_max_u32_e32 v78, v78, v100
	v_max_u32_e32 v81, v81, v84
	v_max_u32_e32 v75, v75, v91
	v_max_u32_e32 v85, v85, v76
	v_max_u32_e32 v72, v72, v92
	v_max_u32_e32 v73, v73, v93
	v_max_u32_e32 v86, v86, v101
	v_max_u32_e32 v96, v70, v102
	v_min_u32_e32 v102, v70, v102
	v_max_u32_e32 v70, v97, v78
	v_min_u32_e32 v78, v97, v78
	v_max_u32_e32 v97, v77, v81
	v_min_u32_e32 v81, v77, v81
	v_max_u32_e32 v77, v99, v75
	v_min_u32_e32 v75, v99, v75
	v_max_u32_e32 v99, v82, v85
	v_min_u32_e32 v85, v82, v85
	v_max_u32_e32 v82, v87, v72
	v_min_u32_e32 v72, v87, v72
	v_max_u32_e32 v87, v94, v73
	v_min_u32_e32 v73, v94, v73
	v_max_u32_e32 v94, v88, v86
	v_min_u32_e32 v86, v88, v86
	v_max_u32_e32 v88, v96, v99
	v_min_u32_e32 v99, v96, v99
	v_max_u32_e32 v96, v70, v82
	v_min_u32_e32 v82, v70, v82
	v_max_u32_e32 v70, v97, v87
	v_min_u32_e32 v87, v97, v87
	v_max_u32_e32 v97, v77, v94
	v_min_u32_e32 v94, v77, v94
	v_max_u32_e32 v77, v102, v85
	v_min_u32_e32 v85, v102, v85
	v_max_u32_e32 v102, v78, v72
	v_min_u32_e32 v72, v78, v72
	v_max_u32_e32 v78, v81, v73
	v_min_u32_e32 v73, v81, v73
	v_max_u32_e32 v81, v75, v86
	v_min_u32_e32 v86, v75, v86
	v_max_u32_e32 v75, v88, v70
	v_min_u32_e32 v70, v88, v70
	v_max_u32_e32 v88, v96, v97
	v_min_u32_e32 v97, v96, v97
	v_max_u32_e32 v96, v99, v87
	v_min_u32_e32 v87, v99, v87
	v_max_u32_e32 v99, v82, v94
	v_min_u32_e32 v94, v82, v94
	v_max_u32_e32 v82, v77, v78
	v_min_u32_e32 v78, v77, v78
	v_max_u32_e32 v77, v102, v81
	v_min_u32_e32 v81, v102, v81
	v_max_u32_e32 v102, v85, v73
	v_min_u32_e32 v73, v85, v73
	v_max_u32_e32 v85, v72, v86
	v_min_u32_e32 v86, v72, v86
	v_max_u32_e32 v72, v75, v88
	v_min_u32_e32 v88, v75, v88
	v_max_u32_e32 v75, v70, v97
	v_min_u32_e32 v97, v70, v97
	v_max_u32_e32 v70, v96, v99
	v_min_u32_e32 v99, v96, v99
	v_max_u32_e32 v96, v87, v94
	v_min_u32_e32 v94, v87, v94
	v_max_u32_e32 v87, v82, v77
	v_min_u32_e32 v77, v82, v77
	v_max_u32_e32 v82, v78, v81
	v_min_u32_e32 v81, v78, v81
	v_max_u32_e32 v78, v102, v85
	v_min_u32_e32 v85, v102, v85
	v_max_u32_e32 v102, v73, v86
	v_min_u32_e32 v86, v73, v86
	s_mov_b64 s[38:39], s[34:35]
	global_load_dwordx4 v[32:35], v66, s[38:39] offset:384
	s_add_u32 s38, s38, 0x8000
	s_addc_u32 s39, s39, 0
	global_load_dwordx4 v[36:39], v66, s[38:39] offset:384
	s_add_u32 s38, s38, 0x8000
	s_addc_u32 s39, s39, 0
	global_load_dwordx4 v[40:43], v66, s[38:39] offset:384
	s_add_u32 s38, s38, 0x8000
	s_addc_u32 s39, s39, 0
	global_load_dwordx4 v[44:47], v66, s[38:39] offset:384
	s_add_u32 s38, s38, 0x8000
	s_addc_u32 s39, s39, 0
	global_load_dwordx4 v[48:51], v66, s[38:39] offset:384
	s_add_u32 s38, s38, 0x8000
	s_addc_u32 s39, s39, 0
	global_load_dwordx4 v[52:55], v66, s[38:39] offset:384
	s_add_u32 s38, s38, 0x8000
	s_addc_u32 s39, s39, 0
	global_load_dwordx4 v[56:59], v66, s[38:39] offset:384
	s_add_u32 s38, s38, 0x8000
	s_addc_u32 s39, s39, 0
	global_load_dwordx4 v[60:63], v66, s[38:39] offset:384
	s_waitcnt vmcnt(8)
	ds_write_b128 v64, v[0:3] offset:0
	ds_write_b128 v64, v[4:7] offset:1152
	ds_write_b128 v64, v[8:11] offset:2304
	ds_write_b128 v64, v[12:15] offset:3456
	ds_write_b128 v64, v[16:19] offset:4608
	ds_write_b128 v64, v[20:23] offset:5760
	ds_write_b128 v64, v[24:27] offset:6912
	ds_write_b128 v64, v[28:31] offset:8064
	s_waitcnt lgkmcnt(0)
	ds_read_b128 v[0:3], v65 offset:0
	ds_read_b128 v[4:7], v65 offset:16
	ds_read_b128 v[8:11], v65 offset:32
	ds_read_b128 v[12:15], v65 offset:48
	ds_read_b128 v[16:19], v65 offset:64
	ds_read_b128 v[20:23], v65 offset:80
	ds_read_b128 v[24:27], v65 offset:96
	ds_read_b128 v[28:31], v65 offset:112
	s_waitcnt lgkmcnt(0)
	v_pk_ashrrev_i16 v73, s42, v0
	v_bitop3_b32 v73, v0, v73, s43 bitop3:0x2d
	v_lshl_or_b32 v98, v73, 16, 63
	v_and_or_b32 v71, v73, s44, 62
	v_pk_ashrrev_i16 v73, s42, v1
	v_bitop3_b32 v73, v1, v73, s43 bitop3:0x2d
	v_lshl_or_b32 v95, v73, 16, 61
	v_and_or_b32 v74, v73, s44, 60
	v_pk_ashrrev_i16 v73, s42, v2
	v_bitop3_b32 v73, v2, v73, s43 bitop3:0x2d
	v_lshl_or_b32 v80, v73, 16, 59
	v_and_or_b32 v79, v73, s44, 58
	v_pk_ashrrev_i16 v73, s42, v3
	v_bitop3_b32 v73, v3, v73, s43 bitop3:0x2d
	v_lshl_or_b32 v89, v73, 16, 57
	v_and_or_b32 v83, v73, s44, 56
	v_pk_ashrrev_i16 v73, s42, v4
	v_bitop3_b32 v73, v4, v73, s43 bitop3:0x2d
	v_lshl_or_b32 v100, v73, 16, 55
	v_and_or_b32 v84, v73, s44, 54
	v_pk_ashrrev_i16 v73, s42, v5
	v_bitop3_b32 v73, v5, v73, s43 bitop3:0x2d
	v_lshl_or_b32 v91, v73, 16, 53
	v_and_or_b32 v76, v73, s44, 52
	v_pk_ashrrev_i16 v73, s42, v6
	v_bitop3_b32 v73, v6, v73, s43 bitop3:0x2d
	v_lshl_or_b32 v92, v73, 16, 51
	v_and_or_b32 v93, v73, s44, 50
	v_pk_ashrrev_i16 v73, s42, v7
	v_bitop3_b32 v73, v7, v73, s43 bitop3:0x2d
	v_lshl_or_b32 v101, v73, 16, 49
	v_and_or_b32 v90, v73, s44, 48
	v_max_u32_e32 v73, v98, v93
	v_min_u32_e32 v93, v98, v93
	v_max_u32_e32 v98, v71, v92
	v_min_u32_e32 v92, v71, v92
	v_max_u32_e32 v71, v95, v90
	v_min_u32_e32 v90, v95, v90
	v_max_u32_e32 v95, v74, v101
	v_min_u32_e32 v101, v74, v101
	v_max_u32_e32 v74, v80, v100
	v_min_u32_e32 v100, v80, v100
	v_max_u32_e32 v80, v79, v89
	v_min_u32_e32 v89, v79, v89
	v_max_u32_e32 v79, v83, v76
	v_min_u32_e32 v76, v83, v76
	v_max_u32_e32 v83, v84, v91
	v_min_u32_e32 v91, v84, v91
	v_max_u32_e32 v84, v73, v80
	v_min_u32_e32 v80, v73, v80
	v_max_u32_e32 v73, v98, v79
	v_min_u32_e32 v79, v98, v79
	v_max_u32_e32 v98, v71, v83
	v_min_u32_e32 v83, v71, v83
	v_max_u32_e32 v71, v95, v74
	v_min_u32_e32 v74, v95, v74
	v_max_u32_e32 v95, v89, v93
	v_min_u32_e32 v93, v89, v93
; __device__ __forceinline__ unsigned f2key(float f) { const unsigned u = __float_as_uint(f); return (u & 0x80000000u) ? ~u : (u | 0x80000000u); }
; #define CE_DESC(a, b) do { const unsigned _mx = (a) > (b) ? (a) : (b), _mn = (a) > (b) ? (b) : (a); (a) = _mx; (b) = _mn; } while (0)
; __device__ __forceinline__ void sort16_desc(unsigned (&k)[16]) {
; #pragma unroll
;     for (int size = 2; size <= 16; size <<= 1)
; #pragma unroll
;         for (int stride = size >> 1; stride > 0; stride >>= 1)
; #pragma unroll
;             for (int i = 0; i < 16; ++i) { const int j = i ^ stride;
;                 if (j > i) { if ((i & size) == 0) CE_DESC(k[i], k[j]); else CE_DESC(k[j], k[i]); } }
; }
; __device__ __forceinline__ void merge16(unsigned (&a)[16], const unsigned (&b)[16]) {
; #pragma unroll
;     for (int i = 0; i < 16; ++i) a[i] = a[i] > b[15 - i] ? a[i] : b[15 - i];
; #pragma unroll
;     for (int stride = 8; stride > 0; stride >>= 1)
; #pragma unroll
;         for (int i = 0; i < 16; ++i) { const int j = i ^ stride; if (j > i) CE_DESC(a[i], a[j]); }
; }
; __device__ __forceinline__ void peer_tile(const Args& A, LAS unsigned char* lds, int tile) {
;     ...
;                   for (int i = 0; i < 16; ++i) {
;                       const float lo = (float)__builtin_bit_cast(_Float16, (unsigned short)(sw[i] & 0xffffu)), hi = (float)__builtin_bit_cast(_Float16, (unsigned short)(sw[i] >> 16));
;                       const unsigned klo = (f2key(lo) & ~127u) | (unsigned)(127 - (32 * g + 2 * i)), khi = (f2key(hi) & ~127u) | (unsigned)(127 - (32 * g + 2 * i + 1));
;                       if (i < 8) { k0[2 * i] = klo; k0[2 * i + 1] = khi; } else { k1[2 * (i - 8)] = klo; k1[2 * (i - 8) + 1] = khi; } } }
;                 sort16_desc(k0); sort16_desc(k1); merge16(k0, k1);
	v_max_u32_e32 v89, v100, v101
	v_min_u32_e32 v101, v100, v101
	v_max_u32_e32 v100, v91, v90
	v_min_u32_e32 v90, v91, v90
	v_max_u32_e32 v91, v76, v92
	v_min_u32_e32 v92, v76, v92
	v_max_u32_e32 v76, v84, v73
	v_min_u32_e32 v73, v84, v73
	v_max_u32_e32 v84, v98, v71
	v_min_u32_e32 v71, v98, v71
	v_max_u32_e32 v98, v74, v80
	v_min_u32_e32 v80, v74, v80
	v_max_u32_e32 v74, v95, v89
	v_min_u32_e32 v89, v95, v89
	v_max_u32_e32 v95, v79, v83
	v_min_u32_e32 v83, v79, v83
	v_max_u32_e32 v79, v100, v91
	v_min_u32_e32 v91, v100, v91
	v_max_u32_e32 v100, v92, v93
	v_min_u32_e32 v93, v92, v93
	v_max_u32_e32 v92, v101, v90
	v_min_u32_e32 v90, v101, v90
	v_max_u32_e32 v101, v76, v84
	v_min_u32_e32 v84, v76, v84
	v_max_u32_e32 v76, v73, v71
	v_min_u32_e32 v71, v73, v71
	v_max_u32_e32 v73, v98, v79
	v_min_u32_e32 v79, v98, v79
	v_max_u32_e32 v98, v80, v91
	v_min_u32_e32 v91, v80, v91
	v_max_u32_e32 v80, v74, v95
	v_min_u32_e32 v95, v74, v95
	v_max_u32_e32 v74, v89, v83
	v_min_u32_e32 v83, v89, v83
	v_max_u32_e32 v89, v100, v92
	v_min_u32_e32 v92, v100, v92
	v_max_u32_e32 v100, v93, v90
	v_min_u32_e32 v90, v93, v90
	v_max_u32_e32 v93, v76, v84
	v_min_u32_e32 v84, v76, v84
	v_max_u32_e32 v76, v71, v89
	v_min_u32_e32 v89, v71, v89
	v_max_u32_e32 v71, v73, v80
	v_min_u32_e32 v80, v73, v80
	v_max_u32_e32 v73, v98, v95
	v_min_u32_e32 v95, v98, v95
	v_max_u32_e32 v98, v74, v79
	v_min_u32_e32 v79, v74, v79
	v_max_u32_e32 v74, v83, v91
	v_min_u32_e32 v91, v83, v91
	v_max_u32_e32 v83, v100, v92
	v_min_u32_e32 v92, v100, v92
	v_max_u32_e32 v100, v93, v71
	v_min_u32_e32 v71, v93, v71
	v_max_u32_e32 v93, v84, v80
	v_min_u32_e32 v80, v84, v80
	v_max_u32_e32 v84, v73, v98
	v_min_u32_e32 v98, v73, v98
	v_max_u32_e32 v73, v95, v79
	v_min_u32_e32 v79, v95, v79
	v_max_u32_e32 v95, v74, v83
	v_min_u32_e32 v83, v74, v83
	v_max_u32_e32 v74, v91, v92
	v_min_u32_e32 v92, v91, v92
	v_max_u32_e32 v91, v93, v71
	v_min_u32_e32 v71, v93, v71
	v_max_u32_e32 v93, v76, v80
	v_min_u32_e32 v80, v76, v80
	v_max_u32_e32 v76, v95, v89
	v_min_u32_e32 v89, v95, v89
	v_max_u32_e32 v95, v74, v83
	v_min_u32_e32 v83, v74, v83
	v_max_u32_e32 v74, v93, v84
	v_min_u32_e32 v84, v93, v84
	v_max_u32_e32 v93, v80, v98
	v_min_u32_e32 v98, v80, v98
	v_max_u32_e32 v80, v73, v76
	v_min_u32_e32 v76, v73, v76
	v_max_u32_e32 v73, v79, v89
	v_min_u32_e32 v89, v79, v89
	v_max_u32_e32 v79, v74, v71
	v_min_u32_e32 v71, v74, v71
	v_max_u32_e32 v74, v84, v93
	v_min_u32_e32 v93, v84, v93
	v_max_u32_e32 v84, v80, v98
	v_min_u32_e32 v98, v80, v98
	v_max_u32_e32 v80, v76, v73
	v_min_u32_e32 v73, v76, v73
	v_max_u32_e32 v76, v95, v89
	v_min_u32_e32 v89, v95, v89
	v_max_u32_e32 v95, v93, v84
	v_min_u32_e32 v84, v93, v84
	v_max_u32_e32 v93, v98, v80
	v_min_u32_e32 v80, v98, v80
	v_pk_ashrrev_i16 v98, s42, v8
	v_bitop3_b32 v98, v8, v98, s43 bitop3:0x2d
	v_lshl_or_b32 v103, v98, 16, 47
	v_and_or_b32 v104, v98, s44, 46
	v_pk_ashrrev_i16 v98, s42, v9
	v_bitop3_b32 v98, v9, v98, s43 bitop3:0x2d
	v_lshl_or_b32 v105, v98, 16, 45
	v_and_or_b32 v106, v98, s44, 44
	v_pk_ashrrev_i16 v98, s42, v10
	v_bitop3_b32 v98, v10, v98, s43 bitop3:0x2d
	v_lshl_or_b32 v107, v98, 16, 43
	v_and_or_b32 v108, v98, s44, 42
	v_pk_ashrrev_i16 v98, s42, v11
	v_bitop3_b32 v98, v11, v98, s43 bitop3:0x2d
	v_lshl_or_b32 v109, v98, 16, 41
	v_and_or_b32 v110, v98, s44, 40
	v_pk_ashrrev_i16 v98, s42, v12
	v_bitop3_b32 v98, v12, v98, s43 bitop3:0x2d
	v_lshl_or_b32 v111, v98, 16, 39
	v_and_or_b32 v112, v98, s44, 38
	v_pk_ashrrev_i16 v98, s42, v13
	v_bitop3_b32 v98, v13, v98, s43 bitop3:0x2d
	v_lshl_or_b32 v114, v98, 16, 37
	v_and_or_b32 v115, v98, s44, 36
	v_pk_ashrrev_i16 v98, s42, v14
	v_bitop3_b32 v98, v14, v98, s43 bitop3:0x2d
	v_lshl_or_b32 v116, v98, 16, 35
	v_and_or_b32 v117, v98, s44, 34
	v_pk_ashrrev_i16 v98, s42, v15
	v_bitop3_b32 v98, v15, v98, s43 bitop3:0x2d
	v_lshl_or_b32 v118, v98, 16, 33
	v_and_or_b32 v119, v98, s44, 32
	v_max_u32_e32 v98, v103, v117
	v_min_u32_e32 v117, v103, v117
	v_max_u32_e32 v103, v104, v116
	v_min_u32_e32 v116, v104, v116
	v_max_u32_e32 v104, v105, v119
	v_min_u32_e32 v119, v105, v119
	v_max_u32_e32 v105, v106, v118
	v_min_u32_e32 v118, v106, v118
	v_max_u32_e32 v106, v107, v111
	v_min_u32_e32 v111, v107, v111
	v_max_u32_e32 v107, v108, v109
	v_min_u32_e32 v109, v108, v109
	v_max_u32_e32 v108, v110, v115
	v_min_u32_e32 v115, v110, v115
	v_max_u32_e32 v110, v112, v114
	v_min_u32_e32 v114, v112, v114
	v_max_u32_e32 v112, v98, v107
	v_min_u32_e32 v107, v98, v107
	v_max_u32_e32 v98, v103, v108
	v_min_u32_e32 v108, v103, v108
	v_max_u32_e32 v103, v104, v110
	v_min_u32_e32 v110, v104, v110
	v_max_u32_e32 v104, v105, v106
	v_min_u32_e32 v106, v105, v106
	v_max_u32_e32 v105, v109, v117
	v_min_u32_e32 v117, v109, v117
	v_max_u32_e32 v109, v111, v118
	v_min_u32_e32 v118, v111, v118
	v_max_u32_e32 v111, v114, v119
	v_min_u32_e32 v119, v114, v119
	v_max_u32_e32 v114, v115, v116
	v_min_u32_e32 v116, v115, v116
	v_max_u32_e32 v115, v112, v98
	v_min_u32_e32 v98, v112, v98
	v_max_u32_e32 v112, v103, v104
	v_min_u32_e32 v104, v103, v104
	v_max_u32_e32 v103, v106, v107
	v_min_u32_e32 v107, v106, v107
	v_max_u32_e32 v106, v105, v109
	v_min_u32_e32 v109, v105, v109
	v_max_u32_e32 v105, v108, v110
	v_min_u32_e32 v110, v108, v110
	v_max_u32_e32 v108, v111, v114
	v_min_u32_e32 v114, v111, v114
	v_max_u32_e32 v111, v116, v117
	v_min_u32_e32 v117, v116, v117
	v_max_u32_e32 v116, v118, v119
	v_min_u32_e32 v119, v118, v119
	v_max_u32_e32 v118, v115, v112
	v_min_u32_e32 v112, v115, v112
	v_max_u32_e32 v115, v98, v104
	v_min_u32_e32 v104, v98, v104
	v_max_u32_e32 v98, v103, v108
	v_min_u32_e32 v108, v103, v108
	v_max_u32_e32 v103, v107, v114
; __device__ __forceinline__ unsigned f2key(float f) { const unsigned u = __float_as_uint(f); return (u & 0x80000000u) ? ~u : (u | 0x80000000u); }
; #define CE_DESC(a, b) do { const unsigned _mx = (a) > (b) ? (a) : (b), _mn = (a) > (b) ? (b) : (a); (a) = _mx; (b) = _mn; } while (0)
; __device__ __forceinline__ void sort16_desc(unsigned (&k)[16]) {
; #pragma unroll
;     for (int size = 2; size <= 16; size <<= 1)
; #pragma unroll
;         for (int stride = size >> 1; stride > 0; stride >>= 1)
; #pragma unroll
;             for (int i = 0; i < 16; ++i) { const int j = i ^ stride;
;                 if (j > i) { if ((i & size) == 0) CE_DESC(k[i], k[j]); else CE_DESC(k[j], k[i]); } }
; }
; __device__ __forceinline__ void merge16(unsigned (&a)[16], const unsigned (&b)[16]) {
; #pragma unroll
;     for (int i = 0; i < 16; ++i) a[i] = a[i] > b[15 - i] ? a[i] : b[15 - i];
; #pragma unroll
;     for (int stride = 8; stride > 0; stride >>= 1)
; #pragma unroll
;         for (int i = 0; i < 16; ++i) { const int j = i ^ stride; if (j > i) CE_DESC(a[i], a[j]); }
; }
; __device__ __forceinline__ void peer_tile(const Args& A, LAS unsigned char* lds, int tile) {
;     ...
;                   for (int i = 0; i < 16; ++i) {
;                       const float lo = (float)__builtin_bit_cast(_Float16, (unsigned short)(sw[i] & 0xffffu)), hi = (float)__builtin_bit_cast(_Float16, (unsigned short)(sw[i] >> 16));
;                       const unsigned klo = (f2key(lo) & ~127u) | (unsigned)(127 - (32 * g + 2 * i)), khi = (f2key(hi) & ~127u) | (unsigned)(127 - (32 * g + 2 * i + 1));
;                       if (i < 8) { k0[2 * i] = klo; k0[2 * i + 1] = khi; } else { k1[2 * (i - 8)] = klo; k1[2 * (i - 8) + 1] = khi; } } }
;                 sort16_desc(k0); sort16_desc(k1); merge16(k0, k1);
	v_min_u32_e32 v114, v107, v114
	v_max_u32_e32 v107, v106, v105
	v_min_u32_e32 v105, v106, v105
	v_max_u32_e32 v106, v109, v110
	v_min_u32_e32 v110, v109, v110
	v_max_u32_e32 v109, v111, v116
	v_min_u32_e32 v116, v111, v116
	v_max_u32_e32 v111, v117, v119
	v_min_u32_e32 v119, v117, v119
	v_max_u32_e32 v117, v115, v112
	v_min_u32_e32 v112, v115, v112
	v_max_u32_e32 v115, v104, v109
	v_min_u32_e32 v109, v104, v109
	v_max_u32_e32 v104, v98, v107
	v_min_u32_e32 v107, v98, v107
	v_max_u32_e32 v98, v103, v105
	v_min_u32_e32 v105, v103, v105
	v_max_u32_e32 v103, v106, v108
	v_min_u32_e32 v108, v106, v108
	v_max_u32_e32 v106, v110, v114
	v_min_u32_e32 v114, v110, v114
	v_max_u32_e32 v110, v111, v116
	v_min_u32_e32 v116, v111, v116
	v_max_u32_e32 v111, v117, v104
	v_min_u32_e32 v104, v117, v104
	v_max_u32_e32 v117, v112, v107
	v_min_u32_e32 v107, v112, v107
	v_max_u32_e32 v112, v98, v103
	v_min_u32_e32 v103, v98, v103
	v_max_u32_e32 v98, v105, v108
	v_min_u32_e32 v108, v105, v108
	v_max_u32_e32 v105, v106, v110
	v_min_u32_e32 v110, v106, v110
	v_max_u32_e32 v106, v114, v116
	v_min_u32_e32 v116, v114, v116
	v_max_u32_e32 v114, v117, v104
	v_min_u32_e32 v104, v117, v104
	v_max_u32_e32 v117, v115, v107
	v_min_u32_e32 v107, v115, v107
	v_max_u32_e32 v115, v105, v109
	v_min_u32_e32 v109, v105, v109
	v_max_u32_e32 v105, v106, v110
	v_min_u32_e32 v110, v106, v110
	v_max_u32_e32 v106, v117, v112
	v_min_u32_e32 v112, v117, v112
	v_max_u32_e32 v117, v107, v103
	v_min_u32_e32 v103, v107, v103
	v_max_u32_e32 v107, v98, v115
	v_min_u32_e32 v115, v98, v115
	v_max_u32_e32 v98, v108, v109
	v_min_u32_e32 v109, v108, v109
	v_max_u32_e32 v108, v106, v104
	v_min_u32_e32 v104, v106, v104
	v_max_u32_e32 v106, v112, v117
	v_min_u32_e32 v117, v112, v117
	v_max_u32_e32 v112, v107, v103
	v_min_u32_e32 v103, v107, v103
	v_max_u32_e32 v107, v115, v98
	v_min_u32_e32 v98, v115, v98
	v_max_u32_e32 v115, v105, v109
	v_min_u32_e32 v109, v105, v109
	v_max_u32_e32 v105, v117, v112
	v_min_u32_e32 v112, v117, v112
	v_max_u32_e32 v117, v103, v107
	v_min_u32_e32 v107, v103, v107
	v_max_u32_e32 v101, v101, v119
	v_max_u32_e32 v100, v100, v116
	v_max_u32_e32 v91, v91, v110
	v_max_u32_e32 v79, v79, v109
	v_max_u32_e32 v71, v71, v115
	v_max_u32_e32 v74, v74, v98
	v_max_u32_e32 v95, v95, v107
	v_max_u32_e32 v84, v84, v117
	v_max_u32_e32 v93, v93, v112
	v_max_u32_e32 v80, v80, v105
	v_max_u32_e32 v73, v73, v106
	v_max_u32_e32 v76, v76, v104
	v_max_u32_e32 v89, v89, v108
	v_max_u32_e32 v83, v83, v114
	v_max_u32_e32 v92, v92, v111
	v_max_u32_e32 v90, v90, v118
	v_max_u32_e32 v119, v101, v93
	v_min_u32_e32 v93, v101, v93
	v_max_u32_e32 v101, v100, v80
	v_min_u32_e32 v80, v100, v80
	v_max_u32_e32 v100, v91, v73
	v_min_u32_e32 v73, v91, v73
	v_max_u32_e32 v91, v79, v76
	v_min_u32_e32 v76, v79, v76
	v_max_u32_e32 v79, v71, v89
	v_min_u32_e32 v89, v71, v89
	v_max_u32_e32 v71, v74, v83
	v_min_u32_e32 v83, v74, v83
	v_max_u32_e32 v74, v95, v92
	v_min_u32_e32 v92, v95, v92
	v_max_u32_e32 v95, v84, v90
	v_min_u32_e32 v90, v84, v90
	v_max_u32_e32 v84, v119, v79
	v_min_u32_e32 v79, v119, v79
	v_max_u32_e32 v119, v101, v71
	v_min_u32_e32 v71, v101, v71
	v_max_u32_e32 v101, v100, v74
	v_min_u32_e32 v74, v100, v74
	v_max_u32_e32 v100, v91, v95
	v_min_u32_e32 v95, v91, v95
	v_max_u32_e32 v91, v93, v89
	v_min_u32_e32 v89, v93, v89
	v_max_u32_e32 v93, v80, v83
	v_min_u32_e32 v83, v80, v83
	v_max_u32_e32 v80, v73, v92
	v_min_u32_e32 v92, v73, v92
	v_max_u32_e32 v73, v76, v90
	v_min_u32_e32 v90, v76, v90
	v_max_u32_e32 v76, v84, v101
	v_min_u32_e32 v101, v84, v101
	v_max_u32_e32 v84, v119, v100
	v_min_u32_e32 v100, v119, v100
	v_max_u32_e32 v119, v79, v74
	v_min_u32_e32 v74, v79, v74
	v_max_u32_e32 v79, v71, v95
	v_min_u32_e32 v95, v71, v95
	v_max_u32_e32 v71, v91, v80
	v_min_u32_e32 v80, v91, v80
	v_max_u32_e32 v91, v93, v73
	v_min_u32_e32 v73, v93, v73
	v_max_u32_e32 v93, v89, v92
	v_min_u32_e32 v92, v89, v92
	v_max_u32_e32 v89, v83, v90
	v_min_u32_e32 v90, v83, v90
	v_max_u32_e32 v83, v76, v84
	v_min_u32_e32 v84, v76, v84
	v_max_u32_e32 v76, v101, v100
	v_min_u32_e32 v100, v101, v100
	v_max_u32_e32 v101, v119, v79
	v_min_u32_e32 v79, v119, v79
	v_max_u32_e32 v119, v74, v95
	v_min_u32_e32 v95, v74, v95
	v_max_u32_e32 v74, v71, v91
	v_min_u32_e32 v91, v71, v91
	v_max_u32_e32 v71, v80, v73
	v_min_u32_e32 v73, v80, v73
	v_max_u32_e32 v80, v93, v89
	v_min_u32_e32 v89, v93, v89
	v_max_u32_e32 v93, v92, v90
	v_min_u32_e32 v90, v92, v90
	v_pk_ashrrev_i16 v92, s42, v16
	v_bitop3_b32 v92, v16, v92, s43 bitop3:0x2d
	v_lshl_or_b32 v116, v92, 16, 31
	v_and_or_b32 v110, v92, s44, 30
	v_pk_ashrrev_i16 v92, s42, v17
	v_bitop3_b32 v92, v17, v92, s43 bitop3:0x2d
	v_lshl_or_b32 v109, v92, 16, 29
	v_and_or_b32 v115, v92, s44, 28
	v_pk_ashrrev_i16 v92, s42, v18
	v_bitop3_b32 v92, v18, v92, s43 bitop3:0x2d
	v_lshl_or_b32 v98, v92, 16, 27
	v_and_or_b32 v107, v92, s44, 26
	v_pk_ashrrev_i16 v92, s42, v19
	v_bitop3_b32 v92, v19, v92, s43 bitop3:0x2d
	v_lshl_or_b32 v117, v92, 16, 25
	v_and_or_b32 v112, v92, s44, 24
	v_pk_ashrrev_i16 v92, s42, v20
	v_bitop3_b32 v92, v20, v92, s43 bitop3:0x2d
	v_lshl_or_b32 v105, v92, 16, 23
	v_and_or_b32 v106, v92, s44, 22
	v_pk_ashrrev_i16 v92, s42, v21
	v_bitop3_b32 v92, v21, v92, s43 bitop3:0x2d
	v_lshl_or_b32 v104, v92, 16, 21
	v_and_or_b32 v108, v92, s44, 20
	v_pk_ashrrev_i16 v92, s42, v22
	v_bitop3_b32 v92, v22, v92, s43 bitop3:0x2d
	v_lshl_or_b32 v114, v92, 16, 19
	v_and_or_b32 v111, v92, s44, 18
	v_pk_ashrrev_i16 v92, s42, v23
	v_bitop3_b32 v92, v23, v92, s43 bitop3:0x2d
	v_lshl_or_b32 v118, v92, 16, 17
	v_and_or_b32 v103, v92, s44, 16
	v_max_u32_e32 v92, v116, v111
	v_min_u32_e32 v111, v116, v111
; __device__ __forceinline__ unsigned f2key(float f) { const unsigned u = __float_as_uint(f); return (u & 0x80000000u) ? ~u : (u | 0x80000000u); }
; #define CE_DESC(a, b) do { const unsigned _mx = (a) > (b) ? (a) : (b), _mn = (a) > (b) ? (b) : (a); (a) = _mx; (b) = _mn; } while (0)
; __device__ __forceinline__ void sort16_desc(unsigned (&k)[16]) {
; #pragma unroll
;     for (int size = 2; size <= 16; size <<= 1)
; #pragma unroll
;         for (int stride = size >> 1; stride > 0; stride >>= 1)
; #pragma unroll
;             for (int i = 0; i < 16; ++i) { const int j = i ^ stride;
;                 if (j > i) { if ((i & size) == 0) CE_DESC(k[i], k[j]); else CE_DESC(k[j], k[i]); } }
; }
; __device__ __forceinline__ void merge16(unsigned (&a)[16], const unsigned (&b)[16]) {
; #pragma unroll
;     for (int i = 0; i < 16; ++i) a[i] = a[i] > b[15 - i] ? a[i] : b[15 - i];
; #pragma unroll
;     for (int stride = 8; stride > 0; stride >>= 1)
; #pragma unroll
;         for (int i = 0; i < 16; ++i) { const int j = i ^ stride; if (j > i) CE_DESC(a[i], a[j]); }
; }
; __device__ __forceinline__ void peer_tile(const Args& A, LAS unsigned char* lds, int tile) {
;     ...
;                   for (int i = 0; i < 16; ++i) {
;                       const float lo = (float)__builtin_bit_cast(_Float16, (unsigned short)(sw[i] & 0xffffu)), hi = (float)__builtin_bit_cast(_Float16, (unsigned short)(sw[i] >> 16));
;                       const unsigned klo = (f2key(lo) & ~127u) | (unsigned)(127 - (32 * g + 2 * i)), khi = (f2key(hi) & ~127u) | (unsigned)(127 - (32 * g + 2 * i + 1));
;                       if (i < 8) { k0[2 * i] = klo; k0[2 * i + 1] = khi; } else { k1[2 * (i - 8)] = klo; k1[2 * (i - 8) + 1] = khi; } } }
;                 sort16_desc(k0); sort16_desc(k1); merge16(k0, k1);
	v_max_u32_e32 v116, v110, v114
	v_min_u32_e32 v114, v110, v114
	v_max_u32_e32 v110, v109, v103
	v_min_u32_e32 v103, v109, v103
	v_max_u32_e32 v109, v115, v118
	v_min_u32_e32 v118, v115, v118
	v_max_u32_e32 v115, v98, v105
	v_min_u32_e32 v105, v98, v105
	v_max_u32_e32 v98, v107, v117
	v_min_u32_e32 v117, v107, v117
	v_max_u32_e32 v107, v112, v108
	v_min_u32_e32 v108, v112, v108
	v_max_u32_e32 v112, v106, v104
	v_min_u32_e32 v104, v106, v104
	v_max_u32_e32 v106, v92, v98
	v_min_u32_e32 v98, v92, v98
	v_max_u32_e32 v92, v116, v107
	v_min_u32_e32 v107, v116, v107
	v_max_u32_e32 v116, v110, v112
	v_min_u32_e32 v112, v110, v112
	v_max_u32_e32 v110, v109, v115
	v_min_u32_e32 v115, v109, v115
	v_max_u32_e32 v109, v117, v111
	v_min_u32_e32 v111, v117, v111
	v_max_u32_e32 v117, v105, v118
	v_min_u32_e32 v118, v105, v118
	v_max_u32_e32 v105, v104, v103
	v_min_u32_e32 v103, v104, v103
	v_max_u32_e32 v104, v108, v114
	v_min_u32_e32 v114, v108, v114
	v_max_u32_e32 v108, v106, v92
	v_min_u32_e32 v92, v106, v92
	v_max_u32_e32 v106, v116, v110
	v_min_u32_e32 v110, v116, v110
	v_max_u32_e32 v116, v115, v98
	v_min_u32_e32 v98, v115, v98
	v_max_u32_e32 v115, v109, v117
	v_min_u32_e32 v117, v109, v117
	v_max_u32_e32 v109, v107, v112
	v_min_u32_e32 v112, v107, v112
	v_max_u32_e32 v107, v105, v104
	v_min_u32_e32 v104, v105, v104
	v_max_u32_e32 v105, v114, v111
	v_min_u32_e32 v111, v114, v111
	v_max_u32_e32 v114, v118, v103
	v_min_u32_e32 v103, v118, v103
	v_max_u32_e32 v118, v108, v106
	v_min_u32_e32 v106, v108, v106
	v_max_u32_e32 v108, v92, v110
	v_min_u32_e32 v110, v92, v110
	v_max_u32_e32 v92, v116, v107
	v_min_u32_e32 v107, v116, v107
	v_max_u32_e32 v116, v98, v104
	v_min_u32_e32 v104, v98, v104
	v_max_u32_e32 v98, v115, v109
	v_min_u32_e32 v109, v115, v109
	v_max_u32_e32 v115, v117, v112
	v_min_u32_e32 v112, v117, v112
	v_max_u32_e32 v117, v105, v114
	v_min_u32_e32 v114, v105, v114
	v_max_u32_e32 v105, v111, v103
	v_min_u32_e32 v103, v111, v103
	v_max_u32_e32 v111, v108, v106
	v_min_u32_e32 v106, v108, v106
	v_max_u32_e32 v108, v110, v117
	v_min_u32_e32 v117, v110, v117
	v_max_u32_e32 v110, v92, v98
	v_min_u32_e32 v98, v92, v98
	v_max_u32_e32 v92, v116, v109
	v_min_u32_e32 v109, v116, v109
	v_max_u32_e32 v116, v115, v107
	v_min_u32_e32 v107, v115, v107
	v_max_u32_e32 v115, v112, v104
	v_min_u32_e32 v104, v112, v104
	v_max_u32_e32 v112, v105, v114
	v_min_u32_e32 v114, v105, v114
	v_max_u32_e32 v105, v111, v110
	v_min_u32_e32 v110, v111, v110
	v_max_u32_e32 v111, v106, v98
	v_min_u32_e32 v98, v106, v98
	v_max_u32_e32 v106, v92, v116
	v_min_u32_e32 v116, v92, v116
	v_max_u32_e32 v92, v109, v107
	v_min_u32_e32 v107, v109, v107
	v_max_u32_e32 v109, v115, v112
	v_min_u32_e32 v112, v115, v112
	v_max_u32_e32 v115, v104, v114
	v_min_u32_e32 v114, v104, v114
	v_max_u32_e32 v104, v111, v110
	v_min_u32_e32 v110, v111, v110
	v_max_u32_e32 v111, v108, v98
	v_min_u32_e32 v98, v108, v98
	v_max_u32_e32 v108, v109, v117
	v_min_u32_e32 v117, v109, v117
	v_max_u32_e32 v109, v115, v112
	v_min_u32_e32 v112, v115, v112
	v_max_u32_e32 v115, v111, v106
	v_min_u32_e32 v106, v111, v106
	v_max_u32_e32 v111, v98, v116
	v_min_u32_e32 v116, v98, v116
	v_max_u32_e32 v98, v92, v108
	v_min_u32_e32 v108, v92, v108
	v_max_u32_e32 v92, v107, v117
	v_min_u32_e32 v117, v107, v117
	v_max_u32_e32 v107, v115, v110
	v_min_u32_e32 v110, v115, v110
	v_max_u32_e32 v115, v106, v111
	v_min_u32_e32 v111, v106, v111
	v_max_u32_e32 v106, v98, v116
	v_min_u32_e32 v116, v98, v116
	v_max_u32_e32 v98, v108, v92
	v_min_u32_e32 v92, v108, v92
	v_max_u32_e32 v108, v109, v117
	v_min_u32_e32 v117, v109, v117
	v_max_u32_e32 v109, v111, v106
	v_min_u32_e32 v106, v111, v106
	v_max_u32_e32 v111, v116, v98
	v_min_u32_e32 v98, v116, v98
	v_max_u32_e32 v83, v83, v103
	v_max_u32_e32 v84, v84, v114
	v_max_u32_e32 v76, v76, v112
	v_max_u32_e32 v100, v100, v117
	v_max_u32_e32 v101, v101, v108
	v_max_u32_e32 v79, v79, v92
	v_max_u32_e32 v119, v119, v98
	v_max_u32_e32 v95, v95, v111
	v_max_u32_e32 v74, v74, v106
	v_max_u32_e32 v91, v91, v109
	v_max_u32_e32 v71, v71, v115
	v_max_u32_e32 v73, v73, v110
	v_max_u32_e32 v80, v80, v107
	v_max_u32_e32 v89, v89, v104
	v_max_u32_e32 v93, v93, v105
	v_max_u32_e32 v90, v90, v118
	v_max_u32_e32 v103, v83, v74
	v_min_u32_e32 v74, v83, v74
	v_max_u32_e32 v83, v84, v91
	v_min_u32_e32 v91, v84, v91
	v_max_u32_e32 v84, v76, v71
	v_min_u32_e32 v71, v76, v71
	v_max_u32_e32 v76, v100, v73
	v_min_u32_e32 v73, v100, v73
	v_max_u32_e32 v100, v101, v80
	v_min_u32_e32 v80, v101, v80
	v_max_u32_e32 v101, v79, v89
	v_min_u32_e32 v89, v79, v89
	v_max_u32_e32 v79, v119, v93
	v_min_u32_e32 v93, v119, v93
	v_max_u32_e32 v119, v95, v90
	v_min_u32_e32 v90, v95, v90
	v_max_u32_e32 v95, v103, v100
	v_min_u32_e32 v100, v103, v100
	v_max_u32_e32 v103, v83, v101
	v_min_u32_e32 v101, v83, v101
	v_max_u32_e32 v83, v84, v79
	v_min_u32_e32 v79, v84, v79
	v_max_u32_e32 v84, v76, v119
	v_min_u32_e32 v119, v76, v119
	v_max_u32_e32 v76, v74, v80
	v_min_u32_e32 v80, v74, v80
	v_max_u32_e32 v74, v91, v89
	v_min_u32_e32 v89, v91, v89
	v_max_u32_e32 v91, v71, v93
	v_min_u32_e32 v93, v71, v93
	v_max_u32_e32 v71, v73, v90
	v_min_u32_e32 v90, v73, v90
	v_max_u32_e32 v73, v95, v83
	v_min_u32_e32 v83, v95, v83
	v_max_u32_e32 v95, v103, v84
	v_min_u32_e32 v84, v103, v84
	v_max_u32_e32 v103, v100, v79
	v_min_u32_e32 v79, v100, v79
	v_max_u32_e32 v100, v101, v119
	v_min_u32_e32 v119, v101, v119
	v_max_u32_e32 v101, v76, v91
	v_min_u32_e32 v91, v76, v91
	v_max_u32_e32 v76, v74, v71
	v_min_u32_e32 v71, v74, v71
	v_max_u32_e32 v74, v80, v93
	v_min_u32_e32 v93, v80, v93
	v_max_u32_e32 v80, v89, v90
	v_min_u32_e32 v90, v89, v90
; __device__ __forceinline__ unsigned f2key(float f) { const unsigned u = __float_as_uint(f); return (u & 0x80000000u) ? ~u : (u | 0x80000000u); }
; #define CE_DESC(a, b) do { const unsigned _mx = (a) > (b) ? (a) : (b), _mn = (a) > (b) ? (b) : (a); (a) = _mx; (b) = _mn; } while (0)
; __device__ __forceinline__ void sort16_desc(unsigned (&k)[16]) {
; #pragma unroll
;     for (int size = 2; size <= 16; size <<= 1)
; #pragma unroll
;         for (int stride = size >> 1; stride > 0; stride >>= 1)
; #pragma unroll
;             for (int i = 0; i < 16; ++i) { const int j = i ^ stride;
;                 if (j > i) { if ((i & size) == 0) CE_DESC(k[i], k[j]); else CE_DESC(k[j], k[i]); } }
; }
; __device__ __forceinline__ void merge16(unsigned (&a)[16], const unsigned (&b)[16]) {
; #pragma unroll
;     for (int i = 0; i < 16; ++i) a[i] = a[i] > b[15 - i] ? a[i] : b[15 - i];
; #pragma unroll
;     for (int stride = 8; stride > 0; stride >>= 1)
; #pragma unroll
;         for (int i = 0; i < 16; ++i) { const int j = i ^ stride; if (j > i) CE_DESC(a[i], a[j]); }
; }
; __device__ __forceinline__ void peer_tile(const Args& A, LAS unsigned char* lds, int tile) {
;     ...
;                   for (int i = 0; i < 16; ++i) {
;                       const float lo = (float)__builtin_bit_cast(_Float16, (unsigned short)(sw[i] & 0xffffu)), hi = (float)__builtin_bit_cast(_Float16, (unsigned short)(sw[i] >> 16));
;                       const unsigned klo = (f2key(lo) & ~127u) | (unsigned)(127 - (32 * g + 2 * i)), khi = (f2key(hi) & ~127u) | (unsigned)(127 - (32 * g + 2 * i + 1));
;                       if (i < 8) { k0[2 * i] = klo; k0[2 * i + 1] = khi; } else { k1[2 * (i - 8)] = klo; k1[2 * (i - 8) + 1] = khi; } } }
;                 sort16_desc(k0); sort16_desc(k1); merge16(k0, k1);
	v_max_u32_e32 v89, v73, v95
	v_min_u32_e32 v95, v73, v95
	v_max_u32_e32 v73, v83, v84
	v_min_u32_e32 v84, v83, v84
	v_max_u32_e32 v83, v103, v100
	v_min_u32_e32 v100, v103, v100
	v_max_u32_e32 v103, v79, v119
	v_min_u32_e32 v119, v79, v119
	v_max_u32_e32 v79, v101, v76
	v_min_u32_e32 v76, v101, v76
	v_max_u32_e32 v101, v91, v71
	v_min_u32_e32 v71, v91, v71
	v_max_u32_e32 v91, v74, v80
	v_min_u32_e32 v80, v74, v80
	v_max_u32_e32 v74, v93, v90
	v_min_u32_e32 v90, v93, v90
	v_pk_ashrrev_i16 v93, s42, v24
	v_bitop3_b32 v93, v24, v93, s43 bitop3:0x2d
	v_lshl_or_b32 v114, v93, 16, 15
	v_and_or_b32 v112, v93, s44, 14
	v_pk_ashrrev_i16 v93, s42, v25
	v_bitop3_b32 v93, v25, v93, s43 bitop3:0x2d
	v_lshl_or_b32 v117, v93, 16, 13
	v_and_or_b32 v108, v93, s44, 12
	v_pk_ashrrev_i16 v93, s42, v26
	v_bitop3_b32 v93, v26, v93, s43 bitop3:0x2d
	v_lshl_or_b32 v92, v93, 16, 11
	v_and_or_b32 v98, v93, s44, 10
	v_pk_ashrrev_i16 v93, s42, v27
	v_bitop3_b32 v93, v27, v93, s43 bitop3:0x2d
	v_lshl_or_b32 v111, v93, 16, 9
	v_and_or_b32 v106, v93, s44, 8
	v_pk_ashrrev_i16 v93, s42, v28
	v_bitop3_b32 v93, v28, v93, s43 bitop3:0x2d
	v_lshl_or_b32 v109, v93, 16, 7
	v_and_or_b32 v115, v93, s44, 6
	v_pk_ashrrev_i16 v93, s42, v29
	v_bitop3_b32 v93, v29, v93, s43 bitop3:0x2d
	v_lshl_or_b32 v110, v93, 16, 5
	v_and_or_b32 v107, v93, s44, 4
	v_pk_ashrrev_i16 v93, s42, v30
	v_bitop3_b32 v93, v30, v93, s43 bitop3:0x2d
	v_lshl_or_b32 v104, v93, 16, 3
	v_and_or_b32 v105, v93, s44, 2
	v_pk_ashrrev_i16 v93, s42, v31
	v_bitop3_b32 v93, v31, v93, s43 bitop3:0x2d
	v_lshl_or_b32 v118, v93, 16, 1
	v_and_or_b32 v116, v93, s44, 0
	v_max_u32_e32 v93, v114, v105
	v_min_u32_e32 v105, v114, v105
	v_max_u32_e32 v114, v112, v104
	v_min_u32_e32 v104, v112, v104
	v_max_u32_e32 v112, v117, v116
	v_min_u32_e32 v116, v117, v116
	v_max_u32_e32 v117, v108, v118
	v_min_u32_e32 v118, v108, v118
	v_max_u32_e32 v108, v92, v109
	v_min_u32_e32 v109, v92, v109
	v_max_u32_e32 v92, v98, v111
	v_min_u32_e32 v111, v98, v111
	v_max_u32_e32 v98, v106, v107
	v_min_u32_e32 v107, v106, v107
	v_max_u32_e32 v106, v115, v110
	v_min_u32_e32 v110, v115, v110
	v_max_u32_e32 v115, v93, v92
	v_min_u32_e32 v92, v93, v92
	v_max_u32_e32 v93, v114, v98
	v_min_u32_e32 v98, v114, v98
	v_max_u32_e32 v114, v112, v106
	v_min_u32_e32 v106, v112, v106
	v_max_u32_e32 v112, v117, v108
	v_min_u32_e32 v108, v117, v108
	v_max_u32_e32 v117, v111, v105
	v_min_u32_e32 v105, v111, v105
	v_max_u32_e32 v111, v109, v118
	v_min_u32_e32 v118, v109, v118
	v_max_u32_e32 v109, v110, v116
	v_min_u32_e32 v116, v110, v116
	v_max_u32_e32 v110, v107, v104
	v_min_u32_e32 v104, v107, v104
	v_max_u32_e32 v107, v115, v93
	v_min_u32_e32 v93, v115, v93
	v_max_u32_e32 v115, v114, v112
	v_min_u32_e32 v112, v114, v112
	v_max_u32_e32 v114, v108, v92
	v_min_u32_e32 v92, v108, v92
	v_max_u32_e32 v108, v117, v111
	v_min_u32_e32 v111, v117, v111
	v_max_u32_e32 v117, v98, v106
	v_min_u32_e32 v106, v98, v106
	v_max_u32_e32 v98, v109, v110
	v_min_u32_e32 v110, v109, v110
	v_max_u32_e32 v109, v104, v105
	v_min_u32_e32 v105, v104, v105
	v_max_u32_e32 v104, v118, v116
	v_min_u32_e32 v116, v118, v116
	v_max_u32_e32 v118, v107, v115
	v_min_u32_e32 v115, v107, v115
	v_max_u32_e32 v107, v93, v112
	v_min_u32_e32 v112, v93, v112
	v_max_u32_e32 v93, v114, v98
	v_min_u32_e32 v98, v114, v98
	v_max_u32_e32 v114, v92, v110
	v_min_u32_e32 v110, v92, v110
	v_max_u32_e32 v92, v108, v117
	v_min_u32_e32 v117, v108, v117
	v_max_u32_e32 v108, v111, v106
	v_min_u32_e32 v106, v111, v106
	v_max_u32_e32 v111, v109, v104
	v_min_u32_e32 v104, v109, v104
	v_max_u32_e32 v109, v105, v116
	v_min_u32_e32 v116, v105, v116
	v_max_u32_e32 v105, v107, v115
	v_min_u32_e32 v115, v107, v115
	v_max_u32_e32 v107, v112, v111
	v_min_u32_e32 v111, v112, v111
	v_max_u32_e32 v112, v93, v92
	v_min_u32_e32 v92, v93, v92
	v_max_u32_e32 v93, v114, v117
	v_min_u32_e32 v117, v114, v117
	v_max_u32_e32 v114, v108, v98
	v_min_u32_e32 v98, v108, v98
	v_max_u32_e32 v108, v106, v110
	v_min_u32_e32 v110, v106, v110
	v_max_u32_e32 v106, v109, v104
	v_min_u32_e32 v104, v109, v104
	v_max_u32_e32 v109, v105, v112
	v_min_u32_e32 v112, v105, v112
	v_max_u32_e32 v105, v115, v92
	v_min_u32_e32 v92, v115, v92
	v_max_u32_e32 v115, v93, v114
	v_min_u32_e32 v114, v93, v114
	v_max_u32_e32 v93, v117, v98
	v_min_u32_e32 v98, v117, v98
	v_max_u32_e32 v117, v108, v106
	v_min_u32_e32 v106, v108, v106
	v_max_u32_e32 v108, v110, v104
	v_min_u32_e32 v104, v110, v104
	v_max_u32_e32 v110, v105, v112
	v_min_u32_e32 v112, v105, v112
	v_max_u32_e32 v105, v107, v92
	v_min_u32_e32 v92, v107, v92
	v_max_u32_e32 v107, v117, v111
	v_min_u32_e32 v111, v117, v111
	v_max_u32_e32 v117, v108, v106
	v_min_u32_e32 v106, v108, v106
	v_max_u32_e32 v108, v105, v115
	v_min_u32_e32 v115, v105, v115
	v_max_u32_e32 v105, v92, v114
	v_min_u32_e32 v114, v92, v114
	v_max_u32_e32 v92, v93, v107
	v_min_u32_e32 v107, v93, v107
	v_max_u32_e32 v93, v98, v111
	v_min_u32_e32 v111, v98, v111
	v_max_u32_e32 v98, v108, v112
	v_min_u32_e32 v112, v108, v112
	v_max_u32_e32 v108, v115, v105
	v_min_u32_e32 v105, v115, v105
	v_max_u32_e32 v115, v92, v114
	v_min_u32_e32 v114, v92, v114
	v_max_u32_e32 v92, v107, v93
	v_min_u32_e32 v93, v107, v93
	v_max_u32_e32 v107, v117, v111
	v_min_u32_e32 v111, v117, v111
	v_max_u32_e32 v117, v105, v115
	v_min_u32_e32 v115, v105, v115
	v_max_u32_e32 v105, v114, v92
	v_min_u32_e32 v92, v114, v92
	v_max_u32_e32 v89, v89, v116
	v_max_u32_e32 v95, v95, v104
	v_max_u32_e32 v73, v73, v106
	v_max_u32_e32 v84, v84, v111
	v_max_u32_e32 v83, v83, v107
	v_max_u32_e32 v100, v100, v93
	v_max_u32_e32 v103, v103, v92
	v_max_u32_e32 v119, v119, v105
	v_max_u32_e32 v79, v79, v115
; __device__ __forceinline__ unsigned f2key(float f) { const unsigned u = __float_as_uint(f); return (u & 0x80000000u) ? ~u : (u | 0x80000000u); }
; #define CE_DESC(a, b) do { const unsigned _mx = (a) > (b) ? (a) : (b), _mn = (a) > (b) ? (b) : (a); (a) = _mx; (b) = _mn; } while (0)
; __device__ __forceinline__ void merge16(unsigned (&a)[16], const unsigned (&b)[16]) {
; #pragma unroll
;     for (int i = 0; i < 16; ++i) a[i] = a[i] > b[15 - i] ? a[i] : b[15 - i];
; #pragma unroll
;     for (int stride = 8; stride > 0; stride >>= 1)
; #pragma unroll
;         for (int i = 0; i < 16; ++i) { const int j = i ^ stride; if (j > i) CE_DESC(a[i], a[j]); }
; }
; __device__ __forceinline__ void peer_tile(const Args& A, LAS unsigned char* lds, int tile) {
;     ...
;                 { const bf16_t* sp = QRY + m * 2048 + hp * 128 + 32 * g;
;                   const u32x4 s0 = *(const u32x4*)sp, s1 = *(const u32x4*)(sp + 8), s2 = *(const u32x4*)(sp + 16), s3 = *(const u32x4*)(sp + 24);
;                   const unsigned sw[16] = {s0.x, s0.y, s0.z, s0.w, s1.x, s1.y, s1.z, s1.w, s2.x, s2.y, s2.z, s2.w, s3.x, s3.y, s3.z, s3.w};
; #pragma unroll
;                   for (int i = 0; i < 16; ++i) {
;                       const float lo = (float)__builtin_bit_cast(_Float16, (unsigned short)(sw[i] & 0xffffu)), hi = (float)__builtin_bit_cast(_Float16, (unsigned short)(sw[i] >> 16));
;                       const unsigned klo = (f2key(lo) & ~127u) | (unsigned)(127 - (32 * g + 2 * i)), khi = (f2key(hi) & ~127u) | (unsigned)(127 - (32 * g + 2 * i + 1));
;                       if (i < 8) { k0[2 * i] = klo; k0[2 * i + 1] = khi; } else { k1[2 * (i - 8)] = klo; k1[2 * (i - 8) + 1] = khi; } } }
;                 sort16_desc(k0); sort16_desc(k1); merge16(k0, k1);
	v_max_u32_e32 v76, v76, v117
	v_max_u32_e32 v101, v101, v108
	v_max_u32_e32 v71, v71, v112
	v_max_u32_e32 v91, v91, v98
	v_max_u32_e32 v80, v80, v110
	v_max_u32_e32 v74, v74, v109
	v_max_u32_e32 v90, v90, v118
	v_max_u32_e32 v116, v89, v79
	v_min_u32_e32 v79, v89, v79
	v_max_u32_e32 v89, v95, v76
	v_min_u32_e32 v76, v95, v76
	v_max_u32_e32 v95, v73, v101
	v_min_u32_e32 v101, v73, v101
	v_max_u32_e32 v73, v84, v71
	v_min_u32_e32 v71, v84, v71
	v_max_u32_e32 v84, v83, v91
	v_min_u32_e32 v91, v83, v91
	v_max_u32_e32 v83, v100, v80
	v_min_u32_e32 v80, v100, v80
	v_max_u32_e32 v100, v103, v74
	v_min_u32_e32 v74, v103, v74
	v_max_u32_e32 v103, v119, v90
	v_min_u32_e32 v90, v119, v90
	v_max_u32_e32 v119, v116, v84
	v_min_u32_e32 v84, v116, v84
	v_max_u32_e32 v116, v89, v83
	v_min_u32_e32 v83, v89, v83
	v_max_u32_e32 v89, v95, v100
	v_min_u32_e32 v100, v95, v100
	v_max_u32_e32 v95, v73, v103
	v_min_u32_e32 v103, v73, v103
	v_max_u32_e32 v73, v79, v91
	v_min_u32_e32 v91, v79, v91
	v_max_u32_e32 v79, v76, v80
	v_min_u32_e32 v80, v76, v80
	v_max_u32_e32 v76, v101, v74
	v_min_u32_e32 v74, v101, v74
	v_max_u32_e32 v101, v71, v90
	v_min_u32_e32 v90, v71, v90
	v_max_u32_e32 v71, v119, v89
	v_min_u32_e32 v89, v119, v89
	v_max_u32_e32 v119, v116, v95
	v_min_u32_e32 v95, v116, v95
	v_max_u32_e32 v116, v84, v100
	v_min_u32_e32 v100, v84, v100
	v_max_u32_e32 v84, v83, v103
	v_min_u32_e32 v103, v83, v103
	v_max_u32_e32 v83, v73, v76
	v_min_u32_e32 v76, v73, v76
	v_max_u32_e32 v73, v79, v101
	v_min_u32_e32 v101, v79, v101
	v_max_u32_e32 v79, v91, v74
	v_min_u32_e32 v74, v91, v74
	v_max_u32_e32 v91, v80, v90
	v_min_u32_e32 v90, v80, v90
	v_max_u32_e32 v80, v71, v119
	v_min_u32_e32 v119, v71, v119
	v_max_u32_e32 v71, v89, v95
	v_min_u32_e32 v95, v89, v95
	v_max_u32_e32 v89, v116, v84
	v_min_u32_e32 v84, v116, v84
	v_max_u32_e32 v116, v100, v103
	v_min_u32_e32 v103, v100, v103
	v_max_u32_e32 v100, v83, v73
	v_min_u32_e32 v73, v83, v73
	v_max_u32_e32 v83, v76, v101
	v_min_u32_e32 v101, v76, v101
	v_max_u32_e32 v76, v79, v91
	v_min_u32_e32 v91, v79, v91
	v_max_u32_e32 v79, v74, v90
	v_min_u32_e32 v90, v74, v90
	v_or_b32_e32 v80, 64, v80
	v_or_b32_e32 v119, 64, v119
	v_or_b32_e32 v71, 64, v71
	v_or_b32_e32 v95, 64, v95
	v_or_b32_e32 v89, 64, v89
	v_or_b32_e32 v84, 64, v84
	v_or_b32_e32 v116, 64, v116
	v_or_b32_e32 v103, 64, v103
	v_or_b32_e32 v100, 64, v100
	v_or_b32_e32 v73, 64, v73
	v_or_b32_e32 v83, 64, v83
	v_or_b32_e32 v101, 64, v101
	v_or_b32_e32 v76, 64, v76
	v_or_b32_e32 v91, 64, v91
	v_or_b32_e32 v79, 64, v79
	v_or_b32_e32 v90, 64, v90
	s_waitcnt vmcnt(0)
	ds_write_b128 v64, v[32:35] offset:0
	ds_write_b128 v64, v[36:39] offset:1152
	ds_write_b128 v64, v[40:43] offset:2304
	ds_write_b128 v64, v[44:47] offset:3456
	ds_write_b128 v64, v[48:51] offset:4608
	ds_write_b128 v64, v[52:55] offset:5760
	ds_write_b128 v64, v[56:59] offset:6912
	ds_write_b128 v64, v[60:63] offset:8064
	s_waitcnt lgkmcnt(0)
	ds_read_b128 v[32:35], v65 offset:0
	ds_read_b128 v[36:39], v65 offset:16
	ds_read_b128 v[40:43], v65 offset:32
	ds_read_b128 v[44:47], v65 offset:48
	ds_read_b128 v[48:51], v65 offset:64
	ds_read_b128 v[52:55], v65 offset:80
	ds_read_b128 v[56:59], v65 offset:96
	ds_read_b128 v[60:63], v65 offset:112
	s_waitcnt lgkmcnt(0)
	v_pk_ashrrev_i16 v74, s42, v32
	v_bitop3_b32 v74, v32, v74, s43 bitop3:0x2d
	v_lshl_or_b32 v104, v74, 16, 63
	v_and_or_b32 v106, v74, s44, 62
	v_pk_ashrrev_i16 v74, s42, v33
	v_bitop3_b32 v74, v33, v74, s43 bitop3:0x2d
	v_lshl_or_b32 v111, v74, 16, 61
	v_and_or_b32 v107, v74, s44, 60
	v_pk_ashrrev_i16 v74, s42, v34
	v_bitop3_b32 v74, v34, v74, s43 bitop3:0x2d
	v_lshl_or_b32 v93, v74, 16, 59
	v_and_or_b32 v92, v74, s44, 58
	v_pk_ashrrev_i16 v74, s42, v35
	v_bitop3_b32 v74, v35, v74, s43 bitop3:0x2d
	v_lshl_or_b32 v105, v74, 16, 57
	v_and_or_b32 v115, v74, s44, 56
	v_pk_ashrrev_i16 v74, s42, v36
	v_bitop3_b32 v74, v36, v74, s43 bitop3:0x2d
	v_lshl_or_b32 v117, v74, 16, 55
	v_and_or_b32 v108, v74, s44, 54
	v_pk_ashrrev_i16 v74, s42, v37
	v_bitop3_b32 v74, v37, v74, s43 bitop3:0x2d
	v_lshl_or_b32 v112, v74, 16, 53
	v_and_or_b32 v98, v74, s44, 52
	v_pk_ashrrev_i16 v74, s42, v38
	v_bitop3_b32 v74, v38, v74, s43 bitop3:0x2d
	v_lshl_or_b32 v110, v74, 16, 51
	v_and_or_b32 v109, v74, s44, 50
	v_pk_ashrrev_i16 v74, s42, v39
	v_bitop3_b32 v74, v39, v74, s43 bitop3:0x2d
	v_lshl_or_b32 v118, v74, 16, 49
	v_and_or_b32 v114, v74, s44, 48
	v_max_u32_e32 v74, v104, v109
	v_min_u32_e32 v109, v104, v109
	v_max_u32_e32 v104, v106, v110
	v_min_u32_e32 v110, v106, v110
	v_max_u32_e32 v106, v111, v114
	v_min_u32_e32 v114, v111, v114
	v_max_u32_e32 v111, v107, v118
	v_min_u32_e32 v118, v107, v118
	v_max_u32_e32 v107, v93, v117
	v_min_u32_e32 v117, v93, v117
	v_max_u32_e32 v93, v92, v105
	v_min_u32_e32 v105, v92, v105
	v_max_u32_e32 v92, v115, v98
	v_min_u32_e32 v98, v115, v98
	v_max_u32_e32 v115, v108, v112
	v_min_u32_e32 v112, v108, v112
	v_max_u32_e32 v108, v74, v93
	v_min_u32_e32 v93, v74, v93
	v_max_u32_e32 v74, v104, v92
	v_min_u32_e32 v92, v104, v92
	v_max_u32_e32 v104, v106, v115
	v_min_u32_e32 v115, v106, v115
	v_max_u32_e32 v106, v111, v107
	v_min_u32_e32 v107, v111, v107
	v_max_u32_e32 v111, v105, v109
	v_min_u32_e32 v109, v105, v109
	v_max_u32_e32 v105, v117, v118
	v_min_u32_e32 v118, v117, v118
	v_max_u32_e32 v117, v112, v114
	v_min_u32_e32 v114, v112, v114
	v_max_u32_e32 v112, v98, v110
	v_min_u32_e32 v110, v98, v110
	v_max_u32_e32 v98, v108, v74
	v_min_u32_e32 v74, v108, v74
	v_max_u32_e32 v108, v104, v106
	v_min_u32_e32 v106, v104, v106
	v_max_u32_e32 v104, v107, v93
	v_min_u32_e32 v93, v107, v93
	v_max_u32_e32 v107, v111, v105
	v_min_u32_e32 v105, v111, v105
; __device__ __forceinline__ unsigned f2key(float f) { const unsigned u = __float_as_uint(f); return (u & 0x80000000u) ? ~u : (u | 0x80000000u); }
; #define CE_DESC(a, b) do { const unsigned _mx = (a) > (b) ? (a) : (b), _mn = (a) > (b) ? (b) : (a); (a) = _mx; (b) = _mn; } while (0)
; __device__ __forceinline__ void sort16_desc(unsigned (&k)[16]) {
; #pragma unroll
;     for (int size = 2; size <= 16; size <<= 1)
; #pragma unroll
;         for (int stride = size >> 1; stride > 0; stride >>= 1)
; #pragma unroll
;             for (int i = 0; i < 16; ++i) { const int j = i ^ stride;
;                 if (j > i) { if ((i & size) == 0) CE_DESC(k[i], k[j]); else CE_DESC(k[j], k[i]); } }
; }
; __device__ __forceinline__ void merge16(unsigned (&a)[16], const unsigned (&b)[16]) {
; #pragma unroll
;     for (int i = 0; i < 16; ++i) a[i] = a[i] > b[15 - i] ? a[i] : b[15 - i];
; #pragma unroll
;     for (int stride = 8; stride > 0; stride >>= 1)
; #pragma unroll
;         for (int i = 0; i < 16; ++i) { const int j = i ^ stride; if (j > i) CE_DESC(a[i], a[j]); }
; }
; __device__ __forceinline__ void peer_tile(const Args& A, LAS unsigned char* lds, int tile) {
;     ...
;                   for (int i = 0; i < 16; ++i) {
;                       const float lo = (float)__builtin_bit_cast(_Float16, (unsigned short)(sw[i] & 0xffffu)), hi = (float)__builtin_bit_cast(_Float16, (unsigned short)(sw[i] >> 16));
;                       const unsigned klo = (f2key(lo) & ~127u) | (unsigned)(127 - (32 * g + 2 * i)), khi = (f2key(hi) & ~127u) | (unsigned)(127 - (32 * g + 2 * i + 1));
;                       if (i < 8) { k0[2 * i] = klo; k0[2 * i + 1] = khi; } else { k1[2 * (i - 8)] = klo; k1[2 * (i - 8) + 1] = khi; } } }
;                 sort16_desc(k0); sort16_desc(k1); merge16(k0, k1);
	v_max_u32_e32 v111, v92, v115
	v_min_u32_e32 v115, v92, v115
	v_max_u32_e32 v92, v117, v112
	v_min_u32_e32 v112, v117, v112
	v_max_u32_e32 v117, v110, v109
	v_min_u32_e32 v109, v110, v109
	v_max_u32_e32 v110, v118, v114
	v_min_u32_e32 v114, v118, v114
	v_max_u32_e32 v118, v98, v108
	v_min_u32_e32 v108, v98, v108
	v_max_u32_e32 v98, v74, v106
	v_min_u32_e32 v106, v74, v106
	v_max_u32_e32 v74, v104, v92
	v_min_u32_e32 v92, v104, v92
	v_max_u32_e32 v104, v93, v112
	v_min_u32_e32 v112, v93, v112
	v_max_u32_e32 v93, v107, v111
	v_min_u32_e32 v111, v107, v111
	v_max_u32_e32 v107, v105, v115
	v_min_u32_e32 v115, v105, v115
	v_max_u32_e32 v105, v117, v110
	v_min_u32_e32 v110, v117, v110
	v_max_u32_e32 v117, v109, v114
	v_min_u32_e32 v114, v109, v114
	v_max_u32_e32 v109, v98, v108
	v_min_u32_e32 v108, v98, v108
	v_max_u32_e32 v98, v106, v105
	v_min_u32_e32 v105, v106, v105
	v_max_u32_e32 v106, v74, v93
	v_min_u32_e32 v93, v74, v93
	v_max_u32_e32 v74, v104, v111
	v_min_u32_e32 v111, v104, v111
	v_max_u32_e32 v104, v107, v92
	v_min_u32_e32 v92, v107, v92
	v_max_u32_e32 v107, v115, v112
	v_min_u32_e32 v112, v115, v112
	v_max_u32_e32 v115, v117, v110
	v_min_u32_e32 v110, v117, v110
	v_max_u32_e32 v117, v109, v106
	v_min_u32_e32 v106, v109, v106
	v_max_u32_e32 v109, v108, v93
	v_min_u32_e32 v93, v108, v93
	v_max_u32_e32 v108, v74, v104
	v_min_u32_e32 v104, v74, v104
	v_max_u32_e32 v74, v111, v92
	v_min_u32_e32 v92, v111, v92
	v_max_u32_e32 v111, v107, v115
	v_min_u32_e32 v115, v107, v115
	v_max_u32_e32 v107, v112, v110
	v_min_u32_e32 v110, v112, v110
	v_max_u32_e32 v112, v109, v106
	v_min_u32_e32 v106, v109, v106
	v_max_u32_e32 v109, v98, v93
	v_min_u32_e32 v93, v98, v93
	v_max_u32_e32 v98, v111, v105
	v_min_u32_e32 v105, v111, v105
	v_max_u32_e32 v111, v107, v115
	v_min_u32_e32 v115, v107, v115
	v_max_u32_e32 v107, v109, v108
	v_min_u32_e32 v108, v109, v108
	v_max_u32_e32 v109, v93, v104
	v_min_u32_e32 v104, v93, v104
	v_max_u32_e32 v93, v74, v98
	v_min_u32_e32 v98, v74, v98
	v_max_u32_e32 v74, v92, v105
	v_min_u32_e32 v105, v92, v105
	v_max_u32_e32 v92, v107, v106
	v_min_u32_e32 v106, v107, v106
	v_max_u32_e32 v107, v108, v109
	v_min_u32_e32 v109, v108, v109
	v_max_u32_e32 v108, v93, v104
	v_min_u32_e32 v104, v93, v104
	v_max_u32_e32 v93, v98, v74
	v_min_u32_e32 v74, v98, v74
	v_max_u32_e32 v98, v111, v105
	v_min_u32_e32 v105, v111, v105
	v_max_u32_e32 v111, v109, v108
	v_min_u32_e32 v108, v109, v108
	v_max_u32_e32 v109, v104, v93
	v_min_u32_e32 v93, v104, v93
	v_max_u32_e32 v80, v80, v114
	v_max_u32_e32 v119, v119, v110
	v_max_u32_e32 v71, v71, v115
	v_max_u32_e32 v95, v95, v105
	v_max_u32_e32 v89, v89, v98
	v_max_u32_e32 v84, v84, v74
	v_max_u32_e32 v116, v116, v93
	v_max_u32_e32 v103, v103, v109
	v_max_u32_e32 v100, v100, v108
	v_max_u32_e32 v73, v73, v111
	v_max_u32_e32 v83, v83, v107
	v_max_u32_e32 v101, v101, v106
	v_max_u32_e32 v76, v76, v92
	v_max_u32_e32 v91, v91, v112
	v_max_u32_e32 v79, v79, v117
	v_max_u32_e32 v90, v90, v118
	v_max_u32_e32 v114, v80, v100
	v_min_u32_e32 v100, v80, v100
	v_max_u32_e32 v80, v119, v73
	v_min_u32_e32 v73, v119, v73
	v_max_u32_e32 v119, v71, v83
	v_min_u32_e32 v83, v71, v83
	v_max_u32_e32 v71, v95, v101
	v_min_u32_e32 v101, v95, v101
	v_max_u32_e32 v95, v89, v76
	v_min_u32_e32 v76, v89, v76
	v_max_u32_e32 v89, v84, v91
	v_min_u32_e32 v91, v84, v91
	v_max_u32_e32 v84, v116, v79
	v_min_u32_e32 v79, v116, v79
	v_max_u32_e32 v116, v103, v90
	v_min_u32_e32 v90, v103, v90
	v_max_u32_e32 v103, v114, v95
	v_min_u32_e32 v95, v114, v95
	v_max_u32_e32 v114, v80, v89
	v_min_u32_e32 v89, v80, v89
	v_max_u32_e32 v80, v119, v84
	v_min_u32_e32 v84, v119, v84
	v_max_u32_e32 v119, v71, v116
	v_min_u32_e32 v116, v71, v116
	v_max_u32_e32 v71, v100, v76
	v_min_u32_e32 v76, v100, v76
	v_max_u32_e32 v100, v73, v91
	v_min_u32_e32 v91, v73, v91
	v_max_u32_e32 v73, v83, v79
	v_min_u32_e32 v79, v83, v79
	v_max_u32_e32 v83, v101, v90
	v_min_u32_e32 v90, v101, v90
	v_max_u32_e32 v101, v103, v80
	v_min_u32_e32 v80, v103, v80
	v_max_u32_e32 v103, v114, v119
	v_min_u32_e32 v119, v114, v119
	v_max_u32_e32 v114, v95, v84
	v_min_u32_e32 v84, v95, v84
	v_max_u32_e32 v95, v89, v116
	v_min_u32_e32 v116, v89, v116
	v_max_u32_e32 v89, v71, v73
	v_min_u32_e32 v73, v71, v73
	v_max_u32_e32 v71, v100, v83
	v_min_u32_e32 v83, v100, v83
	v_max_u32_e32 v100, v76, v79
	v_min_u32_e32 v79, v76, v79
	v_max_u32_e32 v76, v91, v90
	v_min_u32_e32 v90, v91, v90
	v_max_u32_e32 v91, v101, v103
	v_min_u32_e32 v103, v101, v103
	v_max_u32_e32 v101, v80, v119
	v_min_u32_e32 v119, v80, v119
	v_max_u32_e32 v80, v114, v95
	v_min_u32_e32 v95, v114, v95
	v_max_u32_e32 v114, v84, v116
	v_min_u32_e32 v116, v84, v116
	v_max_u32_e32 v84, v89, v71
	v_min_u32_e32 v71, v89, v71
	v_max_u32_e32 v89, v73, v83
	v_min_u32_e32 v83, v73, v83
	v_max_u32_e32 v73, v100, v76
	v_min_u32_e32 v76, v100, v76
	v_max_u32_e32 v100, v79, v90
	v_min_u32_e32 v90, v79, v90
	v_pk_ashrrev_i16 v79, s42, v40
	v_bitop3_b32 v79, v40, v79, s43 bitop3:0x2d
	v_lshl_or_b32 v110, v79, 16, 47
	v_and_or_b32 v115, v79, s44, 46
	v_pk_ashrrev_i16 v79, s42, v41
	v_bitop3_b32 v79, v41, v79, s43 bitop3:0x2d
	v_lshl_or_b32 v105, v79, 16, 45
	v_and_or_b32 v98, v79, s44, 44
	v_pk_ashrrev_i16 v79, s42, v42
	v_bitop3_b32 v79, v42, v79, s43 bitop3:0x2d
	v_lshl_or_b32 v74, v79, 16, 43
	v_and_or_b32 v93, v79, s44, 42
	v_pk_ashrrev_i16 v79, s42, v43
	v_bitop3_b32 v79, v43, v79, s43 bitop3:0x2d
	v_lshl_or_b32 v109, v79, 16, 41
	v_and_or_b32 v108, v79, s44, 40
	v_pk_ashrrev_i16 v79, s42, v44
	v_bitop3_b32 v79, v44, v79, s43 bitop3:0x2d
	v_lshl_or_b32 v111, v79, 16, 39
	v_and_or_b32 v107, v79, s44, 38
	v_pk_ashrrev_i16 v79, s42, v45
; __device__ __forceinline__ unsigned f2key(float f) { const unsigned u = __float_as_uint(f); return (u & 0x80000000u) ? ~u : (u | 0x80000000u); }
; #define CE_DESC(a, b) do { const unsigned _mx = (a) > (b) ? (a) : (b), _mn = (a) > (b) ? (b) : (a); (a) = _mx; (b) = _mn; } while (0)
; __device__ __forceinline__ void sort16_desc(unsigned (&k)[16]) {
; #pragma unroll
;     for (int size = 2; size <= 16; size <<= 1)
; #pragma unroll
;         for (int stride = size >> 1; stride > 0; stride >>= 1)
; #pragma unroll
;             for (int i = 0; i < 16; ++i) { const int j = i ^ stride;
;                 if (j > i) { if ((i & size) == 0) CE_DESC(k[i], k[j]); else CE_DESC(k[j], k[i]); } }
; }
; __device__ __forceinline__ void merge16(unsigned (&a)[16], const unsigned (&b)[16]) {
; #pragma unroll
;     for (int i = 0; i < 16; ++i) a[i] = a[i] > b[15 - i] ? a[i] : b[15 - i];
; #pragma unroll
;     for (int stride = 8; stride > 0; stride >>= 1)
; #pragma unroll
;         for (int i = 0; i < 16; ++i) { const int j = i ^ stride; if (j > i) CE_DESC(a[i], a[j]); }
; }
; __device__ __forceinline__ void peer_tile(const Args& A, LAS unsigned char* lds, int tile) {
;     ...
;                   for (int i = 0; i < 16; ++i) {
;                       const float lo = (float)__builtin_bit_cast(_Float16, (unsigned short)(sw[i] & 0xffffu)), hi = (float)__builtin_bit_cast(_Float16, (unsigned short)(sw[i] >> 16));
;                       const unsigned klo = (f2key(lo) & ~127u) | (unsigned)(127 - (32 * g + 2 * i)), khi = (f2key(hi) & ~127u) | (unsigned)(127 - (32 * g + 2 * i + 1));
;                       if (i < 8) { k0[2 * i] = klo; k0[2 * i + 1] = khi; } else { k1[2 * (i - 8)] = klo; k1[2 * (i - 8) + 1] = khi; } } }
;                 sort16_desc(k0); sort16_desc(k1); merge16(k0, k1);
; #pragma unroll
;                 for (int msk = 16; msk <= 32; msk <<= 1) {
; #pragma unroll
;                     for (int i = 0; i < 16; ++i) k1[i] = (unsigned)__shfl_xor((int)k0[i], msk);
;                     merge16(k0, k1); }
	v_bitop3_b32 v79, v45, v79, s43 bitop3:0x2d
	v_lshl_or_b32 v106, v79, 16, 37
	v_and_or_b32 v92, v79, s44, 36
	v_pk_ashrrev_i16 v79, s42, v46
	v_bitop3_b32 v79, v46, v79, s43 bitop3:0x2d
	v_lshl_or_b32 v112, v79, 16, 35
	v_and_or_b32 v117, v79, s44, 34
	v_pk_ashrrev_i16 v79, s42, v47
	v_bitop3_b32 v79, v47, v79, s43 bitop3:0x2d
	v_lshl_or_b32 v118, v79, 16, 33
	v_and_or_b32 v104, v79, s44, 32
	v_max_u32_e32 v79, v110, v117
	v_min_u32_e32 v117, v110, v117
	v_max_u32_e32 v110, v115, v112
	v_min_u32_e32 v112, v115, v112
	v_max_u32_e32 v115, v105, v104
	v_min_u32_e32 v104, v105, v104
	v_max_u32_e32 v105, v98, v118
	v_min_u32_e32 v118, v98, v118
	v_max_u32_e32 v98, v74, v111
	v_min_u32_e32 v111, v74, v111
	v_max_u32_e32 v74, v93, v109
	v_min_u32_e32 v109, v93, v109
	v_max_u32_e32 v93, v108, v92
	v_min_u32_e32 v92, v108, v92
	v_max_u32_e32 v108, v107, v106
	v_min_u32_e32 v106, v107, v106
	v_max_u32_e32 v107, v79, v74
	v_min_u32_e32 v74, v79, v74
	v_max_u32_e32 v79, v110, v93
	v_min_u32_e32 v93, v110, v93
	v_max_u32_e32 v110, v115, v108
	v_min_u32_e32 v108, v115, v108
	v_max_u32_e32 v115, v105, v98
	v_min_u32_e32 v98, v105, v98
	v_max_u32_e32 v105, v109, v117
	v_min_u32_e32 v117, v109, v117
	v_max_u32_e32 v109, v111, v118
	v_min_u32_e32 v118, v111, v118
	v_max_u32_e32 v111, v106, v104
	v_min_u32_e32 v104, v106, v104
	v_max_u32_e32 v106, v92, v112
	v_min_u32_e32 v112, v92, v112
	v_max_u32_e32 v92, v107, v79
	v_min_u32_e32 v79, v107, v79
	v_max_u32_e32 v107, v110, v115
	v_min_u32_e32 v115, v110, v115
	v_max_u32_e32 v110, v98, v74
	v_min_u32_e32 v74, v98, v74
	v_max_u32_e32 v98, v105, v109
	v_min_u32_e32 v109, v105, v109
	v_max_u32_e32 v105, v93, v108
	v_min_u32_e32 v108, v93, v108
	v_max_u32_e32 v93, v111, v106
	v_min_u32_e32 v106, v111, v106
	v_max_u32_e32 v111, v112, v117
	v_min_u32_e32 v117, v112, v117
	v_max_u32_e32 v112, v118, v104
	v_min_u32_e32 v104, v118, v104
	v_max_u32_e32 v118, v92, v107
	v_min_u32_e32 v107, v92, v107
	v_max_u32_e32 v92, v79, v115
	v_min_u32_e32 v115, v79, v115
	v_max_u32_e32 v79, v110, v93
	v_min_u32_e32 v93, v110, v93
	v_max_u32_e32 v110, v74, v106
	v_min_u32_e32 v106, v74, v106
	v_max_u32_e32 v74, v98, v105
	v_min_u32_e32 v105, v98, v105
	v_max_u32_e32 v98, v109, v108
	v_min_u32_e32 v108, v109, v108
	v_max_u32_e32 v109, v111, v112
	v_min_u32_e32 v112, v111, v112
	v_max_u32_e32 v111, v117, v104
	v_min_u32_e32 v104, v117, v104
	v_max_u32_e32 v117, v92, v107
	v_min_u32_e32 v107, v92, v107
	v_max_u32_e32 v92, v115, v109
	v_min_u32_e32 v109, v115, v109
	v_max_u32_e32 v115, v79, v74
	v_min_u32_e32 v74, v79, v74
	v_max_u32_e32 v79, v110, v105
	v_min_u32_e32 v105, v110, v105
	v_max_u32_e32 v110, v98, v93
	v_min_u32_e32 v93, v98, v93
	v_max_u32_e32 v98, v108, v106
	v_min_u32_e32 v106, v108, v106
	v_max_u32_e32 v108, v111, v112
	v_min_u32_e32 v112, v111, v112
	v_max_u32_e32 v111, v117, v115
	v_min_u32_e32 v115, v117, v115
	v_max_u32_e32 v117, v107, v74
	v_min_u32_e32 v74, v107, v74
	v_max_u32_e32 v107, v79, v110
	v_min_u32_e32 v110, v79, v110
	v_max_u32_e32 v79, v105, v93
	v_min_u32_e32 v93, v105, v93
	v_max_u32_e32 v105, v98, v108
	v_min_u32_e32 v108, v98, v108
	v_max_u32_e32 v98, v106, v112
	v_min_u32_e32 v112, v106, v112
	v_max_u32_e32 v106, v117, v115
	v_min_u32_e32 v115, v117, v115
	v_max_u32_e32 v117, v92, v74
	v_min_u32_e32 v74, v92, v74
	v_max_u32_e32 v92, v105, v109
	v_min_u32_e32 v109, v105, v109
	v_max_u32_e32 v105, v98, v108
	v_min_u32_e32 v108, v98, v108
	v_max_u32_e32 v98, v117, v107
	v_min_u32_e32 v107, v117, v107
	v_max_u32_e32 v117, v74, v110
	v_min_u32_e32 v110, v74, v110
	v_max_u32_e32 v74, v79, v92
	v_min_u32_e32 v92, v79, v92
	v_max_u32_e32 v79, v93, v109
	v_min_u32_e32 v109, v93, v109
	v_max_u32_e32 v93, v98, v115
	v_min_u32_e32 v115, v98, v115
	v_max_u32_e32 v98, v107, v117
	v_min_u32_e32 v117, v107, v117
	v_max_u32_e32 v107, v74, v110
	v_min_u32_e32 v110, v74, v110
	v_max_u32_e32 v74, v92, v79
	v_min_u32_e32 v79, v92, v79
	v_max_u32_e32 v92, v105, v109
	v_min_u32_e32 v109, v105, v109
	v_max_u32_e32 v105, v117, v107
	v_min_u32_e32 v107, v117, v107
	v_max_u32_e32 v117, v110, v74
	v_min_u32_e32 v74, v110, v74
	v_max_u32_e32 v91, v91, v104
	v_max_u32_e32 v103, v103, v112
	v_max_u32_e32 v101, v101, v108
	v_max_u32_e32 v119, v119, v109
	v_max_u32_e32 v80, v80, v92
	v_max_u32_e32 v95, v95, v79
	v_max_u32_e32 v114, v114, v74
	v_max_u32_e32 v116, v116, v117
	v_max_u32_e32 v84, v84, v107
	v_max_u32_e32 v71, v71, v105
	v_max_u32_e32 v89, v89, v98
	v_max_u32_e32 v83, v83, v115
	v_max_u32_e32 v73, v73, v93
	v_max_u32_e32 v76, v76, v106
	v_max_u32_e32 v100, v100, v111
	v_max_u32_e32 v90, v90, v118
	v_max_u32_e32 v104, v91, v84
	v_min_u32_e32 v84, v91, v84
	v_max_u32_e32 v91, v103, v71
	v_min_u32_e32 v71, v103, v71
	v_max_u32_e32 v103, v101, v89
	v_min_u32_e32 v89, v101, v89
	v_max_u32_e32 v101, v119, v83
	v_min_u32_e32 v83, v119, v83
	v_max_u32_e32 v119, v80, v73
	v_min_u32_e32 v73, v80, v73
	v_max_u32_e32 v80, v95, v76
	v_min_u32_e32 v76, v95, v76
	v_max_u32_e32 v95, v114, v100
	v_min_u32_e32 v100, v114, v100
	v_max_u32_e32 v114, v116, v90
	v_min_u32_e32 v90, v116, v90
	v_max_u32_e32 v116, v104, v119
	v_min_u32_e32 v119, v104, v119
	v_max_u32_e32 v104, v91, v80
	v_min_u32_e32 v80, v91, v80
	v_max_u32_e32 v91, v103, v95
	v_min_u32_e32 v95, v103, v95
	v_max_u32_e32 v103, v101, v114
	v_min_u32_e32 v114, v101, v114
	v_max_u32_e32 v101, v84, v73
	v_min_u32_e32 v73, v84, v73
	v_max_u32_e32 v84, v71, v76
	v_min_u32_e32 v76, v71, v76
	v_max_u32_e32 v71, v89, v100
	v_min_u32_e32 v100, v89, v100
	v_max_u32_e32 v89, v83, v90
	v_min_u32_e32 v90, v83, v90
	v_max_u32_e32 v83, v116, v91
	v_min_u32_e32 v91, v116, v91
; __device__ __forceinline__ unsigned f2key(float f) { const unsigned u = __float_as_uint(f); return (u & 0x80000000u) ? ~u : (u | 0x80000000u); }
; #define CE_DESC(a, b) do { const unsigned _mx = (a) > (b) ? (a) : (b), _mn = (a) > (b) ? (b) : (a); (a) = _mx; (b) = _mn; } while (0)
; __device__ __forceinline__ void sort16_desc(unsigned (&k)[16]) {
; #pragma unroll
;     for (int size = 2; size <= 16; size <<= 1)
; #pragma unroll
;         for (int stride = size >> 1; stride > 0; stride >>= 1)
; #pragma unroll
;             for (int i = 0; i < 16; ++i) { const int j = i ^ stride;
;                 if (j > i) { if ((i & size) == 0) CE_DESC(k[i], k[j]); else CE_DESC(k[j], k[i]); } }
; }
; __device__ __forceinline__ void merge16(unsigned (&a)[16], const unsigned (&b)[16]) {
; #pragma unroll
;     for (int i = 0; i < 16; ++i) a[i] = a[i] > b[15 - i] ? a[i] : b[15 - i];
; #pragma unroll
;     for (int stride = 8; stride > 0; stride >>= 1)
; #pragma unroll
;         for (int i = 0; i < 16; ++i) { const int j = i ^ stride; if (j > i) CE_DESC(a[i], a[j]); }
; }
; __device__ __forceinline__ void peer_tile(const Args& A, LAS unsigned char* lds, int tile) {
;     ...
;                   for (int i = 0; i < 16; ++i) {
;                       const float lo = (float)__builtin_bit_cast(_Float16, (unsigned short)(sw[i] & 0xffffu)), hi = (float)__builtin_bit_cast(_Float16, (unsigned short)(sw[i] >> 16));
;                       const unsigned klo = (f2key(lo) & ~127u) | (unsigned)(127 - (32 * g + 2 * i)), khi = (f2key(hi) & ~127u) | (unsigned)(127 - (32 * g + 2 * i + 1));
;                       if (i < 8) { k0[2 * i] = klo; k0[2 * i + 1] = khi; } else { k1[2 * (i - 8)] = klo; k1[2 * (i - 8) + 1] = khi; } } }
;                 sort16_desc(k0); sort16_desc(k1); merge16(k0, k1);
; #pragma unroll
;                 for (int msk = 16; msk <= 32; msk <<= 1) {
; #pragma unroll
;                     for (int i = 0; i < 16; ++i) k1[i] = (unsigned)__shfl_xor((int)k0[i], msk);
;                     merge16(k0, k1); }
	v_max_u32_e32 v116, v104, v103
	v_min_u32_e32 v103, v104, v103
	v_max_u32_e32 v104, v119, v95
	v_min_u32_e32 v95, v119, v95
	v_max_u32_e32 v119, v80, v114
	v_min_u32_e32 v114, v80, v114
	v_max_u32_e32 v80, v101, v71
	v_min_u32_e32 v71, v101, v71
	v_max_u32_e32 v101, v84, v89
	v_min_u32_e32 v89, v84, v89
	v_max_u32_e32 v84, v73, v100
	v_min_u32_e32 v100, v73, v100
	v_max_u32_e32 v73, v76, v90
	v_min_u32_e32 v90, v76, v90
	v_max_u32_e32 v76, v83, v116
	v_min_u32_e32 v116, v83, v116
	v_max_u32_e32 v83, v91, v103
	v_min_u32_e32 v103, v91, v103
	v_max_u32_e32 v91, v104, v119
	v_min_u32_e32 v119, v104, v119
	v_max_u32_e32 v104, v95, v114
	v_min_u32_e32 v114, v95, v114
	v_max_u32_e32 v95, v80, v101
	v_min_u32_e32 v101, v80, v101
	v_max_u32_e32 v80, v71, v89
	v_min_u32_e32 v89, v71, v89
	v_max_u32_e32 v71, v84, v73
	v_min_u32_e32 v73, v84, v73
	v_max_u32_e32 v84, v100, v90
	v_min_u32_e32 v90, v100, v90
	v_pk_ashrrev_i16 v100, s42, v48
	v_bitop3_b32 v100, v48, v100, s43 bitop3:0x2d
	v_lshl_or_b32 v112, v100, 16, 31
	v_and_or_b32 v108, v100, s44, 30
	v_pk_ashrrev_i16 v100, s42, v49
	v_bitop3_b32 v100, v49, v100, s43 bitop3:0x2d
	v_lshl_or_b32 v109, v100, 16, 29
	v_and_or_b32 v92, v100, s44, 28
	v_pk_ashrrev_i16 v100, s42, v50
	v_bitop3_b32 v100, v50, v100, s43 bitop3:0x2d
	v_lshl_or_b32 v79, v100, 16, 27
	v_and_or_b32 v74, v100, s44, 26
	v_pk_ashrrev_i16 v100, s42, v51
	v_bitop3_b32 v100, v51, v100, s43 bitop3:0x2d
	v_lshl_or_b32 v117, v100, 16, 25
	v_and_or_b32 v107, v100, s44, 24
	v_pk_ashrrev_i16 v100, s42, v52
	v_bitop3_b32 v100, v52, v100, s43 bitop3:0x2d
	v_lshl_or_b32 v105, v100, 16, 23
	v_and_or_b32 v98, v100, s44, 22
	v_pk_ashrrev_i16 v100, s42, v53
	v_bitop3_b32 v100, v53, v100, s43 bitop3:0x2d
	v_lshl_or_b32 v115, v100, 16, 21
	v_and_or_b32 v93, v100, s44, 20
	v_pk_ashrrev_i16 v100, s42, v54
	v_bitop3_b32 v100, v54, v100, s43 bitop3:0x2d
	v_lshl_or_b32 v106, v100, 16, 19
	v_and_or_b32 v111, v100, s44, 18
	v_pk_ashrrev_i16 v100, s42, v55
	v_bitop3_b32 v100, v55, v100, s43 bitop3:0x2d
	v_lshl_or_b32 v118, v100, 16, 17
	v_and_or_b32 v110, v100, s44, 16
	v_max_u32_e32 v100, v112, v111
	v_min_u32_e32 v111, v112, v111
	v_max_u32_e32 v112, v108, v106
	v_min_u32_e32 v106, v108, v106
	v_max_u32_e32 v108, v109, v110
	v_min_u32_e32 v110, v109, v110
	v_max_u32_e32 v109, v92, v118
	v_min_u32_e32 v118, v92, v118
	v_max_u32_e32 v92, v79, v105
	v_min_u32_e32 v105, v79, v105
	v_max_u32_e32 v79, v74, v117
	v_min_u32_e32 v117, v74, v117
	v_max_u32_e32 v74, v107, v93
	v_min_u32_e32 v93, v107, v93
	v_max_u32_e32 v107, v98, v115
	v_min_u32_e32 v115, v98, v115
	v_max_u32_e32 v98, v100, v79
	v_min_u32_e32 v79, v100, v79
	v_max_u32_e32 v100, v112, v74
	v_min_u32_e32 v74, v112, v74
	v_max_u32_e32 v112, v108, v107
	v_min_u32_e32 v107, v108, v107
	v_max_u32_e32 v108, v109, v92
	v_min_u32_e32 v92, v109, v92
	v_max_u32_e32 v109, v117, v111
	v_min_u32_e32 v111, v117, v111
	v_max_u32_e32 v117, v105, v118
	v_min_u32_e32 v118, v105, v118
	v_max_u32_e32 v105, v115, v110
	v_min_u32_e32 v110, v115, v110
	v_max_u32_e32 v115, v93, v106
	v_min_u32_e32 v106, v93, v106
	v_max_u32_e32 v93, v98, v100
	v_min_u32_e32 v100, v98, v100
	v_max_u32_e32 v98, v112, v108
	v_min_u32_e32 v108, v112, v108
	v_max_u32_e32 v112, v92, v79
	v_min_u32_e32 v79, v92, v79
	v_max_u32_e32 v92, v109, v117
	v_min_u32_e32 v117, v109, v117
	v_max_u32_e32 v109, v74, v107
	v_min_u32_e32 v107, v74, v107
	v_max_u32_e32 v74, v105, v115
	v_min_u32_e32 v115, v105, v115
	v_max_u32_e32 v105, v106, v111
	v_min_u32_e32 v111, v106, v111
	v_max_u32_e32 v106, v118, v110
	v_min_u32_e32 v110, v118, v110
	v_max_u32_e32 v118, v93, v98
	v_min_u32_e32 v98, v93, v98
	v_max_u32_e32 v93, v100, v108
	v_min_u32_e32 v108, v100, v108
	v_max_u32_e32 v100, v112, v74
	v_min_u32_e32 v74, v112, v74
	v_max_u32_e32 v112, v79, v115
	v_min_u32_e32 v115, v79, v115
	v_max_u32_e32 v79, v92, v109
	v_min_u32_e32 v109, v92, v109
	v_max_u32_e32 v92, v117, v107
	v_min_u32_e32 v107, v117, v107
	v_max_u32_e32 v117, v105, v106
	v_min_u32_e32 v106, v105, v106
	v_max_u32_e32 v105, v111, v110
	v_min_u32_e32 v110, v111, v110
	v_max_u32_e32 v111, v93, v98
	v_min_u32_e32 v98, v93, v98
	v_max_u32_e32 v93, v108, v117
	v_min_u32_e32 v117, v108, v117
	v_max_u32_e32 v108, v100, v79
	v_min_u32_e32 v79, v100, v79
	v_max_u32_e32 v100, v112, v109
	v_min_u32_e32 v109, v112, v109
	v_max_u32_e32 v112, v92, v74
	v_min_u32_e32 v74, v92, v74
	v_max_u32_e32 v92, v107, v115
	v_min_u32_e32 v115, v107, v115
	v_max_u32_e32 v107, v105, v106
	v_min_u32_e32 v106, v105, v106
	v_max_u32_e32 v105, v111, v108
	v_min_u32_e32 v108, v111, v108
	v_max_u32_e32 v111, v98, v79
	v_min_u32_e32 v79, v98, v79
	v_max_u32_e32 v98, v100, v112
	v_min_u32_e32 v112, v100, v112
	v_max_u32_e32 v100, v109, v74
	v_min_u32_e32 v74, v109, v74
	v_max_u32_e32 v109, v92, v107
	v_min_u32_e32 v107, v92, v107
	v_max_u32_e32 v92, v115, v106
	v_min_u32_e32 v106, v115, v106
	v_max_u32_e32 v115, v111, v108
	v_min_u32_e32 v108, v111, v108
	v_max_u32_e32 v111, v93, v79
	v_min_u32_e32 v79, v93, v79
	v_max_u32_e32 v93, v109, v117
	v_min_u32_e32 v117, v109, v117
	v_max_u32_e32 v109, v92, v107
	v_min_u32_e32 v107, v92, v107
	v_max_u32_e32 v92, v111, v98
	v_min_u32_e32 v98, v111, v98
	v_max_u32_e32 v111, v79, v112
	v_min_u32_e32 v112, v79, v112
	v_max_u32_e32 v79, v100, v93
	v_min_u32_e32 v93, v100, v93
	v_max_u32_e32 v100, v74, v117
	v_min_u32_e32 v117, v74, v117
	v_max_u32_e32 v74, v92, v108
	v_min_u32_e32 v108, v92, v108
	v_max_u32_e32 v92, v98, v111
	v_min_u32_e32 v111, v98, v111
	v_max_u32_e32 v98, v79, v112
	v_min_u32_e32 v112, v79, v112
	v_max_u32_e32 v79, v93, v100
	v_min_u32_e32 v100, v93, v100
	v_max_u32_e32 v93, v109, v117
; __device__ __forceinline__ unsigned f2key(float f) { const unsigned u = __float_as_uint(f); return (u & 0x80000000u) ? ~u : (u | 0x80000000u); }
; #define CE_DESC(a, b) do { const unsigned _mx = (a) > (b) ? (a) : (b), _mn = (a) > (b) ? (b) : (a); (a) = _mx; (b) = _mn; } while (0)
; __device__ __forceinline__ void sort16_desc(unsigned (&k)[16]) {
; #pragma unroll
;     for (int size = 2; size <= 16; size <<= 1)
; #pragma unroll
;         for (int stride = size >> 1; stride > 0; stride >>= 1)
; #pragma unroll
;             for (int i = 0; i < 16; ++i) { const int j = i ^ stride;
;                 if (j > i) { if ((i & size) == 0) CE_DESC(k[i], k[j]); else CE_DESC(k[j], k[i]); } }
; }
; __device__ __forceinline__ void merge16(unsigned (&a)[16], const unsigned (&b)[16]) {
; #pragma unroll
;     for (int i = 0; i < 16; ++i) a[i] = a[i] > b[15 - i] ? a[i] : b[15 - i];
; #pragma unroll
;     for (int stride = 8; stride > 0; stride >>= 1)
; #pragma unroll
;         for (int i = 0; i < 16; ++i) { const int j = i ^ stride; if (j > i) CE_DESC(a[i], a[j]); }
; }
; __device__ __forceinline__ void peer_tile(const Args& A, LAS unsigned char* lds, int tile) {
;     ...
;                   for (int i = 0; i < 16; ++i) {
;                       const float lo = (float)__builtin_bit_cast(_Float16, (unsigned short)(sw[i] & 0xffffu)), hi = (float)__builtin_bit_cast(_Float16, (unsigned short)(sw[i] >> 16));
;                       const unsigned klo = (f2key(lo) & ~127u) | (unsigned)(127 - (32 * g + 2 * i)), khi = (f2key(hi) & ~127u) | (unsigned)(127 - (32 * g + 2 * i + 1));
;                       if (i < 8) { k0[2 * i] = klo; k0[2 * i + 1] = khi; } else { k1[2 * (i - 8)] = klo; k1[2 * (i - 8) + 1] = khi; } } }
;                 sort16_desc(k0); sort16_desc(k1); merge16(k0, k1);
; #pragma unroll
;                 for (int msk = 16; msk <= 32; msk <<= 1) {
; #pragma unroll
;                     for (int i = 0; i < 16; ++i) k1[i] = (unsigned)__shfl_xor((int)k0[i], msk);
;                     merge16(k0, k1); }
	v_min_u32_e32 v117, v109, v117
	v_max_u32_e32 v109, v111, v98
	v_min_u32_e32 v98, v111, v98
	v_max_u32_e32 v111, v112, v79
	v_min_u32_e32 v79, v112, v79
	v_max_u32_e32 v76, v76, v110
	v_max_u32_e32 v116, v116, v106
	v_max_u32_e32 v83, v83, v107
	v_max_u32_e32 v103, v103, v117
	v_max_u32_e32 v91, v91, v93
	v_max_u32_e32 v119, v119, v100
	v_max_u32_e32 v104, v104, v79
	v_max_u32_e32 v114, v114, v111
	v_max_u32_e32 v95, v95, v98
	v_max_u32_e32 v101, v101, v109
	v_max_u32_e32 v80, v80, v92
	v_max_u32_e32 v89, v89, v108
	v_max_u32_e32 v71, v71, v74
	v_max_u32_e32 v73, v73, v115
	v_max_u32_e32 v84, v84, v105
	v_max_u32_e32 v90, v90, v118
	v_max_u32_e32 v110, v76, v95
	v_min_u32_e32 v95, v76, v95
	v_max_u32_e32 v76, v116, v101
	v_min_u32_e32 v101, v116, v101
	v_max_u32_e32 v116, v83, v80
	v_min_u32_e32 v80, v83, v80
	v_max_u32_e32 v83, v103, v89
	v_min_u32_e32 v89, v103, v89
	v_max_u32_e32 v103, v91, v71
	v_min_u32_e32 v71, v91, v71
	v_max_u32_e32 v91, v119, v73
	v_min_u32_e32 v73, v119, v73
	v_max_u32_e32 v119, v104, v84
	v_min_u32_e32 v84, v104, v84
	v_max_u32_e32 v104, v114, v90
	v_min_u32_e32 v90, v114, v90
	v_max_u32_e32 v114, v110, v103
	v_min_u32_e32 v103, v110, v103
	v_max_u32_e32 v110, v76, v91
	v_min_u32_e32 v91, v76, v91
	v_max_u32_e32 v76, v116, v119
	v_min_u32_e32 v119, v116, v119
	v_max_u32_e32 v116, v83, v104
	v_min_u32_e32 v104, v83, v104
	v_max_u32_e32 v83, v95, v71
	v_min_u32_e32 v71, v95, v71
	v_max_u32_e32 v95, v101, v73
	v_min_u32_e32 v73, v101, v73
	v_max_u32_e32 v101, v80, v84
	v_min_u32_e32 v84, v80, v84
	v_max_u32_e32 v80, v89, v90
	v_min_u32_e32 v90, v89, v90
	v_max_u32_e32 v89, v114, v76
	v_min_u32_e32 v76, v114, v76
	v_max_u32_e32 v114, v110, v116
	v_min_u32_e32 v116, v110, v116
	v_max_u32_e32 v110, v103, v119
	v_min_u32_e32 v119, v103, v119
	v_max_u32_e32 v103, v91, v104
	v_min_u32_e32 v104, v91, v104
	v_max_u32_e32 v91, v83, v101
	v_min_u32_e32 v101, v83, v101
	v_max_u32_e32 v83, v95, v80
	v_min_u32_e32 v80, v95, v80
	v_max_u32_e32 v95, v71, v84
	v_min_u32_e32 v84, v71, v84
	v_max_u32_e32 v71, v73, v90
	v_min_u32_e32 v90, v73, v90
	v_max_u32_e32 v73, v89, v114
	v_min_u32_e32 v114, v89, v114
	v_max_u32_e32 v89, v76, v116
	v_min_u32_e32 v116, v76, v116
	v_max_u32_e32 v76, v110, v103
	v_min_u32_e32 v103, v110, v103
	v_max_u32_e32 v110, v119, v104
	v_min_u32_e32 v104, v119, v104
	v_max_u32_e32 v119, v91, v83
	v_min_u32_e32 v83, v91, v83
	v_max_u32_e32 v91, v101, v80
	v_min_u32_e32 v80, v101, v80
	v_max_u32_e32 v101, v95, v71
	v_min_u32_e32 v71, v95, v71
	v_max_u32_e32 v95, v84, v90
	v_min_u32_e32 v90, v84, v90
	v_pk_ashrrev_i16 v84, s42, v56
	v_bitop3_b32 v84, v56, v84, s43 bitop3:0x2d
	v_lshl_or_b32 v106, v84, 16, 15
	v_and_or_b32 v107, v84, s44, 14
	v_pk_ashrrev_i16 v84, s42, v57
	v_bitop3_b32 v84, v57, v84, s43 bitop3:0x2d
	v_lshl_or_b32 v117, v84, 16, 13
	v_and_or_b32 v93, v84, s44, 12
	v_pk_ashrrev_i16 v84, s42, v58
	v_bitop3_b32 v84, v58, v84, s43 bitop3:0x2d
	v_lshl_or_b32 v100, v84, 16, 11
	v_and_or_b32 v79, v84, s44, 10
	v_pk_ashrrev_i16 v84, s42, v59
	v_bitop3_b32 v84, v59, v84, s43 bitop3:0x2d
	v_lshl_or_b32 v111, v84, 16, 9
	v_and_or_b32 v98, v84, s44, 8
	v_pk_ashrrev_i16 v84, s42, v60
	v_bitop3_b32 v84, v60, v84, s43 bitop3:0x2d
	v_lshl_or_b32 v109, v84, 16, 7
	v_and_or_b32 v92, v84, s44, 6
	v_pk_ashrrev_i16 v84, s42, v61
	v_bitop3_b32 v84, v61, v84, s43 bitop3:0x2d
	v_lshl_or_b32 v108, v84, 16, 5
	v_and_or_b32 v74, v84, s44, 4
	v_pk_ashrrev_i16 v84, s42, v62
	v_bitop3_b32 v84, v62, v84, s43 bitop3:0x2d
	v_lshl_or_b32 v115, v84, 16, 3
	v_and_or_b32 v105, v84, s44, 2
	v_pk_ashrrev_i16 v84, s42, v63
	v_bitop3_b32 v84, v63, v84, s43 bitop3:0x2d
	v_lshl_or_b32 v118, v84, 16, 1
	v_and_or_b32 v112, v84, s44, 0
	v_max_u32_e32 v84, v106, v105
	v_min_u32_e32 v105, v106, v105
	v_max_u32_e32 v106, v107, v115
	v_min_u32_e32 v115, v107, v115
	v_max_u32_e32 v107, v117, v112
	v_min_u32_e32 v112, v117, v112
	v_max_u32_e32 v117, v93, v118
	v_min_u32_e32 v118, v93, v118
	v_max_u32_e32 v93, v100, v109
	v_min_u32_e32 v109, v100, v109
	v_max_u32_e32 v100, v79, v111
	v_min_u32_e32 v111, v79, v111
	v_max_u32_e32 v79, v98, v74
	v_min_u32_e32 v74, v98, v74
	v_max_u32_e32 v98, v92, v108
	v_min_u32_e32 v108, v92, v108
	v_max_u32_e32 v92, v84, v100
	v_min_u32_e32 v100, v84, v100
	v_max_u32_e32 v84, v106, v79
	v_min_u32_e32 v79, v106, v79
	v_max_u32_e32 v106, v107, v98
	v_min_u32_e32 v98, v107, v98
	v_max_u32_e32 v107, v117, v93
	v_min_u32_e32 v93, v117, v93
	v_max_u32_e32 v117, v111, v105
	v_min_u32_e32 v105, v111, v105
	v_max_u32_e32 v111, v109, v118
	v_min_u32_e32 v118, v109, v118
	v_max_u32_e32 v109, v108, v112
	v_min_u32_e32 v112, v108, v112
	v_max_u32_e32 v108, v74, v115
	v_min_u32_e32 v115, v74, v115
	v_max_u32_e32 v74, v92, v84
	v_min_u32_e32 v84, v92, v84
	v_max_u32_e32 v92, v106, v107
	v_min_u32_e32 v107, v106, v107
	v_max_u32_e32 v106, v93, v100
	v_min_u32_e32 v100, v93, v100
	v_max_u32_e32 v93, v117, v111
	v_min_u32_e32 v111, v117, v111
	v_max_u32_e32 v117, v79, v98
	v_min_u32_e32 v98, v79, v98
	v_max_u32_e32 v79, v109, v108
	v_min_u32_e32 v108, v109, v108
	v_max_u32_e32 v109, v115, v105
	v_min_u32_e32 v105, v115, v105
	v_max_u32_e32 v115, v118, v112
	v_min_u32_e32 v112, v118, v112
	v_max_u32_e32 v118, v74, v92
	v_min_u32_e32 v92, v74, v92
	v_max_u32_e32 v74, v84, v107
	v_min_u32_e32 v107, v84, v107
	v_max_u32_e32 v84, v106, v79
	v_min_u32_e32 v79, v106, v79
	v_max_u32_e32 v106, v100, v108
	v_min_u32_e32 v108, v100, v108
	v_max_u32_e32 v100, v93, v117
	v_min_u32_e32 v117, v93, v117
	v_max_u32_e32 v93, v111, v98
	v_min_u32_e32 v98, v111, v98
	v_max_u32_e32 v111, v109, v115
	v_min_u32_e32 v115, v109, v115
; __device__ __forceinline__ float key2f(unsigned k) { const unsigned u = (k & 0x80000000u) ? (k & 0x7fffffffu) : ~k; return __uint_as_float(u); }
; #define CE_DESC(a, b) do { const unsigned _mx = (a) > (b) ? (a) : (b), _mn = (a) > (b) ? (b) : (a); (a) = _mx; (b) = _mn; } while (0)
; __device__ __forceinline__ void sort16_desc(unsigned (&k)[16]) {
; #pragma unroll
;     for (int size = 2; size <= 16; size <<= 1)
; #pragma unroll
;         for (int stride = size >> 1; stride > 0; stride >>= 1)
; #pragma unroll
;             for (int i = 0; i < 16; ++i) { const int j = i ^ stride;
;                 if (j > i) { if ((i & size) == 0) CE_DESC(k[i], k[j]); else CE_DESC(k[j], k[i]); } }
; }
; __device__ __forceinline__ void merge16(unsigned (&a)[16], const unsigned (&b)[16]) {
; #pragma unroll
;     for (int i = 0; i < 16; ++i) a[i] = a[i] > b[15 - i] ? a[i] : b[15 - i];
; #pragma unroll
;     for (int stride = 8; stride > 0; stride >>= 1)
; #pragma unroll
;         for (int i = 0; i < 16; ++i) { const int j = i ^ stride; if (j > i) CE_DESC(a[i], a[j]); }
; }
; __device__ __forceinline__ void peer_tile(const Args& A, LAS unsigned char* lds, int tile) {
;     ...
;             const int h = 4 * hg + g;
;             unsigned L2[2][16];
; #pragma unroll
;             for (int p = 0; p < 2; ++p)
; #pragma unroll
;                 for (int i = 0; i < 16; ++i) L2[p][i] = (g & 2) ? ((g & 1) ? LA[3][p][i] : LA[2][p][i]) : ((g & 1) ? LA[1][p][i] : LA[0][p][i]);
;             float va[16], vb[16];
; #pragma unroll
;             for (int i = 0; i < 16; ++i) { va[i] = key2f(L2[0][i] & ~127u); vb[i] = key2f(L2[1][i] & ~127u); idx[i] = 127u - (L2[0][i] & 127u); idx[16 + i] = 127u - (L2[1][i] & 127u); }
	v_max_u32_e32 v109, v105, v112
	v_min_u32_e32 v112, v105, v112
	v_max_u32_e32 v105, v74, v92
	v_min_u32_e32 v92, v74, v92
	v_max_u32_e32 v74, v107, v111
	v_min_u32_e32 v111, v107, v111
	v_max_u32_e32 v107, v84, v100
	v_min_u32_e32 v100, v84, v100
	v_max_u32_e32 v84, v106, v117
	v_min_u32_e32 v117, v106, v117
	v_max_u32_e32 v106, v93, v79
	v_min_u32_e32 v79, v93, v79
	v_max_u32_e32 v93, v98, v108
	v_min_u32_e32 v108, v98, v108
	v_max_u32_e32 v98, v109, v115
	v_min_u32_e32 v115, v109, v115
	v_max_u32_e32 v109, v105, v107
	v_min_u32_e32 v107, v105, v107
	v_max_u32_e32 v105, v92, v100
	v_min_u32_e32 v100, v92, v100
	v_max_u32_e32 v92, v84, v106
	v_min_u32_e32 v106, v84, v106
	v_max_u32_e32 v84, v117, v79
	v_min_u32_e32 v79, v117, v79
	v_max_u32_e32 v117, v93, v98
	v_min_u32_e32 v98, v93, v98
	v_max_u32_e32 v93, v108, v115
	v_min_u32_e32 v115, v108, v115
	v_max_u32_e32 v108, v105, v107
	v_min_u32_e32 v107, v105, v107
	v_max_u32_e32 v105, v74, v100
	v_min_u32_e32 v100, v74, v100
	v_max_u32_e32 v74, v117, v111
	v_min_u32_e32 v111, v117, v111
	v_max_u32_e32 v117, v93, v98
	v_min_u32_e32 v98, v93, v98
	v_max_u32_e32 v93, v105, v92
	v_min_u32_e32 v92, v105, v92
	v_max_u32_e32 v105, v100, v106
	v_min_u32_e32 v106, v100, v106
	v_max_u32_e32 v100, v84, v74
	v_min_u32_e32 v74, v84, v74
	v_max_u32_e32 v84, v79, v111
	v_min_u32_e32 v111, v79, v111
	v_max_u32_e32 v79, v93, v107
	v_min_u32_e32 v107, v93, v107
	v_max_u32_e32 v93, v92, v105
	v_min_u32_e32 v105, v92, v105
	v_max_u32_e32 v92, v100, v106
	v_min_u32_e32 v106, v100, v106
	v_max_u32_e32 v100, v74, v84
	v_min_u32_e32 v84, v74, v84
	v_max_u32_e32 v74, v117, v111
	v_min_u32_e32 v111, v117, v111
	v_max_u32_e32 v117, v105, v92
	v_min_u32_e32 v92, v105, v92
	v_max_u32_e32 v105, v106, v100
	v_min_u32_e32 v100, v106, v100
	v_max_u32_e32 v73, v73, v112
	v_max_u32_e32 v114, v114, v115
	v_max_u32_e32 v89, v89, v98
	v_max_u32_e32 v116, v116, v111
	v_max_u32_e32 v76, v76, v74
	v_max_u32_e32 v103, v103, v84
	v_max_u32_e32 v110, v110, v100
	v_max_u32_e32 v104, v104, v105
	v_max_u32_e32 v119, v119, v92
	v_max_u32_e32 v83, v83, v117
	v_max_u32_e32 v91, v91, v93
	v_max_u32_e32 v80, v80, v107
	v_max_u32_e32 v101, v101, v79
	v_max_u32_e32 v71, v71, v108
	v_max_u32_e32 v95, v95, v109
	v_max_u32_e32 v90, v90, v118
	v_max_u32_e32 v112, v73, v119
	v_min_u32_e32 v119, v73, v119
	v_max_u32_e32 v73, v114, v83
	v_min_u32_e32 v83, v114, v83
	v_max_u32_e32 v114, v89, v91
	v_min_u32_e32 v91, v89, v91
	v_max_u32_e32 v89, v116, v80
	v_min_u32_e32 v80, v116, v80
	v_max_u32_e32 v116, v76, v101
	v_min_u32_e32 v101, v76, v101
	v_max_u32_e32 v76, v103, v71
	v_min_u32_e32 v71, v103, v71
	v_max_u32_e32 v103, v110, v95
	v_min_u32_e32 v95, v110, v95
	v_max_u32_e32 v110, v104, v90
	v_min_u32_e32 v90, v104, v90
	v_max_u32_e32 v104, v112, v116
	v_min_u32_e32 v116, v112, v116
	v_max_u32_e32 v112, v73, v76
	v_min_u32_e32 v76, v73, v76
	v_max_u32_e32 v73, v114, v103
	v_min_u32_e32 v103, v114, v103
	v_max_u32_e32 v114, v89, v110
	v_min_u32_e32 v110, v89, v110
	v_max_u32_e32 v89, v119, v101
	v_min_u32_e32 v101, v119, v101
	v_max_u32_e32 v119, v83, v71
	v_min_u32_e32 v71, v83, v71
	v_max_u32_e32 v83, v91, v95
	v_min_u32_e32 v95, v91, v95
	v_max_u32_e32 v91, v80, v90
	v_min_u32_e32 v90, v80, v90
	v_max_u32_e32 v80, v104, v73
	v_min_u32_e32 v73, v104, v73
	v_max_u32_e32 v104, v112, v114
	v_min_u32_e32 v114, v112, v114
	v_max_u32_e32 v112, v116, v103
	v_min_u32_e32 v103, v116, v103
	v_max_u32_e32 v116, v76, v110
	v_min_u32_e32 v110, v76, v110
	v_max_u32_e32 v76, v89, v83
	v_min_u32_e32 v83, v89, v83
	v_max_u32_e32 v89, v119, v91
	v_min_u32_e32 v91, v119, v91
	v_max_u32_e32 v119, v101, v95
	v_min_u32_e32 v95, v101, v95
	v_max_u32_e32 v101, v71, v90
	v_min_u32_e32 v90, v71, v90
	v_max_u32_e32 v71, v80, v104
	v_min_u32_e32 v104, v80, v104
	v_max_u32_e32 v80, v73, v114
	v_min_u32_e32 v114, v73, v114
	v_max_u32_e32 v73, v112, v116
	v_min_u32_e32 v116, v112, v116
	v_max_u32_e32 v112, v103, v110
	v_min_u32_e32 v110, v103, v110
	v_max_u32_e32 v103, v76, v89
	v_min_u32_e32 v89, v76, v89
	v_max_u32_e32 v76, v83, v91
	v_min_u32_e32 v91, v83, v91
	v_max_u32_e32 v83, v119, v101
	v_min_u32_e32 v101, v119, v101
	v_max_u32_e32 v119, v95, v90
	v_min_u32_e32 v90, v95, v90
	v_xor_b32_e32 v95, 0x7f, v72
	v_xor_b32_e32 v115, 0x7f, v88
	v_and_b32_e32 v95, 0x7f, v95
	v_and_b32_e32 v115, 0x7f, v115
	ds_write2_b32 v67, v95, v115 offset0:0 offset1:1
	v_xor_b32_e32 v115, 0x7f, v75
	v_xor_b32_e32 v95, 0x7f, v97
	v_and_b32_e32 v115, 0x7f, v115
	v_and_b32_e32 v95, 0x7f, v95
	ds_write2_b32 v67, v115, v95 offset0:2 offset1:3
	v_xor_b32_e32 v95, 0x7f, v70
	v_xor_b32_e32 v115, 0x7f, v99
	v_and_b32_e32 v95, 0x7f, v95
	v_and_b32_e32 v115, 0x7f, v115
	ds_write2_b32 v67, v95, v115 offset0:4 offset1:5
	v_xor_b32_e32 v115, 0x7f, v96
	v_xor_b32_e32 v95, 0x7f, v94
	v_and_b32_e32 v115, 0x7f, v115
	v_and_b32_e32 v95, 0x7f, v95
	ds_write2_b32 v67, v115, v95 offset0:6 offset1:7
	v_xor_b32_e32 v95, 0x7f, v87
	v_xor_b32_e32 v115, 0x7f, v77
	v_and_b32_e32 v95, 0x7f, v95
	v_and_b32_e32 v115, 0x7f, v115
	ds_write2_b32 v67, v95, v115 offset0:8 offset1:9
	v_xor_b32_e32 v115, 0x7f, v82
	v_xor_b32_e32 v95, 0x7f, v81
	v_and_b32_e32 v115, 0x7f, v115
	v_and_b32_e32 v95, 0x7f, v95
	ds_write2_b32 v67, v115, v95 offset0:10 offset1:11
	v_xor_b32_e32 v95, 0x7f, v78
	v_xor_b32_e32 v115, 0x7f, v85
	v_and_b32_e32 v95, 0x7f, v95
	v_and_b32_e32 v115, 0x7f, v115
	ds_write2_b32 v67, v95, v115 offset0:12 offset1:13
	v_xor_b32_e32 v115, 0x7f, v102
	v_xor_b32_e32 v95, 0x7f, v86
	v_and_b32_e32 v115, 0x7f, v115
	v_and_b32_e32 v95, 0x7f, v95
	ds_write2_b32 v67, v115, v95 offset0:14 offset1:15
	v_xor_b32_e32 v95, 0x7f, v71
; __device__ __forceinline__ float key2f(unsigned k) { const unsigned u = (k & 0x80000000u) ? (k & 0x7fffffffu) : ~k; return __uint_as_float(u); }
; __device__ __forceinline__ void peer_tile(const Args& A, LAS unsigned char* lds, int tile) {
;     ...
;                 for (int i = 0; i < 16; ++i) L2[p][i] = (g & 2) ? ((g & 1) ? LA[3][p][i] : LA[2][p][i]) : ((g & 1) ? LA[1][p][i] : LA[0][p][i]);
;             float va[16], vb[16];
; #pragma unroll
;             for (int i = 0; i < 16; ++i) { va[i] = key2f(L2[0][i] & ~127u); vb[i] = key2f(L2[1][i] & ~127u); idx[i] = 127u - (L2[0][i] & 127u); idx[16 + i] = 127u - (L2[1][i] & 127u); }
	v_xor_b32_e32 v115, 0x7f, v104
	v_and_b32_e32 v95, 0x7f, v95
	v_and_b32_e32 v115, 0x7f, v115
	ds_write2_b32 v67, v95, v115 offset0:16 offset1:17
	v_xor_b32_e32 v115, 0x7f, v80
	v_xor_b32_e32 v95, 0x7f, v114
	v_and_b32_e32 v115, 0x7f, v115
	v_and_b32_e32 v95, 0x7f, v95
	ds_write2_b32 v67, v115, v95 offset0:18 offset1:19
	v_xor_b32_e32 v95, 0x7f, v73
	v_xor_b32_e32 v115, 0x7f, v116
	v_and_b32_e32 v95, 0x7f, v95
	v_and_b32_e32 v115, 0x7f, v115
	ds_write2_b32 v67, v95, v115 offset0:20 offset1:21
	v_xor_b32_e32 v115, 0x7f, v112
	v_xor_b32_e32 v95, 0x7f, v110
	v_and_b32_e32 v115, 0x7f, v115
	v_and_b32_e32 v95, 0x7f, v95
	ds_write2_b32 v67, v115, v95 offset0:22 offset1:23
	v_xor_b32_e32 v95, 0x7f, v103
	v_xor_b32_e32 v115, 0x7f, v89
	v_and_b32_e32 v95, 0x7f, v95
	v_and_b32_e32 v115, 0x7f, v115
	ds_write2_b32 v67, v95, v115 offset0:24 offset1:25
	v_xor_b32_e32 v115, 0x7f, v76
	v_xor_b32_e32 v95, 0x7f, v91
	v_and_b32_e32 v115, 0x7f, v115
	v_and_b32_e32 v95, 0x7f, v95
	ds_write2_b32 v67, v115, v95 offset0:26 offset1:27
	v_xor_b32_e32 v95, 0x7f, v83
	v_xor_b32_e32 v115, 0x7f, v101
	v_and_b32_e32 v95, 0x7f, v95
	v_and_b32_e32 v115, 0x7f, v115
	ds_write2_b32 v67, v95, v115 offset0:28 offset1:29
	v_xor_b32_e32 v115, 0x7f, v119
	v_xor_b32_e32 v95, 0x7f, v90
	v_and_b32_e32 v115, 0x7f, v115
	v_and_b32_e32 v95, 0x7f, v95
	ds_write2_b32 v67, v115, v95 offset0:30 offset1:31
	v_ashrrev_i32_e32 v115, 31, v72
	v_bitop3_b32 v115, v72, v115, s41 bitop3:0x87
	v_cvt_f32_f16_sdwa v95, v115 dst_sel:DWORD dst_unused:UNUSED_PAD src0_sel:WORD_1
	v_ashrrev_i32_e32 v98, 31, v88
	v_bitop3_b32 v98, v88, v98, s41 bitop3:0x87
	v_cvt_f32_f16_sdwa v115, v98 dst_sel:DWORD dst_unused:UNUSED_PAD src0_sel:WORD_1
	v_ashrrev_i32_e32 v111, 31, v75
	v_bitop3_b32 v111, v75, v111, s41 bitop3:0x87
	v_cvt_f32_f16_sdwa v98, v111 dst_sel:DWORD dst_unused:UNUSED_PAD src0_sel:WORD_1
	v_ashrrev_i32_e32 v74, 31, v97
	v_bitop3_b32 v74, v97, v74, s41 bitop3:0x87
	v_cvt_f32_f16_sdwa v111, v74 dst_sel:DWORD dst_unused:UNUSED_PAD src0_sel:WORD_1
	v_ashrrev_i32_e32 v84, 31, v70
	v_bitop3_b32 v84, v70, v84, s41 bitop3:0x87
	v_cvt_f32_f16_sdwa v74, v84 dst_sel:DWORD dst_unused:UNUSED_PAD src0_sel:WORD_1
	v_ashrrev_i32_e32 v100, 31, v99
	v_bitop3_b32 v100, v99, v100, s41 bitop3:0x87
	v_cvt_f32_f16_sdwa v84, v100 dst_sel:DWORD dst_unused:UNUSED_PAD src0_sel:WORD_1
	v_ashrrev_i32_e32 v105, 31, v96
	v_bitop3_b32 v105, v96, v105, s41 bitop3:0x87
	v_cvt_f32_f16_sdwa v100, v105 dst_sel:DWORD dst_unused:UNUSED_PAD src0_sel:WORD_1
	v_ashrrev_i32_e32 v92, 31, v94
	v_bitop3_b32 v92, v94, v92, s41 bitop3:0x87
	v_cvt_f32_f16_sdwa v105, v92 dst_sel:DWORD dst_unused:UNUSED_PAD src0_sel:WORD_1
	v_ashrrev_i32_e32 v117, 31, v87
	v_bitop3_b32 v117, v87, v117, s41 bitop3:0x87
	v_cvt_f32_f16_sdwa v92, v117 dst_sel:DWORD dst_unused:UNUSED_PAD src0_sel:WORD_1
	v_ashrrev_i32_e32 v93, 31, v77
	v_bitop3_b32 v93, v77, v93, s41 bitop3:0x87
	v_cvt_f32_f16_sdwa v117, v93 dst_sel:DWORD dst_unused:UNUSED_PAD src0_sel:WORD_1
	v_ashrrev_i32_e32 v107, 31, v82
	v_bitop3_b32 v107, v82, v107, s41 bitop3:0x87
	v_cvt_f32_f16_sdwa v93, v107 dst_sel:DWORD dst_unused:UNUSED_PAD src0_sel:WORD_1
	v_ashrrev_i32_e32 v79, 31, v81
	v_bitop3_b32 v79, v81, v79, s41 bitop3:0x87
	v_cvt_f32_f16_sdwa v107, v79 dst_sel:DWORD dst_unused:UNUSED_PAD src0_sel:WORD_1
	v_ashrrev_i32_e32 v108, 31, v78
	v_bitop3_b32 v108, v78, v108, s41 bitop3:0x87
	v_cvt_f32_f16_sdwa v79, v108 dst_sel:DWORD dst_unused:UNUSED_PAD src0_sel:WORD_1
	v_ashrrev_i32_e32 v109, 31, v85
	v_bitop3_b32 v109, v85, v109, s41 bitop3:0x87
	v_cvt_f32_f16_sdwa v108, v109 dst_sel:DWORD dst_unused:UNUSED_PAD src0_sel:WORD_1
	v_ashrrev_i32_e32 v118, 31, v102
	v_bitop3_b32 v118, v102, v118, s41 bitop3:0x87
	v_cvt_f32_f16_sdwa v109, v118 dst_sel:DWORD dst_unused:UNUSED_PAD src0_sel:WORD_1
	v_ashrrev_i32_e32 v106, 31, v86
	v_bitop3_b32 v106, v86, v106, s41 bitop3:0x87
	v_cvt_f32_f16_sdwa v118, v106 dst_sel:DWORD dst_unused:UNUSED_PAD src0_sel:WORD_1
	v_ashrrev_i32_e32 v120, 31, v71
	v_bitop3_b32 v120, v71, v120, s41 bitop3:0x87
	v_cvt_f32_f16_sdwa v106, v120 dst_sel:DWORD dst_unused:UNUSED_PAD src0_sel:WORD_1
	v_ashrrev_i32_e32 v121, 31, v104
	v_bitop3_b32 v121, v104, v121, s41 bitop3:0x87
	v_cvt_f32_f16_sdwa v120, v121 dst_sel:DWORD dst_unused:UNUSED_PAD src0_sel:WORD_1
	v_ashrrev_i32_e32 v122, 31, v80
	v_bitop3_b32 v122, v80, v122, s41 bitop3:0x87
	v_cvt_f32_f16_sdwa v121, v122 dst_sel:DWORD dst_unused:UNUSED_PAD src0_sel:WORD_1
	v_ashrrev_i32_e32 v123, 31, v114
	v_bitop3_b32 v123, v114, v123, s41 bitop3:0x87
	v_cvt_f32_f16_sdwa v122, v123 dst_sel:DWORD dst_unused:UNUSED_PAD src0_sel:WORD_1
	v_ashrrev_i32_e32 v124, 31, v73
	v_bitop3_b32 v124, v73, v124, s41 bitop3:0x87
	v_cvt_f32_f16_sdwa v123, v124 dst_sel:DWORD dst_unused:UNUSED_PAD src0_sel:WORD_1
	v_ashrrev_i32_e32 v125, 31, v116
	v_bitop3_b32 v125, v116, v125, s41 bitop3:0x87
	v_cvt_f32_f16_sdwa v124, v125 dst_sel:DWORD dst_unused:UNUSED_PAD src0_sel:WORD_1
	v_ashrrev_i32_e32 v126, 31, v112
	v_bitop3_b32 v126, v112, v126, s41 bitop3:0x87
	v_cvt_f32_f16_sdwa v125, v126 dst_sel:DWORD dst_unused:UNUSED_PAD src0_sel:WORD_1
	v_ashrrev_i32_e32 v127, 31, v110
	v_bitop3_b32 v127, v110, v127, s41 bitop3:0x87
	v_cvt_f32_f16_sdwa v126, v127 dst_sel:DWORD dst_unused:UNUSED_PAD src0_sel:WORD_1
	v_ashrrev_i32_e32 v128, 31, v103
	v_bitop3_b32 v128, v103, v128, s41 bitop3:0x87
	v_cvt_f32_f16_sdwa v127, v128 dst_sel:DWORD dst_unused:UNUSED_PAD src0_sel:WORD_1
	v_ashrrev_i32_e32 v129, 31, v89
	v_bitop3_b32 v129, v89, v129, s41 bitop3:0x87
	v_cvt_f32_f16_sdwa v128, v129 dst_sel:DWORD dst_unused:UNUSED_PAD src0_sel:WORD_1
	v_ashrrev_i32_e32 v130, 31, v76
; #define CK(i, j) ((f2key(va[i] + vb[j]) & ~255u) | (unsigned)(255 - (16 * (i) + (j))))
; __device__ __forceinline__ void peer_tile(const Args& A, LAS unsigned char* lds, int tile) {
;     ...
;             unsigned Lf[16], Bt[16];
; #pragma unroll
;             for (int j = 0; j < 16; ++j) Lf[j] = CK(0, j);
; #pragma unroll
;             for (int j = 0; j < 8; ++j) Bt[j] = CK(1, j);
; #pragma unroll
;             for (int j = 0; j < 5; ++j) Bt[8 + j] = CK(2, j);
; #pragma unroll
;             for (int j = 0; j < 3; ++j) Bt[13 + j] = CK(4, j);
	v_bitop3_b32 v130, v76, v130, s41 bitop3:0x87
	v_cvt_f32_f16_sdwa v129, v130 dst_sel:DWORD dst_unused:UNUSED_PAD src0_sel:WORD_1
	v_ashrrev_i32_e32 v131, 31, v91
	v_bitop3_b32 v131, v91, v131, s41 bitop3:0x87
	v_cvt_f32_f16_sdwa v130, v131 dst_sel:DWORD dst_unused:UNUSED_PAD src0_sel:WORD_1
	v_ashrrev_i32_e32 v132, 31, v83
	v_bitop3_b32 v132, v83, v132, s41 bitop3:0x87
	v_cvt_f32_f16_sdwa v131, v132 dst_sel:DWORD dst_unused:UNUSED_PAD src0_sel:WORD_1
	v_ashrrev_i32_e32 v133, 31, v101
	v_bitop3_b32 v133, v101, v133, s41 bitop3:0x87
	v_cvt_f32_f16_sdwa v132, v133 dst_sel:DWORD dst_unused:UNUSED_PAD src0_sel:WORD_1
	v_ashrrev_i32_e32 v134, 31, v119
	v_bitop3_b32 v134, v119, v134, s41 bitop3:0x87
	v_cvt_f32_f16_sdwa v133, v134 dst_sel:DWORD dst_unused:UNUSED_PAD src0_sel:WORD_1
	v_ashrrev_i32_e32 v135, 31, v90
	v_bitop3_b32 v135, v90, v135, s41 bitop3:0x87
	v_cvt_f32_f16_sdwa v134, v135 dst_sel:DWORD dst_unused:UNUSED_PAD src0_sel:WORD_1
	v_add_f32_e32 v90, v95, v106
	v_ashrrev_i32_e32 v119, 31, v90
	v_bitop3_b32 v90, v90, v119, s41 bitop3:0x78
	v_and_b32_e32 v90, 0xffffff00, v90
	v_xor_b32_e32 v90, 0x800000ff, v90
	v_add_f32_e32 v119, v95, v120
	v_ashrrev_i32_e32 v101, 31, v119
	v_bitop3_b32 v119, v119, v101, s41 bitop3:0x78
	v_and_b32_e32 v119, 0xffffff00, v119
	v_xor_b32_e32 v119, 0x800000fe, v119
	v_add_f32_e32 v101, v95, v121
	v_ashrrev_i32_e32 v83, 31, v101
	v_bitop3_b32 v101, v101, v83, s41 bitop3:0x78
	v_and_b32_e32 v101, 0xffffff00, v101
	v_xor_b32_e32 v101, 0x800000fd, v101
	v_add_f32_e32 v83, v95, v122
	v_ashrrev_i32_e32 v91, 31, v83
	v_bitop3_b32 v83, v83, v91, s41 bitop3:0x78
	v_and_b32_e32 v83, 0xffffff00, v83
	v_xor_b32_e32 v83, 0x800000fc, v83
	v_add_f32_e32 v91, v95, v123
	v_ashrrev_i32_e32 v76, 31, v91
	v_bitop3_b32 v91, v91, v76, s41 bitop3:0x78
	v_and_b32_e32 v91, 0xffffff00, v91
	v_xor_b32_e32 v91, 0x800000fb, v91
	v_add_f32_e32 v76, v95, v124
	v_ashrrev_i32_e32 v89, 31, v76
	v_bitop3_b32 v76, v76, v89, s41 bitop3:0x78
	v_and_b32_e32 v76, 0xffffff00, v76
	v_xor_b32_e32 v76, 0x800000fa, v76
	v_add_f32_e32 v89, v95, v125
	v_ashrrev_i32_e32 v103, 31, v89
	v_bitop3_b32 v89, v89, v103, s41 bitop3:0x78
	v_and_b32_e32 v89, 0xffffff00, v89
	v_xor_b32_e32 v89, 0x800000f9, v89
	v_add_f32_e32 v103, v95, v126
	v_ashrrev_i32_e32 v110, 31, v103
	v_bitop3_b32 v103, v103, v110, s41 bitop3:0x78
	v_and_b32_e32 v103, 0xffffff00, v103
	v_xor_b32_e32 v103, 0x800000f8, v103
	v_add_f32_e32 v110, v95, v127
	v_ashrrev_i32_e32 v112, 31, v110
	v_bitop3_b32 v110, v110, v112, s41 bitop3:0x78
	v_and_b32_e32 v110, 0xffffff00, v110
	v_xor_b32_e32 v110, 0x800000f7, v110
	v_add_f32_e32 v112, v95, v128
	v_ashrrev_i32_e32 v116, 31, v112
	v_bitop3_b32 v112, v112, v116, s41 bitop3:0x78
	v_and_b32_e32 v112, 0xffffff00, v112
	v_xor_b32_e32 v112, 0x800000f6, v112
	v_add_f32_e32 v116, v95, v129
	v_ashrrev_i32_e32 v73, 31, v116
	v_bitop3_b32 v116, v116, v73, s41 bitop3:0x78
	v_and_b32_e32 v116, 0xffffff00, v116
	v_xor_b32_e32 v116, 0x800000f5, v116
	v_add_f32_e32 v73, v95, v130
	v_ashrrev_i32_e32 v114, 31, v73
	v_bitop3_b32 v73, v73, v114, s41 bitop3:0x78
	v_and_b32_e32 v73, 0xffffff00, v73
	v_xor_b32_e32 v73, 0x800000f4, v73
	v_add_f32_e32 v114, v95, v131
	v_ashrrev_i32_e32 v80, 31, v114
	v_bitop3_b32 v114, v114, v80, s41 bitop3:0x78
	v_and_b32_e32 v114, 0xffffff00, v114
	v_xor_b32_e32 v114, 0x800000f3, v114
	v_add_f32_e32 v80, v95, v132
	v_ashrrev_i32_e32 v104, 31, v80
	v_bitop3_b32 v80, v80, v104, s41 bitop3:0x78
	v_and_b32_e32 v80, 0xffffff00, v80
	v_xor_b32_e32 v80, 0x800000f2, v80
	v_add_f32_e32 v104, v95, v133
	v_ashrrev_i32_e32 v71, 31, v104
	v_bitop3_b32 v104, v104, v71, s41 bitop3:0x78
	v_and_b32_e32 v104, 0xffffff00, v104
	v_xor_b32_e32 v104, 0x800000f1, v104
	v_add_f32_e32 v71, v95, v134
	v_ashrrev_i32_e32 v86, 31, v71
	v_bitop3_b32 v71, v71, v86, s41 bitop3:0x78
	v_and_b32_e32 v71, 0xffffff00, v71
	v_xor_b32_e32 v71, 0x800000f0, v71
	v_add_f32_e32 v86, v115, v106
	v_ashrrev_i32_e32 v102, 31, v86
	v_bitop3_b32 v86, v86, v102, s41 bitop3:0x78
	v_and_b32_e32 v86, 0xffffff00, v86
	v_xor_b32_e32 v86, 0x800000ef, v86
	v_add_f32_e32 v102, v115, v120
	v_ashrrev_i32_e32 v85, 31, v102
	v_bitop3_b32 v102, v102, v85, s41 bitop3:0x78
	v_and_b32_e32 v102, 0xffffff00, v102
	v_xor_b32_e32 v102, 0x800000ee, v102
	v_add_f32_e32 v85, v115, v121
	v_ashrrev_i32_e32 v78, 31, v85
	v_bitop3_b32 v85, v85, v78, s41 bitop3:0x78
	v_and_b32_e32 v85, 0xffffff00, v85
	v_xor_b32_e32 v85, 0x800000ed, v85
	v_add_f32_e32 v78, v115, v122
	v_ashrrev_i32_e32 v81, 31, v78
	v_bitop3_b32 v78, v78, v81, s41 bitop3:0x78
	v_and_b32_e32 v78, 0xffffff00, v78
	v_xor_b32_e32 v78, 0x800000ec, v78
	v_add_f32_e32 v81, v115, v123
	v_ashrrev_i32_e32 v82, 31, v81
	v_bitop3_b32 v81, v81, v82, s41 bitop3:0x78
	v_and_b32_e32 v81, 0xffffff00, v81
	v_xor_b32_e32 v81, 0x800000eb, v81
	v_add_f32_e32 v82, v115, v124
	v_ashrrev_i32_e32 v77, 31, v82
	v_bitop3_b32 v82, v82, v77, s41 bitop3:0x78
	v_and_b32_e32 v82, 0xffffff00, v82
	v_xor_b32_e32 v82, 0x800000ea, v82
	v_add_f32_e32 v77, v115, v125
	v_ashrrev_i32_e32 v87, 31, v77
	v_bitop3_b32 v77, v77, v87, s41 bitop3:0x78
	v_and_b32_e32 v77, 0xffffff00, v77
	v_xor_b32_e32 v77, 0x800000e9, v77
	v_add_f32_e32 v87, v115, v126
	v_ashrrev_i32_e32 v94, 31, v87
	v_bitop3_b32 v87, v87, v94, s41 bitop3:0x78
	v_and_b32_e32 v87, 0xffffff00, v87
	v_xor_b32_e32 v87, 0x800000e8, v87
	v_add_f32_e32 v94, v98, v106
	v_ashrrev_i32_e32 v96, 31, v94
	v_bitop3_b32 v94, v94, v96, s41 bitop3:0x78
	v_and_b32_e32 v94, 0xffffff00, v94
	v_xor_b32_e32 v94, 0x800000df, v94
	v_add_f32_e32 v96, v98, v120
	v_ashrrev_i32_e32 v99, 31, v96
	v_bitop3_b32 v96, v96, v99, s41 bitop3:0x78
; #define CE_DESC(a, b) do { const unsigned _mx = (a) > (b) ? (a) : (b), _mn = (a) > (b) ? (b) : (a); (a) = _mx; (b) = _mn; } while (0)
; #define CK(i, j) ((f2key(va[i] + vb[j]) & ~255u) | (unsigned)(255 - (16 * (i) + (j))))
; __device__ __forceinline__ void sort16_desc(unsigned (&k)[16]) {
; #pragma unroll
;     for (int size = 2; size <= 16; size <<= 1)
; #pragma unroll
;         for (int stride = size >> 1; stride > 0; stride >>= 1)
; #pragma unroll
;             for (int i = 0; i < 16; ++i) { const int j = i ^ stride;
;                 if (j > i) { if ((i & size) == 0) CE_DESC(k[i], k[j]); else CE_DESC(k[j], k[i]); } }
; }
; __device__ __forceinline__ void merge16(unsigned (&a)[16], const unsigned (&b)[16]) {
; #pragma unroll
;     for (int i = 0; i < 16; ++i) a[i] = a[i] > b[15 - i] ? a[i] : b[15 - i];
; #pragma unroll
;     for (int stride = 8; stride > 0; stride >>= 1)
; #pragma unroll
;         for (int i = 0; i < 16; ++i) { const int j = i ^ stride; if (j > i) CE_DESC(a[i], a[j]); }
; }
; __device__ __forceinline__ void peer_tile(const Args& A, LAS unsigned char* lds, int tile) {
;     ...
;             unsigned Lf[16], Bt[16];
; #pragma unroll
;             for (int j = 0; j < 16; ++j) Lf[j] = CK(0, j);
; #pragma unroll
;             for (int j = 0; j < 8; ++j) Bt[j] = CK(1, j);
; #pragma unroll
;             for (int j = 0; j < 5; ++j) Bt[8 + j] = CK(2, j);
; #pragma unroll
;             for (int j = 0; j < 3; ++j) Bt[13 + j] = CK(4, j);
;             sort16_desc(Bt); merge16(Lf, Bt);
	v_and_b32_e32 v96, 0xffffff00, v96
	v_xor_b32_e32 v96, 0x800000de, v96
	v_add_f32_e32 v99, v98, v121
	v_ashrrev_i32_e32 v70, 31, v99
	v_bitop3_b32 v99, v99, v70, s41 bitop3:0x78
	v_and_b32_e32 v99, 0xffffff00, v99
	v_xor_b32_e32 v99, 0x800000dd, v99
	v_add_f32_e32 v70, v98, v122
	v_ashrrev_i32_e32 v97, 31, v70
	v_bitop3_b32 v70, v70, v97, s41 bitop3:0x78
	v_and_b32_e32 v70, 0xffffff00, v70
	v_xor_b32_e32 v70, 0x800000dc, v70
	v_add_f32_e32 v97, v98, v123
	v_ashrrev_i32_e32 v75, 31, v97
	v_bitop3_b32 v97, v97, v75, s41 bitop3:0x78
	v_and_b32_e32 v97, 0xffffff00, v97
	v_xor_b32_e32 v97, 0x800000db, v97
	v_add_f32_e32 v75, v74, v106
	v_ashrrev_i32_e32 v88, 31, v75
	v_bitop3_b32 v75, v75, v88, s41 bitop3:0x78
	v_and_b32_e32 v75, 0xffffff00, v75
	v_xor_b32_e32 v75, 0x800000bf, v75
	v_add_f32_e32 v88, v74, v120
	v_ashrrev_i32_e32 v72, 31, v88
	v_bitop3_b32 v88, v88, v72, s41 bitop3:0x78
	v_and_b32_e32 v88, 0xffffff00, v88
	v_xor_b32_e32 v88, 0x800000be, v88
	v_add_f32_e32 v72, v74, v121
	v_ashrrev_i32_e32 v135, 31, v72
	v_bitop3_b32 v72, v72, v135, s41 bitop3:0x78
	v_and_b32_e32 v72, 0xffffff00, v72
	v_xor_b32_e32 v72, 0x800000bd, v72
	v_max_u32_e32 v135, v86, v75
	v_min_u32_e32 v75, v86, v75
	v_max_u32_e32 v86, v102, v97
	v_min_u32_e32 v97, v102, v97
	v_max_u32_e32 v102, v85, v72
	v_min_u32_e32 v72, v85, v72
	v_max_u32_e32 v85, v78, v88
	v_min_u32_e32 v88, v78, v88
	v_max_u32_e32 v78, v81, v94
	v_min_u32_e32 v94, v81, v94
	v_max_u32_e32 v81, v82, v77
	v_min_u32_e32 v77, v82, v77
	v_max_u32_e32 v82, v87, v70
	v_min_u32_e32 v70, v87, v70
	v_max_u32_e32 v87, v96, v99
	v_min_u32_e32 v99, v96, v99
	v_max_u32_e32 v96, v135, v81
	v_min_u32_e32 v81, v135, v81
	v_max_u32_e32 v135, v86, v82
	v_min_u32_e32 v82, v86, v82
	v_max_u32_e32 v86, v102, v87
	v_min_u32_e32 v87, v102, v87
	v_max_u32_e32 v102, v85, v78
	v_min_u32_e32 v78, v85, v78
	v_max_u32_e32 v85, v77, v75
	v_min_u32_e32 v75, v77, v75
	v_max_u32_e32 v77, v94, v88
	v_min_u32_e32 v88, v94, v88
	v_max_u32_e32 v94, v99, v72
	v_min_u32_e32 v72, v99, v72
	v_max_u32_e32 v99, v70, v97
	v_min_u32_e32 v97, v70, v97
	v_max_u32_e32 v70, v96, v135
	v_min_u32_e32 v135, v96, v135
	v_max_u32_e32 v96, v86, v102
	v_min_u32_e32 v102, v86, v102
	v_max_u32_e32 v86, v78, v81
	v_min_u32_e32 v81, v78, v81
	v_max_u32_e32 v78, v85, v77
	v_min_u32_e32 v77, v85, v77
	v_max_u32_e32 v85, v82, v87
	v_min_u32_e32 v87, v82, v87
	v_max_u32_e32 v82, v94, v99
	v_min_u32_e32 v99, v94, v99
	v_max_u32_e32 v94, v97, v75
	v_min_u32_e32 v75, v97, v75
	v_max_u32_e32 v97, v88, v72
	v_min_u32_e32 v72, v88, v72
	v_max_u32_e32 v88, v70, v96
	v_min_u32_e32 v96, v70, v96
	v_max_u32_e32 v70, v135, v102
	v_min_u32_e32 v102, v135, v102
	v_max_u32_e32 v135, v86, v82
	v_min_u32_e32 v82, v86, v82
	v_max_u32_e32 v86, v81, v99
	v_min_u32_e32 v99, v81, v99
	v_max_u32_e32 v81, v78, v85
	v_min_u32_e32 v85, v78, v85
	v_max_u32_e32 v78, v77, v87
	v_min_u32_e32 v87, v77, v87
	v_max_u32_e32 v77, v94, v97
	v_min_u32_e32 v97, v94, v97
	v_max_u32_e32 v94, v75, v72
	v_min_u32_e32 v72, v75, v72
	v_max_u32_e32 v75, v70, v96
	v_min_u32_e32 v96, v70, v96
	v_max_u32_e32 v70, v102, v77
	v_min_u32_e32 v77, v102, v77
	v_max_u32_e32 v102, v135, v81
	v_min_u32_e32 v81, v135, v81
	v_max_u32_e32 v135, v86, v85
	v_min_u32_e32 v85, v86, v85
	v_max_u32_e32 v86, v78, v82
	v_min_u32_e32 v82, v78, v82
	v_max_u32_e32 v78, v87, v99
	v_min_u32_e32 v99, v87, v99
	v_max_u32_e32 v87, v94, v97
	v_min_u32_e32 v97, v94, v97
	v_max_u32_e32 v94, v75, v102
	v_min_u32_e32 v102, v75, v102
	v_max_u32_e32 v75, v96, v81
	v_min_u32_e32 v81, v96, v81
	v_max_u32_e32 v96, v135, v86
	v_min_u32_e32 v86, v135, v86
	v_max_u32_e32 v135, v85, v82
	v_min_u32_e32 v82, v85, v82
	v_max_u32_e32 v85, v78, v87
	v_min_u32_e32 v87, v78, v87
	v_max_u32_e32 v78, v99, v97
	v_min_u32_e32 v97, v99, v97
	v_max_u32_e32 v99, v75, v102
	v_min_u32_e32 v102, v75, v102
	v_max_u32_e32 v75, v70, v81
	v_min_u32_e32 v81, v70, v81
	v_max_u32_e32 v70, v85, v77
	v_min_u32_e32 v77, v85, v77
	v_max_u32_e32 v85, v78, v87
	v_min_u32_e32 v87, v78, v87
	v_max_u32_e32 v78, v75, v96
	v_min_u32_e32 v96, v75, v96
	v_max_u32_e32 v75, v81, v86
	v_min_u32_e32 v86, v81, v86
	v_max_u32_e32 v81, v135, v70
	v_min_u32_e32 v70, v135, v70
	v_max_u32_e32 v135, v82, v77
	v_min_u32_e32 v77, v82, v77
	v_max_u32_e32 v82, v78, v102
	v_min_u32_e32 v102, v78, v102
	v_max_u32_e32 v78, v96, v75
	v_min_u32_e32 v75, v96, v75
	v_max_u32_e32 v96, v81, v86
	v_min_u32_e32 v86, v81, v86
	v_max_u32_e32 v81, v70, v135
	v_min_u32_e32 v135, v70, v135
	v_max_u32_e32 v70, v85, v77
	v_min_u32_e32 v77, v85, v77
	v_max_u32_e32 v85, v75, v96
	v_min_u32_e32 v96, v75, v96
	v_max_u32_e32 v75, v86, v81
	v_min_u32_e32 v81, v86, v81
	v_max_u32_e32 v90, v90, v72
	v_max_u32_e32 v119, v119, v97
	v_max_u32_e32 v101, v101, v87
	v_max_u32_e32 v83, v83, v77
	v_max_u32_e32 v91, v91, v70
	v_max_u32_e32 v76, v76, v135
	v_max_u32_e32 v89, v89, v81
	v_max_u32_e32 v103, v103, v75
	v_max_u32_e32 v110, v110, v96
	v_max_u32_e32 v112, v112, v85
	v_max_u32_e32 v116, v116, v78
	v_max_u32_e32 v73, v73, v102
	v_max_u32_e32 v114, v114, v82
	v_max_u32_e32 v80, v80, v99
	v_max_u32_e32 v104, v104, v94
	v_max_u32_e32 v71, v71, v88
	v_max_u32_e32 v72, v90, v110
	v_min_u32_e32 v110, v90, v110
	v_max_u32_e32 v90, v119, v112
	v_min_u32_e32 v112, v119, v112
	v_max_u32_e32 v119, v101, v116
	v_min_u32_e32 v116, v101, v116
	v_max_u32_e32 v101, v83, v73
	v_min_u32_e32 v73, v83, v73
	v_max_u32_e32 v83, v91, v114
	v_min_u32_e32 v114, v91, v114
	v_max_u32_e32 v91, v76, v80
	v_min_u32_e32 v80, v76, v80
	v_max_u32_e32 v76, v89, v104
	v_min_u32_e32 v104, v89, v104
	v_max_u32_e32 v89, v103, v71
	v_min_u32_e32 v71, v103, v71
; #define CE_DESC(a, b) do { const unsigned _mx = (a) > (b) ? (a) : (b), _mn = (a) > (b) ? (b) : (a); (a) = _mx; (b) = _mn; } while (0)
; #define CK(i, j) ((f2key(va[i] + vb[j]) & ~255u) | (unsigned)(255 - (16 * (i) + (j))))
; __device__ __forceinline__ void sort16_desc(unsigned (&k)[16]) {
; #pragma unroll
;     for (int size = 2; size <= 16; size <<= 1)
; #pragma unroll
;         for (int stride = size >> 1; stride > 0; stride >>= 1)
; #pragma unroll
;             for (int i = 0; i < 16; ++i) { const int j = i ^ stride;
;                 if (j > i) { if ((i & size) == 0) CE_DESC(k[i], k[j]); else CE_DESC(k[j], k[i]); } }
; }
; __device__ __forceinline__ void merge16(unsigned (&a)[16], const unsigned (&b)[16]) {
; #pragma unroll
;     for (int i = 0; i < 16; ++i) a[i] = a[i] > b[15 - i] ? a[i] : b[15 - i];
; #pragma unroll
;     for (int stride = 8; stride > 0; stride >>= 1)
; #pragma unroll
;         for (int i = 0; i < 16; ++i) { const int j = i ^ stride; if (j > i) CE_DESC(a[i], a[j]); }
; }
; __device__ __forceinline__ void peer_tile(const Args& A, LAS unsigned char* lds, int tile) {
;     ...
;             for (int j = 0; j < 4; ++j) Bt[j] = CK(3, j);
;             Bt[4] = CK(5, 0); Bt[5] = CK(5, 1); Bt[6] = CK(6, 0); Bt[7] = CK(6, 1); Bt[8] = CK(7, 0); Bt[9] = CK(7, 1);
;             Bt[10] = CK(8, 0); Bt[11] = CK(9, 0); Bt[12] = CK(10, 0); Bt[13] = CK(11, 0); Bt[14] = CK(12, 0); Bt[15] = CK(13, 0);
;             sort16_desc(Bt); merge16(Lf, Bt);
	v_max_u32_e32 v103, v72, v83
	v_min_u32_e32 v83, v72, v83
	v_max_u32_e32 v72, v90, v91
	v_min_u32_e32 v91, v90, v91
	v_max_u32_e32 v90, v119, v76
	v_min_u32_e32 v76, v119, v76
	v_max_u32_e32 v119, v101, v89
	v_min_u32_e32 v89, v101, v89
	v_max_u32_e32 v101, v110, v114
	v_min_u32_e32 v114, v110, v114
	v_max_u32_e32 v110, v112, v80
	v_min_u32_e32 v80, v112, v80
	v_max_u32_e32 v112, v116, v104
	v_min_u32_e32 v104, v116, v104
	v_max_u32_e32 v116, v73, v71
	v_min_u32_e32 v71, v73, v71
	v_max_u32_e32 v73, v103, v90
	v_min_u32_e32 v90, v103, v90
	v_max_u32_e32 v103, v72, v119
	v_min_u32_e32 v119, v72, v119
	v_max_u32_e32 v72, v83, v76
	v_min_u32_e32 v76, v83, v76
	v_max_u32_e32 v83, v91, v89
	v_min_u32_e32 v89, v91, v89
	v_max_u32_e32 v91, v101, v112
	v_min_u32_e32 v112, v101, v112
	v_max_u32_e32 v101, v110, v116
	v_min_u32_e32 v116, v110, v116
	v_max_u32_e32 v110, v114, v104
	v_min_u32_e32 v104, v114, v104
	v_max_u32_e32 v114, v80, v71
	v_min_u32_e32 v71, v80, v71
	v_max_u32_e32 v80, v73, v103
	v_min_u32_e32 v103, v73, v103
	v_max_u32_e32 v73, v90, v119
	v_min_u32_e32 v119, v90, v119
	v_max_u32_e32 v90, v72, v83
	v_min_u32_e32 v83, v72, v83
	v_max_u32_e32 v72, v76, v89
	v_min_u32_e32 v89, v76, v89
	v_max_u32_e32 v76, v91, v101
	v_min_u32_e32 v101, v91, v101
	v_max_u32_e32 v91, v112, v116
	v_min_u32_e32 v116, v112, v116
	v_max_u32_e32 v112, v110, v114
	v_min_u32_e32 v114, v110, v114
	v_max_u32_e32 v110, v104, v71
	v_min_u32_e32 v71, v104, v71
	v_add_f32_e32 v104, v111, v106
	v_ashrrev_i32_e32 v97, 31, v104
	v_bitop3_b32 v104, v104, v97, s41 bitop3:0x78
	v_and_b32_e32 v104, 0xffffff00, v104
	v_xor_b32_e32 v104, 0x800000cf, v104
	v_add_f32_e32 v97, v111, v120
	v_ashrrev_i32_e32 v87, 31, v97
	v_bitop3_b32 v97, v97, v87, s41 bitop3:0x78
	v_and_b32_e32 v97, 0xffffff00, v97
	v_xor_b32_e32 v97, 0x800000ce, v97
	v_add_f32_e32 v87, v111, v121
	v_ashrrev_i32_e32 v77, 31, v87
	v_bitop3_b32 v87, v87, v77, s41 bitop3:0x78
	v_and_b32_e32 v87, 0xffffff00, v87
	v_xor_b32_e32 v87, 0x800000cd, v87
	v_add_f32_e32 v77, v111, v122
	v_ashrrev_i32_e32 v70, 31, v77
	v_bitop3_b32 v77, v77, v70, s41 bitop3:0x78
	v_and_b32_e32 v77, 0xffffff00, v77
	v_xor_b32_e32 v77, 0x800000cc, v77
	v_add_f32_e32 v70, v84, v106
	v_ashrrev_i32_e32 v135, 31, v70
	v_bitop3_b32 v70, v70, v135, s41 bitop3:0x78
	v_and_b32_e32 v70, 0xffffff00, v70
	v_xor_b32_e32 v70, 0x800000af, v70
	v_add_f32_e32 v135, v84, v120
	v_ashrrev_i32_e32 v81, 31, v135
	v_bitop3_b32 v135, v135, v81, s41 bitop3:0x78
	v_and_b32_e32 v135, 0xffffff00, v135
	v_xor_b32_e32 v135, 0x800000ae, v135
	v_add_f32_e32 v81, v100, v106
	v_ashrrev_i32_e32 v75, 31, v81
	v_bitop3_b32 v81, v81, v75, s41 bitop3:0x78
	v_and_b32_e32 v81, 0xffffff00, v81
	v_xor_b32_e32 v81, 0x8000009f, v81
	v_add_f32_e32 v75, v100, v120
	v_ashrrev_i32_e32 v96, 31, v75
	v_bitop3_b32 v75, v75, v96, s41 bitop3:0x78
	v_and_b32_e32 v75, 0xffffff00, v75
	v_xor_b32_e32 v75, 0x8000009e, v75
	v_add_f32_e32 v96, v105, v106
	v_ashrrev_i32_e32 v85, 31, v96
	v_bitop3_b32 v96, v96, v85, s41 bitop3:0x78
	v_and_b32_e32 v96, 0xffffff00, v96
	v_xor_b32_e32 v96, 0x8000008f, v96
	v_add_f32_e32 v85, v105, v120
	v_ashrrev_i32_e32 v78, 31, v85
	v_bitop3_b32 v85, v85, v78, s41 bitop3:0x78
	v_and_b32_e32 v85, 0xffffff00, v85
	v_xor_b32_e32 v85, 0x8000008e, v85
	v_add_f32_e32 v78, v92, v106
	v_ashrrev_i32_e32 v102, 31, v78
	v_bitop3_b32 v78, v78, v102, s41 bitop3:0x78
	v_and_b32_e32 v78, 0xffffff00, v78
	v_xor_b32_e32 v78, 0x8000007f, v78
	v_add_f32_e32 v102, v117, v106
	v_ashrrev_i32_e32 v82, 31, v102
	v_bitop3_b32 v102, v102, v82, s41 bitop3:0x78
	v_and_b32_e32 v102, 0xffffff00, v102
	v_xor_b32_e32 v102, 0x8000006f, v102
	v_add_f32_e32 v82, v93, v106
	v_ashrrev_i32_e32 v99, 31, v82
	v_bitop3_b32 v82, v82, v99, s41 bitop3:0x78
	v_and_b32_e32 v82, 0xffffff00, v82
	v_xor_b32_e32 v82, 0x8000005f, v82
	v_add_f32_e32 v99, v107, v106
	v_ashrrev_i32_e32 v94, 31, v99
	v_bitop3_b32 v99, v99, v94, s41 bitop3:0x78
	v_and_b32_e32 v99, 0xffffff00, v99
	v_xor_b32_e32 v99, 0x8000004f, v99
	v_add_f32_e32 v94, v79, v106
	v_ashrrev_i32_e32 v88, 31, v94
	v_bitop3_b32 v94, v94, v88, s41 bitop3:0x78
	v_and_b32_e32 v94, 0xffffff00, v94
	v_xor_b32_e32 v94, 0x8000003f, v94
	v_add_f32_e32 v88, v108, v106
	v_ashrrev_i32_e32 v86, 31, v88
	v_bitop3_b32 v88, v88, v86, s41 bitop3:0x78
	v_and_b32_e32 v88, 0xffffff00, v88
	v_xor_b32_e32 v88, 0x8000002f, v88
	v_max_u32_e32 v86, v104, v99
	v_min_u32_e32 v99, v104, v99
	v_max_u32_e32 v104, v97, v82
	v_min_u32_e32 v82, v97, v82
	v_max_u32_e32 v97, v87, v88
	v_min_u32_e32 v88, v87, v88
	v_max_u32_e32 v87, v77, v94
	v_min_u32_e32 v94, v77, v94
	v_max_u32_e32 v77, v70, v96
	v_min_u32_e32 v96, v70, v96
	v_max_u32_e32 v70, v135, v81
	v_min_u32_e32 v81, v135, v81
	v_max_u32_e32 v135, v75, v102
	v_min_u32_e32 v102, v75, v102
	v_max_u32_e32 v75, v85, v78
	v_min_u32_e32 v78, v85, v78
	v_max_u32_e32 v85, v86, v70
	v_min_u32_e32 v70, v86, v70
	v_max_u32_e32 v86, v104, v135
	v_min_u32_e32 v135, v104, v135
	v_max_u32_e32 v104, v97, v75
	v_min_u32_e32 v75, v97, v75
	v_max_u32_e32 v97, v87, v77
	v_min_u32_e32 v77, v87, v77
	v_max_u32_e32 v87, v81, v99
	v_min_u32_e32 v99, v81, v99
	v_max_u32_e32 v81, v96, v94
	v_min_u32_e32 v94, v96, v94
	v_max_u32_e32 v96, v78, v88
	v_min_u32_e32 v88, v78, v88
	v_max_u32_e32 v78, v102, v82
	v_min_u32_e32 v82, v102, v82
	v_max_u32_e32 v102, v85, v86
	v_min_u32_e32 v86, v85, v86
	v_max_u32_e32 v85, v104, v97
	v_min_u32_e32 v97, v104, v97
	v_max_u32_e32 v104, v77, v70
	v_min_u32_e32 v70, v77, v70
	v_max_u32_e32 v77, v87, v81
	v_min_u32_e32 v81, v87, v81
	v_max_u32_e32 v87, v135, v75
	v_min_u32_e32 v75, v135, v75
	v_max_u32_e32 v135, v96, v78
; #define CE_DESC(a, b) do { const unsigned _mx = (a) > (b) ? (a) : (b), _mn = (a) > (b) ? (b) : (a); (a) = _mx; (b) = _mn; } while (0)
; #define CK(i, j) ((f2key(va[i] + vb[j]) & ~255u) | (unsigned)(255 - (16 * (i) + (j))))
; __device__ __forceinline__ void sort16_desc(unsigned (&k)[16]) {
; #pragma unroll
;     for (int size = 2; size <= 16; size <<= 1)
; #pragma unroll
;         for (int stride = size >> 1; stride > 0; stride >>= 1)
; #pragma unroll
;             for (int i = 0; i < 16; ++i) { const int j = i ^ stride;
;                 if (j > i) { if ((i & size) == 0) CE_DESC(k[i], k[j]); else CE_DESC(k[j], k[i]); } }
; }
; __device__ __forceinline__ void merge16(unsigned (&a)[16], const unsigned (&b)[16]) {
; #pragma unroll
;     for (int i = 0; i < 16; ++i) a[i] = a[i] > b[15 - i] ? a[i] : b[15 - i];
; #pragma unroll
;     for (int stride = 8; stride > 0; stride >>= 1)
; #pragma unroll
;         for (int i = 0; i < 16; ++i) { const int j = i ^ stride; if (j > i) CE_DESC(a[i], a[j]); }
; }
; __device__ __forceinline__ void peer_tile(const Args& A, LAS unsigned char* lds, int tile) {
;     ...
;             for (int j = 0; j < 4; ++j) Bt[j] = CK(3, j);
;             Bt[4] = CK(5, 0); Bt[5] = CK(5, 1); Bt[6] = CK(6, 0); Bt[7] = CK(6, 1); Bt[8] = CK(7, 0); Bt[9] = CK(7, 1);
;             Bt[10] = CK(8, 0); Bt[11] = CK(9, 0); Bt[12] = CK(10, 0); Bt[13] = CK(11, 0); Bt[14] = CK(12, 0); Bt[15] = CK(13, 0);
;             sort16_desc(Bt); merge16(Lf, Bt);
;             { unsigned x0 = CK(14, 0), x1 = CK(15, 0);
; #pragma unroll
;               for (int i = 0; i < 16; ++i) CE_DESC(Lf[i], x0);
; #pragma unroll
;               for (int i = 0; i < 16; ++i) CE_DESC(Lf[i], x1); }
	v_min_u32_e32 v78, v96, v78
	v_max_u32_e32 v96, v82, v99
	v_min_u32_e32 v99, v82, v99
	v_max_u32_e32 v82, v94, v88
	v_min_u32_e32 v88, v94, v88
	v_max_u32_e32 v94, v102, v85
	v_min_u32_e32 v85, v102, v85
	v_max_u32_e32 v102, v86, v97
	v_min_u32_e32 v97, v86, v97
	v_max_u32_e32 v86, v104, v135
	v_min_u32_e32 v135, v104, v135
	v_max_u32_e32 v104, v70, v78
	v_min_u32_e32 v78, v70, v78
	v_max_u32_e32 v70, v77, v87
	v_min_u32_e32 v87, v77, v87
	v_max_u32_e32 v77, v81, v75
	v_min_u32_e32 v75, v81, v75
	v_max_u32_e32 v81, v96, v82
	v_min_u32_e32 v82, v96, v82
	v_max_u32_e32 v96, v99, v88
	v_min_u32_e32 v88, v99, v88
	v_max_u32_e32 v99, v102, v85
	v_min_u32_e32 v85, v102, v85
	v_max_u32_e32 v102, v97, v81
	v_min_u32_e32 v81, v97, v81
	v_max_u32_e32 v97, v86, v70
	v_min_u32_e32 v70, v86, v70
	v_max_u32_e32 v86, v104, v87
	v_min_u32_e32 v87, v104, v87
	v_max_u32_e32 v104, v77, v135
	v_min_u32_e32 v135, v77, v135
	v_max_u32_e32 v77, v75, v78
	v_min_u32_e32 v78, v75, v78
	v_max_u32_e32 v75, v96, v82
	v_min_u32_e32 v82, v96, v82
	v_max_u32_e32 v96, v99, v97
	v_min_u32_e32 v97, v99, v97
	v_max_u32_e32 v99, v85, v70
	v_min_u32_e32 v70, v85, v70
	v_max_u32_e32 v85, v86, v104
	v_min_u32_e32 v104, v86, v104
	v_max_u32_e32 v86, v87, v135
	v_min_u32_e32 v135, v87, v135
	v_max_u32_e32 v87, v77, v75
	v_min_u32_e32 v75, v77, v75
	v_max_u32_e32 v77, v78, v82
	v_min_u32_e32 v82, v78, v82
	v_max_u32_e32 v78, v99, v97
	v_min_u32_e32 v97, v99, v97
	v_max_u32_e32 v99, v102, v70
	v_min_u32_e32 v70, v102, v70
	v_max_u32_e32 v102, v87, v81
	v_min_u32_e32 v81, v87, v81
	v_max_u32_e32 v87, v77, v75
	v_min_u32_e32 v75, v77, v75
	v_max_u32_e32 v77, v99, v85
	v_min_u32_e32 v85, v99, v85
	v_max_u32_e32 v99, v70, v104
	v_min_u32_e32 v104, v70, v104
	v_max_u32_e32 v70, v86, v102
	v_min_u32_e32 v102, v86, v102
	v_max_u32_e32 v86, v135, v81
	v_min_u32_e32 v81, v135, v81
	v_max_u32_e32 v135, v77, v97
	v_min_u32_e32 v97, v77, v97
	v_max_u32_e32 v77, v85, v99
	v_min_u32_e32 v99, v85, v99
	v_max_u32_e32 v85, v70, v104
	v_min_u32_e32 v104, v70, v104
	v_max_u32_e32 v70, v102, v86
	v_min_u32_e32 v86, v102, v86
	v_max_u32_e32 v102, v87, v81
	v_min_u32_e32 v81, v87, v81
	v_max_u32_e32 v87, v99, v85
	v_min_u32_e32 v85, v99, v85
	v_max_u32_e32 v99, v104, v70
	v_min_u32_e32 v70, v104, v70
	v_max_u32_e32 v80, v80, v88
	v_max_u32_e32 v103, v103, v82
	v_max_u32_e32 v73, v73, v75
	v_max_u32_e32 v119, v119, v81
	v_max_u32_e32 v90, v90, v102
	v_max_u32_e32 v83, v83, v86
	v_max_u32_e32 v72, v72, v70
	v_max_u32_e32 v89, v89, v99
	v_max_u32_e32 v76, v76, v85
	v_max_u32_e32 v101, v101, v87
	v_max_u32_e32 v91, v91, v77
	v_max_u32_e32 v116, v116, v97
	v_max_u32_e32 v112, v112, v135
	v_max_u32_e32 v114, v114, v78
	v_max_u32_e32 v110, v110, v96
	v_max_u32_e32 v71, v71, v94
	v_max_u32_e32 v88, v80, v76
	v_min_u32_e32 v76, v80, v76
	v_max_u32_e32 v80, v103, v101
	v_min_u32_e32 v101, v103, v101
	v_max_u32_e32 v103, v73, v91
	v_min_u32_e32 v91, v73, v91
	v_max_u32_e32 v73, v119, v116
	v_min_u32_e32 v116, v119, v116
	v_max_u32_e32 v119, v90, v112
	v_min_u32_e32 v112, v90, v112
	v_max_u32_e32 v90, v83, v114
	v_min_u32_e32 v114, v83, v114
	v_max_u32_e32 v83, v72, v110
	v_min_u32_e32 v110, v72, v110
	v_max_u32_e32 v72, v89, v71
	v_min_u32_e32 v71, v89, v71
	v_max_u32_e32 v89, v88, v119
	v_min_u32_e32 v119, v88, v119
	v_max_u32_e32 v88, v80, v90
	v_min_u32_e32 v90, v80, v90
	v_max_u32_e32 v80, v103, v83
	v_min_u32_e32 v83, v103, v83
	v_max_u32_e32 v103, v73, v72
	v_min_u32_e32 v72, v73, v72
	v_max_u32_e32 v73, v76, v112
	v_min_u32_e32 v112, v76, v112
	v_max_u32_e32 v76, v101, v114
	v_min_u32_e32 v114, v101, v114
	v_max_u32_e32 v101, v91, v110
	v_min_u32_e32 v110, v91, v110
	v_max_u32_e32 v91, v116, v71
	v_min_u32_e32 v71, v116, v71
	v_max_u32_e32 v116, v89, v80
	v_min_u32_e32 v80, v89, v80
	v_max_u32_e32 v89, v88, v103
	v_min_u32_e32 v103, v88, v103
	v_max_u32_e32 v88, v119, v83
	v_min_u32_e32 v83, v119, v83
	v_max_u32_e32 v119, v90, v72
	v_min_u32_e32 v72, v90, v72
	v_max_u32_e32 v90, v73, v101
	v_min_u32_e32 v101, v73, v101
	v_max_u32_e32 v73, v76, v91
	v_min_u32_e32 v91, v76, v91
	v_max_u32_e32 v76, v112, v110
	v_min_u32_e32 v110, v112, v110
	v_max_u32_e32 v112, v114, v71
	v_min_u32_e32 v71, v114, v71
	v_max_u32_e32 v114, v116, v89
	v_min_u32_e32 v89, v116, v89
	v_max_u32_e32 v116, v80, v103
	v_min_u32_e32 v103, v80, v103
	v_max_u32_e32 v80, v88, v119
	v_min_u32_e32 v119, v88, v119
	v_max_u32_e32 v88, v83, v72
	v_min_u32_e32 v72, v83, v72
	v_max_u32_e32 v83, v90, v73
	v_min_u32_e32 v73, v90, v73
	v_max_u32_e32 v90, v101, v91
	v_min_u32_e32 v91, v101, v91
	v_max_u32_e32 v101, v76, v112
	v_min_u32_e32 v112, v76, v112
	v_max_u32_e32 v76, v110, v71
	v_min_u32_e32 v71, v110, v71
	v_add_f32_e32 v110, v109, v106
	v_ashrrev_i32_e32 v82, 31, v110
	v_bitop3_b32 v110, v110, v82, s41 bitop3:0x78
	v_and_b32_e32 v110, 0xffffff00, v110
	v_xor_b32_e32 v110, 0x8000001f, v110
	v_max_u32_e32 v82, v114, v110
	v_med3_u32 v75, v114, v89, v110
	v_med3_u32 v81, v89, v116, v110
	v_med3_u32 v102, v116, v103, v110
	v_med3_u32 v86, v103, v80, v110
	v_med3_u32 v70, v80, v119, v110
	v_med3_u32 v99, v119, v88, v110
	v_med3_u32 v85, v88, v72, v110
	v_med3_u32 v87, v72, v83, v110
	v_med3_u32 v77, v83, v73, v110
	v_med3_u32 v97, v73, v90, v110
	v_med3_u32 v135, v90, v91, v110
	v_med3_u32 v78, v91, v101, v110
	v_med3_u32 v96, v101, v112, v110
	v_med3_u32 v94, v112, v76, v110
	v_med3_u32 v104, v76, v71, v110
	v_add_f32_e32 v110, v118, v106
	v_ashrrev_i32_e32 v71, 31, v110
	v_bitop3_b32 v110, v110, v71, s41 bitop3:0x78
	v_and_b32_e32 v110, 0xffffff00, v110
	v_xor_b32_e32 v110, 0x8000000f, v110
	v_max_u32_e32 v71, v82, v110
	v_med3_u32 v76, v82, v75, v110
; __device__ __forceinline__ float key2f(unsigned k) { const unsigned u = (k & 0x80000000u) ? (k & 0x7fffffffu) : ~k; return __uint_as_float(u); }
; #define CE_DESC(a, b) do { const unsigned _mx = (a) > (b) ? (a) : (b), _mn = (a) > (b) ? (b) : (a); (a) = _mx; (b) = _mn; } while (0)
; #define CK(i, j) ((f2key(va[i] + vb[j]) & ~255u) | (unsigned)(255 - (16 * (i) + (j))))
; __device__ __forceinline__ void peer_tile(const Args& A, LAS unsigned char* lds, int tile) {
;     ...
;             { unsigned x0 = CK(14, 0), x1 = CK(15, 0);
; #pragma unroll
;               for (int i = 0; i < 16; ++i) CE_DESC(Lf[i], x0);
; #pragma unroll
;               for (int i = 0; i < 16; ++i) CE_DESC(Lf[i], x1); }
;     ...
;             float fv[16], den = 0.f; const float f0 = key2f(Lf[0] & ~255u);
; #pragma unroll
;             for (int k = 0; k < 16; ++k) { fv[k] = __expf(key2f(Lf[k] & ~255u) - f0); den += fv[k]; }
;             const float rden = 1.f / den;
	v_med3_u32 v112, v75, v81, v110
	v_med3_u32 v101, v81, v102, v110
	v_med3_u32 v91, v102, v86, v110
	v_med3_u32 v90, v86, v70, v110
	v_med3_u32 v73, v70, v99, v110
	v_med3_u32 v83, v99, v85, v110
	v_med3_u32 v72, v85, v87, v110
	v_med3_u32 v88, v87, v77, v110
	v_med3_u32 v119, v77, v97, v110
	v_med3_u32 v80, v97, v135, v110
	v_med3_u32 v103, v135, v78, v110
	v_med3_u32 v116, v78, v96, v110
	v_med3_u32 v89, v96, v94, v110
	v_med3_u32 v114, v94, v104, v110
	v_ashrrev_i32_e32 v133, 31, v71
	v_and_b32_e32 v134, 0xffffff00, v71
	v_bitop3_b32 v134, v134, v133, s41 bitop3:0x87
	v_ashrrev_i32_e32 v131, 31, v71
	v_and_b32_e32 v132, 0xffffff00, v71
	v_bitop3_b32 v132, v132, v131, s41 bitop3:0x87
	v_sub_f32_e32 v132, v132, v134
	v_mul_f32_e32 v132, 0x3fb8aa3b, v132
	v_exp_f32_e32 v132, v132
	v_ashrrev_i32_e32 v130, 31, v76
	v_and_b32_e32 v131, 0xffffff00, v76
	v_bitop3_b32 v131, v131, v130, s41 bitop3:0x87
	v_sub_f32_e32 v131, v131, v134
	v_mul_f32_e32 v131, 0x3fb8aa3b, v131
	v_exp_f32_e32 v131, v131
	v_ashrrev_i32_e32 v129, 31, v112
	v_and_b32_e32 v130, 0xffffff00, v112
	v_bitop3_b32 v130, v130, v129, s41 bitop3:0x87
	v_sub_f32_e32 v130, v130, v134
	v_mul_f32_e32 v130, 0x3fb8aa3b, v130
	v_exp_f32_e32 v130, v130
	v_ashrrev_i32_e32 v128, 31, v101
	v_and_b32_e32 v129, 0xffffff00, v101
	v_bitop3_b32 v129, v129, v128, s41 bitop3:0x87
	v_sub_f32_e32 v129, v129, v134
	v_mul_f32_e32 v129, 0x3fb8aa3b, v129
	v_exp_f32_e32 v129, v129
	v_ashrrev_i32_e32 v127, 31, v91
	v_and_b32_e32 v128, 0xffffff00, v91
	v_bitop3_b32 v128, v128, v127, s41 bitop3:0x87
	v_sub_f32_e32 v128, v128, v134
	v_mul_f32_e32 v128, 0x3fb8aa3b, v128
	v_exp_f32_e32 v128, v128
	v_ashrrev_i32_e32 v126, 31, v90
	v_and_b32_e32 v127, 0xffffff00, v90
	v_bitop3_b32 v127, v127, v126, s41 bitop3:0x87
	v_sub_f32_e32 v127, v127, v134
	v_mul_f32_e32 v127, 0x3fb8aa3b, v127
	v_exp_f32_e32 v127, v127
	v_ashrrev_i32_e32 v125, 31, v73
	v_and_b32_e32 v126, 0xffffff00, v73
	v_bitop3_b32 v126, v126, v125, s41 bitop3:0x87
	v_sub_f32_e32 v126, v126, v134
	v_mul_f32_e32 v126, 0x3fb8aa3b, v126
	v_exp_f32_e32 v126, v126
	v_ashrrev_i32_e32 v124, 31, v83
	v_and_b32_e32 v125, 0xffffff00, v83
	v_bitop3_b32 v125, v125, v124, s41 bitop3:0x87
	v_sub_f32_e32 v125, v125, v134
	v_mul_f32_e32 v125, 0x3fb8aa3b, v125
	v_exp_f32_e32 v125, v125
	v_ashrrev_i32_e32 v123, 31, v72
	v_and_b32_e32 v124, 0xffffff00, v72
	v_bitop3_b32 v124, v124, v123, s41 bitop3:0x87
	v_sub_f32_e32 v124, v124, v134
	v_mul_f32_e32 v124, 0x3fb8aa3b, v124
	v_exp_f32_e32 v124, v124
	v_ashrrev_i32_e32 v122, 31, v88
	v_and_b32_e32 v123, 0xffffff00, v88
	v_bitop3_b32 v123, v123, v122, s41 bitop3:0x87
	v_sub_f32_e32 v123, v123, v134
	v_mul_f32_e32 v123, 0x3fb8aa3b, v123
	v_exp_f32_e32 v123, v123
	v_ashrrev_i32_e32 v121, 31, v119
	v_and_b32_e32 v122, 0xffffff00, v119
	v_bitop3_b32 v122, v122, v121, s41 bitop3:0x87
	v_sub_f32_e32 v122, v122, v134
	v_mul_f32_e32 v122, 0x3fb8aa3b, v122
	v_exp_f32_e32 v122, v122
	v_ashrrev_i32_e32 v120, 31, v80
	v_and_b32_e32 v121, 0xffffff00, v80
	v_bitop3_b32 v121, v121, v120, s41 bitop3:0x87
	v_sub_f32_e32 v121, v121, v134
	v_mul_f32_e32 v121, 0x3fb8aa3b, v121
	v_exp_f32_e32 v121, v121
	v_ashrrev_i32_e32 v106, 31, v103
	v_and_b32_e32 v120, 0xffffff00, v103
	v_bitop3_b32 v120, v120, v106, s41 bitop3:0x87
	v_sub_f32_e32 v120, v120, v134
	v_mul_f32_e32 v120, 0x3fb8aa3b, v120
	v_exp_f32_e32 v120, v120
	v_ashrrev_i32_e32 v118, 31, v116
	v_and_b32_e32 v106, 0xffffff00, v116
	v_bitop3_b32 v106, v106, v118, s41 bitop3:0x87
	v_sub_f32_e32 v106, v106, v134
	v_mul_f32_e32 v106, 0x3fb8aa3b, v106
	v_exp_f32_e32 v106, v106
	v_ashrrev_i32_e32 v109, 31, v89
	v_and_b32_e32 v118, 0xffffff00, v89
	v_bitop3_b32 v118, v118, v109, s41 bitop3:0x87
	v_sub_f32_e32 v118, v118, v134
	v_mul_f32_e32 v118, 0x3fb8aa3b, v118
	v_exp_f32_e32 v118, v118
	v_ashrrev_i32_e32 v108, 31, v114
	v_and_b32_e32 v109, 0xffffff00, v114
	v_bitop3_b32 v109, v109, v108, s41 bitop3:0x87
	v_sub_f32_e32 v109, v109, v134
	v_mul_f32_e32 v109, 0x3fb8aa3b, v109
	v_exp_f32_e32 v109, v109
	v_add_f32_e32 v133, 0, v132
	v_add_f32_e32 v133, v133, v131
	v_add_f32_e32 v133, v133, v130
	v_add_f32_e32 v133, v133, v129
	v_add_f32_e32 v133, v133, v128
	v_add_f32_e32 v133, v133, v127
	v_add_f32_e32 v133, v133, v126
	v_add_f32_e32 v133, v133, v125
	v_add_f32_e32 v133, v133, v124
	v_add_f32_e32 v133, v133, v123
	v_add_f32_e32 v133, v133, v122
	v_add_f32_e32 v133, v133, v121
	v_add_f32_e32 v133, v133, v120
	v_add_f32_e32 v133, v133, v106
	v_add_f32_e32 v133, v133, v118
	v_add_f32_e32 v133, v133, v109
	v_div_scale_f32 v108, s[0:1], v133, v133, 1.0
	v_rcp_f32_e32 v79, v108
	s_nop 0
	v_fma_f32 v107, -v108, v79, 1.0
	v_fmac_f32_e32 v79, v107, v79
	v_div_scale_f32 v107, vcc, 1.0, v133, 1.0
	v_mul_f32_e32 v93, v107, v79
	v_fma_f32 v117, -v108, v93, v107
	v_fmac_f32_e32 v93, v117, v79
	v_fma_f32 v108, -v108, v93, v107
	s_nop 1
	v_div_fmas_f32 v108, v108, v79, v93
	v_div_fixup_f32 v108, v108, v133, 1.0
	s_waitcnt lgkmcnt(0)
; #define LDS_WAIT() asm volatile("s_waitcnt lgkmcnt(0)" ::: "memory")
; __device__ __forceinline__ void peer_tile(const Args& A, LAS unsigned char* lds, int tile) {
;     ...
;             LDS_WAIT();
; #pragma unroll
;             for (int k = 0; k < 16; ++k) { const unsigned code = 255u - (Lf[k] & 255u); const unsigned e = idx[code >> 4] * 128u + idx[16 + (code & 15u)];
;                 u32x2 sv; sv.x = e; sv.y = __float_as_uint(fv[k] * rden); SEL[(tl * 8 + h) * 16 + k] = sv; }
	v_xor_b32_e32 v117, 0xff, v71
	v_bfe_u32 v93, v117, 4, 4
	v_and_b32_e32 v117, 15, v117
	v_lshl_add_u32 v93, v93, 2, v67
	v_lshl_add_u32 v117, v117, 2, v67
	ds_read_b32 v93, v93
	ds_read_b32 v117, v117 offset:64
	v_xor_b32_e32 v107, 0xff, v76
	v_bfe_u32 v79, v107, 4, 4
	v_and_b32_e32 v107, 15, v107
	v_lshl_add_u32 v79, v79, 2, v67
	v_lshl_add_u32 v107, v107, 2, v67
	ds_read_b32 v79, v79
	ds_read_b32 v107, v107 offset:64
	v_xor_b32_e32 v92, 0xff, v112
	v_bfe_u32 v105, v92, 4, 4
	v_and_b32_e32 v92, 15, v92
	v_lshl_add_u32 v105, v105, 2, v67
	v_lshl_add_u32 v92, v92, 2, v67
	ds_read_b32 v105, v105
	ds_read_b32 v92, v92 offset:64
	v_xor_b32_e32 v100, 0xff, v101
	v_bfe_u32 v84, v100, 4, 4
	v_and_b32_e32 v100, 15, v100
	v_lshl_add_u32 v84, v84, 2, v67
	v_lshl_add_u32 v100, v100, 2, v67
	ds_read_b32 v84, v84
	ds_read_b32 v100, v100 offset:64
	v_xor_b32_e32 v74, 0xff, v91
	v_bfe_u32 v111, v74, 4, 4
	v_and_b32_e32 v74, 15, v74
	v_lshl_add_u32 v111, v111, 2, v67
	v_lshl_add_u32 v74, v74, 2, v67
	ds_read_b32 v111, v111
	ds_read_b32 v74, v74 offset:64
	v_xor_b32_e32 v98, 0xff, v90
	v_bfe_u32 v115, v98, 4, 4
	v_and_b32_e32 v98, 15, v98
	v_lshl_add_u32 v115, v115, 2, v67
	v_lshl_add_u32 v98, v98, 2, v67
	ds_read_b32 v115, v115
	ds_read_b32 v98, v98 offset:64
	v_xor_b32_e32 v95, 0xff, v73
	v_bfe_u32 v110, v95, 4, 4
	v_and_b32_e32 v95, 15, v95
	v_lshl_add_u32 v110, v110, 2, v67
	v_lshl_add_u32 v95, v95, 2, v67
	ds_read_b32 v110, v110
	ds_read_b32 v95, v95 offset:64
	v_xor_b32_e32 v104, 0xff, v83
	v_bfe_u32 v94, v104, 4, 4
	v_and_b32_e32 v104, 15, v104
	v_lshl_add_u32 v94, v94, 2, v67
	v_lshl_add_u32 v104, v104, 2, v67
	ds_read_b32 v94, v94
	ds_read_b32 v104, v104 offset:64
	v_xor_b32_e32 v96, 0xff, v72
	v_bfe_u32 v78, v96, 4, 4
	v_and_b32_e32 v96, 15, v96
	v_lshl_add_u32 v78, v78, 2, v67
	v_lshl_add_u32 v96, v96, 2, v67
	ds_read_b32 v78, v78
	ds_read_b32 v96, v96 offset:64
	v_xor_b32_e32 v135, 0xff, v88
	v_bfe_u32 v97, v135, 4, 4
	v_and_b32_e32 v135, 15, v135
	v_lshl_add_u32 v97, v97, 2, v67
	v_lshl_add_u32 v135, v135, 2, v67
	ds_read_b32 v97, v97
	ds_read_b32 v135, v135 offset:64
	v_xor_b32_e32 v77, 0xff, v119
	v_bfe_u32 v87, v77, 4, 4
	v_and_b32_e32 v77, 15, v77
	v_lshl_add_u32 v87, v87, 2, v67
	v_lshl_add_u32 v77, v77, 2, v67
	ds_read_b32 v87, v87
	ds_read_b32 v77, v77 offset:64
	v_xor_b32_e32 v85, 0xff, v80
	v_bfe_u32 v99, v85, 4, 4
	v_and_b32_e32 v85, 15, v85
	v_lshl_add_u32 v99, v99, 2, v67
	v_lshl_add_u32 v85, v85, 2, v67
	ds_read_b32 v99, v99
	ds_read_b32 v85, v85 offset:64
	v_xor_b32_e32 v70, 0xff, v103
	v_bfe_u32 v86, v70, 4, 4
	v_and_b32_e32 v70, 15, v70
	v_lshl_add_u32 v86, v86, 2, v67
	v_lshl_add_u32 v70, v70, 2, v67
	ds_read_b32 v86, v86
	ds_read_b32 v70, v70 offset:64
	v_xor_b32_e32 v102, 0xff, v116
	v_bfe_u32 v81, v102, 4, 4
	v_and_b32_e32 v102, 15, v102
	v_lshl_add_u32 v81, v81, 2, v67
	v_lshl_add_u32 v102, v102, 2, v67
	ds_read_b32 v81, v81
	ds_read_b32 v102, v102 offset:64
	v_xor_b32_e32 v75, 0xff, v89
	v_bfe_u32 v82, v75, 4, 4
	v_and_b32_e32 v75, 15, v75
	v_lshl_add_u32 v82, v82, 2, v67
	v_lshl_add_u32 v75, v75, 2, v67
	ds_read_b32 v82, v82
	ds_read_b32 v75, v75 offset:64
	v_xor_b32_e32 v136, 0xff, v114
	v_bfe_u32 v137, v136, 4, 4
	v_and_b32_e32 v136, 15, v136
	v_lshl_add_u32 v137, v137, 2, v67
	v_lshl_add_u32 v136, v136, 2, v67
	ds_read_b32 v137, v137
	ds_read_b32 v136, v136 offset:64
	s_waitcnt lgkmcnt(0)
	v_lshl_add_u32 v138, v93, 7, v117
	v_mul_f32_e32 v139, v132, v108
	v_lshl_add_u32 v140, v79, 7, v107
	v_mul_f32_e32 v141, v131, v108
	ds_write_b128 v68, v[138:141] offset:0
	v_lshl_add_u32 v138, v105, 7, v92
	v_mul_f32_e32 v139, v130, v108
	v_lshl_add_u32 v140, v84, 7, v100
	v_mul_f32_e32 v141, v129, v108
	ds_write_b128 v68, v[138:141] offset:16
	v_lshl_add_u32 v138, v111, 7, v74
	v_mul_f32_e32 v139, v128, v108
	v_lshl_add_u32 v140, v115, 7, v98
	v_mul_f32_e32 v141, v127, v108
	ds_write_b128 v68, v[138:141] offset:32
	v_lshl_add_u32 v138, v110, 7, v95
	v_mul_f32_e32 v139, v126, v108
	v_lshl_add_u32 v140, v94, 7, v104
	v_mul_f32_e32 v141, v125, v108
	ds_write_b128 v68, v[138:141] offset:48
	v_lshl_add_u32 v138, v78, 7, v96
	v_mul_f32_e32 v139, v124, v108
	v_lshl_add_u32 v140, v97, 7, v135
	v_mul_f32_e32 v141, v123, v108
	ds_write_b128 v68, v[138:141] offset:64
	v_lshl_add_u32 v138, v87, 7, v77
	v_mul_f32_e32 v139, v122, v108
	v_lshl_add_u32 v140, v99, 7, v85
	v_mul_f32_e32 v141, v121, v108
	ds_write_b128 v68, v[138:141] offset:80
	v_lshl_add_u32 v138, v86, 7, v70
	v_mul_f32_e32 v139, v120, v108
	v_lshl_add_u32 v140, v81, 7, v102
	v_mul_f32_e32 v141, v106, v108
	ds_write_b128 v68, v[138:141] offset:96
	v_lshl_add_u32 v138, v82, 7, v75
	v_mul_f32_e32 v139, v118, v108
	v_lshl_add_u32 v140, v137, 7, v136
	v_mul_f32_e32 v141, v109, v108
	ds_write_b128 v68, v[138:141] offset:112

; __device__ __forceinline__ unsigned pk2(float lo, float hi) { const f32x2 v = {lo, hi}; const bf16x2_t b = __builtin_convertvector(v, bf16x2_t); return __builtin_bit_cast(unsigned, b); }
; __device__ __forceinline__ float bflo(unsigned u) { return __uint_as_float(u << 16); }
; __device__ __forceinline__ float bfhi(unsigned u) { return __uint_as_float(u & 0xffff0000u); }
; __device__ __forceinline__ void peer_tile(const Args& A, LAS unsigned char* lds, int tile) {
;     ...
;     const unsigned char* T8v = T8 + (size_t)16384 * 1024;
;     const bf16_t* A3 = (const bf16_t*)(A.ws + WS_A3); const float* RSq = (const float*)(A.ws + WS_RS);
;     for (int pass = 0; pass < 2; ++pass) {
;         const int tb = 8 * w + 4 * pass;
;         u32x4 xpa[4], xpb[4]; f32x2 oacc[4][8];
; #pragma unroll
;         for (int tk = 0; tk < 4; ++tk) { const size_t m = (size_t)tile * 64 + tb + tk;
;             { const u32x4 ra = *(const u32x4*)(A3 + m * 1024 + 16 * lane), rb = *(const u32x4*)(A3 + m * 1024 + 16 * lane + 8);
;               float xr_; { const f32x4 p0 = *(const f32x4*)(RSq + m * 16), p1 = *(const f32x4*)(RSq + m * 16 + 4), p2 = *(const f32x4*)(RSq + m * 16 + 8), p3 = *(const f32x4*)(RSq + m * 16 + 12);
;                 const f32x4 ps = (p0 + p1) + (p2 + p3); xr_ = rsqrtf(((ps[0] + ps[1]) + (ps[2] + ps[3])) * (1.f / 1024.f) + 1e-6f); }
;               const unsigned rr[8] = {ra.x, ra.y, ra.z, ra.w, rb.x, rb.y, rb.z, rb.w}; unsigned hh[8];
;               const float* sp = MOD + (int)(m >> 11) * 6144 + 3072 + 16 * lane;
; #pragma unroll
;               for (int q = 0; q < 8; ++q) { const f32x2 sh = *(const f32x2*)(sp + 2 * q); hh[q] = pk2(bflo(rr[q]) * xr_ + sh[0], bfhi(rr[q]) * xr_ + sh[1]); }
;               xpa[tk] = (u32x4){hh[0], hh[1], hh[2], hh[3]}; xpb[tk] = (u32x4){hh[4], hh[5], hh[6], hh[7]}; }
	s_mov_b64 exec, -1
	v_and_b32_e32 v240, 63, v214
	v_lshrrev_b32_e32 v242, 6, v214
	v_lshlrev_b32_e32 v240, 4, v240
	v_readfirstlane_b32 s16, v242
	v_lshlrev_b32_e32 v245, 1, v240
	v_lshlrev_b32_e32 v246, 2, v240
	v_lshrrev_b32_e32 v247, 4, v240
	v_and_b32_e32 v247, 48, v247
	v_mov_b32_e32 v244, 0
	v_mov_b32_e32 v243, 0x358637bd
	v_mov_b32_e32 v242, 0xbf3a00e3
	s_add_u32 s4, s50, 0x1000000
	s_addc_u32 s5, s51, 0
	s_add_u32 s6, s50, 0x2000000
	s_addc_u32 s7, s51, 0
	s_add_u32 s8, s50, 0x3000000
	s_addc_u32 s9, s51, 0
	s_add_u32 s52, s50, 0x3010000
	s_addc_u32 s53, s51, 0
	s_add_u32 s12, s50, 0xb000000
	s_addc_u32 s13, s51, 0
	s_add_u32 s14, s50, 0xd000000
	s_addc_u32 s15, s51, 0
	s_lshr_b32 s0, s2, 5
	s_mul_i32 s0, s0, 0x6000
	s_add_u32 s10, s50, s0
	s_addc_u32 s11, s51, 0
	s_add_u32 s80, s10, 0x4000
	s_addc_u32 s81, s11, 0
	s_add_u32 s82, s10, 0x6000
	s_addc_u32 s83, s11, 0
	s_mul_i32 s22, s16, 9920
	s_cmp_eq_u32 s16, 7
	s_cselect_b32 s22, 0x21000, s22
	s_mov_b32 s85, 0xffffffff
	s_mov_b32 s72, 0x3e6d3388
	s_mov_b32 s56, s4
	s_and_b32 s57, s5, 0xffff
	s_or_b32 s57, s57, 0x04000000
	s_mov_b32 s58, 16384
	s_mov_b32 s59, 0x00027000
	s_mov_b32 s60, s6
	s_and_b32 s61, s7, 0xffff
	s_or_b32 s61, s61, 0x04000000
	s_mov_b32 s62, 16384
	s_mov_b32 s63, 0x00027000
	s_lshl_b32 s76, s16, 3
	s_lshl_b32 s0, s2, 6
	s_add_i32 s77, s0, s76
	global_load_dwordx4 v[192:195], v246, s[80:81] offset:0
	global_load_dwordx4 v[196:199], v246, s[80:81] offset:16
	global_load_dwordx4 v[200:203], v246, s[80:81] offset:32
	global_load_dwordx4 v[204:207], v246, s[80:81] offset:48
	s_add_i32 s0, s77, 0
	s_lshl_b32 s1, s0, 11
	s_add_u32 s78, s12, s1
	s_addc_u32 s79, s13, 0
	global_load_dwordx4 v[128:131], v245, s[78:79]
	global_load_dwordx4 v[132:135], v245, s[78:79] offset:16
	global_load_dwordx4 v[136:139], v245, s[78:79] offset:2048
	global_load_dwordx4 v[140:143], v245, s[78:79] offset:2064
	s_lshl_b32 s1, s0, 6
	s_add_u32 s78, s14, s1
	s_addc_u32 s79, s15, 0
	global_load_dwordx4 v[144:147], v244, s[78:79] offset:0
	global_load_dwordx4 v[148:151], v244, s[78:79] offset:16
	global_load_dwordx4 v[152:155], v244, s[78:79] offset:32
	global_load_dwordx4 v[156:159], v244, s[78:79] offset:48
	global_load_dwordx4 v[160:163], v244, s[78:79] offset:64
	global_load_dwordx4 v[164:167], v244, s[78:79] offset:80
	global_load_dwordx4 v[168:171], v244, s[78:79] offset:96
	global_load_dwordx4 v[172:175], v244, s[78:79] offset:112
	s_waitcnt lgkmcnt(0)
	s_barrier
	s_add_i32 s0, s77, 2
	s_lshl_b32 s1, s0, 11
	s_add_u32 s78, s12, s1
	s_addc_u32 s79, s13, 0
	global_load_dwordx4 v[176:179], v245, s[78:79]
	global_load_dwordx4 v[180:183], v245, s[78:79] offset:16
	global_load_dwordx4 v[184:187], v245, s[78:79] offset:2048
	global_load_dwordx4 v[188:191], v245, s[78:79] offset:2064
	s_lshl_b32 s1, s0, 6
	s_add_u32 s78, s14, s1
	s_addc_u32 s79, s15, 0
	global_load_dwordx4 v[216:219], v244, s[78:79] offset:0
	global_load_dwordx4 v[220:223], v244, s[78:79] offset:16
	global_load_dwordx4 v[224:227], v244, s[78:79] offset:32
	global_load_dwordx4 v[228:231], v244, s[78:79] offset:48
	global_load_dwordx4 v[232:235], v244, s[78:79] offset:64
	global_load_dwordx4 v[236:239], v244, s[78:79] offset:80
	global_load_dwordx4 v[248:251], v244, s[78:79] offset:96
	global_load_dwordx4 v[252:255], v244, s[78:79] offset:112
	s_waitcnt vmcnt(12)
	v_pk_add_f32 v[144:145], v[144:145], v[148:149]
	v_pk_add_f32 v[146:147], v[146:147], v[150:151]
	v_pk_add_f32 v[152:153], v[152:153], v[156:157]
	v_pk_add_f32 v[154:155], v[154:155], v[158:159]
	v_pk_add_f32 v[144:145], v[144:145], v[152:153]
	v_pk_add_f32 v[146:147], v[146:147], v[154:155]
	v_add_f32_e32 v144, v144, v145
	v_add_f32_e32 v146, v146, v147
	v_add_f32_e32 v144, v144, v146
	v_fmamk_f32 v144, v144, 0x3a800000, v243
	v_rsq_f32_e32 v144, v144
	v_pk_add_f32 v[160:161], v[160:161], v[164:165]
	v_pk_add_f32 v[162:163], v[162:163], v[166:167]
	v_pk_add_f32 v[168:169], v[168:169], v[172:173]
	v_pk_add_f32 v[170:171], v[170:171], v[174:175]
	v_pk_add_f32 v[160:161], v[160:161], v[168:169]
	v_pk_add_f32 v[162:163], v[162:163], v[170:171]
	v_add_f32_e32 v160, v160, v161
	v_add_f32_e32 v162, v162, v163
	v_add_f32_e32 v160, v160, v162
	v_fmamk_f32 v160, v160, 0x3a800000, v243
	v_rsq_f32_e32 v160, v160
	v_lshlrev_b32_e32 v208, 16, v128
	v_and_b32_e32 v209, 0xffff0000, v128
	v_fma_f32 v208, v208, v144, v192
	v_fma_f32 v209, v209, v144, v193
	v_cvt_pk_bf16_f32 v210, v208, v209
	v_lshlrev_b32_e32 v0, 16, v210
	v_and_b32_e32 v1, 0xffff0000, v210
	v_lshlrev_b32_e32 v208, 16, v129
	v_and_b32_e32 v209, 0xffff0000, v129
	v_fma_f32 v208, v208, v144, v194
	v_fma_f32 v209, v209, v144, v195
	v_cvt_pk_bf16_f32 v210, v208, v209
	v_lshlrev_b32_e32 v2, 16, v210
	v_and_b32_e32 v3, 0xffff0000, v210
	v_lshlrev_b32_e32 v208, 16, v130
	v_and_b32_e32 v209, 0xffff0000, v130
	v_fma_f32 v208, v208, v144, v196
	v_fma_f32 v209, v209, v144, v197
	v_cvt_pk_bf16_f32 v210, v208, v209
	v_lshlrev_b32_e32 v4, 16, v210
	v_and_b32_e32 v5, 0xffff0000, v210
	v_lshlrev_b32_e32 v208, 16, v131
	v_and_b32_e32 v209, 0xffff0000, v131
	v_fma_f32 v208, v208, v144, v198
	v_fma_f32 v209, v209, v144, v199
	v_cvt_pk_bf16_f32 v210, v208, v209
	v_lshlrev_b32_e32 v6, 16, v210
	v_and_b32_e32 v7, 0xffff0000, v210
	v_lshlrev_b32_e32 v208, 16, v132
	v_and_b32_e32 v209, 0xffff0000, v132
	v_fma_f32 v208, v208, v144, v200
	v_fma_f32 v209, v209, v144, v201
	v_cvt_pk_bf16_f32 v210, v208, v209
	v_lshlrev_b32_e32 v8, 16, v210
	v_and_b32_e32 v9, 0xffff0000, v210
	v_lshlrev_b32_e32 v208, 16, v133
	v_and_b32_e32 v209, 0xffff0000, v133
	v_fma_f32 v208, v208, v144, v202
	v_fma_f32 v209, v209, v144, v203
	v_cvt_pk_bf16_f32 v210, v208, v209
; __device__ __forceinline__ unsigned pk2(float lo, float hi) { const f32x2 v = {lo, hi}; const bf16x2_t b = __builtin_convertvector(v, bf16x2_t); return __builtin_bit_cast(unsigned, b); }
; __device__ __forceinline__ float bflo(unsigned u) { return __uint_as_float(u << 16); }
; __device__ __forceinline__ float bfhi(unsigned u) { return __uint_as_float(u & 0xffff0000u); }
; __device__ __forceinline__ void peer_tile(const Args& A, LAS unsigned char* lds, int tile) {
;     ...
;         for (int tk = 0; tk < 4; ++tk) { const size_t m = (size_t)tile * 64 + tb + tk;
;             { const u32x4 ra = *(const u32x4*)(A3 + m * 1024 + 16 * lane), rb = *(const u32x4*)(A3 + m * 1024 + 16 * lane + 8);
;               float xr_; { const f32x4 p0 = *(const f32x4*)(RSq + m * 16), p1 = *(const f32x4*)(RSq + m * 16 + 4), p2 = *(const f32x4*)(RSq + m * 16 + 8), p3 = *(const f32x4*)(RSq + m * 16 + 12);
;                 const f32x4 ps = (p0 + p1) + (p2 + p3); xr_ = rsqrtf(((ps[0] + ps[1]) + (ps[2] + ps[3])) * (1.f / 1024.f) + 1e-6f); }
;               const unsigned rr[8] = {ra.x, ra.y, ra.z, ra.w, rb.x, rb.y, rb.z, rb.w}; unsigned hh[8];
;               const float* sp = MOD + (int)(m >> 11) * 6144 + 3072 + 16 * lane;
; #pragma unroll
;               for (int q = 0; q < 8; ++q) { const f32x2 sh = *(const f32x2*)(sp + 2 * q); hh[q] = pk2(bflo(rr[q]) * xr_ + sh[0], bfhi(rr[q]) * xr_ + sh[1]); }
;               xpa[tk] = (u32x4){hh[0], hh[1], hh[2], hh[3]}; xpb[tk] = (u32x4){hh[4], hh[5], hh[6], hh[7]}; }
;     ...
;                 { const unsigned xx[8] = {xpa[tk].x, xpa[tk].y, xpa[tk].z, xpa[tk].w, xpb[tk].x, xpb[tk].y, xpb[tk].z, xpb[tk].w};
; #pragma unroll
;                   for (int q = 0; q < 8; ++q) xf[q] = (f32x2){bflo(xx[q]), bfhi(xx[q])}; }
	v_lshlrev_b32_e32 v10, 16, v210
	v_and_b32_e32 v11, 0xffff0000, v210
	v_lshlrev_b32_e32 v208, 16, v134
	v_and_b32_e32 v209, 0xffff0000, v134
	v_fma_f32 v208, v208, v144, v204
	v_fma_f32 v209, v209, v144, v205
	v_cvt_pk_bf16_f32 v210, v208, v209
	v_lshlrev_b32_e32 v12, 16, v210
	v_and_b32_e32 v13, 0xffff0000, v210
	v_lshlrev_b32_e32 v208, 16, v135
	v_and_b32_e32 v209, 0xffff0000, v135
	v_fma_f32 v208, v208, v144, v206
	v_fma_f32 v209, v209, v144, v207
	v_cvt_pk_bf16_f32 v210, v208, v209
	v_lshlrev_b32_e32 v14, 16, v210
	v_and_b32_e32 v15, 0xffff0000, v210
	v_lshlrev_b32_e32 v208, 16, v136
	v_and_b32_e32 v209, 0xffff0000, v136
	v_fma_f32 v208, v208, v160, v192
	v_fma_f32 v209, v209, v160, v193
	v_cvt_pk_bf16_f32 v210, v208, v209
	v_lshlrev_b32_e32 v16, 16, v210
	v_and_b32_e32 v17, 0xffff0000, v210
	v_lshlrev_b32_e32 v208, 16, v137
	v_and_b32_e32 v209, 0xffff0000, v137
	v_fma_f32 v208, v208, v160, v194
	v_fma_f32 v209, v209, v160, v195
	v_cvt_pk_bf16_f32 v210, v208, v209
	v_lshlrev_b32_e32 v18, 16, v210
	v_and_b32_e32 v19, 0xffff0000, v210
	v_lshlrev_b32_e32 v208, 16, v138
	v_and_b32_e32 v209, 0xffff0000, v138
	v_fma_f32 v208, v208, v160, v196
	v_fma_f32 v209, v209, v160, v197
	v_cvt_pk_bf16_f32 v210, v208, v209
	v_lshlrev_b32_e32 v20, 16, v210
	v_and_b32_e32 v21, 0xffff0000, v210
	v_lshlrev_b32_e32 v208, 16, v139
	v_and_b32_e32 v209, 0xffff0000, v139
	v_fma_f32 v208, v208, v160, v198
	v_fma_f32 v209, v209, v160, v199
	v_cvt_pk_bf16_f32 v210, v208, v209
	v_lshlrev_b32_e32 v22, 16, v210
	v_and_b32_e32 v23, 0xffff0000, v210
	v_lshlrev_b32_e32 v208, 16, v140
	v_and_b32_e32 v209, 0xffff0000, v140
	v_fma_f32 v208, v208, v160, v200
	v_fma_f32 v209, v209, v160, v201
	v_cvt_pk_bf16_f32 v210, v208, v209
	v_lshlrev_b32_e32 v24, 16, v210
	v_and_b32_e32 v25, 0xffff0000, v210
	v_lshlrev_b32_e32 v208, 16, v141
	v_and_b32_e32 v209, 0xffff0000, v141
	v_fma_f32 v208, v208, v160, v202
	v_fma_f32 v209, v209, v160, v203
	v_cvt_pk_bf16_f32 v210, v208, v209
	v_lshlrev_b32_e32 v26, 16, v210
	v_and_b32_e32 v27, 0xffff0000, v210
	v_lshlrev_b32_e32 v208, 16, v142
	v_and_b32_e32 v209, 0xffff0000, v142
	v_fma_f32 v208, v208, v160, v204
	v_fma_f32 v209, v209, v160, v205
	v_cvt_pk_bf16_f32 v210, v208, v209
	v_lshlrev_b32_e32 v28, 16, v210
	v_and_b32_e32 v29, 0xffff0000, v210
	v_lshlrev_b32_e32 v208, 16, v143
	v_and_b32_e32 v209, 0xffff0000, v143
	v_fma_f32 v208, v208, v160, v206
	v_fma_f32 v209, v209, v160, v207
	v_cvt_pk_bf16_f32 v210, v208, v209
	v_lshlrev_b32_e32 v30, 16, v210
	v_and_b32_e32 v31, 0xffff0000, v210
	s_nop 0
	s_add_i32 s0, s77, 4
	s_lshl_b32 s1, s0, 11
	s_add_u32 s78, s12, s1
	s_addc_u32 s79, s13, 0
	global_load_dwordx4 v[128:131], v245, s[78:79]
	global_load_dwordx4 v[132:135], v245, s[78:79] offset:16
	global_load_dwordx4 v[136:139], v245, s[78:79] offset:2048
	global_load_dwordx4 v[140:143], v245, s[78:79] offset:2064
	s_lshl_b32 s1, s0, 6
	s_add_u32 s78, s14, s1
	s_addc_u32 s79, s15, 0
	global_load_dwordx4 v[144:147], v244, s[78:79] offset:0
	global_load_dwordx4 v[148:151], v244, s[78:79] offset:16
	global_load_dwordx4 v[152:155], v244, s[78:79] offset:32
	global_load_dwordx4 v[156:159], v244, s[78:79] offset:48
	global_load_dwordx4 v[160:163], v244, s[78:79] offset:64
	global_load_dwordx4 v[164:167], v244, s[78:79] offset:80
	global_load_dwordx4 v[168:171], v244, s[78:79] offset:96
	global_load_dwordx4 v[172:175], v244, s[78:79] offset:112
	s_waitcnt vmcnt(12)
	v_pk_add_f32 v[216:217], v[216:217], v[220:221]
	v_pk_add_f32 v[218:219], v[218:219], v[222:223]
	v_pk_add_f32 v[224:225], v[224:225], v[228:229]
	v_pk_add_f32 v[226:227], v[226:227], v[230:231]
	v_pk_add_f32 v[216:217], v[216:217], v[224:225]
	v_pk_add_f32 v[218:219], v[218:219], v[226:227]
	v_add_f32_e32 v216, v216, v217
	v_add_f32_e32 v218, v218, v219
	v_add_f32_e32 v216, v216, v218
	v_fmamk_f32 v216, v216, 0x3a800000, v243
	v_rsq_f32_e32 v216, v216
	v_pk_add_f32 v[232:233], v[232:233], v[236:237]
	v_pk_add_f32 v[234:235], v[234:235], v[238:239]
	v_pk_add_f32 v[248:249], v[248:249], v[252:253]
	v_pk_add_f32 v[250:251], v[250:251], v[254:255]
	v_pk_add_f32 v[232:233], v[232:233], v[248:249]
	v_pk_add_f32 v[234:235], v[234:235], v[250:251]
	v_add_f32_e32 v232, v232, v233
	v_add_f32_e32 v234, v234, v235
	v_add_f32_e32 v232, v232, v234
	v_fmamk_f32 v232, v232, 0x3a800000, v243
	v_rsq_f32_e32 v232, v232
	v_lshlrev_b32_e32 v208, 16, v176
	v_and_b32_e32 v209, 0xffff0000, v176
	v_fma_f32 v208, v208, v216, v192
	v_fma_f32 v209, v209, v216, v193
	v_cvt_pk_bf16_f32 v210, v208, v209
	v_lshlrev_b32_e32 v32, 16, v210
	v_and_b32_e32 v33, 0xffff0000, v210
	v_lshlrev_b32_e32 v208, 16, v177
	v_and_b32_e32 v209, 0xffff0000, v177
	v_fma_f32 v208, v208, v216, v194
	v_fma_f32 v209, v209, v216, v195
	v_cvt_pk_bf16_f32 v210, v208, v209
	v_lshlrev_b32_e32 v34, 16, v210
	v_and_b32_e32 v35, 0xffff0000, v210
	v_lshlrev_b32_e32 v208, 16, v178
	v_and_b32_e32 v209, 0xffff0000, v178
	v_fma_f32 v208, v208, v216, v196
	v_fma_f32 v209, v209, v216, v197
	v_cvt_pk_bf16_f32 v210, v208, v209
	v_lshlrev_b32_e32 v36, 16, v210
	v_and_b32_e32 v37, 0xffff0000, v210
	v_lshlrev_b32_e32 v208, 16, v179
	v_and_b32_e32 v209, 0xffff0000, v179
	v_fma_f32 v208, v208, v216, v198
	v_fma_f32 v209, v209, v216, v199
	v_cvt_pk_bf16_f32 v210, v208, v209
	v_lshlrev_b32_e32 v38, 16, v210
	v_and_b32_e32 v39, 0xffff0000, v210
	v_lshlrev_b32_e32 v208, 16, v180
	v_and_b32_e32 v209, 0xffff0000, v180
	v_fma_f32 v208, v208, v216, v200
	v_fma_f32 v209, v209, v216, v201
	v_cvt_pk_bf16_f32 v210, v208, v209
	v_lshlrev_b32_e32 v40, 16, v210
	v_and_b32_e32 v41, 0xffff0000, v210
	v_lshlrev_b32_e32 v208, 16, v181
	v_and_b32_e32 v209, 0xffff0000, v181
; __device__ __forceinline__ unsigned pk2(float lo, float hi) { const f32x2 v = {lo, hi}; const bf16x2_t b = __builtin_convertvector(v, bf16x2_t); return __builtin_bit_cast(unsigned, b); }
; __device__ __forceinline__ float bflo(unsigned u) { return __uint_as_float(u << 16); }
; __device__ __forceinline__ float bfhi(unsigned u) { return __uint_as_float(u & 0xffff0000u); }
; __device__ __forceinline__ void peer_tile(const Args& A, LAS unsigned char* lds, int tile) {
;     ...
;         for (int tk = 0; tk < 4; ++tk) { const size_t m = (size_t)tile * 64 + tb + tk;
;             { const u32x4 ra = *(const u32x4*)(A3 + m * 1024 + 16 * lane), rb = *(const u32x4*)(A3 + m * 1024 + 16 * lane + 8);
;               float xr_; { const f32x4 p0 = *(const f32x4*)(RSq + m * 16), p1 = *(const f32x4*)(RSq + m * 16 + 4), p2 = *(const f32x4*)(RSq + m * 16 + 8), p3 = *(const f32x4*)(RSq + m * 16 + 12);
;                 const f32x4 ps = (p0 + p1) + (p2 + p3); xr_ = rsqrtf(((ps[0] + ps[1]) + (ps[2] + ps[3])) * (1.f / 1024.f) + 1e-6f); }
;               const unsigned rr[8] = {ra.x, ra.y, ra.z, ra.w, rb.x, rb.y, rb.z, rb.w}; unsigned hh[8];
;               const float* sp = MOD + (int)(m >> 11) * 6144 + 3072 + 16 * lane;
; #pragma unroll
;               for (int q = 0; q < 8; ++q) { const f32x2 sh = *(const f32x2*)(sp + 2 * q); hh[q] = pk2(bflo(rr[q]) * xr_ + sh[0], bfhi(rr[q]) * xr_ + sh[1]); }
;               xpa[tk] = (u32x4){hh[0], hh[1], hh[2], hh[3]}; xpb[tk] = (u32x4){hh[4], hh[5], hh[6], hh[7]}; }
;     ...
;                 { const unsigned xx[8] = {xpa[tk].x, xpa[tk].y, xpa[tk].z, xpa[tk].w, xpb[tk].x, xpb[tk].y, xpb[tk].z, xpb[tk].w};
; #pragma unroll
;                   for (int q = 0; q < 8; ++q) xf[q] = (f32x2){bflo(xx[q]), bfhi(xx[q])}; }
	v_fma_f32 v208, v208, v216, v202
	v_fma_f32 v209, v209, v216, v203
	v_cvt_pk_bf16_f32 v210, v208, v209
	v_lshlrev_b32_e32 v42, 16, v210
	v_and_b32_e32 v43, 0xffff0000, v210
	v_lshlrev_b32_e32 v208, 16, v182
	v_and_b32_e32 v209, 0xffff0000, v182
	v_fma_f32 v208, v208, v216, v204
	v_fma_f32 v209, v209, v216, v205
	v_cvt_pk_bf16_f32 v210, v208, v209
	v_lshlrev_b32_e32 v44, 16, v210
	v_and_b32_e32 v45, 0xffff0000, v210
	v_lshlrev_b32_e32 v208, 16, v183
	v_and_b32_e32 v209, 0xffff0000, v183
	v_fma_f32 v208, v208, v216, v206
	v_fma_f32 v209, v209, v216, v207
	v_cvt_pk_bf16_f32 v210, v208, v209
	v_lshlrev_b32_e32 v46, 16, v210
	v_and_b32_e32 v47, 0xffff0000, v210
	v_lshlrev_b32_e32 v208, 16, v184
	v_and_b32_e32 v209, 0xffff0000, v184
	v_fma_f32 v208, v208, v232, v192
	v_fma_f32 v209, v209, v232, v193
	v_cvt_pk_bf16_f32 v210, v208, v209
	v_lshlrev_b32_e32 v48, 16, v210
	v_and_b32_e32 v49, 0xffff0000, v210
	v_lshlrev_b32_e32 v208, 16, v185
	v_and_b32_e32 v209, 0xffff0000, v185
	v_fma_f32 v208, v208, v232, v194
	v_fma_f32 v209, v209, v232, v195
	v_cvt_pk_bf16_f32 v210, v208, v209
	v_lshlrev_b32_e32 v50, 16, v210
	v_and_b32_e32 v51, 0xffff0000, v210
	v_lshlrev_b32_e32 v208, 16, v186
	v_and_b32_e32 v209, 0xffff0000, v186
	v_fma_f32 v208, v208, v232, v196
	v_fma_f32 v209, v209, v232, v197
	v_cvt_pk_bf16_f32 v210, v208, v209
	v_lshlrev_b32_e32 v52, 16, v210
	v_and_b32_e32 v53, 0xffff0000, v210
	v_lshlrev_b32_e32 v208, 16, v187
	v_and_b32_e32 v209, 0xffff0000, v187
	v_fma_f32 v208, v208, v232, v198
	v_fma_f32 v209, v209, v232, v199
	v_cvt_pk_bf16_f32 v210, v208, v209
	v_lshlrev_b32_e32 v54, 16, v210
	v_and_b32_e32 v55, 0xffff0000, v210
	v_lshlrev_b32_e32 v208, 16, v188
	v_and_b32_e32 v209, 0xffff0000, v188
	v_fma_f32 v208, v208, v232, v200
	v_fma_f32 v209, v209, v232, v201
	v_cvt_pk_bf16_f32 v210, v208, v209
	v_lshlrev_b32_e32 v56, 16, v210
	v_and_b32_e32 v57, 0xffff0000, v210
	v_lshlrev_b32_e32 v208, 16, v189
	v_and_b32_e32 v209, 0xffff0000, v189
	v_fma_f32 v208, v208, v232, v202
	v_fma_f32 v209, v209, v232, v203
	v_cvt_pk_bf16_f32 v210, v208, v209
	v_lshlrev_b32_e32 v58, 16, v210
	v_and_b32_e32 v59, 0xffff0000, v210
	v_lshlrev_b32_e32 v208, 16, v190
	v_and_b32_e32 v209, 0xffff0000, v190
	v_fma_f32 v208, v208, v232, v204
	v_fma_f32 v209, v209, v232, v205
	v_cvt_pk_bf16_f32 v210, v208, v209
	v_lshlrev_b32_e32 v60, 16, v210
	v_and_b32_e32 v61, 0xffff0000, v210
	v_lshlrev_b32_e32 v208, 16, v191
	v_and_b32_e32 v209, 0xffff0000, v191
	v_fma_f32 v208, v208, v232, v206
	v_fma_f32 v209, v209, v232, v207
	v_cvt_pk_bf16_f32 v210, v208, v209
	v_lshlrev_b32_e32 v62, 16, v210
	v_and_b32_e32 v63, 0xffff0000, v210
	s_nop 0
	s_add_i32 s0, s77, 6
	s_lshl_b32 s1, s0, 11
	s_add_u32 s78, s12, s1
	s_addc_u32 s79, s13, 0
	global_load_dwordx4 v[176:179], v245, s[78:79]
	global_load_dwordx4 v[180:183], v245, s[78:79] offset:16
	global_load_dwordx4 v[184:187], v245, s[78:79] offset:2048
	global_load_dwordx4 v[188:191], v245, s[78:79] offset:2064
	s_lshl_b32 s1, s0, 6
	s_add_u32 s78, s14, s1
	s_addc_u32 s79, s15, 0
	global_load_dwordx4 v[216:219], v244, s[78:79] offset:0
	global_load_dwordx4 v[220:223], v244, s[78:79] offset:16
	global_load_dwordx4 v[224:227], v244, s[78:79] offset:32
	global_load_dwordx4 v[228:231], v244, s[78:79] offset:48
	global_load_dwordx4 v[232:235], v244, s[78:79] offset:64
	global_load_dwordx4 v[236:239], v244, s[78:79] offset:80
	global_load_dwordx4 v[248:251], v244, s[78:79] offset:96
	global_load_dwordx4 v[252:255], v244, s[78:79] offset:112
	s_waitcnt vmcnt(12)
	v_pk_add_f32 v[144:145], v[144:145], v[148:149]
	v_pk_add_f32 v[146:147], v[146:147], v[150:151]
	v_pk_add_f32 v[152:153], v[152:153], v[156:157]
	v_pk_add_f32 v[154:155], v[154:155], v[158:159]
	v_pk_add_f32 v[144:145], v[144:145], v[152:153]
	v_pk_add_f32 v[146:147], v[146:147], v[154:155]
	v_add_f32_e32 v144, v144, v145
	v_add_f32_e32 v146, v146, v147
	v_add_f32_e32 v144, v144, v146
	v_fmamk_f32 v144, v144, 0x3a800000, v243
	v_rsq_f32_e32 v144, v144
	v_pk_add_f32 v[160:161], v[160:161], v[164:165]
	v_pk_add_f32 v[162:163], v[162:163], v[166:167]
	v_pk_add_f32 v[168:169], v[168:169], v[172:173]
	v_pk_add_f32 v[170:171], v[170:171], v[174:175]
	v_pk_add_f32 v[160:161], v[160:161], v[168:169]
	v_pk_add_f32 v[162:163], v[162:163], v[170:171]
	v_add_f32_e32 v160, v160, v161
	v_add_f32_e32 v162, v162, v163
	v_add_f32_e32 v160, v160, v162
	v_fmamk_f32 v160, v160, 0x3a800000, v243
	v_rsq_f32_e32 v160, v160
	v_lshlrev_b32_e32 v208, 16, v128
	v_and_b32_e32 v209, 0xffff0000, v128
	v_fma_f32 v208, v208, v144, v192
	v_fma_f32 v209, v209, v144, v193
	v_cvt_pk_bf16_f32 v210, v208, v209
	v_lshlrev_b32_e32 v64, 16, v210
	v_and_b32_e32 v65, 0xffff0000, v210
	v_lshlrev_b32_e32 v208, 16, v129
	v_and_b32_e32 v209, 0xffff0000, v129
	v_fma_f32 v208, v208, v144, v194
	v_fma_f32 v209, v209, v144, v195
	v_cvt_pk_bf16_f32 v210, v208, v209
	v_lshlrev_b32_e32 v66, 16, v210
	v_and_b32_e32 v67, 0xffff0000, v210
	v_lshlrev_b32_e32 v208, 16, v130
	v_and_b32_e32 v209, 0xffff0000, v130
	v_fma_f32 v208, v208, v144, v196
	v_fma_f32 v209, v209, v144, v197
	v_cvt_pk_bf16_f32 v210, v208, v209
	v_lshlrev_b32_e32 v68, 16, v210
	v_and_b32_e32 v69, 0xffff0000, v210
	v_lshlrev_b32_e32 v208, 16, v131
	v_and_b32_e32 v209, 0xffff0000, v131
	v_fma_f32 v208, v208, v144, v198
	v_fma_f32 v209, v209, v144, v199
	v_cvt_pk_bf16_f32 v210, v208, v209
	v_lshlrev_b32_e32 v70, 16, v210
	v_and_b32_e32 v71, 0xffff0000, v210
	v_lshlrev_b32_e32 v208, 16, v132
	v_and_b32_e32 v209, 0xffff0000, v132
	v_fma_f32 v208, v208, v144, v200
	v_fma_f32 v209, v209, v144, v201
	v_cvt_pk_bf16_f32 v210, v208, v209
	v_lshlrev_b32_e32 v72, 16, v210
; __device__ __forceinline__ unsigned pk2(float lo, float hi) { const f32x2 v = {lo, hi}; const bf16x2_t b = __builtin_convertvector(v, bf16x2_t); return __builtin_bit_cast(unsigned, b); }
; __device__ __forceinline__ float bflo(unsigned u) { return __uint_as_float(u << 16); }
; __device__ __forceinline__ float bfhi(unsigned u) { return __uint_as_float(u & 0xffff0000u); }
; __device__ __forceinline__ void peer_tile(const Args& A, LAS unsigned char* lds, int tile) {
;     ...
;         for (int tk = 0; tk < 4; ++tk) { const size_t m = (size_t)tile * 64 + tb + tk;
;             { const u32x4 ra = *(const u32x4*)(A3 + m * 1024 + 16 * lane), rb = *(const u32x4*)(A3 + m * 1024 + 16 * lane + 8);
;               float xr_; { const f32x4 p0 = *(const f32x4*)(RSq + m * 16), p1 = *(const f32x4*)(RSq + m * 16 + 4), p2 = *(const f32x4*)(RSq + m * 16 + 8), p3 = *(const f32x4*)(RSq + m * 16 + 12);
;                 const f32x4 ps = (p0 + p1) + (p2 + p3); xr_ = rsqrtf(((ps[0] + ps[1]) + (ps[2] + ps[3])) * (1.f / 1024.f) + 1e-6f); }
;               const unsigned rr[8] = {ra.x, ra.y, ra.z, ra.w, rb.x, rb.y, rb.z, rb.w}; unsigned hh[8];
;               const float* sp = MOD + (int)(m >> 11) * 6144 + 3072 + 16 * lane;
; #pragma unroll
;               for (int q = 0; q < 8; ++q) { const f32x2 sh = *(const f32x2*)(sp + 2 * q); hh[q] = pk2(bflo(rr[q]) * xr_ + sh[0], bfhi(rr[q]) * xr_ + sh[1]); }
;               xpa[tk] = (u32x4){hh[0], hh[1], hh[2], hh[3]}; xpb[tk] = (u32x4){hh[4], hh[5], hh[6], hh[7]}; }
;     ...
;                 { const unsigned xx[8] = {xpa[tk].x, xpa[tk].y, xpa[tk].z, xpa[tk].w, xpb[tk].x, xpb[tk].y, xpb[tk].z, xpb[tk].w};
; #pragma unroll
;                   for (int q = 0; q < 8; ++q) xf[q] = (f32x2){bflo(xx[q]), bfhi(xx[q])}; }
	v_and_b32_e32 v73, 0xffff0000, v210
	v_lshlrev_b32_e32 v208, 16, v133
	v_and_b32_e32 v209, 0xffff0000, v133
	v_fma_f32 v208, v208, v144, v202
	v_fma_f32 v209, v209, v144, v203
	v_cvt_pk_bf16_f32 v210, v208, v209
	v_lshlrev_b32_e32 v74, 16, v210
	v_and_b32_e32 v75, 0xffff0000, v210
	v_lshlrev_b32_e32 v208, 16, v134
	v_and_b32_e32 v209, 0xffff0000, v134
	v_fma_f32 v208, v208, v144, v204
	v_fma_f32 v209, v209, v144, v205
	v_cvt_pk_bf16_f32 v210, v208, v209
	v_lshlrev_b32_e32 v76, 16, v210
	v_and_b32_e32 v77, 0xffff0000, v210
	v_lshlrev_b32_e32 v208, 16, v135
	v_and_b32_e32 v209, 0xffff0000, v135
	v_fma_f32 v208, v208, v144, v206
	v_fma_f32 v209, v209, v144, v207
	v_cvt_pk_bf16_f32 v210, v208, v209
	v_lshlrev_b32_e32 v78, 16, v210
	v_and_b32_e32 v79, 0xffff0000, v210
	v_lshlrev_b32_e32 v208, 16, v136
	v_and_b32_e32 v209, 0xffff0000, v136
	v_fma_f32 v208, v208, v160, v192
	v_fma_f32 v209, v209, v160, v193
	v_cvt_pk_bf16_f32 v210, v208, v209
	v_lshlrev_b32_e32 v80, 16, v210
	v_and_b32_e32 v81, 0xffff0000, v210
	v_lshlrev_b32_e32 v208, 16, v137
	v_and_b32_e32 v209, 0xffff0000, v137
	v_fma_f32 v208, v208, v160, v194
	v_fma_f32 v209, v209, v160, v195
	v_cvt_pk_bf16_f32 v210, v208, v209
	v_lshlrev_b32_e32 v82, 16, v210
	v_and_b32_e32 v83, 0xffff0000, v210
	v_lshlrev_b32_e32 v208, 16, v138
	v_and_b32_e32 v209, 0xffff0000, v138
	v_fma_f32 v208, v208, v160, v196
	v_fma_f32 v209, v209, v160, v197
	v_cvt_pk_bf16_f32 v210, v208, v209
	v_lshlrev_b32_e32 v84, 16, v210
	v_and_b32_e32 v85, 0xffff0000, v210
	v_lshlrev_b32_e32 v208, 16, v139
	v_and_b32_e32 v209, 0xffff0000, v139
	v_fma_f32 v208, v208, v160, v198
	v_fma_f32 v209, v209, v160, v199
	v_cvt_pk_bf16_f32 v210, v208, v209
	v_lshlrev_b32_e32 v86, 16, v210
	v_and_b32_e32 v87, 0xffff0000, v210
	v_lshlrev_b32_e32 v208, 16, v140
	v_and_b32_e32 v209, 0xffff0000, v140
	v_fma_f32 v208, v208, v160, v200
	v_fma_f32 v209, v209, v160, v201
	v_cvt_pk_bf16_f32 v210, v208, v209
	v_lshlrev_b32_e32 v88, 16, v210
	v_and_b32_e32 v89, 0xffff0000, v210
	v_lshlrev_b32_e32 v208, 16, v141
	v_and_b32_e32 v209, 0xffff0000, v141
	v_fma_f32 v208, v208, v160, v202
	v_fma_f32 v209, v209, v160, v203
	v_cvt_pk_bf16_f32 v210, v208, v209
	v_lshlrev_b32_e32 v90, 16, v210
	v_and_b32_e32 v91, 0xffff0000, v210
	v_lshlrev_b32_e32 v208, 16, v142
	v_and_b32_e32 v209, 0xffff0000, v142
	v_fma_f32 v208, v208, v160, v204
	v_fma_f32 v209, v209, v160, v205
	v_cvt_pk_bf16_f32 v210, v208, v209
	v_lshlrev_b32_e32 v92, 16, v210
	v_and_b32_e32 v93, 0xffff0000, v210
	v_lshlrev_b32_e32 v208, 16, v143
	v_and_b32_e32 v209, 0xffff0000, v143
	v_fma_f32 v208, v208, v160, v206
	v_fma_f32 v209, v209, v160, v207
	v_cvt_pk_bf16_f32 v210, v208, v209
	v_lshlrev_b32_e32 v94, 16, v210
	v_and_b32_e32 v95, 0xffff0000, v210
	s_nop 0
	s_waitcnt vmcnt(0)
	v_pk_add_f32 v[216:217], v[216:217], v[220:221]
	v_pk_add_f32 v[218:219], v[218:219], v[222:223]
	v_pk_add_f32 v[224:225], v[224:225], v[228:229]
	v_pk_add_f32 v[226:227], v[226:227], v[230:231]
	v_pk_add_f32 v[216:217], v[216:217], v[224:225]
	v_pk_add_f32 v[218:219], v[218:219], v[226:227]
	v_add_f32_e32 v216, v216, v217
	v_add_f32_e32 v218, v218, v219
	v_add_f32_e32 v216, v216, v218
	v_fmamk_f32 v216, v216, 0x3a800000, v243
	v_rsq_f32_e32 v216, v216
	v_pk_add_f32 v[232:233], v[232:233], v[236:237]
	v_pk_add_f32 v[234:235], v[234:235], v[238:239]
	v_pk_add_f32 v[248:249], v[248:249], v[252:253]
	v_pk_add_f32 v[250:251], v[250:251], v[254:255]
	v_pk_add_f32 v[232:233], v[232:233], v[248:249]
	v_pk_add_f32 v[234:235], v[234:235], v[250:251]
	v_add_f32_e32 v232, v232, v233
	v_add_f32_e32 v234, v234, v235
	v_add_f32_e32 v232, v232, v234
	v_fmamk_f32 v232, v232, 0x3a800000, v243
	v_rsq_f32_e32 v232, v232
	v_lshlrev_b32_e32 v208, 16, v176
	v_and_b32_e32 v209, 0xffff0000, v176
	v_fma_f32 v208, v208, v216, v192
	v_fma_f32 v209, v209, v216, v193
	v_cvt_pk_bf16_f32 v210, v208, v209
	v_lshlrev_b32_e32 v96, 16, v210
	v_and_b32_e32 v97, 0xffff0000, v210
	v_lshlrev_b32_e32 v208, 16, v177
	v_and_b32_e32 v209, 0xffff0000, v177
	v_fma_f32 v208, v208, v216, v194
	v_fma_f32 v209, v209, v216, v195
	v_cvt_pk_bf16_f32 v210, v208, v209
	v_lshlrev_b32_e32 v98, 16, v210
	v_and_b32_e32 v99, 0xffff0000, v210
	v_lshlrev_b32_e32 v208, 16, v178
	v_and_b32_e32 v209, 0xffff0000, v178
	v_fma_f32 v208, v208, v216, v196
	v_fma_f32 v209, v209, v216, v197
	v_cvt_pk_bf16_f32 v210, v208, v209
	v_lshlrev_b32_e32 v100, 16, v210
	v_and_b32_e32 v101, 0xffff0000, v210
	v_lshlrev_b32_e32 v208, 16, v179
	v_and_b32_e32 v209, 0xffff0000, v179
	v_fma_f32 v208, v208, v216, v198
	v_fma_f32 v209, v209, v216, v199
	v_cvt_pk_bf16_f32 v210, v208, v209
	v_lshlrev_b32_e32 v102, 16, v210
	v_and_b32_e32 v103, 0xffff0000, v210
	v_lshlrev_b32_e32 v208, 16, v180
	v_and_b32_e32 v209, 0xffff0000, v180
	v_fma_f32 v208, v208, v216, v200
	v_fma_f32 v209, v209, v216, v201
	v_cvt_pk_bf16_f32 v210, v208, v209
	v_lshlrev_b32_e32 v104, 16, v210
	v_and_b32_e32 v105, 0xffff0000, v210
	v_lshlrev_b32_e32 v208, 16, v181
	v_and_b32_e32 v209, 0xffff0000, v181
	v_fma_f32 v208, v208, v216, v202
	v_fma_f32 v209, v209, v216, v203
	v_cvt_pk_bf16_f32 v210, v208, v209
	v_lshlrev_b32_e32 v106, 16, v210
	v_and_b32_e32 v107, 0xffff0000, v210
	v_lshlrev_b32_e32 v208, 16, v182
	v_and_b32_e32 v209, 0xffff0000, v182
	v_fma_f32 v208, v208, v216, v204
	v_fma_f32 v209, v209, v216, v205
	v_cvt_pk_bf16_f32 v210, v208, v209
	v_lshlrev_b32_e32 v108, 16, v210
	v_and_b32_e32 v109, 0xffff0000, v210
	v_lshlrev_b32_e32 v208, 16, v183
	v_and_b32_e32 v209, 0xffff0000, v183
	v_fma_f32 v208, v208, v216, v206
	v_fma_f32 v209, v209, v216, v207
	v_cvt_pk_bf16_f32 v210, v208, v209
	v_lshlrev_b32_e32 v110, 16, v210
; __device__ __forceinline__ unsigned pk2(float lo, float hi) { const f32x2 v = {lo, hi}; const bf16x2_t b = __builtin_convertvector(v, bf16x2_t); return __builtin_bit_cast(unsigned, b); }
; __device__ __forceinline__ float bflo(unsigned u) { return __uint_as_float(u << 16); }
; __device__ __forceinline__ float bfhi(unsigned u) { return __uint_as_float(u & 0xffff0000u); }
; __device__ __forceinline__ void peer_tile(const Args& A, LAS unsigned char* lds, int tile) {
;     ...
;     for (int ti = 0; ti < 8; ++ti) {
;         const int tl = 8 * w + ti;
;         const u32x2 e0 = SEL[tl * 128 + lane], e1 = SEL[tl * 128 + 64 + lane];
;         const int p0 = (int)(e0.x >> 10), p1 = (int)(e1.x >> 10);
;         int off = 0;
;         for (int p = 0; p < 16; ++p) {
;             const unsigned long long m0 = __ballot(p0 == p), m1 = __ballot(p1 == p);
;             const int c0 = __popcll(m0), c1 = __popcll(m1);
;             const int r0 = __builtin_amdgcn_mbcnt_hi((unsigned)(m0 >> 32), __builtin_amdgcn_mbcnt_lo((unsigned)m0, 0u));
;     ...
;         for (int tk = 0; tk < 4; ++tk) { const size_t m = (size_t)tile * 64 + tb + tk;
;             { const u32x4 ra = *(const u32x4*)(A3 + m * 1024 + 16 * lane), rb = *(const u32x4*)(A3 + m * 1024 + 16 * lane + 8);
;               float xr_; { const f32x4 p0 = *(const f32x4*)(RSq + m * 16), p1 = *(const f32x4*)(RSq + m * 16 + 4), p2 = *(const f32x4*)(RSq + m * 16 + 8), p3 = *(const f32x4*)(RSq + m * 16 + 12);
;                 const f32x4 ps = (p0 + p1) + (p2 + p3); xr_ = rsqrtf(((ps[0] + ps[1]) + (ps[2] + ps[3])) * (1.f / 1024.f) + 1e-6f); }
;               const unsigned rr[8] = {ra.x, ra.y, ra.z, ra.w, rb.x, rb.y, rb.z, rb.w}; unsigned hh[8];
;               const float* sp = MOD + (int)(m >> 11) * 6144 + 3072 + 16 * lane;
; #pragma unroll
;               for (int q = 0; q < 8; ++q) { const f32x2 sh = *(const f32x2*)(sp + 2 * q); hh[q] = pk2(bflo(rr[q]) * xr_ + sh[0], bfhi(rr[q]) * xr_ + sh[1]); }
;               xpa[tk] = (u32x4){hh[0], hh[1], hh[2], hh[3]}; xpb[tk] = (u32x4){hh[4], hh[5], hh[6], hh[7]}; }
	v_and_b32_e32 v111, 0xffff0000, v210
	v_lshlrev_b32_e32 v208, 16, v184
	v_and_b32_e32 v209, 0xffff0000, v184
	v_fma_f32 v208, v208, v232, v192
	v_fma_f32 v209, v209, v232, v193
	v_cvt_pk_bf16_f32 v210, v208, v209
	v_lshlrev_b32_e32 v112, 16, v210
	v_and_b32_e32 v113, 0xffff0000, v210
	v_lshlrev_b32_e32 v208, 16, v185
	v_and_b32_e32 v209, 0xffff0000, v185
	v_fma_f32 v208, v208, v232, v194
	v_fma_f32 v209, v209, v232, v195
	v_cvt_pk_bf16_f32 v210, v208, v209
	v_lshlrev_b32_e32 v114, 16, v210
	v_and_b32_e32 v115, 0xffff0000, v210
	v_lshlrev_b32_e32 v208, 16, v186
	v_and_b32_e32 v209, 0xffff0000, v186
	v_fma_f32 v208, v208, v232, v196
	v_fma_f32 v209, v209, v232, v197
	v_cvt_pk_bf16_f32 v210, v208, v209
	v_lshlrev_b32_e32 v116, 16, v210
	v_and_b32_e32 v117, 0xffff0000, v210
	v_lshlrev_b32_e32 v208, 16, v187
	v_and_b32_e32 v209, 0xffff0000, v187
	v_fma_f32 v208, v208, v232, v198
	v_fma_f32 v209, v209, v232, v199
	v_cvt_pk_bf16_f32 v210, v208, v209
	v_lshlrev_b32_e32 v118, 16, v210
	v_and_b32_e32 v119, 0xffff0000, v210
	v_lshlrev_b32_e32 v208, 16, v188
	v_and_b32_e32 v209, 0xffff0000, v188
	v_fma_f32 v208, v208, v232, v200
	v_fma_f32 v209, v209, v232, v201
	v_cvt_pk_bf16_f32 v210, v208, v209
	v_lshlrev_b32_e32 v120, 16, v210
	v_and_b32_e32 v121, 0xffff0000, v210
	v_lshlrev_b32_e32 v208, 16, v189
	v_and_b32_e32 v209, 0xffff0000, v189
	v_fma_f32 v208, v208, v232, v202
	v_fma_f32 v209, v209, v232, v203
	v_cvt_pk_bf16_f32 v210, v208, v209
	v_lshlrev_b32_e32 v122, 16, v210
	v_and_b32_e32 v123, 0xffff0000, v210
	v_lshlrev_b32_e32 v208, 16, v190
	v_and_b32_e32 v209, 0xffff0000, v190
	v_fma_f32 v208, v208, v232, v204
	v_fma_f32 v209, v209, v232, v205
	v_cvt_pk_bf16_f32 v210, v208, v209
	v_lshlrev_b32_e32 v124, 16, v210
	v_and_b32_e32 v125, 0xffff0000, v210
	v_lshlrev_b32_e32 v208, 16, v191
	v_and_b32_e32 v209, 0xffff0000, v191
	v_fma_f32 v208, v208, v232, v206
	v_fma_f32 v209, v209, v232, v207
	v_cvt_pk_bf16_f32 v210, v208, v209
	v_lshlrev_b32_e32 v126, 16, v210
	v_and_b32_e32 v127, 0xffff0000, v210
	s_nop 0
	s_mov_b32 s24, s8
	s_and_b32 s25, s9, 0xffff
	s_mov_b32 s26, 0x20000
	s_mov_b32 s27, 0x00027000
	s_lshl_b32 s0, s76, 10
	s_add_i32 s0, s0, 0x11000
	s_sub_i32 s85, s0, s22
	v_mov_b32_e32 v224, 0x7fffffff
	v_mov_b32_e32 v225, 0x7fffffff
	v_mov_b32_e32 v226, 0x7fffffff
	v_mov_b32_e32 v227, 0x7fffffff
	v_mov_b32_e32 v228, 0
	v_mov_b32_e32 v229, 0
	v_mov_b32_e32 v230, 0
	v_mov_b32_e32 v231, 0
	v_add_u32_e32 v232, s22, v240
	ds_write_b128 v232, v[224:227] offset:0
	ds_write_b128 v232, v[228:231] offset:4992
	ds_write_b128 v232, v[224:227] offset:1024
	ds_write_b128 v232, v[228:231] offset:6016
	ds_write_b128 v232, v[224:227] offset:2048
	ds_write_b128 v232, v[228:231] offset:7040
	ds_write_b128 v232, v[224:227] offset:3072
	ds_write_b128 v232, v[228:231] offset:8064
	s_mov_b32 exec_hi, 0x00ffffff
	ds_write_b128 v232, v[224:227] offset:4096
	s_mov_b32 exec_hi, 0x000fffff
	ds_write_b128 v232, v[228:231] offset:9088
	s_mov_b64 exec, -1
	v_lshrrev_b32_e32 v221, 2, v240
	v_add_u32_e32 v221, s22, v221
	ds_write_b32 v221, v228 offset:4224
	v_lshrrev_b32_e32 v233, 1, v240
	s_lshl_b32 s0, s76, 10
	s_add_i32 s0, s0, 0x11000
	v_add_u32_e32 v233, s0, v233
	ds_read_b64 v[128:129], v233 offset:0
	ds_read_b64 v[130:131], v233 offset:512
	ds_read_b64 v[132:133], v233 offset:1024
	ds_read_b64 v[134:135], v233 offset:1536
	ds_read_b64 v[136:137], v233 offset:2048
	ds_read_b64 v[138:139], v233 offset:2560
	ds_read_b64 v[140:141], v233 offset:3072
	ds_read_b64 v[142:143], v233 offset:3584
	ds_read_b64 v[144:145], v233 offset:4096
	ds_read_b64 v[146:147], v233 offset:4608
	ds_read_b64 v[148:149], v233 offset:5120
	ds_read_b64 v[150:151], v233 offset:5632
	ds_read_b64 v[152:153], v233 offset:6144
	ds_read_b64 v[154:155], v233 offset:6656
	ds_read_b64 v[156:157], v233 offset:7168
	ds_read_b64 v[158:159], v233 offset:7680
	v_mov_b32_e32 v220, 1
	v_lshrrev_b32_e32 v200, 4, v240
	v_lshrrev_b32_e32 v201, 3, v200
	v_and_b32_e32 v200, 7, v200
	s_add_i32 s3, s22, 4224
	s_and_b32 s1, s32, 7
	s_waitcnt lgkmcnt(0)
	v_lshrrev_b32_e32 v160, 11, v128
	v_subrev_u32_e32 v160, s1, v160
	v_and_b32_e32 v160, 7, v160
	v_lshl_add_u32 v176, v160, 2, s3
	v_lshrrev_b32_e32 v161, 11, v130
	v_subrev_u32_e32 v161, s1, v161
	v_and_b32_e32 v161, 7, v161
	v_lshl_add_u32 v177, v161, 2, s3
	v_lshrrev_b32_e32 v162, 11, v132
	v_subrev_u32_e32 v162, s1, v162
	v_and_b32_e32 v162, 7, v162
	v_lshl_add_u32 v178, v162, 2, s3
	v_lshrrev_b32_e32 v163, 11, v134
	v_subrev_u32_e32 v163, s1, v163
	v_and_b32_e32 v163, 7, v163
	v_lshl_add_u32 v179, v163, 2, s3
	v_lshrrev_b32_e32 v164, 11, v136
	v_subrev_u32_e32 v164, s1, v164
	v_and_b32_e32 v164, 7, v164
	v_lshl_add_u32 v180, v164, 2, s3
	v_lshrrev_b32_e32 v165, 11, v138
	v_subrev_u32_e32 v165, s1, v165
	v_and_b32_e32 v165, 7, v165
	v_lshl_add_u32 v181, v165, 2, s3
	v_lshrrev_b32_e32 v166, 11, v140
	v_subrev_u32_e32 v166, s1, v166
	v_and_b32_e32 v166, 7, v166
	v_lshl_add_u32 v182, v166, 2, s3
	v_lshrrev_b32_e32 v167, 11, v142
	v_subrev_u32_e32 v167, s1, v167
	v_and_b32_e32 v167, 7, v167
	v_lshl_add_u32 v183, v167, 2, s3
	v_lshrrev_b32_e32 v168, 11, v144
	v_subrev_u32_e32 v168, s1, v168
	v_and_b32_e32 v168, 7, v168
	v_lshl_add_u32 v184, v168, 2, s3
	v_lshrrev_b32_e32 v169, 11, v146
	v_subrev_u32_e32 v169, s1, v169
	v_and_b32_e32 v169, 7, v169
	v_lshl_add_u32 v185, v169, 2, s3
	v_lshrrev_b32_e32 v170, 11, v148
	v_subrev_u32_e32 v170, s1, v170
	v_and_b32_e32 v170, 7, v170
	v_lshl_add_u32 v186, v170, 2, s3
	v_lshrrev_b32_e32 v171, 11, v150
	v_subrev_u32_e32 v171, s1, v171
	v_and_b32_e32 v171, 7, v171
	v_lshl_add_u32 v187, v171, 2, s3
	v_lshrrev_b32_e32 v172, 11, v152
; __device__ __forceinline__ void peer_tile(const Args& A, LAS unsigned char* lds, int tile) {
;     ...
;     for (int ti = 0; ti < 8; ++ti) {
;         const int tl = 8 * w + ti;
;         const u32x2 e0 = SEL[tl * 128 + lane], e1 = SEL[tl * 128 + 64 + lane];
;         const int p0 = (int)(e0.x >> 10), p1 = (int)(e1.x >> 10);
;         int off = 0;
;         for (int p = 0; p < 16; ++p) {
;             const unsigned long long m0 = __ballot(p0 == p), m1 = __ballot(p1 == p);
;             const int c0 = __popcll(m0), c1 = __popcll(m1);
;             const int r0 = __builtin_amdgcn_mbcnt_hi((unsigned)(m0 >> 32), __builtin_amdgcn_mbcnt_lo((unsigned)m0, 0u));
;             const int r1 = __builtin_amdgcn_mbcnt_hi((unsigned)(m1 >> 32), __builtin_amdgcn_mbcnt_lo((unsigned)m1, 0u));
;             if (p0 == p) SORT[tl * 128 + off + r0] = e0;
;             if (p1 == p) SORT[tl * 128 + off + c0 + r1] = e1;
;             if (lane == 0) OFFS[tl * 17 + p] = off;
;             off += c0 + c1;
;         }
;         if (lane == 0) OFFS[tl * 17 + 16] = off;
	v_subrev_u32_e32 v172, s1, v172
	v_and_b32_e32 v172, 7, v172
	v_lshl_add_u32 v188, v172, 2, s3
	v_lshrrev_b32_e32 v173, 11, v154
	v_subrev_u32_e32 v173, s1, v173
	v_and_b32_e32 v173, 7, v173
	v_lshl_add_u32 v189, v173, 2, s3
	v_lshrrev_b32_e32 v174, 11, v156
	v_subrev_u32_e32 v174, s1, v174
	v_and_b32_e32 v174, 7, v174
	v_lshl_add_u32 v190, v174, 2, s3
	v_lshrrev_b32_e32 v175, 11, v158
	v_subrev_u32_e32 v175, s1, v175
	v_and_b32_e32 v175, 7, v175
	v_lshl_add_u32 v191, v175, 2, s3
	v_lshlrev_b32_e32 v206, 3, v128
	buffer_load_dwordx2 v[224:225], v206, s[24:27], 0 offen
	v_lshlrev_b32_e32 v206, 3, v130
	buffer_load_dwordx2 v[226:227], v206, s[24:27], 0 offen
	v_lshlrev_b32_e32 v206, 3, v132
	buffer_load_dwordx2 v[228:229], v206, s[24:27], 0 offen
	v_lshlrev_b32_e32 v206, 3, v134
	buffer_load_dwordx2 v[230:231], v206, s[24:27], 0 offen
	v_lshlrev_b32_e32 v206, 3, v136
	buffer_load_dwordx2 v[232:233], v206, s[24:27], 0 offen
	v_lshlrev_b32_e32 v206, 3, v138
	buffer_load_dwordx2 v[234:235], v206, s[24:27], 0 offen
	v_lshlrev_b32_e32 v206, 3, v140
	buffer_load_dwordx2 v[236:237], v206, s[24:27], 0 offen
	v_lshlrev_b32_e32 v206, 3, v142
	buffer_load_dwordx2 v[238:239], v206, s[24:27], 0 offen
	v_lshlrev_b32_e32 v206, 3, v144
	buffer_load_dwordx2 v[248:249], v206, s[24:27], 0 offen
	v_lshlrev_b32_e32 v206, 3, v146
	buffer_load_dwordx2 v[250:251], v206, s[24:27], 0 offen
	v_lshlrev_b32_e32 v206, 3, v148
	buffer_load_dwordx2 v[252:253], v206, s[24:27], 0 offen
	v_lshlrev_b32_e32 v206, 3, v150
	buffer_load_dwordx2 v[254:255], v206, s[24:27], 0 offen
	ds_add_rtn_u32 v176, v176, v220 offset:0
	ds_add_rtn_u32 v177, v177, v220 offset:0
	ds_add_rtn_u32 v178, v178, v220 offset:32
	ds_add_rtn_u32 v179, v179, v220 offset:32
	ds_add_rtn_u32 v180, v180, v220 offset:64
	ds_add_rtn_u32 v181, v181, v220 offset:64
	ds_add_rtn_u32 v182, v182, v220 offset:96
	ds_add_rtn_u32 v183, v183, v220 offset:96
	ds_add_rtn_u32 v184, v184, v220 offset:128
	ds_add_rtn_u32 v185, v185, v220 offset:128
	ds_add_rtn_u32 v186, v186, v220 offset:160
	ds_add_rtn_u32 v187, v187, v220 offset:160
	ds_add_rtn_u32 v188, v188, v220 offset:192
	ds_add_rtn_u32 v189, v189, v220 offset:192
	ds_add_rtn_u32 v190, v190, v220 offset:224
	ds_add_rtn_u32 v191, v191, v220 offset:224
	v_lshl_add_u32 v207, v201, 5, s3
	ds_read_b32 v203, v221 offset:4224
	ds_read_b128 v[192:195], v207
	ds_read_b128 v[196:199], v207 offset:16
	v_mov_b32_e32 v202, 0
	s_waitcnt lgkmcnt(0)
	v_cmp_lt_u32_e64 s[38:39], 0, v200
	v_cmp_lt_u32_e64 s[40:41], 1, v200
	v_cmp_lt_u32_e64 s[42:43], 2, v200
	v_cmp_lt_u32_e64 s[44:45], 3, v200
	v_cmp_lt_u32_e64 s[64:65], 4, v200
	v_cmp_lt_u32_e64 s[66:67], 5, v200
	v_cmp_lt_u32_e64 s[94:95], 6, v200
	v_cndmask_b32_e64 v206, 0, v192, s[38:39]
	v_add_u32_e32 v202, v202, v206
	v_cndmask_b32_e64 v206, 0, v193, s[40:41]
	v_add_u32_e32 v202, v202, v206
	v_cndmask_b32_e64 v206, 0, v194, s[42:43]
	v_add_u32_e32 v202, v202, v206
	v_cndmask_b32_e64 v206, 0, v195, s[44:45]
	v_add_u32_e32 v202, v202, v206
	v_cndmask_b32_e64 v206, 0, v196, s[64:65]
	v_add_u32_e32 v202, v202, v206
	v_cndmask_b32_e64 v206, 0, v197, s[66:67]
	v_add_u32_e32 v202, v202, v206
	v_cndmask_b32_e64 v206, 0, v198, s[94:95]
	v_add_u32_e32 v202, v202, v206
	v_add_u32_e32 v204, 3, v202
	v_add3_u32 v212, v202, v203, 3
	v_lshrrev_b32_e32 v204, 2, v204
	v_lshrrev_b32_e32 v212, 2, v212
	v_sub_u32_e32 v212, v212, v204
	v_lshl_add_u32 v207, v200, 3, v201
	v_lshl_add_u32 v207, v207, 2, s3
	ds_write_b32 v207, v212 offset:256
	v_lshl_add_u32 v208, v200, 5, s3
	ds_read_b128 v[192:195], v208 offset:256
	ds_read_b128 v[196:199], v208 offset:272
	v_mov_b32_e32 v205, 0
	s_waitcnt lgkmcnt(0)
	v_cmp_lt_u32_e64 s[38:39], 0, v201
	v_cmp_lt_u32_e64 s[40:41], 1, v201
	v_cmp_lt_u32_e64 s[42:43], 2, v201
	v_cmp_lt_u32_e64 s[44:45], 3, v201
	v_cmp_lt_u32_e64 s[64:65], 4, v201
	v_cmp_lt_u32_e64 s[66:67], 5, v201
	v_cmp_lt_u32_e64 s[94:95], 6, v201
	v_cndmask_b32_e64 v206, 0, v192, s[38:39]
	v_add_u32_e32 v205, v205, v206
	v_cndmask_b32_e64 v206, 0, v193, s[40:41]
	v_add_u32_e32 v205, v205, v206
	v_cndmask_b32_e64 v206, 0, v194, s[42:43]
	v_add_u32_e32 v205, v205, v206
	v_cndmask_b32_e64 v206, 0, v195, s[44:45]
	v_add_u32_e32 v205, v205, v206
	v_cndmask_b32_e64 v206, 0, v196, s[64:65]
	v_add_u32_e32 v205, v205, v206
	v_cndmask_b32_e64 v206, 0, v197, s[66:67]
	v_add_u32_e32 v205, v205, v206
	v_cndmask_b32_e64 v206, 0, v198, s[94:95]
	v_add_u32_e32 v205, v205, v206
	v_add_u32_e32 v206, v192, v193
	v_add_u32_e32 v206, v206, v194
	v_add_u32_e32 v206, v206, v195
	v_add_u32_e32 v206, v206, v196
	v_add_u32_e32 v206, v206, v197
	v_add_u32_e32 v206, v206, v198
	v_add_u32_e32 v206, v206, v199
	v_lshl_add_u32 v207, v200, 2, s3
	ds_write_b32 v207, v206 offset:512
	v_mov_b32_e32 v207, s3
	ds_read_b128 v[192:195], v207 offset:512
	ds_read_b128 v[196:199], v207 offset:528
	ds_write_b32 v221, v202 offset:4224
	s_waitcnt lgkmcnt(0)
	v_cmp_lt_u32_e64 s[38:39], 0, v200
	v_cmp_lt_u32_e64 s[40:41], 1, v200
	v_cmp_lt_u32_e64 s[42:43], 2, v200
	v_cmp_lt_u32_e64 s[44:45], 3, v200
	v_cmp_lt_u32_e64 s[64:65], 4, v200
	v_cmp_lt_u32_e64 s[66:67], 5, v200
	v_cmp_lt_u32_e64 s[94:95], 6, v200
	v_cndmask_b32_e64 v206, 0, v192, s[38:39]
	v_add_u32_e32 v205, v205, v206
	v_cndmask_b32_e64 v206, 0, v193, s[40:41]
	v_add_u32_e32 v205, v205, v206
	v_cndmask_b32_e64 v206, 0, v194, s[42:43]
	v_add_u32_e32 v205, v205, v206
	v_cndmask_b32_e64 v206, 0, v195, s[44:45]
	v_add_u32_e32 v205, v205, v206
	v_cndmask_b32_e64 v206, 0, v196, s[64:65]
	v_add_u32_e32 v205, v205, v206
	v_cndmask_b32_e64 v206, 0, v197, s[66:67]
	v_add_u32_e32 v205, v205, v206
	v_cndmask_b32_e64 v206, 0, v198, s[94:95]
	v_add_u32_e32 v205, v205, v206
	v_sub_u32_e32 v205, v205, v204
	v_lshrrev_b32_e32 v208, 4, v240
	v_and_b32_e32 v222, 31, v208
	v_lshrrev_b32_e32 v208, 5, v208
	v_add_u32_e32 v207, 0, v208
	v_lshl_add_u32 v206, v207, 5, s3
	ds_read_b128 v[192:195], v206
	ds_read_b128 v[196:199], v206 offset:16
	v_lshlrev_b32_e32 v206, 2, v222
	v_lshlrev_b32_e32 v223, 3, v207
	s_waitcnt lgkmcnt(0)
; __device__ __forceinline__ void peer_tile(const Args& A, LAS unsigned char* lds, int tile) {
;     ...
;     for (int ti = 0; ti < 8; ++ti) {
;         const int tl = 8 * w + ti;
;         const u32x2 e0 = SEL[tl * 128 + lane], e1 = SEL[tl * 128 + 64 + lane];
;         const int p0 = (int)(e0.x >> 10), p1 = (int)(e1.x >> 10);
;         int off = 0;
;         for (int p = 0; p < 16; ++p) {
;             const unsigned long long m0 = __ballot(p0 == p), m1 = __ballot(p1 == p);
;             const int c0 = __popcll(m0), c1 = __popcll(m1);
;             const int r0 = __builtin_amdgcn_mbcnt_hi((unsigned)(m0 >> 32), __builtin_amdgcn_mbcnt_lo((unsigned)m0, 0u));
;             const int r1 = __builtin_amdgcn_mbcnt_hi((unsigned)(m1 >> 32), __builtin_amdgcn_mbcnt_lo((unsigned)m1, 0u));
;             if (p0 == p) SORT[tl * 128 + off + r0] = e0;
;             if (p1 == p) SORT[tl * 128 + off + c0 + r1] = e1;
;             if (lane == 0) OFFS[tl * 17 + p] = off;
;             off += c0 + c1;
;         }
;         if (lane == 0) OFFS[tl * 17 + 16] = off;
	v_cmp_le_u32_e64 s[38:39], v193, v206
	v_cmp_le_u32_e64 s[40:41], v194, v206
	v_cmp_le_u32_e64 s[42:43], v195, v206
	v_cmp_le_u32_e64 s[44:45], v196, v206
	v_cmp_le_u32_e64 s[64:65], v197, v206
	v_cmp_le_u32_e64 s[66:67], v198, v206
	v_cmp_le_u32_e64 s[94:95], v199, v206
	v_addc_co_u32_e64 v223, s[92:93], 0, v223, s[38:39]
	v_addc_co_u32_e64 v223, s[92:93], 0, v223, s[40:41]
	v_addc_co_u32_e64 v223, s[92:93], 0, v223, s[42:43]
	v_addc_co_u32_e64 v223, s[92:93], 0, v223, s[44:45]
	v_addc_co_u32_e64 v223, s[92:93], 0, v223, s[64:65]
	v_addc_co_u32_e64 v223, s[92:93], 0, v223, s[66:67]
	v_addc_co_u32_e64 v223, s[92:93], 0, v223, s[94:95]
	v_lshlrev_b32_e32 v223, 2, v223
	ds_bpermute_b32 v216, v223, v205
	v_add_u32_e32 v207, 2, v208
	v_lshl_add_u32 v206, v207, 5, s3
	ds_read_b128 v[192:195], v206
	ds_read_b128 v[196:199], v206 offset:16
	v_lshlrev_b32_e32 v206, 2, v222
	v_lshlrev_b32_e32 v223, 3, v207
	s_waitcnt lgkmcnt(0)
	v_cmp_le_u32_e64 s[38:39], v193, v206
	v_cmp_le_u32_e64 s[40:41], v194, v206
	v_cmp_le_u32_e64 s[42:43], v195, v206
	v_cmp_le_u32_e64 s[44:45], v196, v206
	v_cmp_le_u32_e64 s[64:65], v197, v206
	v_cmp_le_u32_e64 s[66:67], v198, v206
	v_cmp_le_u32_e64 s[94:95], v199, v206
	v_addc_co_u32_e64 v223, s[92:93], 0, v223, s[38:39]
	v_addc_co_u32_e64 v223, s[92:93], 0, v223, s[40:41]
	v_addc_co_u32_e64 v223, s[92:93], 0, v223, s[42:43]
	v_addc_co_u32_e64 v223, s[92:93], 0, v223, s[44:45]
	v_addc_co_u32_e64 v223, s[92:93], 0, v223, s[64:65]
	v_addc_co_u32_e64 v223, s[92:93], 0, v223, s[66:67]
	v_addc_co_u32_e64 v223, s[92:93], 0, v223, s[94:95]
	v_lshlrev_b32_e32 v223, 2, v223
	ds_bpermute_b32 v217, v223, v205
	v_add_u32_e32 v207, 4, v208
	v_lshl_add_u32 v206, v207, 5, s3
	ds_read_b128 v[192:195], v206
	ds_read_b128 v[196:199], v206 offset:16
	v_lshlrev_b32_e32 v206, 2, v222
	v_lshlrev_b32_e32 v223, 3, v207
	s_waitcnt lgkmcnt(0)
	v_cmp_le_u32_e64 s[38:39], v193, v206
	v_cmp_le_u32_e64 s[40:41], v194, v206
	v_cmp_le_u32_e64 s[42:43], v195, v206
	v_cmp_le_u32_e64 s[44:45], v196, v206
	v_cmp_le_u32_e64 s[64:65], v197, v206
	v_cmp_le_u32_e64 s[66:67], v198, v206
	v_cmp_le_u32_e64 s[94:95], v199, v206
	v_addc_co_u32_e64 v223, s[92:93], 0, v223, s[38:39]
	v_addc_co_u32_e64 v223, s[92:93], 0, v223, s[40:41]
	v_addc_co_u32_e64 v223, s[92:93], 0, v223, s[42:43]
	v_addc_co_u32_e64 v223, s[92:93], 0, v223, s[44:45]
	v_addc_co_u32_e64 v223, s[92:93], 0, v223, s[64:65]
	v_addc_co_u32_e64 v223, s[92:93], 0, v223, s[66:67]
	v_addc_co_u32_e64 v223, s[92:93], 0, v223, s[94:95]
	v_lshlrev_b32_e32 v223, 2, v223
	ds_bpermute_b32 v218, v223, v205
	v_add_u32_e32 v207, 6, v208
	v_lshl_add_u32 v206, v207, 5, s3
	ds_read_b128 v[192:195], v206
	ds_read_b128 v[196:199], v206 offset:16
	v_lshlrev_b32_e32 v206, 2, v222
	v_lshlrev_b32_e32 v223, 3, v207
	s_waitcnt lgkmcnt(0)
	v_cmp_le_u32_e64 s[38:39], v193, v206
	v_cmp_le_u32_e64 s[40:41], v194, v206
	v_cmp_le_u32_e64 s[42:43], v195, v206
	v_cmp_le_u32_e64 s[44:45], v196, v206
	v_cmp_le_u32_e64 s[64:65], v197, v206
	v_cmp_le_u32_e64 s[66:67], v198, v206
	v_cmp_le_u32_e64 s[94:95], v199, v206
	v_addc_co_u32_e64 v223, s[92:93], 0, v223, s[38:39]
	v_addc_co_u32_e64 v223, s[92:93], 0, v223, s[40:41]
	v_addc_co_u32_e64 v223, s[92:93], 0, v223, s[42:43]
	v_addc_co_u32_e64 v223, s[92:93], 0, v223, s[44:45]
	v_addc_co_u32_e64 v223, s[92:93], 0, v223, s[64:65]
	v_addc_co_u32_e64 v223, s[92:93], 0, v223, s[66:67]
	v_addc_co_u32_e64 v223, s[92:93], 0, v223, s[94:95]
	v_lshlrev_b32_e32 v223, 2, v223
	ds_bpermute_b32 v219, v223, v205
	s_waitcnt lgkmcnt(0)
	v_add_u32_e32 v216, v216, v222
	v_add_u32_e32 v217, v217, v222
	v_add_u32_e32 v218, v218, v222
	v_add_u32_e32 v219, v219, v222
	v_lshlrev_b32_e32 v206, 3, v152
	buffer_load_dwordx2 v[192:193], v206, s[24:27], 0 offen
	v_lshlrev_b32_e32 v206, 3, v154
	buffer_load_dwordx2 v[194:195], v206, s[24:27], 0 offen
	v_lshlrev_b32_e32 v206, 3, v156
	buffer_load_dwordx2 v[196:197], v206, s[24:27], 0 offen
	v_lshlrev_b32_e32 v206, 3, v158
	buffer_load_dwordx2 v[198:199], v206, s[24:27], 0 offen
	v_lshlrev_b32_e32 v160, 2, v160
	ds_bpermute_b32 v160, v160, v202
	v_lshlrev_b32_e32 v161, 2, v161
	ds_bpermute_b32 v161, v161, v202
	v_lshlrev_b32_e32 v162, 2, v162
	v_add_u32_e32 v162, 32, v162
	ds_bpermute_b32 v162, v162, v202
	v_lshlrev_b32_e32 v163, 2, v163
	v_add_u32_e32 v163, 32, v163
	ds_bpermute_b32 v163, v163, v202
	v_lshlrev_b32_e32 v164, 2, v164
	v_add_u32_e32 v164, 64, v164
	ds_bpermute_b32 v164, v164, v202
	v_lshlrev_b32_e32 v165, 2, v165
	v_add_u32_e32 v165, 64, v165
	ds_bpermute_b32 v165, v165, v202
	v_lshlrev_b32_e32 v166, 2, v166
	v_add_u32_e32 v166, 96, v166
	ds_bpermute_b32 v166, v166, v202
	v_lshlrev_b32_e32 v167, 2, v167
	v_add_u32_e32 v167, 96, v167
	ds_bpermute_b32 v167, v167, v202
	v_lshlrev_b32_e32 v168, 2, v168
	v_add_u32_e32 v168, 128, v168
	ds_bpermute_b32 v168, v168, v202
	v_lshlrev_b32_e32 v169, 2, v169
	v_add_u32_e32 v169, 128, v169
	ds_bpermute_b32 v169, v169, v202
	v_lshlrev_b32_e32 v170, 2, v170
	v_add_u32_e32 v170, 160, v170
	ds_bpermute_b32 v170, v170, v202
	v_lshlrev_b32_e32 v171, 2, v171
	v_add_u32_e32 v171, 160, v171
	ds_bpermute_b32 v171, v171, v202
	v_lshlrev_b32_e32 v172, 2, v172
	v_add_u32_e32 v172, 192, v172
	ds_bpermute_b32 v172, v172, v202
	v_lshlrev_b32_e32 v173, 2, v173
	v_add_u32_e32 v173, 192, v173
	ds_bpermute_b32 v173, v173, v202
	v_lshlrev_b32_e32 v174, 2, v174
	v_add_u32_e32 v174, 224, v174
	ds_bpermute_b32 v174, v174, v202
	v_lshlrev_b32_e32 v175, 2, v175
	v_add_u32_e32 v175, 224, v175
	ds_bpermute_b32 v175, v175, v202
	s_waitcnt lgkmcnt(0)
; __device__ __forceinline__ void peer_tile(const Args& A, LAS unsigned char* lds, int tile) {
;     ...
;             if (p0 == p) SORT[tl * 128 + off + r0] = e0;
;             if (p1 == p) SORT[tl * 128 + off + c0 + r1] = e1;
	v_add_u32_e32 v176, v176, v160
	v_lshrrev_b32_e32 v160, 2, v176
	v_and_b32_e32 v176, 3, v176
	v_lshlrev_b32_e32 v160, 2, v160
	ds_bpermute_b32 v160, v160, v216
	v_add_u32_e32 v177, v177, v161
	v_lshrrev_b32_e32 v161, 2, v177
	v_and_b32_e32 v177, 3, v177
	v_lshlrev_b32_e32 v161, 2, v161
	ds_bpermute_b32 v161, v161, v216
	v_add_u32_e32 v178, v178, v162
	v_lshrrev_b32_e32 v162, 2, v178
	v_and_b32_e32 v178, 3, v178
	v_lshlrev_b32_e32 v162, 2, v162
	v_add_u32_e32 v162, 128, v162
	ds_bpermute_b32 v162, v162, v216
	v_add_u32_e32 v179, v179, v163
	v_lshrrev_b32_e32 v163, 2, v179
	v_and_b32_e32 v179, 3, v179
	v_lshlrev_b32_e32 v163, 2, v163
	v_add_u32_e32 v163, 128, v163
	ds_bpermute_b32 v163, v163, v216
	v_add_u32_e32 v180, v180, v164
	v_lshrrev_b32_e32 v164, 2, v180
	v_and_b32_e32 v180, 3, v180
	v_lshlrev_b32_e32 v164, 2, v164
	ds_bpermute_b32 v164, v164, v217
	v_add_u32_e32 v181, v181, v165
	v_lshrrev_b32_e32 v165, 2, v181
	v_and_b32_e32 v181, 3, v181
	v_lshlrev_b32_e32 v165, 2, v165
	ds_bpermute_b32 v165, v165, v217
	v_add_u32_e32 v182, v182, v166
	v_lshrrev_b32_e32 v166, 2, v182
	v_and_b32_e32 v182, 3, v182
	v_lshlrev_b32_e32 v166, 2, v166
	v_add_u32_e32 v166, 128, v166
	ds_bpermute_b32 v166, v166, v217
	v_add_u32_e32 v183, v183, v167
	v_lshrrev_b32_e32 v167, 2, v183
	v_and_b32_e32 v183, 3, v183
	v_lshlrev_b32_e32 v167, 2, v167
	v_add_u32_e32 v167, 128, v167
	ds_bpermute_b32 v167, v167, v217
	v_add_u32_e32 v184, v184, v168
	v_lshrrev_b32_e32 v168, 2, v184
	v_and_b32_e32 v184, 3, v184
	v_lshlrev_b32_e32 v168, 2, v168
	ds_bpermute_b32 v168, v168, v218
	v_add_u32_e32 v185, v185, v169
	v_lshrrev_b32_e32 v169, 2, v185
	v_and_b32_e32 v185, 3, v185
	v_lshlrev_b32_e32 v169, 2, v169
	ds_bpermute_b32 v169, v169, v218
	v_add_u32_e32 v186, v186, v170
	v_lshrrev_b32_e32 v170, 2, v186
	v_and_b32_e32 v186, 3, v186
	v_lshlrev_b32_e32 v170, 2, v170
	v_add_u32_e32 v170, 128, v170
	ds_bpermute_b32 v170, v170, v218
	v_add_u32_e32 v187, v187, v171
	v_lshrrev_b32_e32 v171, 2, v187
	v_and_b32_e32 v187, 3, v187
	v_lshlrev_b32_e32 v171, 2, v171
	v_add_u32_e32 v171, 128, v171
	ds_bpermute_b32 v171, v171, v218
	v_add_u32_e32 v188, v188, v172
	v_lshrrev_b32_e32 v172, 2, v188
	v_and_b32_e32 v188, 3, v188
	v_lshlrev_b32_e32 v172, 2, v172
	ds_bpermute_b32 v172, v172, v219
	v_add_u32_e32 v189, v189, v173
	v_lshrrev_b32_e32 v173, 2, v189
	v_and_b32_e32 v189, 3, v189
	v_lshlrev_b32_e32 v173, 2, v173
	ds_bpermute_b32 v173, v173, v219
	v_add_u32_e32 v190, v190, v174
	v_lshrrev_b32_e32 v174, 2, v190
	v_and_b32_e32 v190, 3, v190
	v_lshlrev_b32_e32 v174, 2, v174
	v_add_u32_e32 v174, 128, v174
	ds_bpermute_b32 v174, v174, v219
	v_add_u32_e32 v191, v191, v175
	v_lshrrev_b32_e32 v175, 2, v191
	v_and_b32_e32 v191, 3, v191
	v_lshlrev_b32_e32 v175, 2, v175
	v_add_u32_e32 v175, 128, v175
	ds_bpermute_b32 v175, v175, v219
	s_waitcnt lgkmcnt(0)
	v_lshl_add_u32 v160, v160, 4, s22
	v_lshl_add_u32 v160, v176, 2, v160
	ds_write_b32 v160, v128
	ds_write_b32 v160, v129 offset:4992
	v_lshl_add_u32 v161, v161, 4, s22
	v_lshl_add_u32 v161, v177, 2, v161
	ds_write_b32 v161, v130
	ds_write_b32 v161, v131 offset:4992
	v_lshl_add_u32 v162, v162, 4, s22
	v_lshl_add_u32 v162, v178, 2, v162
	ds_write_b32 v162, v132
	ds_write_b32 v162, v133 offset:4992
	v_lshl_add_u32 v163, v163, 4, s22
	v_lshl_add_u32 v163, v179, 2, v163
	ds_write_b32 v163, v134
	ds_write_b32 v163, v135 offset:4992
	v_lshl_add_u32 v164, v164, 4, s22
	v_lshl_add_u32 v164, v180, 2, v164
	ds_write_b32 v164, v136
	ds_write_b32 v164, v137 offset:4992
	v_lshl_add_u32 v165, v165, 4, s22
	v_lshl_add_u32 v165, v181, 2, v165
	ds_write_b32 v165, v138
	ds_write_b32 v165, v139 offset:4992
	v_lshl_add_u32 v166, v166, 4, s22
	v_lshl_add_u32 v166, v182, 2, v166
	ds_write_b32 v166, v140
	ds_write_b32 v166, v141 offset:4992
	v_lshl_add_u32 v167, v167, 4, s22
	v_lshl_add_u32 v167, v183, 2, v167
	ds_write_b32 v167, v142
	ds_write_b32 v167, v143 offset:4992
	v_lshl_add_u32 v168, v168, 4, s22
	v_lshl_add_u32 v168, v184, 2, v168
	ds_write_b32 v168, v144
	ds_write_b32 v168, v145 offset:4992
	v_lshl_add_u32 v169, v169, 4, s22
	v_lshl_add_u32 v169, v185, 2, v169
	ds_write_b32 v169, v146
	ds_write_b32 v169, v147 offset:4992
	v_lshl_add_u32 v170, v170, 4, s22
	v_lshl_add_u32 v170, v186, 2, v170
	ds_write_b32 v170, v148
	ds_write_b32 v170, v149 offset:4992
	v_lshl_add_u32 v171, v171, 4, s22
	v_lshl_add_u32 v171, v187, 2, v171
	ds_write_b32 v171, v150
	ds_write_b32 v171, v151 offset:4992
	v_lshl_add_u32 v172, v172, 4, s22
	v_lshl_add_u32 v172, v188, 2, v172
	ds_write_b32 v172, v152
	ds_write_b32 v172, v153 offset:4992
	v_lshl_add_u32 v173, v173, 4, s22
	v_lshl_add_u32 v173, v189, 2, v173
	ds_write_b32 v173, v154
	ds_write_b32 v173, v155 offset:4992
	v_lshl_add_u32 v174, v174, 4, s22
	v_lshl_add_u32 v174, v190, 2, v174
	ds_write_b32 v174, v156
	ds_write_b32 v174, v157 offset:4992
	v_lshl_add_u32 v175, v175, 4, s22
	v_lshl_add_u32 v175, v191, 2, v175
	ds_write_b32 v175, v158
	ds_write_b32 v175, v159 offset:4992
	s_waitcnt vmcnt(0)
; #define IT_ADVANCE() do { it_j += 4; while (it_j >= it_end) { if (it_done) break; ++it_tk; if (it_tk == 4) { it_tk = 0; ++it_p; if (it_p == 16) { it_done = true; it_p = 15; it_j = 0; it_end = 1; break; } } \
;             it_j = __builtin_amdgcn_readfirstlane(OFFS[(tb + it_tk) * 17 + it_p]); it_end = __builtin_amdgcn_readfirstlane(OFFS[(tb + it_tk) * 17 + it_p + 1]); } } while (0)
; __device__ __forceinline__ void peer_tile(const Args& A, LAS unsigned char* lds, int tile) {
;     ...
;         int it_p = 0, it_tk = -1, it_j = 0, it_end = 0; bool it_done = false;
;     ...
;         u32x4 uA[4], vA[4], uB[4], vB[4]; float cgA = 0.f, suA = 0.f, svA = 0.f, cgB = 0.f, suB = 0.f, svB = 0.f;
; #pragma unroll
;         for (int k = 0; k < 4; ++k) { uA[k] = (u32x4){0u, 0u, 0u, 0u}; vA[k] = uA[k]; uB[k] = uA[k]; vB[k] = uA[k]; }
;         IT_ADVANCE();
;         LOAD_SET(uA, vA, cgA, suA, svA);
	v_add_u32_e32 v160, s85, v160
	ds_write_b32 v160, v224
	ds_write_b32 v160, v225 offset:4096
	v_add_u32_e32 v161, s85, v161
	ds_write_b32 v161, v226
	ds_write_b32 v161, v227 offset:4096
	v_add_u32_e32 v162, s85, v162
	ds_write_b32 v162, v228
	ds_write_b32 v162, v229 offset:4096
	v_add_u32_e32 v163, s85, v163
	ds_write_b32 v163, v230
	ds_write_b32 v163, v231 offset:4096
	v_add_u32_e32 v164, s85, v164
	ds_write_b32 v164, v232
	ds_write_b32 v164, v233 offset:4096
	v_add_u32_e32 v165, s85, v165
	ds_write_b32 v165, v234
	ds_write_b32 v165, v235 offset:4096
	v_add_u32_e32 v166, s85, v166
	ds_write_b32 v166, v236
	ds_write_b32 v166, v237 offset:4096
	v_add_u32_e32 v167, s85, v167
	ds_write_b32 v167, v238
	ds_write_b32 v167, v239 offset:4096
	v_add_u32_e32 v168, s85, v168
	ds_write_b32 v168, v248
	ds_write_b32 v168, v249 offset:4096
	v_add_u32_e32 v169, s85, v169
	ds_write_b32 v169, v250
	ds_write_b32 v169, v251 offset:4096
	v_add_u32_e32 v170, s85, v170
	ds_write_b32 v170, v252
	ds_write_b32 v170, v253 offset:4096
	v_add_u32_e32 v171, s85, v171
	ds_write_b32 v171, v254
	ds_write_b32 v171, v255 offset:4096
	v_add_u32_e32 v172, s85, v172
	ds_write_b32 v172, v192
	ds_write_b32 v172, v193 offset:4096
	v_add_u32_e32 v173, s85, v173
	ds_write_b32 v173, v194
	ds_write_b32 v173, v195 offset:4096
	v_add_u32_e32 v174, s85, v174
	ds_write_b32 v174, v196
	ds_write_b32 v174, v197 offset:4096
	v_add_u32_e32 v175, s85, v175
	ds_write_b32 v175, v198
	ds_write_b32 v175, v199 offset:4096
	v_mov_b32_e32 v206, 0x7fffffff
	ds_write_b32 v221, v206 offset:4224
	ds_write_b32 v221, v206 offset:4480
	ds_write_b32 v221, v206 offset:4736
	s_mov_b32 s91, 256
	s_add_i32 s20, s91, 3
	s_and_b32 s20, s20, -4
	s_mov_b32 s24, s8
	s_and_b32 s25, s9, 0xffff
	s_mov_b32 s26, 0x20000
	s_mov_b32 s27, 0x00027000
	s_mov_b32 s28, s52
	s_and_b32 s29, s53, 0xffff
	s_mov_b32 s30, 0x20000
	s_mov_b32 s31, 0x00027000
	s_waitcnt vmcnt(0) lgkmcnt(0)
	v_mov_b32_e32 v213, s22
	v_mov_b32_e32 v233, v240
	v_mov_b32_e32 v235, v240
	v_mov_b32_e32 v237, v240
	v_mov_b32_e32 v239, v240
	ds_read_b32 v232, v213 offset:0
	ds_read_b32 v234, v213 offset:4
	ds_read_b32 v236, v213 offset:8
	ds_read_b32 v238, v213 offset:12
	s_waitcnt lgkmcnt(0)
	buffer_load_dwordx4 v[128:131], v[232:233], s[56:59], 0 idxen offen
	buffer_load_dwordx4 v[132:135], v[234:235], s[56:59], 0 idxen offen
	buffer_load_dwordx4 v[136:139], v[236:237], s[56:59], 0 idxen offen
	buffer_load_dwordx4 v[140:143], v[238:239], s[56:59], 0 idxen offen
	ds_read_b32 v232, v213 offset:16
	ds_read_b32 v234, v213 offset:20
	ds_read_b32 v236, v213 offset:24
	ds_read_b32 v238, v213 offset:28
	s_waitcnt lgkmcnt(0)
	buffer_load_dwordx4 v[144:147], v[232:233], s[56:59], 0 idxen offen
	buffer_load_dwordx4 v[148:151], v[234:235], s[56:59], 0 idxen offen
	buffer_load_dwordx4 v[152:155], v[236:237], s[56:59], 0 idxen offen
	buffer_load_dwordx4 v[156:159], v[238:239], s[56:59], 0 idxen offen
	ds_read_b32 v232, v213 offset:32
	ds_read_b32 v234, v213 offset:36
	ds_read_b32 v236, v213 offset:40
	ds_read_b32 v238, v213 offset:44
	s_waitcnt lgkmcnt(0)
	buffer_load_dwordx4 v[160:163], v[232:233], s[56:59], 0 idxen offen
	buffer_load_dwordx4 v[164:167], v[234:235], s[56:59], 0 idxen offen
	buffer_load_dwordx4 v[168:171], v[236:237], s[56:59], 0 idxen offen
	buffer_load_dwordx4 v[172:175], v[238:239], s[56:59], 0 idxen offen
	ds_read_b32 v232, v213 offset:48
	ds_read_b32 v234, v213 offset:52
	ds_read_b32 v236, v213 offset:56
	ds_read_b32 v238, v213 offset:60
	s_mov_b32 s21, 0
	s_mov_b32 s89, -1
	s_mov_b32 s86, 0
	v_lshrrev_b32_e32 v208, 6, v240
	v_and_b32_e32 v208, 3, v208
	v_lshrrev_b32_e32 v209, 1, v208
	v_lshlrev_b32_e32 v208, 1, v208
	v_and_b32_e32 v208, 2, v208
	v_or_b32_e32 v208, v208, v209
	v_lshlrev_b32_e32 v208, 2, v208
	v_add3_u32 v211, v208, v247, s22
	v_add_u32_e32 v250, s85, v211
	ds_read_b32 v252, v250
	ds_read_b32 v253, v250 offset:4096
	ds_read_b32 v249, v211 offset:4992
	s_branch .LU_sw0
